# gdn_intra: conv masking via v_cndmask instead of per-element exec diamonds; Timg/T22f writes as straight-line masked stores; remaining epilogue divisions via rcp+Newton+fixup
# baseline (speedup 1.0000x reference)
; DI int TID() { int t = __builtin_amdgcn_workitem_id_x(); asm volatile("" : "+v"(t)); return t; }
; DI void unpack8(u32x4 w, float* f) { f[0] = bflo(w.x); f[1] = bfhi(w.x); f[2] = bflo(w.y); f[3] = bfhi(w.y); f[4] = bflo(w.z); f[5] = bfhi(w.z); f[6] = bflo(w.w); f[7] = bfhi(w.w); }
; DI u32x4 pack8(const float* f) { u32x4 w; w.x = pk2(f[0], f[1]); w.y = pk2(f[2], f[3]); w.z = pk2(f[4], f[5]); w.w = pk2(f[6], f[7]); return w; }
; DI float siluf_(float x) { return x / (1.f + __expf(-x)); }
; DI void phase_normgate(PP p, int l, int nblk, int bid) {
;     bf16_t* obf = (bf16_t*)(p->ws + O_OBF); const bf16_t* z = (const bf16_t*)(p->ws + O_Z);
;     const int o8 = TID() & 15;
;     const f32x4 w0 = *(const f32x4*)(p->in[18] + l * 128 + o8 * 8), w1 = *(const f32x4*)(p->in[18] + l * 128 + o8 * 8 + 4);
;     for (int grp0 = bid * 128 + (TID() >> 4); grp0 < L * 8; grp0 += nblk * 128) {
;         u32x4 ov[4], zv[4];
; #pragma unroll
;         for (int q = 0; q < 4; ++q) { const int grp = grp0 + 32 * q; const size_t base = (size_t)(grp >> 3) * 1024 + (grp & 7) * 128 + o8 * 8;
;             ov[q] = *(const u32x4*)(obf + base); zv[q] = *(const u32x4*)(z + base); }
; #pragma unroll
;         for (int q = 0; q < 4; ++q) { const int grp = grp0 + 32 * q; const size_t base = (size_t)(grp >> 3) * 1024 + (grp & 7) * 128 + o8 * 8;
;             float o[8], zz[8]; unpack8(ov[q], o); unpack8(zv[q], zz);
;             float ss = 0.f;
; #pragma unroll
;             for (int i = 0; i < 8; ++i) ss += o[i] * o[i];
;             ss += __shfl_xor(ss, 1); ss += __shfl_xor(ss, 2); ss += __shfl_xor(ss, 4); ss += __shfl_xor(ss, 8);
;             const float sc = rsqrtf(ss * (1.f / 128.f) + 1e-6f);
; #pragma unroll
;             for (int i = 0; i < 4; ++i) { o[i] = o[i] * sc * w0[i] * siluf_(zz[i]); o[4 + i] = o[4 + i] * sc * w1[i] * siluf_(zz[4 + i]); }
;             *(u32x4*)(obf + base) = pack8(o); }
.LBB0_98:
	v_and_b32_e32 v2, 0x380, v74
	v_ashrrev_i32_e32 v12, 3, v69
	v_or_b32_e32 v14, v2, v68
	v_ashrrev_i32_e32 v13, 31, v12
	v_lshlrev_b32_e32 v16, 1, v14
	v_lshlrev_b64 v[52:53], 11, v[12:13]
	v_or_b32_e32 v12, v52, v16
	v_mov_b32_e32 v13, v53
	v_lshl_add_u64 v[14:15], s[26:27], 0, v[12:13]
	v_lshl_add_u64 v[12:13], s[30:31], 0, v[12:13]
	global_load_dwordx4 v[36:39], v[14:15], off
	global_load_dwordx4 v[40:43], v[12:13], off
	v_lshlrev_b32_e32 v2, 1, v2
	v_lshl_add_u64 v[46:47], v[0:1], 0, v[2:3]
	v_add_u32_e32 v12, 32, v69
	v_ashrrev_i32_e32 v12, 3, v12
	v_ashrrev_i32_e32 v13, 31, v12
	v_lshlrev_b64 v[50:51], 11, v[12:13]
	v_or_b32_e32 v12, v50, v16
	v_mov_b32_e32 v13, v51
	v_lshl_add_u64 v[14:15], s[26:27], 0, v[12:13]
	v_lshl_add_u64 v[12:13], s[30:31], 0, v[12:13]
	global_load_dwordx4 v[28:31], v[14:15], off
	global_load_dwordx4 v[32:35], v[12:13], off
	v_add_u32_e32 v12, 64, v69
	v_ashrrev_i32_e32 v12, 3, v12
	v_ashrrev_i32_e32 v13, 31, v12
	v_lshlrev_b64 v[48:49], 11, v[12:13]
	v_or_b32_e32 v12, v48, v16
	v_mov_b32_e32 v13, v49
	v_lshl_add_u64 v[14:15], s[26:27], 0, v[12:13]
	v_lshl_add_u64 v[12:13], s[30:31], 0, v[12:13]
	global_load_dwordx4 v[20:23], v[14:15], off
	global_load_dwordx4 v[24:27], v[12:13], off
	v_add_u32_e32 v12, 0x60, v69
	v_ashrrev_i32_e32 v12, 3, v12
	v_ashrrev_i32_e32 v13, 31, v12
	v_lshlrev_b64 v[44:45], 11, v[12:13]
	v_or_b32_e32 v16, v44, v16
	v_mov_b32_e32 v17, v45
	v_lshl_add_u64 v[12:13], s[26:27], 0, v[16:17]
	v_lshl_add_u64 v[16:17], s[30:31], 0, v[16:17]
	v_lshl_add_u64 v[52:53], v[46:47], 0, v[52:53]
	global_load_dwordx4 v[12:15], v[12:13], off
	v_lshl_add_u64 v[48:49], v[46:47], 0, v[48:49]
	global_load_dwordx4 v[16:19], v[16:17], off
	v_add_u32_e32 v69, s20, v69
	v_add_u32_e32 v74, s21, v74
	s_waitcnt vmcnt(0)
	v_lshlrev_b32_e32 v54, 16, v39
	v_lshlrev_b32_e32 v2, 16, v43
	v_and_b32_e32 v75, 0xffff0000, v43
	v_lshlrev_b32_e32 v43, 16, v42
	v_and_b32_e32 v42, 0xffff0000, v42
	v_and_b32_e32 v55, 0xffff0000, v39
	v_lshlrev_b32_e32 v56, 16, v38
	v_and_b32_e32 v57, 0xffff0000, v38
	v_mul_f32_e32 v38, 0xbfb8aa3b, v43
	v_mul_f32_e32 v39, 0xbfb8aa3b, v42
	v_exp_f32_e32 v38, v38
	v_exp_f32_e32 v39, v39
	v_pk_mul_f32 v[60:61], v[56:57], v[56:57]
	v_and_b32_e32 v82, 0xffff0000, v34
	v_and_b32_e32 v94, 0xffff0000, v35
	v_pk_add_f32 v[38:39], v[38:39], 1.0 op_sel_hi:[1,0]
	v_pk_mul_f32 v[58:59], v[54:55], v[54:55]
	v_rcp_f32_e32 v63, v39
	s_nop 0
	v_mul_f32_e32 v65, v42, v63
	v_fma_f32 v66, -v39, v65, v42
	v_fmac_f32_e32 v65, v66, v63
	v_div_fixup_f32 v39, v65, v39, v42
	v_rcp_f32_e32 v62, v38
	s_nop 0
	v_mul_f32_e32 v64, v43, v62
	v_fma_f32 v65, -v38, v64, v43
	v_fmac_f32_e32 v64, v65, v62
	v_div_fixup_f32 v38, v64, v38, v43
	v_mul_f32_e32 v42, 0xbfb8aa3b, v2
	v_exp_f32_e32 v76, v42
	v_lshlrev_b32_e32 v42, 16, v37
	v_and_b32_e32 v43, 0xffff0000, v37
	v_lshlrev_b32_e32 v37, 16, v41
	v_and_b32_e32 v41, 0xffff0000, v41
	v_mul_f32_e32 v62, 0xbfb8aa3b, v37
	v_mul_f32_e32 v63, 0xbfb8aa3b, v41
	v_exp_f32_e32 v62, v62
	v_exp_f32_e32 v63, v63
	v_pk_mul_f32 v[66:67], v[42:43], v[42:43]
	v_pk_add_f32 v[62:63], v[62:63], 1.0 op_sel_hi:[1,0]
	s_nop 0
	v_rcp_f32_e32 v65, v63
	s_nop 0
	v_mul_f32_e32 v78, v41, v65
	v_fma_f32 v79, -v63, v78, v41
	v_fmac_f32_e32 v78, v79, v65
	v_div_fixup_f32 v63, v78, v63, v41
	v_rcp_f32_e32 v64, v62
	s_nop 0
	v_mul_f32_e32 v77, v37, v64
	v_fma_f32 v78, -v62, v77, v37
	v_fmac_f32_e32 v77, v78, v64
	v_div_fixup_f32 v62, v77, v62, v37
	v_lshlrev_b32_e32 v41, 16, v40
	v_and_b32_e32 v40, 0xffff0000, v40
	v_lshlrev_b32_e32 v64, 16, v36
	v_and_b32_e32 v65, 0xffff0000, v36
	v_mul_f32_e32 v36, 0xbfb8aa3b, v41
	v_mul_f32_e32 v37, 0xbfb8aa3b, v40
	v_exp_f32_e32 v36, v36
	v_exp_f32_e32 v37, v37
	s_nop 0
	v_pk_add_f32 v[36:37], v[36:37], 1.0 op_sel_hi:[1,0]
	s_nop 0
	v_rcp_f32_e32 v78, v37
	s_nop 0
	v_mul_f32_e32 v80, v40, v78
	v_fma_f32 v81, -v37, v80, v40
	v_fmac_f32_e32 v80, v81, v78
	v_div_fixup_f32 v37, v80, v37, v40
	v_rcp_f32_e32 v77, v36
	s_nop 0
	v_and_b32_e32 v81, 0xffff0000, v30
	v_mul_f32_e32 v79, v41, v77
	v_fma_f32 v80, -v36, v79, v41
	v_fmac_f32_e32 v79, v80, v77
	v_div_fixup_f32 v36, v79, v36, v41
	v_mul_f32_e32 v40, 0xbfb8aa3b, v75
	v_exp_f32_e32 v77, v40
	s_nop 0
	v_pk_add_f32 v[40:41], v[76:77], 1.0 op_sel_hi:[1,0]
	s_nop 0
	v_rcp_f32_e32 v77, v41
	s_nop 0
	v_mul_f32_e32 v79, v75, v77
	v_fma_f32 v80, -v41, v79, v75
	v_fmac_f32_e32 v79, v80, v77
	v_div_fixup_f32 v41, v79, v41, v75
	v_rcp_f32_e32 v76, v40
	s_nop 0
	v_lshlrev_b32_e32 v80, 16, v30
	v_mul_f32_e32 v78, v2, v76
	v_fma_f32 v79, -v40, v78, v2
	v_fmac_f32_e32 v78, v79, v76
	v_div_fixup_f32 v40, v78, v40, v2
	v_lshlrev_b32_e32 v2, 16, v34
	v_lshlrev_b32_e32 v75, 16, v35
	v_mul_f32_e32 v34, 0xbfb8aa3b, v2
	v_mul_f32_e32 v35, 0xbfb8aa3b, v82
	v_exp_f32_e32 v34, v34
	v_exp_f32_e32 v35, v35
	v_lshlrev_b32_e32 v76, 16, v31
	v_and_b32_e32 v77, 0xffff0000, v31
	v_pk_mul_f32 v[30:31], v[80:81], v[80:81]
	v_pk_add_f32 v[34:35], v[34:35], 1.0 op_sel_hi:[1,0]
	v_pk_mul_f32 v[78:79], v[76:77], v[76:77]
	v_rcp_f32_e32 v84, v35
	s_nop 0
	v_mul_f32_e32 v86, v82, v84
	v_fma_f32 v87, -v35, v86, v82
	v_fmac_f32_e32 v86, v87, v84
	v_div_fixup_f32 v35, v86, v35, v82
	v_rcp_f32_e32 v83, v34
	s_nop 0
	v_mul_f32_e32 v85, v2, v83
	v_fma_f32 v86, -v34, v85, v2
	v_fmac_f32_e32 v85, v86, v83
	v_div_fixup_f32 v34, v85, v34, v2
	v_mul_f32_e32 v2, 0xbfb8aa3b, v75
	v_exp_f32_e32 v82, v2
	v_lshlrev_b32_e32 v2, 16, v33
	v_lshlrev_b32_e32 v84, 16, v29
	v_and_b32_e32 v85, 0xffff0000, v29
	v_and_b32_e32 v29, 0xffff0000, v33
	v_mul_f32_e32 v33, 0xbfb8aa3b, v2
	v_exp_f32_e32 v88, v33
	v_mul_f32_e32 v33, 0xbfb8aa3b, v29
	v_exp_f32_e32 v89, v33
; DI void unpack8(u32x4 w, float* f) { f[0] = bflo(w.x); f[1] = bfhi(w.x); f[2] = bflo(w.y); f[3] = bfhi(w.y); f[4] = bflo(w.z); f[5] = bfhi(w.z); f[6] = bflo(w.w); f[7] = bfhi(w.w); }
; DI u32x4 pack8(const float* f) { u32x4 w; w.x = pk2(f[0], f[1]); w.y = pk2(f[2], f[3]); w.z = pk2(f[4], f[5]); w.w = pk2(f[6], f[7]); return w; }
; DI float siluf_(float x) { return x / (1.f + __expf(-x)); }
; DI void phase_normgate(PP p, int l, int nblk, int bid) {
;     ...
;         for (int q = 0; q < 4; ++q) { const int grp = grp0 + 32 * q; const size_t base = (size_t)(grp >> 3) * 1024 + (grp & 7) * 128 + o8 * 8;
;             float o[8], zz[8]; unpack8(ov[q], o); unpack8(zv[q], zz);
;             float ss = 0.f;
; #pragma unroll
;             for (int i = 0; i < 8; ++i) ss += o[i] * o[i];
;             ss += __shfl_xor(ss, 1); ss += __shfl_xor(ss, 2); ss += __shfl_xor(ss, 4); ss += __shfl_xor(ss, 8);
;             const float sc = rsqrtf(ss * (1.f / 128.f) + 1e-6f);
; #pragma unroll
;             for (int i = 0; i < 4; ++i) { o[i] = o[i] * sc * w0[i] * siluf_(zz[i]); o[4 + i] = o[4 + i] * sc * w1[i] * siluf_(zz[4 + i]); }
;             *(u32x4*)(obf + base) = pack8(o); }
	v_pk_mul_f32 v[86:87], v[84:85], v[84:85]
	v_pk_add_f32 v[88:89], v[88:89], 1.0 op_sel_hi:[1,0]
	s_nop 0
	v_rcp_f32_e32 v83, v89
	s_nop 0
	v_mul_f32_e32 v91, v29, v83
	v_fma_f32 v92, -v89, v91, v29
	v_fmac_f32_e32 v91, v92, v83
	v_div_fixup_f32 v89, v91, v89, v29
	v_rcp_f32_e32 v33, v88
	s_nop 0
	v_mul_f32_e32 v90, v2, v33
	v_fma_f32 v91, -v88, v90, v2
	v_fmac_f32_e32 v90, v91, v33
	v_div_fixup_f32 v88, v90, v88, v2
	v_lshlrev_b32_e32 v2, 16, v32
	v_and_b32_e32 v32, 0xffff0000, v32
	v_lshlrev_b32_e32 v90, 16, v28
	v_and_b32_e32 v91, 0xffff0000, v28
	v_mul_f32_e32 v28, 0xbfb8aa3b, v2
	v_mul_f32_e32 v29, 0xbfb8aa3b, v32
	v_exp_f32_e32 v28, v28
	v_exp_f32_e32 v29, v29
	s_nop 0
	v_pk_add_f32 v[28:29], v[28:29], 1.0 op_sel_hi:[1,0]
	s_nop 0
	v_rcp_f32_e32 v83, v29
	s_nop 0
	v_mul_f32_e32 v93, v32, v83
	v_fma_f32 v95, -v29, v93, v32
	v_fmac_f32_e32 v93, v95, v83
	v_div_fixup_f32 v93, v93, v29, v32
	v_rcp_f32_e32 v32, v28
	s_nop 0
	s_mov_b32 s2, 0x358637bd
	v_mul_f32_e32 v83, v2, v32
	v_fma_f32 v92, -v28, v83, v2
	v_fmac_f32_e32 v83, v92, v32
	v_mov_b32_e32 v32, v91
	v_mov_b32_e32 v33, v65
	v_div_fixup_f32 v92, v83, v28, v2
	v_mov_b32_e32 v28, v90
	v_mov_b32_e32 v29, v64
	v_pk_mul_f32 v[32:33], v[32:33], v[32:33]
	s_nop 0
	v_pk_fma_f32 v[28:29], v[28:29], v[28:29], v[32:33]
	v_mov_b32_e32 v32, v86
	v_mov_b32_e32 v33, v66
	v_pk_add_f32 v[28:29], v[32:33], v[28:29]
	v_mov_b32_e32 v66, v87
	v_pk_add_f32 v[28:29], v[66:67], v[28:29]
	v_mov_b32_e32 v32, v30
	v_mov_b32_e32 v33, v60
	v_pk_add_f32 v[28:29], v[32:33], v[28:29]
	v_mov_b32_e32 v60, v31
	v_pk_add_f32 v[28:29], v[60:61], v[28:29]
	v_mov_b32_e32 v30, v78
	v_mov_b32_e32 v31, v58
	v_pk_add_f32 v[28:29], v[30:31], v[28:29]
	v_mov_b32_e32 v58, v79
	v_pk_add_f32 v[28:29], v[58:59], v[28:29]
	ds_bpermute_b32 v31, v70, v29
	ds_bpermute_b32 v30, v70, v28
	v_mov_b64_e32 v[32:33], s[2:3]
	s_waitcnt lgkmcnt(0)
	v_pk_add_f32 v[28:29], v[28:29], v[30:31]
	ds_bpermute_b32 v31, v71, v29
	ds_bpermute_b32 v30, v71, v28
	s_waitcnt lgkmcnt(0)
	v_pk_add_f32 v[28:29], v[28:29], v[30:31]
	ds_bpermute_b32 v31, v72, v29
	ds_bpermute_b32 v30, v72, v28
	s_waitcnt lgkmcnt(0)
	v_pk_add_f32 v[28:29], v[28:29], v[30:31]
	ds_bpermute_b32 v31, v73, v29
	ds_bpermute_b32 v30, v73, v28
	s_waitcnt lgkmcnt(0)
	v_pk_add_f32 v[28:29], v[28:29], v[30:31]
	s_nop 0
	v_pk_fma_f32 v[58:59], v[28:29], s[36:37], v[32:33] op_sel_hi:[1,0,0]
	s_nop 0
	v_mul_f32_e32 v2, 0x4b800000, v59
	v_cmp_gt_f32_e64 s[22:23], s10, v59
	v_cmp_gt_f32_e32 vcc, s10, v58
	s_nop 0
	v_cndmask_b32_e64 v2, v59, v2, s[22:23]
	v_rsq_f32_e32 v2, v2
	s_nop 0
	v_mul_f32_e32 v28, 0x45800000, v2
	v_cndmask_b32_e64 v2, v2, v28, s[22:23]
	v_pk_mul_f32 v[28:29], v[2:3], v[64:65] op_sel_hi:[0,1]
	v_pk_mul_f32 v[30:31], v[2:3], v[56:57] op_sel_hi:[0,1]
	v_pk_mul_f32 v[28:29], v[8:9], v[28:29]
	v_pk_mul_f32 v[30:31], v[4:5], v[30:31]
	v_pk_mul_f32 v[28:29], v[36:37], v[28:29]
	v_pk_mul_f32 v[30:31], v[38:39], v[30:31]
	v_pk_mul_f32 v[36:37], v[2:3], v[42:43] op_sel_hi:[0,1]
	v_pk_mul_f32 v[38:39], v[2:3], v[54:55] op_sel_hi:[0,1]
	v_mul_f32_e32 v2, 0x4b800000, v58
	v_cndmask_b32_e32 v2, v58, v2, vcc
	v_rsq_f32_e32 v2, v2
	v_pk_mul_f32 v[36:37], v[10:11], v[36:37]
	v_pk_mul_f32 v[38:39], v[6:7], v[38:39]
	v_pk_mul_f32 v[36:37], v[62:63], v[36:37]
	v_pk_mul_f32 v[38:39], v[40:41], v[38:39]
	v_cvt_pk_bf16_f32 v28, v28, v29
	v_cvt_pk_bf16_f32 v29, v36, v37
	v_cvt_pk_bf16_f32 v30, v30, v31
	v_cvt_pk_bf16_f32 v31, v38, v39
	global_store_dwordx4 v[52:53], v[28:31], off
	v_and_b32_e32 v52, 0xffff0000, v27
	s_nop 0
	v_mul_f32_e32 v28, 0x45800000, v2
	v_cndmask_b32_e32 v2, v2, v28, vcc
	v_pk_mul_f32 v[30:31], v[2:3], v[80:81] op_sel_hi:[0,1]
	v_pk_mul_f32 v[30:31], v[4:5], v[30:31]
	v_pk_mul_f32 v[28:29], v[2:3], v[90:91] op_sel_hi:[0,1]
	v_pk_mul_f32 v[30:31], v[34:35], v[30:31]
	v_pk_mul_f32 v[34:35], v[2:3], v[84:85] op_sel_hi:[0,1]
	v_pk_mul_f32 v[36:37], v[2:3], v[76:77] op_sel_hi:[0,1]
	v_mul_f32_e32 v2, 0xbfb8aa3b, v94
	v_exp_f32_e32 v83, v2
	v_pk_mul_f32 v[28:29], v[8:9], v[28:29]
	v_pk_mul_f32 v[34:35], v[10:11], v[34:35]
	v_pk_mul_f32 v[36:37], v[6:7], v[36:37]
	v_pk_add_f32 v[38:39], v[82:83], 1.0 op_sel_hi:[1,0]
	v_pk_mul_f32 v[28:29], v[92:93], v[28:29]
	v_rcp_f32_e32 v40, v39
	s_nop 0
	v_pk_mul_f32 v[34:35], v[88:89], v[34:35]
	v_cvt_pk_bf16_f32 v28, v28, v29
	v_cvt_pk_bf16_f32 v29, v34, v35
	v_mul_f32_e32 v42, v94, v40
	v_fma_f32 v43, -v39, v42, v94
	v_fmac_f32_e32 v42, v43, v40
	v_div_fixup_f32 v39, v42, v39, v94
	v_rcp_f32_e32 v40, v38
	s_nop 0
	v_cvt_pk_bf16_f32 v30, v30, v31
	v_lshl_add_u64 v[34:35], v[46:47], 0, v[50:51]
	v_and_b32_e32 v76, 0xffff0000, v19
	v_mul_f32_e32 v42, v75, v40
	v_fma_f32 v43, -v38, v42, v75
	v_fmac_f32_e32 v42, v43, v40
	v_div_fixup_f32 v38, v42, v38, v75
	v_pk_mul_f32 v[36:37], v[38:39], v[36:37]
	v_lshlrev_b32_e32 v2, 16, v27
	v_cvt_pk_bf16_f32 v31, v36, v37
	v_lshlrev_b32_e32 v36, 16, v26
	v_and_b32_e32 v37, 0xffff0000, v26
	global_store_dwordx4 v[34:35], v[28:31], off
	v_lshlrev_b32_e32 v75, 16, v19
	s_nop 0
	v_lshlrev_b32_e32 v28, 16, v23
	v_and_b32_e32 v29, 0xffff0000, v23
	v_lshlrev_b32_e32 v30, 16, v22
	v_and_b32_e32 v31, 0xffff0000, v22
	v_mul_f32_e32 v22, 0xbfb8aa3b, v36
	v_mul_f32_e32 v23, 0xbfb8aa3b, v37
	v_exp_f32_e32 v22, v22
	v_exp_f32_e32 v23, v23
	v_pk_mul_f32 v[26:27], v[30:31], v[30:31]
	v_pk_mul_f32 v[34:35], v[28:29], v[28:29]
	v_pk_add_f32 v[22:23], v[22:23], 1.0 op_sel_hi:[1,0]
	s_nop 0
	v_rcp_f32_e32 v39, v23
	s_nop 0
	v_mul_f32_e32 v41, v37, v39
	v_fma_f32 v42, -v23, v41, v37
	v_fmac_f32_e32 v41, v42, v39
	v_div_fixup_f32 v23, v41, v23, v37
	v_rcp_f32_e32 v38, v22
	s_nop 0
	v_mul_f32_e32 v40, v36, v38
; DI void unpack8(u32x4 w, float* f) { f[0] = bflo(w.x); f[1] = bfhi(w.x); f[2] = bflo(w.y); f[3] = bfhi(w.y); f[4] = bflo(w.z); f[5] = bfhi(w.z); f[6] = bflo(w.w); f[7] = bfhi(w.w); }
; DI float siluf_(float x) { return x / (1.f + __expf(-x)); }
; DI void phase_normgate(PP p, int l, int nblk, int bid) {
;     ...
;         for (int q = 0; q < 4; ++q) { const int grp = grp0 + 32 * q; const size_t base = (size_t)(grp >> 3) * 1024 + (grp & 7) * 128 + o8 * 8;
;             ov[q] = *(const u32x4*)(obf + base); zv[q] = *(const u32x4*)(z + base); }
; #pragma unroll
;         for (int q = 0; q < 4; ++q) { const int grp = grp0 + 32 * q; const size_t base = (size_t)(grp >> 3) * 1024 + (grp & 7) * 128 + o8 * 8;
;             float o[8], zz[8]; unpack8(ov[q], o); unpack8(zv[q], zz);
;             float ss = 0.f;
; #pragma unroll
;             for (int i = 0; i < 8; ++i) ss += o[i] * o[i];
;             ss += __shfl_xor(ss, 1); ss += __shfl_xor(ss, 2); ss += __shfl_xor(ss, 4); ss += __shfl_xor(ss, 8);
;             const float sc = rsqrtf(ss * (1.f / 128.f) + 1e-6f);
; #pragma unroll
;             for (int i = 0; i < 4; ++i) { o[i] = o[i] * sc * w0[i] * siluf_(zz[i]); o[4 + i] = o[4 + i] * sc * w1[i] * siluf_(zz[4 + i]); }
	v_fma_f32 v41, -v22, v40, v36
	v_fmac_f32_e32 v40, v41, v38
	v_div_fixup_f32 v22, v40, v22, v36
	v_mul_f32_e32 v36, 0xbfb8aa3b, v2
	v_exp_f32_e32 v50, v36
	v_lshlrev_b32_e32 v36, 16, v21
	v_and_b32_e32 v37, 0xffff0000, v21
	v_lshlrev_b32_e32 v21, 16, v25
	v_and_b32_e32 v25, 0xffff0000, v25
	v_mul_f32_e32 v38, 0xbfb8aa3b, v21
	v_mul_f32_e32 v39, 0xbfb8aa3b, v25
	v_exp_f32_e32 v38, v38
	v_exp_f32_e32 v39, v39
	v_pk_mul_f32 v[42:43], v[36:37], v[36:37]
	v_pk_add_f32 v[38:39], v[38:39], 1.0 op_sel_hi:[1,0]
	s_nop 0
	v_rcp_f32_e32 v41, v39
	s_nop 0
	v_mul_f32_e32 v53, v25, v41
	v_fma_f32 v54, -v39, v53, v25
	v_fmac_f32_e32 v53, v54, v41
	v_div_fixup_f32 v39, v53, v39, v25
	v_rcp_f32_e32 v40, v38
	s_nop 0
	v_mul_f32_e32 v51, v21, v40
	v_fma_f32 v53, -v38, v51, v21
	v_fmac_f32_e32 v51, v53, v40
	v_div_fixup_f32 v38, v51, v38, v21
	v_lshlrev_b32_e32 v25, 16, v24
	v_and_b32_e32 v24, 0xffff0000, v24
	v_lshlrev_b32_e32 v40, 16, v20
	v_and_b32_e32 v41, 0xffff0000, v20
	v_mul_f32_e32 v20, 0xbfb8aa3b, v25
	v_mul_f32_e32 v21, 0xbfb8aa3b, v24
	v_exp_f32_e32 v20, v20
	v_exp_f32_e32 v21, v21
	s_nop 0
	v_pk_add_f32 v[20:21], v[20:21], 1.0 op_sel_hi:[1,0]
	s_nop 0
	v_rcp_f32_e32 v53, v21
	s_nop 0
	v_mul_f32_e32 v55, v24, v53
	v_fma_f32 v56, -v21, v55, v24
	v_fmac_f32_e32 v55, v56, v53
	v_div_fixup_f32 v21, v55, v21, v24
	v_rcp_f32_e32 v51, v20
	s_nop 0
	v_and_b32_e32 v56, 0xffff0000, v18
	v_mul_f32_e32 v19, 0xbfb8aa3b, v56
	v_exp_f32_e32 v19, v19
	v_mul_f32_e32 v54, v25, v51
	v_fma_f32 v55, -v20, v54, v25
	v_fmac_f32_e32 v54, v55, v51
	v_div_fixup_f32 v20, v54, v20, v25
	v_mul_f32_e32 v24, 0xbfb8aa3b, v52
	v_exp_f32_e32 v51, v24
	s_nop 0
	v_pk_add_f32 v[24:25], v[50:51], 1.0 op_sel_hi:[1,0]
	s_nop 0
	v_rcp_f32_e32 v51, v25
	s_nop 0
	v_mul_f32_e32 v54, v52, v51
	v_fma_f32 v55, -v25, v54, v52
	v_fmac_f32_e32 v54, v55, v51
	v_div_fixup_f32 v25, v54, v25, v52
	v_rcp_f32_e32 v51, v24
	s_nop 0
	v_and_b32_e32 v55, 0xffff0000, v14
	v_mul_f32_e32 v53, v2, v51
	v_fma_f32 v54, -v24, v53, v2
	v_fmac_f32_e32 v53, v54, v51
	v_div_fixup_f32 v24, v53, v24, v2
	v_lshlrev_b32_e32 v2, 16, v18
	v_mul_f32_e32 v18, 0xbfb8aa3b, v2
	v_exp_f32_e32 v18, v18
	v_lshlrev_b32_e32 v54, 16, v14
	v_lshlrev_b32_e32 v50, 16, v15
	v_and_b32_e32 v51, 0xffff0000, v15
	v_pk_add_f32 v[18:19], v[18:19], 1.0 op_sel_hi:[1,0]
	v_pk_mul_f32 v[14:15], v[54:55], v[54:55]
	v_rcp_f32_e32 v58, v19
	s_nop 0
	v_pk_mul_f32 v[52:53], v[50:51], v[50:51]
	v_mul_f32_e32 v60, v56, v58
	v_fma_f32 v61, -v19, v60, v56
	v_fmac_f32_e32 v60, v61, v58
	v_div_fixup_f32 v19, v60, v19, v56
	v_rcp_f32_e32 v57, v18
	s_nop 0
	v_mul_f32_e32 v59, v2, v57
	v_fma_f32 v60, -v18, v59, v2
	v_fmac_f32_e32 v59, v60, v57
	v_div_fixup_f32 v18, v59, v18, v2
	v_mul_f32_e32 v2, 0xbfb8aa3b, v75
	v_exp_f32_e32 v56, v2
	v_lshlrev_b32_e32 v2, 16, v17
	v_lshlrev_b32_e32 v58, 16, v13
	v_and_b32_e32 v59, 0xffff0000, v13
	v_and_b32_e32 v13, 0xffff0000, v17
	v_mul_f32_e32 v17, 0xbfb8aa3b, v2
	v_exp_f32_e32 v62, v17
	v_mul_f32_e32 v17, 0xbfb8aa3b, v13
	v_exp_f32_e32 v63, v17
	v_pk_mul_f32 v[60:61], v[58:59], v[58:59]
	v_pk_add_f32 v[62:63], v[62:63], 1.0 op_sel_hi:[1,0]
	s_nop 0
	v_rcp_f32_e32 v57, v63
	s_nop 0
	v_mul_f32_e32 v65, v13, v57
	v_fma_f32 v66, -v63, v65, v13
	v_fmac_f32_e32 v65, v66, v57
	v_div_fixup_f32 v63, v65, v63, v13
	v_rcp_f32_e32 v17, v62
	s_nop 0
	v_mul_f32_e32 v64, v2, v17
	v_fma_f32 v65, -v62, v64, v2
	v_fmac_f32_e32 v64, v65, v17
	v_div_fixup_f32 v62, v64, v62, v2
	v_lshlrev_b32_e32 v2, 16, v16
	v_and_b32_e32 v16, 0xffff0000, v16
	v_lshlrev_b32_e32 v64, 16, v12
	v_and_b32_e32 v65, 0xffff0000, v12
	v_mul_f32_e32 v12, 0xbfb8aa3b, v2
	v_mul_f32_e32 v13, 0xbfb8aa3b, v16
	v_exp_f32_e32 v12, v12
	v_exp_f32_e32 v13, v13
	s_nop 0
	v_pk_add_f32 v[12:13], v[12:13], 1.0 op_sel_hi:[1,0]
	s_nop 0
	v_rcp_f32_e32 v57, v13
	s_nop 0
	v_mul_f32_e32 v67, v16, v57
	v_fma_f32 v77, -v13, v67, v16
	v_fmac_f32_e32 v67, v77, v57
	v_div_fixup_f32 v17, v67, v13, v16
	v_div_scale_f32 v13, s[2:3], v12, v12, v2
	v_rcp_f32_e32 v16, v13
	s_nop 0
	v_fma_f32 v57, -v13, v16, 1.0
	v_fmac_f32_e32 v16, v57, v16
	v_div_scale_f32 v57, vcc, v2, v12, v2
	v_mul_f32_e32 v66, v57, v16
	v_fma_f32 v67, -v13, v66, v57
	v_fmac_f32_e32 v66, v67, v16
	v_fma_f32 v13, -v13, v66, v57
	v_div_fmas_f32 v13, v13, v16, v66
	v_mov_b32_e32 v66, v65
	v_mov_b32_e32 v67, v41
	v_div_fixup_f32 v16, v13, v12, v2
	v_mov_b32_e32 v12, v64
	v_mov_b32_e32 v13, v40
	v_pk_mul_f32 v[66:67], v[66:67], v[66:67]
	s_nop 0
	v_pk_fma_f32 v[12:13], v[12:13], v[12:13], v[66:67]
	v_mov_b32_e32 v66, v60
	v_mov_b32_e32 v67, v42
	v_pk_add_f32 v[12:13], v[66:67], v[12:13]
	v_mov_b32_e32 v42, v61
	v_pk_add_f32 v[12:13], v[42:43], v[12:13]
	v_mov_b32_e32 v42, v14
	v_mov_b32_e32 v43, v26
	v_pk_add_f32 v[12:13], v[42:43], v[12:13]
	v_mov_b32_e32 v26, v15
	v_pk_add_f32 v[12:13], v[26:27], v[12:13]
	v_mov_b32_e32 v14, v52
	v_mov_b32_e32 v15, v34
	v_pk_add_f32 v[12:13], v[14:15], v[12:13]
	v_mov_b32_e32 v34, v53
	v_pk_add_f32 v[12:13], v[34:35], v[12:13]
	ds_bpermute_b32 v15, v70, v13
	ds_bpermute_b32 v14, v70, v12
	s_waitcnt lgkmcnt(0)
; DI u32x4 pack8(const float* f) { u32x4 w; w.x = pk2(f[0], f[1]); w.y = pk2(f[2], f[3]); w.z = pk2(f[4], f[5]); w.w = pk2(f[6], f[7]); return w; }
; DI float siluf_(float x) { return x / (1.f + __expf(-x)); }
; DI void phase_normgate(PP p, int l, int nblk, int bid) {
;     ...
; #pragma unroll
;             for (int i = 0; i < 8; ++i) ss += o[i] * o[i];
;             ss += __shfl_xor(ss, 1); ss += __shfl_xor(ss, 2); ss += __shfl_xor(ss, 4); ss += __shfl_xor(ss, 8);
;             const float sc = rsqrtf(ss * (1.f / 128.f) + 1e-6f);
; #pragma unroll
;             for (int i = 0; i < 4; ++i) { o[i] = o[i] * sc * w0[i] * siluf_(zz[i]); o[4 + i] = o[4 + i] * sc * w1[i] * siluf_(zz[4 + i]); }
;             *(u32x4*)(obf + base) = pack8(o); }
;     }
	v_pk_add_f32 v[12:13], v[12:13], v[14:15]
	ds_bpermute_b32 v15, v71, v13
	ds_bpermute_b32 v14, v71, v12
	s_waitcnt lgkmcnt(0)
	v_pk_add_f32 v[12:13], v[12:13], v[14:15]
	ds_bpermute_b32 v15, v72, v13
	ds_bpermute_b32 v14, v72, v12
	s_waitcnt lgkmcnt(0)
	v_pk_add_f32 v[12:13], v[12:13], v[14:15]
	ds_bpermute_b32 v15, v73, v13
	ds_bpermute_b32 v14, v73, v12
	s_waitcnt lgkmcnt(0)
	v_pk_add_f32 v[12:13], v[12:13], v[14:15]
	s_nop 0
	v_pk_fma_f32 v[26:27], v[12:13], s[36:37], v[32:33] op_sel_hi:[1,0,0]
	s_nop 0
	v_mul_f32_e32 v2, 0x4b800000, v27
	v_cmp_gt_f32_e64 s[22:23], s10, v27
	v_cmp_gt_f32_e32 vcc, s10, v26
	s_nop 0
	v_cndmask_b32_e64 v2, v27, v2, s[22:23]
	v_rsq_f32_e32 v2, v2
	s_nop 0
	v_mul_f32_e32 v12, 0x45800000, v2
	v_cndmask_b32_e64 v2, v2, v12, s[22:23]
	v_pk_mul_f32 v[12:13], v[2:3], v[40:41] op_sel_hi:[0,1]
	v_pk_mul_f32 v[14:15], v[2:3], v[30:31] op_sel_hi:[0,1]
	v_pk_mul_f32 v[12:13], v[8:9], v[12:13]
	v_pk_mul_f32 v[14:15], v[4:5], v[14:15]
	v_pk_mul_f32 v[12:13], v[20:21], v[12:13]
	v_pk_mul_f32 v[14:15], v[22:23], v[14:15]
	v_pk_mul_f32 v[20:21], v[2:3], v[36:37] op_sel_hi:[0,1]
	v_pk_mul_f32 v[22:23], v[2:3], v[28:29] op_sel_hi:[0,1]
	v_mul_f32_e32 v2, 0x4b800000, v26
	v_cndmask_b32_e32 v2, v26, v2, vcc
	v_rsq_f32_e32 v2, v2
	v_pk_mul_f32 v[20:21], v[10:11], v[20:21]
	v_pk_mul_f32 v[22:23], v[6:7], v[22:23]
	v_pk_mul_f32 v[20:21], v[38:39], v[20:21]
	v_pk_mul_f32 v[22:23], v[24:25], v[22:23]
	v_cvt_pk_bf16_f32 v12, v12, v13
	v_cvt_pk_bf16_f32 v13, v20, v21
	v_cvt_pk_bf16_f32 v14, v14, v15
	v_cvt_pk_bf16_f32 v15, v22, v23
	global_store_dwordx4 v[48:49], v[12:15], off
	s_nop 1
	v_mul_f32_e32 v12, 0x45800000, v2
	v_cndmask_b32_e32 v2, v2, v12, vcc
	v_pk_mul_f32 v[12:13], v[2:3], v[64:65] op_sel_hi:[0,1]
	v_pk_mul_f32 v[14:15], v[2:3], v[54:55] op_sel_hi:[0,1]
	v_pk_mul_f32 v[12:13], v[8:9], v[12:13]
	v_pk_mul_f32 v[14:15], v[4:5], v[14:15]
	v_pk_mul_f32 v[12:13], v[16:17], v[12:13]
	v_pk_mul_f32 v[14:15], v[18:19], v[14:15]
	v_pk_mul_f32 v[16:17], v[2:3], v[58:59] op_sel_hi:[0,1]
	v_pk_mul_f32 v[18:19], v[2:3], v[50:51] op_sel_hi:[0,1]
	v_mul_f32_e32 v2, 0xbfb8aa3b, v76
	v_exp_f32_e32 v57, v2
	v_pk_mul_f32 v[16:17], v[10:11], v[16:17]
	v_pk_mul_f32 v[18:19], v[6:7], v[18:19]
	v_pk_mul_f32 v[16:17], v[62:63], v[16:17]
	v_pk_add_f32 v[20:21], v[56:57], 1.0 op_sel_hi:[1,0]
	v_cvt_pk_bf16_f32 v12, v12, v13
	v_rcp_f32_e32 v22, v21
	s_nop 0
	v_cvt_pk_bf16_f32 v13, v16, v17
	v_cvt_pk_bf16_f32 v14, v14, v15
	v_lshl_add_u64 v[16:17], v[46:47], 0, v[44:45]
	v_mul_f32_e32 v24, v76, v22
	v_fma_f32 v25, -v21, v24, v76
	v_fmac_f32_e32 v24, v25, v22
	v_div_fixup_f32 v21, v24, v21, v76
	v_rcp_f32_e32 v22, v20
	s_nop 0
	s_mov_b32 s2, 0x1ffff
	v_mul_f32_e32 v24, v75, v22
	v_fma_f32 v25, -v20, v24, v75
	v_fmac_f32_e32 v24, v25, v22
	v_div_fixup_f32 v20, v24, v20, v75
	v_pk_mul_f32 v[18:19], v[20:21], v[18:19]
	v_cmp_lt_i32_e32 vcc, s2, v69
	v_cvt_pk_bf16_f32 v15, v18, v19
	s_or_b64 s[34:35], vcc, s[34:35]
	global_store_dwordx4 v[16:17], v[12:15], off
	s_andn2_b64 exec, exec, s[34:35]
	s_cbranch_execnz .LBB0_98

; #define PG8_STAGE(bufoff, gbase, voff) do { _Pragma("unroll") for (int _i = 0; _i < 2; ++_i) \
;         __builtin_amdgcn_global_load_lds((const unsigned*)((const char*)(gbase) + (voff)[_i]), (LAS unsigned*)(lds + (bufoff) + ldsw + _i * 8192), 16, 0, 0); } while (0)
; #define PG8_LDA(dst, b, h) do { _Pragma("unroll") for (int m = 0; m < 4; ++m) _Pragma("unroll") for (int k = 0; k < 2; ++k) dst[m][k] = *(const LAS bf16x8*)(lds + PG8_SA(b, h) + aoff + m * 2048 + k * 1024); } while (0)
; #define PG8_LDB(dst, b, h) do { _Pragma("unroll") for (int n = 0; n < 2; ++n) _Pragma("unroll") for (int k = 0; k < 2; ++k) dst[n][k] = *(const LAS bf16x8*)(lds + PG8_SB(b, h) + boff + n * 2048 + k * 1024); } while (0)
; #define PG8_MMA(ai, bj, At, Bt) do { __builtin_amdgcn_s_setprio(1); _Pragma("unroll") for (int m = 0; m < 4; ++m) _Pragma("unroll") for (int n = 0; n < 2; ++n) _Pragma("unroll") for (int k = 0; k < 2; ++k) \
;         acc[ai][bj][m][n] = __builtin_amdgcn_mfma_f32_16x16x32_bf16(Bt[n][k], At[m][k], acc[ai][bj][m][n], 0, 0, 0); __builtin_amdgcn_s_setprio(0); } while (0)
; #define PG8_WAIT_V(n) asm volatile("s_waitcnt vmcnt(" #n ")" ::: "memory")
; #define PG8_WAIT_L(n) asm volatile("s_waitcnt lgkmcnt(" #n ")" ::: "memory")
; #define PG8_BAR __builtin_amdgcn_s_barrier()
; #define PG8_SCHED __builtin_amdgcn_sched_barrier(0)
; template <class Epi, class Sched>
; DI void gemm_phase(LAS unsigned char* lds, const Gemm g, const Sched& S, const Epi& E) {
;     ...
;             PG8_LDB(B0, 0, 0); PG8_SCHED; PG8_LDA(At, 0, 0); PG8_STAGE(PG8_SA(1, 1), a1 + hstepA, voffA);
;             PG8_WAIT_L(8); PG8_BAR; PG8_WAIT_L(0); PG8_MMA(0, 0, At, B0); PG8_BAR; PG8_SCHED;
;             PG8_LDB(B1, 0, 1); PG8_STAGE(PG8_SB(0, 0), b2, voffB);
;             PG8_BAR; PG8_WAIT_L(0); PG8_MMA(0, 1, At, B1); PG8_BAR;
;             PG8_LDA(At, 0, 1); PG8_STAGE(PG8_SA(0, 0), a2, voffA);
;             PG8_BAR; PG8_WAIT_L(0); PG8_MMA(1, 0, At, B0); PG8_BAR; PG8_SCHED;
;             PG8_STAGE(PG8_SB(0, 1), b2 + hstepB, voffB);
;             PG8_WAIT_V(6); PG8_BAR; PG8_MMA(1, 1, At, B1); PG8_BAR;
.LBB0_137:
	s_add_u32 s2, s20, 0xfffc0080
	s_addc_u32 s3, s21, -1
	s_add_i32 s83, 0, 0x10000
	v_add_u32_e32 v40, s83, v181
	ds_read_b128 v[20:23], v40
	ds_read_b128 v[24:27], v40 offset:1024
	ds_read_b128 v[36:39], v40 offset:2048
	ds_read_b128 v[40:43], v40 offset:3072
	s_cmp_eq_u32 s82, 12
	s_cselect_b32 s39, s31, s3
	s_cselect_b32 s38, s55, s2
	s_cselect_b32 s3, s29, s65
	s_cselect_b32 s2, s56, s64
	v_lshl_add_u64 v[202:203], s[20:21], 0, v[168:169]
	s_add_i32 m0, s43, 0xc000
	ds_read_b128 v[132:135], v183
	ds_read_b128 v[144:147], v183 offset:1024
	ds_read_b128 v[152:155], v183 offset:2048
	ds_read_b128 v[160:163], v183 offset:3072
	ds_read_b128 v[172:175], v183 offset:4096
	ds_read_b128 v[176:179], v183 offset:5120
	ds_read_b128 v[184:187], v183 offset:6144
	ds_read_b128 v[188:191], v183 offset:7168
	global_load_lds_dwordx4 v[202:203], off
	v_lshl_add_u64 v[202:203], s[20:21], 0, v[170:171]
	s_add_i32 m0, s43, 0xe000
	s_nop 0
	global_load_lds_dwordx4 v[202:203], off
	s_waitcnt lgkmcnt(8)
	s_barrier
	s_waitcnt lgkmcnt(0)
	s_setprio 1
	s_waitcnt lgkmcnt(0)
	v_mfma_f32_16x16x32_bf16 v[156:159], v[20:23], v[132:135], v[156:159]
	v_mfma_f32_16x16x32_bf16 v[148:151], v[36:39], v[132:135], v[148:151]
	v_mfma_f32_16x16x32_bf16 v[128:131], v[20:23], v[152:155], v[128:131]
	v_mfma_f32_16x16x32_bf16 v[124:127], v[36:39], v[152:155], v[124:127]
	v_mfma_f32_16x16x32_bf16 v[112:115], v[20:23], v[172:175], v[112:115]
	v_mfma_f32_16x16x32_bf16 v[108:111], v[36:39], v[172:175], v[108:111]
	v_mfma_f32_16x16x32_bf16 v[96:99], v[20:23], v[184:187], v[96:99]
	v_mfma_f32_16x16x32_bf16 v[92:95], v[36:39], v[184:187], v[92:95]
	v_mfma_f32_16x16x32_bf16 v[156:159], v[24:27], v[144:147], v[156:159]
	v_mfma_f32_16x16x32_bf16 v[148:151], v[40:43], v[144:147], v[148:151]
	v_mfma_f32_16x16x32_bf16 v[128:131], v[24:27], v[160:163], v[128:131]
	v_mfma_f32_16x16x32_bf16 v[124:127], v[40:43], v[160:163], v[124:127]
	v_mfma_f32_16x16x32_bf16 v[112:115], v[24:27], v[176:179], v[112:115]
	v_mfma_f32_16x16x32_bf16 v[108:111], v[40:43], v[176:179], v[108:111]
	v_mfma_f32_16x16x32_bf16 v[96:99], v[24:27], v[188:191], v[96:99]
	v_mfma_f32_16x16x32_bf16 v[92:95], v[40:43], v[188:191], v[92:95]
	s_setprio 0
	s_barrier
	s_add_i32 s92, 0, 0x14000
	s_add_i32 s83, s83, s42
	v_add_u32_e32 v214, s92, v181
	v_lshl_add_u64 v[230:231], s[2:3], 0, v[2:3]
	s_mov_b32 m0, s83
	ds_read_b128 v[202:205], v214
	ds_read_b128 v[206:209], v214 offset:1024
	ds_read_b128 v[210:213], v214 offset:2048
	ds_read_b128 v[214:217], v214 offset:3072
	global_load_lds_dwordx4 v[230:231], off
	v_lshl_add_u64 v[232:233], s[2:3], 0, v[0:1]
	s_add_i32 m0, s83, 0x2000
	s_nop 0
	global_load_lds_dwordx4 v[232:233], off
	s_barrier
	s_waitcnt lgkmcnt(0)
	s_setprio 1
	s_waitcnt lgkmcnt(0)
	v_mfma_f32_16x16x32_bf16 v[140:143], v[202:205], v[132:135], v[140:143]
	v_mfma_f32_16x16x32_bf16 v[120:123], v[202:205], v[152:155], v[120:123]
	v_mfma_f32_16x16x32_bf16 v[116:119], v[210:213], v[152:155], v[116:119]
	v_mfma_f32_16x16x32_bf16 v[104:107], v[202:205], v[172:175], v[104:107]
	v_mfma_f32_16x16x32_bf16 v[100:103], v[210:213], v[172:175], v[100:103]
	v_mfma_f32_16x16x32_bf16 v[88:91], v[202:205], v[184:187], v[88:91]
	v_mfma_f32_16x16x32_bf16 v[84:87], v[210:213], v[184:187], v[84:87]
	v_mfma_f32_16x16x32_bf16 v[140:143], v[206:209], v[144:147], v[140:143]
	v_mfma_f32_16x16x32_bf16 v[132:135], v[210:213], v[132:135], v[136:139]
	v_mfma_f32_16x16x32_bf16 v[120:123], v[206:209], v[160:163], v[120:123]
	v_mfma_f32_16x16x32_bf16 v[116:119], v[214:217], v[160:163], v[116:119]
	v_mfma_f32_16x16x32_bf16 v[104:107], v[206:209], v[176:179], v[104:107]
	v_mfma_f32_16x16x32_bf16 v[100:103], v[214:217], v[176:179], v[100:103]
	v_mfma_f32_16x16x32_bf16 v[88:91], v[206:209], v[188:191], v[88:91]
	v_mfma_f32_16x16x32_bf16 v[84:87], v[214:217], v[188:191], v[84:87]
	v_mfma_f32_16x16x32_bf16 v[132:135], v[214:217], v[144:147], v[132:135]
	s_setprio 0
	s_mov_b32 m0, s43
	v_lshl_add_u64 v[234:235], s[38:39], 0, v[166:167]
	s_barrier
	ds_read_b128 v[136:139], v183 offset:16384
	ds_read_b128 v[144:147], v183 offset:17408
	ds_read_b128 v[152:155], v183 offset:18432
	ds_read_b128 v[160:163], v183 offset:19456
	ds_read_b128 v[172:175], v183 offset:20480
	ds_read_b128 v[176:179], v183 offset:21504
	ds_read_b128 v[184:187], v183 offset:22528
	ds_read_b128 v[188:191], v183 offset:23552
	global_load_lds_dwordx4 v[234:235], off
	v_lshl_add_u64 v[236:237], s[38:39], 0, v[164:165]
	s_mov_b32 m0, s45
	s_nop 0
	global_load_lds_dwordx4 v[236:237], off
	s_barrier
	s_waitcnt lgkmcnt(0)
	s_setprio 1
	s_waitcnt lgkmcnt(0)
	v_mfma_f32_16x16x32_bf16 v[80:83], v[20:23], v[136:139], v[80:83]
	v_mfma_f32_16x16x32_bf16 v[76:79], v[36:39], v[136:139], v[76:79]
	v_mfma_f32_16x16x32_bf16 v[64:67], v[20:23], v[152:155], v[64:67]
	v_mfma_f32_16x16x32_bf16 v[60:63], v[36:39], v[152:155], v[60:63]
	v_mfma_f32_16x16x32_bf16 v[48:51], v[20:23], v[172:175], v[48:51]
	v_mfma_f32_16x16x32_bf16 v[44:47], v[36:39], v[172:175], v[44:47]
	v_mfma_f32_16x16x32_bf16 v[16:19], v[20:23], v[184:187], v[16:19]
	v_mfma_f32_16x16x32_bf16 v[12:15], v[36:39], v[184:187], v[12:15]
	v_mfma_f32_16x16x32_bf16 v[80:83], v[24:27], v[144:147], v[80:83]
	v_mfma_f32_16x16x32_bf16 v[76:79], v[40:43], v[144:147], v[76:79]
	v_mfma_f32_16x16x32_bf16 v[64:67], v[24:27], v[160:163], v[64:67]
	v_mfma_f32_16x16x32_bf16 v[60:63], v[40:43], v[160:163], v[60:63]
	v_mfma_f32_16x16x32_bf16 v[48:51], v[24:27], v[176:179], v[48:51]
	v_mfma_f32_16x16x32_bf16 v[44:47], v[40:43], v[176:179], v[44:47]
	v_mfma_f32_16x16x32_bf16 v[16:19], v[24:27], v[188:191], v[16:19]
	v_mfma_f32_16x16x32_bf16 v[12:15], v[40:43], v[188:191], v[12:15]
	s_setprio 0
	s_barrier
; #define PG8_STAGE(bufoff, gbase, voff) do { _Pragma("unroll") for (int _i = 0; _i < 2; ++_i) \
;         __builtin_amdgcn_global_load_lds((const unsigned*)((const char*)(gbase) + (voff)[_i]), (LAS unsigned*)(lds + (bufoff) + ldsw + _i * 8192), 16, 0, 0); } while (0)
; #define PG8_LDA(dst, b, h) do { _Pragma("unroll") for (int m = 0; m < 4; ++m) _Pragma("unroll") for (int k = 0; k < 2; ++k) dst[m][k] = *(const LAS bf16x8*)(lds + PG8_SA(b, h) + aoff + m * 2048 + k * 1024); } while (0)
; #define PG8_LDB(dst, b, h) do { _Pragma("unroll") for (int n = 0; n < 2; ++n) _Pragma("unroll") for (int k = 0; k < 2; ++k) dst[n][k] = *(const LAS bf16x8*)(lds + PG8_SB(b, h) + boff + n * 2048 + k * 1024); } while (0)
; #define PG8_MMA(ai, bj, At, Bt) do { __builtin_amdgcn_s_setprio(1); _Pragma("unroll") for (int m = 0; m < 4; ++m) _Pragma("unroll") for (int n = 0; n < 2; ++n) _Pragma("unroll") for (int k = 0; k < 2; ++k) \
;         acc[ai][bj][m][n] = __builtin_amdgcn_mfma_f32_16x16x32_bf16(Bt[n][k], At[m][k], acc[ai][bj][m][n], 0, 0, 0); __builtin_amdgcn_s_setprio(0); } while (0)
; #define PG8_WAIT_V(n) asm volatile("s_waitcnt vmcnt(" #n ")" ::: "memory")
; #define PG8_WAIT_L(n) asm volatile("s_waitcnt lgkmcnt(" #n ")" ::: "memory")
; #define PG8_BAR __builtin_amdgcn_s_barrier()
; #define PG8_SCHED __builtin_amdgcn_sched_barrier(0)
; template <class Epi, class Sched>
; DI void gemm_phase(LAS unsigned char* lds, const Gemm g, const Sched& S, const Epi& E) {
;     ...
;             PG8_LDA(At, 0, 1); PG8_STAGE(PG8_SA(0, 0), a2, voffA);
;             PG8_BAR; PG8_WAIT_L(0); PG8_MMA(1, 0, At, B0); PG8_BAR; PG8_SCHED;
;             PG8_STAGE(PG8_SB(0, 1), b2 + hstepB, voffB);
;             PG8_WAIT_V(6); PG8_BAR; PG8_MMA(1, 1, At, B1); PG8_BAR;
;             PG8_LDB(B0, 1, 0); PG8_SCHED; PG8_LDA(At, 1, 0); PG8_STAGE(PG8_SA(0, 1), a2 + hstepA, voffA);
;             PG8_WAIT_L(8); PG8_BAR; PG8_WAIT_L(0); PG8_MMA(0, 0, At, B0); PG8_BAR; PG8_SCHED;
;             PG8_LDB(B1, 1, 1); PG8_STAGE(PG8_SB(1, 0), b3, voffB);
;             PG8_BAR; PG8_WAIT_L(0); PG8_MMA(0, 1, At, B1); PG8_BAR;
;             PG8_LDA(At, 1, 1); PG8_STAGE(PG8_SA(1, 0), a3, voffA);
;             PG8_BAR; PG8_WAIT_L(0); PG8_MMA(1, 0, At, B0); PG8_BAR; PG8_SCHED;
;             PG8_STAGE(PG8_SB(1, 1), b3 + hstepB, voffB);
	s_add_u32 s84, s2, 0x40000
	s_addc_u32 s85, s3, 0
	s_add_i32 s83, s92, s42
	v_lshl_add_u64 v[20:21], s[84:85], 0, v[2:3]
	s_mov_b32 m0, s83
	s_nop 0
	global_load_lds_dwordx4 v[20:21], off
	v_lshl_add_u64 v[20:21], s[84:85], 0, v[0:1]
	s_add_i32 m0, s83, 0x2000
	s_nop 0
	global_load_lds_dwordx4 v[20:21], off
	s_waitcnt vmcnt(6)
	s_barrier
	s_setprio 1
	v_mfma_f32_16x16x32_bf16 v[32:35], v[202:205], v[172:175], v[32:35]
	v_mfma_f32_16x16x32_bf16 v[28:31], v[210:213], v[172:175], v[28:31]
	v_mfma_f32_16x16x32_bf16 v[8:11], v[202:205], v[184:187], v[8:11]
	v_mfma_f32_16x16x32_bf16 v[4:7], v[210:213], v[184:187], v[4:7]
	v_mfma_f32_16x16x32_bf16 v[20:23], v[202:205], v[136:139], v[72:75]
	v_mfma_f32_16x16x32_bf16 v[24:27], v[210:213], v[136:139], v[68:71]
	v_mfma_f32_16x16x32_bf16 v[36:39], v[202:205], v[152:155], v[56:59]
	v_mfma_f32_16x16x32_bf16 v[40:43], v[210:213], v[152:155], v[52:55]
	v_mfma_f32_16x16x32_bf16 v[32:35], v[206:209], v[176:179], v[32:35]
	v_mfma_f32_16x16x32_bf16 v[28:31], v[214:217], v[176:179], v[28:31]
	v_mfma_f32_16x16x32_bf16 v[8:11], v[206:209], v[188:191], v[8:11]
	v_mfma_f32_16x16x32_bf16 v[4:7], v[214:217], v[188:191], v[4:7]
	v_mfma_f32_16x16x32_bf16 v[20:23], v[206:209], v[144:147], v[20:23]
	v_mfma_f32_16x16x32_bf16 v[24:27], v[214:217], v[144:147], v[24:27]
	v_mfma_f32_16x16x32_bf16 v[36:39], v[206:209], v[160:163], v[36:39]
	v_mfma_f32_16x16x32_bf16 v[40:43], v[214:217], v[160:163], v[40:43]
	s_setprio 0
	s_add_i32 s83, 0, 0x18000
	v_add_u32_e32 v72, s83, v181
	s_barrier
	ds_read_b128 v[52:55], v72
	ds_read_b128 v[56:59], v72 offset:1024
	ds_read_b128 v[68:71], v72 offset:2048
	ds_read_b128 v[72:75], v72 offset:3072
	s_add_u32 s38, s38, 0x40000
	s_addc_u32 s39, s39, 0
	s_mov_b32 m0, s48
	v_lshl_add_u64 v[202:203], s[38:39], 0, v[166:167]
	ds_read_b128 v[136:139], v183 offset:32768
	ds_read_b128 v[144:147], v183 offset:33792
	ds_read_b128 v[152:155], v183 offset:34816
	ds_read_b128 v[160:163], v183 offset:35840
	ds_read_b128 v[172:175], v183 offset:36864
	ds_read_b128 v[176:179], v183 offset:37888
	ds_read_b128 v[184:187], v183 offset:38912
	ds_read_b128 v[188:191], v183 offset:39936
	global_load_lds_dwordx4 v[202:203], off
	v_lshl_add_u64 v[202:203], s[38:39], 0, v[164:165]
	s_mov_b32 m0, s49
	s_nop 0
	global_load_lds_dwordx4 v[202:203], off
	s_waitcnt lgkmcnt(8)
	s_barrier
	s_waitcnt lgkmcnt(0)
	s_setprio 1
	s_waitcnt lgkmcnt(0)
	v_mfma_f32_16x16x32_bf16 v[156:159], v[52:55], v[136:139], v[156:159]
	v_mfma_f32_16x16x32_bf16 v[148:151], v[68:71], v[136:139], v[148:151]
	v_mfma_f32_16x16x32_bf16 v[128:131], v[52:55], v[152:155], v[128:131]
	v_mfma_f32_16x16x32_bf16 v[124:127], v[68:71], v[152:155], v[124:127]
	v_mfma_f32_16x16x32_bf16 v[112:115], v[52:55], v[172:175], v[112:115]
	v_mfma_f32_16x16x32_bf16 v[108:111], v[68:71], v[172:175], v[108:111]
	v_mfma_f32_16x16x32_bf16 v[96:99], v[52:55], v[184:187], v[96:99]
	v_mfma_f32_16x16x32_bf16 v[92:95], v[68:71], v[184:187], v[92:95]
	v_mfma_f32_16x16x32_bf16 v[156:159], v[56:59], v[144:147], v[156:159]
	v_mfma_f32_16x16x32_bf16 v[148:151], v[72:75], v[144:147], v[148:151]
	v_mfma_f32_16x16x32_bf16 v[128:131], v[56:59], v[160:163], v[128:131]
	v_mfma_f32_16x16x32_bf16 v[124:127], v[72:75], v[160:163], v[124:127]
	v_mfma_f32_16x16x32_bf16 v[112:115], v[56:59], v[176:179], v[112:115]
	v_mfma_f32_16x16x32_bf16 v[108:111], v[72:75], v[176:179], v[108:111]
	v_mfma_f32_16x16x32_bf16 v[96:99], v[56:59], v[188:191], v[96:99]
	v_mfma_f32_16x16x32_bf16 v[92:95], v[72:75], v[188:191], v[92:95]
	s_setprio 0
	s_barrier
	s_add_i32 s38, 0, 0x1c000
	s_add_i32 s39, s83, s42
	v_add_u32_e32 v214, s38, v181
	v_lshl_add_u64 v[230:231], v[230:231], 0, s[78:79]
	s_mov_b32 m0, s39
	ds_read_b128 v[202:205], v214
	ds_read_b128 v[206:209], v214 offset:1024
	ds_read_b128 v[210:213], v214 offset:2048
	ds_read_b128 v[214:217], v214 offset:3072
	global_load_lds_dwordx4 v[230:231], off
	v_lshl_add_u64 v[230:231], v[232:233], 0, s[78:79]
	s_add_i32 m0, s39, 0x2000
	s_nop 0
	global_load_lds_dwordx4 v[230:231], off
	s_barrier
	s_waitcnt lgkmcnt(0)
	s_setprio 1
	s_waitcnt lgkmcnt(0)
	v_mfma_f32_16x16x32_bf16 v[140:143], v[202:205], v[136:139], v[140:143]
	v_mfma_f32_16x16x32_bf16 v[132:135], v[210:213], v[136:139], v[132:135]
	v_mfma_f32_16x16x32_bf16 v[120:123], v[202:205], v[152:155], v[120:123]
	v_mfma_f32_16x16x32_bf16 v[116:119], v[210:213], v[152:155], v[116:119]
	v_mfma_f32_16x16x32_bf16 v[104:107], v[202:205], v[172:175], v[104:107]
	v_mfma_f32_16x16x32_bf16 v[100:103], v[210:213], v[172:175], v[100:103]
	v_mfma_f32_16x16x32_bf16 v[88:91], v[202:205], v[184:187], v[88:91]
	v_mfma_f32_16x16x32_bf16 v[84:87], v[210:213], v[184:187], v[84:87]
	v_mfma_f32_16x16x32_bf16 v[140:143], v[206:209], v[144:147], v[140:143]
	v_mfma_f32_16x16x32_bf16 v[136:139], v[214:217], v[144:147], v[132:135]
	v_mfma_f32_16x16x32_bf16 v[120:123], v[206:209], v[160:163], v[120:123]
	v_mfma_f32_16x16x32_bf16 v[116:119], v[214:217], v[160:163], v[116:119]
	v_mfma_f32_16x16x32_bf16 v[104:107], v[206:209], v[176:179], v[104:107]
	v_mfma_f32_16x16x32_bf16 v[100:103], v[214:217], v[176:179], v[100:103]
	v_mfma_f32_16x16x32_bf16 v[88:91], v[206:209], v[188:191], v[88:91]
	v_mfma_f32_16x16x32_bf16 v[84:87], v[214:217], v[188:191], v[84:87]
	s_setprio 0
	s_mov_b32 m0, s50
	v_lshl_add_u64 v[230:231], v[234:235], 0, s[78:79]
	s_barrier
	ds_read_b128 v[132:135], v183 offset:49152
	ds_read_b128 v[144:147], v183 offset:50176
	ds_read_b128 v[152:155], v183 offset:51200
	ds_read_b128 v[160:163], v183 offset:52224
	ds_read_b128 v[172:175], v183 offset:53248
	ds_read_b128 v[176:179], v183 offset:54272
	ds_read_b128 v[184:187], v183 offset:55296
	ds_read_b128 v[188:191], v183 offset:56320
	global_load_lds_dwordx4 v[230:231], off
	v_lshl_add_u64 v[230:231], v[236:237], 0, s[78:79]
	s_mov_b32 m0, s51
	s_nop 0
	global_load_lds_dwordx4 v[230:231], off
	s_barrier
; DI void unpack8(u32x4 w, float* f) { f[0] = bflo(w.x); f[1] = bfhi(w.x); f[2] = bflo(w.y); f[3] = bfhi(w.y); f[4] = bflo(w.z); f[5] = bfhi(w.z); f[6] = bflo(w.w); f[7] = bfhi(w.w); }
; DI float sigmoidf_(float x) { return 1.f / (1.f + __expf(-x)); }
; #define PG8_STAGE(bufoff, gbase, voff) do { _Pragma("unroll") for (int _i = 0; _i < 2; ++_i) \
;         __builtin_amdgcn_global_load_lds((const unsigned*)((const char*)(gbase) + (voff)[_i]), (LAS unsigned*)(lds + (bufoff) + ldsw + _i * 8192), 16, 0, 0); } while (0)
; #define PG8_WAIT_V(n) asm volatile("s_waitcnt vmcnt(" #n ")" ::: "memory")
; template <class Epi, class Sched>
; DI void gemm_phase(LAS unsigned char* lds, const Gemm g, const Sched& S, const Epi& E) {
;     ...
;             PG8_BAR; PG8_WAIT_L(0); PG8_MMA(1, 0, At, B0); PG8_BAR; PG8_SCHED;
;             PG8_STAGE(PG8_SB(1, 1), b3 + hstepB, voffB);
;             PG8_WAIT_V(6); PG8_BAR; PG8_MMA(1, 1, At, B1); PG8_BAR;
;         }
;         E(acc, cur, wr, wc, fr, fq);
;     DI void operator()(const Acc& acc, const Unit& u, int wr, int wc, int fr, int fq) const {
;         f32x4 bv[2][2];
; #pragma unroll
;         for (int bj = 0; bj < 2; ++bj) { const int col = u.pn * 256 + bj * 128 + wc * 32 + 8 * fq; bv[bj][0] = *(const f32x4*)(bias + col); bv[bj][1] = *(const f32x4*)(bias + col + 4); }
; #pragma unroll
;         for (int ai = 0; ai < 2; ++ai)
; #pragma unroll
;             for (int mp = 0; mp < 2; ++mp) {
;                 u32x4 zv[2][2];
; #pragma unroll
;                 for (int mi = 0; mi < 2; ++mi)
; #pragma unroll
;                     for (int bj = 0; bj < 2; ++bj) { const int row = u.pm * 256 + ai * 128 + wr * 64 + (2 * mp + mi) * 16 + fr, col = u.pn * 256 + bj * 128 + wc * 32 + 8 * fq;
;                         zv[mi][bj] = *(const u32x4*)(zs + (size_t)row * 1024 + col); }
; #pragma unroll
;                 for (int mi = 0; mi < 2; ++mi)
; #pragma unroll
;                     for (int bj = 0; bj < 2; ++bj) { const int m = 2 * mp + mi, row = u.pm * 256 + ai * 128 + wr * 64 + m * 16 + fr, col = u.pn * 256 + bj * 128 + wc * 32 + 8 * fq;
;                         f32x4 v0 = acc[ai][bj][m][0], v1 = acc[ai][bj][m][1]; float zf[8]; unpack8(zv[mi][bj], zf);
;                         for (int j = 0; j < 4; ++j) { v0[j] = zf[j] * sigmoidf_(v0[j] + bv[bj][0][j]); v1[j] = zf[4 + j] * sigmoidf_(v1[j] + bv[bj][1][j]); }
	s_waitcnt lgkmcnt(0)
	s_setprio 1
	s_waitcnt lgkmcnt(0)
	v_mfma_f32_16x16x32_bf16 v[80:83], v[52:55], v[132:135], v[80:83]
	v_mfma_f32_16x16x32_bf16 v[76:79], v[68:71], v[132:135], v[76:79]
	v_mfma_f32_16x16x32_bf16 v[64:67], v[52:55], v[152:155], v[64:67]
	v_mfma_f32_16x16x32_bf16 v[60:63], v[68:71], v[152:155], v[60:63]
	v_mfma_f32_16x16x32_bf16 v[48:51], v[52:55], v[172:175], v[48:51]
	v_mfma_f32_16x16x32_bf16 v[44:47], v[68:71], v[172:175], v[44:47]
	v_mfma_f32_16x16x32_bf16 v[16:19], v[52:55], v[184:187], v[16:19]
	v_mfma_f32_16x16x32_bf16 v[12:15], v[68:71], v[184:187], v[12:15]
	v_mfma_f32_16x16x32_bf16 v[80:83], v[56:59], v[144:147], v[80:83]
	v_mfma_f32_16x16x32_bf16 v[76:79], v[72:75], v[144:147], v[76:79]
	v_mfma_f32_16x16x32_bf16 v[64:67], v[56:59], v[160:163], v[64:67]
	v_mfma_f32_16x16x32_bf16 v[60:63], v[72:75], v[160:163], v[60:63]
	v_mfma_f32_16x16x32_bf16 v[48:51], v[56:59], v[176:179], v[48:51]
	v_mfma_f32_16x16x32_bf16 v[44:47], v[72:75], v[176:179], v[44:47]
	v_mfma_f32_16x16x32_bf16 v[16:19], v[56:59], v[188:191], v[16:19]
	v_mfma_f32_16x16x32_bf16 v[12:15], v[72:75], v[188:191], v[12:15]
	s_setprio 0
	s_barrier
	s_add_u32 s2, s2, 0x40080
	s_addc_u32 s3, s3, 0
	s_add_i32 s38, s38, s42
	v_lshl_add_u64 v[52:53], s[2:3], 0, v[2:3]
	s_mov_b32 m0, s38
	s_nop 0
	global_load_lds_dwordx4 v[52:53], off
	v_lshl_add_u64 v[52:53], s[2:3], 0, v[0:1]
	s_add_i32 m0, s38, 0x2000
	s_nop 0
	global_load_lds_dwordx4 v[52:53], off
	s_waitcnt vmcnt(6)
	s_barrier
	s_setprio 1
	v_mfma_f32_16x16x32_bf16 v[20:23], v[202:205], v[132:135], v[20:23]
	v_mfma_f32_16x16x32_bf16 v[72:75], v[206:209], v[144:147], v[20:23]
	v_mfma_f32_16x16x32_bf16 v[20:23], v[210:213], v[132:135], v[24:27]
	v_mfma_f32_16x16x32_bf16 v[68:71], v[214:217], v[144:147], v[20:23]
	v_mfma_f32_16x16x32_bf16 v[20:23], v[202:205], v[152:155], v[36:39]
	v_mfma_f32_16x16x32_bf16 v[56:59], v[206:209], v[160:163], v[20:23]
	v_mfma_f32_16x16x32_bf16 v[20:23], v[210:213], v[152:155], v[40:43]
	v_mfma_f32_16x16x32_bf16 v[52:55], v[214:217], v[160:163], v[20:23]
	v_mfma_f32_16x16x32_bf16 v[20:23], v[202:205], v[172:175], v[32:35]
	v_mfma_f32_16x16x32_bf16 v[32:35], v[206:209], v[176:179], v[20:23]
	v_mfma_f32_16x16x32_bf16 v[20:23], v[210:213], v[172:175], v[28:31]
	v_mfma_f32_16x16x32_bf16 v[8:11], v[202:205], v[184:187], v[8:11]
	v_mfma_f32_16x16x32_bf16 v[4:7], v[210:213], v[184:187], v[4:7]
	v_mfma_f32_16x16x32_bf16 v[28:31], v[214:217], v[176:179], v[20:23]
	v_mfma_f32_16x16x32_bf16 v[8:11], v[206:209], v[188:191], v[8:11]
	v_mfma_f32_16x16x32_bf16 v[4:7], v[214:217], v[188:191], v[4:7]
	s_setprio 0
	s_add_i32 s82, s82, 2
	s_add_u32 s20, s20, 0x100
	s_addc_u32 s21, s21, 0
	s_add_u32 s64, s64, 0x100
	s_addc_u32 s65, s65, 0
	s_cmp_gt_u32 s82, 13
	s_barrier
	s_cbranch_scc0 .LBB0_137
	v_lshl_or_b32 v132, s54, 8, v182
	v_ashrrev_i32_e32 v133, 31, v132
	v_lshl_add_u64 v[24:25], v[132:133], 2, s[26:27]
	global_load_dwordx4 v[36:39], v[24:25], off offset:16
	global_load_dwordx4 v[40:43], v[24:25], off
	global_load_dwordx4 v[20:23], v[24:25], off offset:528
	s_nop 0
	global_load_dwordx4 v[24:27], v[24:25], off offset:512
	v_lshl_add_u32 v174, s53, 8, v180
	v_ashrrev_i32_e32 v175, 31, v174
	v_lshlrev_b64 v[178:179], 11, v[174:175]
	v_lshl_add_u64 v[134:135], s[4:5], 0, v[178:179]
	v_lshlrev_b64 v[172:173], 1, v[132:133]
	v_lshl_add_u64 v[132:133], v[134:135], 0, v[172:173]
	global_load_dwordx4 v[160:163], v[132:133], off
	global_load_dwordx4 v[152:155], v[132:133], off offset:256
	v_or_b32_e32 v132, 16, v174
	v_ashrrev_i32_e32 v133, 31, v132
	v_lshlrev_b64 v[176:177], 11, v[132:133]
	v_lshl_add_u64 v[132:133], s[4:5], 0, v[176:177]
	v_lshl_add_u64 v[132:133], v[132:133], 0, v[172:173]
	global_load_dwordx4 v[144:147], v[132:133], off
	s_nop 0
	global_load_dwordx4 v[132:135], v[132:133], off offset:256
	s_mov_b32 s54, s28
	s_mov_b32 s53, s30
	s_mov_b64 s[20:21], s[34:35]
	v_readlane_b32 s85, v254, 37
	s_waitcnt vmcnt(0)
	v_add_f32_e32 v148, v148, v36
	v_add_f32_e32 v156, v156, v40
	v_add_f32_e32 v157, v157, v41
	v_mul_f32_e32 v156, 0xbfb8aa3b, v156
	v_mul_f32_e32 v157, 0xbfb8aa3b, v157
	v_exp_f32_e32 v156, v156
	v_exp_f32_e32 v157, v157
	v_add_f32_e32 v149, v149, v37
	v_mul_f32_e32 v148, 0xbfb8aa3b, v148
	v_lshlrev_b32_e32 v184, 16, v160
	v_pk_add_f32 v[156:157], v[156:157], 1.0 op_sel_hi:[1,0]
	v_and_b32_e32 v185, 0xffff0000, v160
	v_rcp_f32_e32 v175, v157
	s_nop 0
	v_mul_f32_e32 v149, 0xbfb8aa3b, v149
	v_exp_f32_e32 v148, v148
	v_exp_f32_e32 v149, v149
	v_mul_f32_e32 v187, 1.0, v175
	v_fma_f32 v188, -v157, v187, 1.0
	v_fmac_f32_e32 v187, v188, v175
	v_div_fixup_f32 v157, v187, v157, 1.0
	v_rcp_f32_e32 v175, v156
	s_nop 0
	v_pk_add_f32 v[148:149], v[148:149], 1.0 op_sel_hi:[1,0]
	v_add_f32_e32 v158, v158, v42
	v_mul_f32_e32 v158, 0xbfb8aa3b, v158
	v_mul_f32_e32 v187, 1.0, v175
	v_fma_f32 v188, -v156, v187, 1.0
	v_fmac_f32_e32 v187, v188, v175
	v_div_fixup_f32 v156, v187, v156, 1.0
	v_pk_mul_f32 v[156:157], v[156:157], v[184:185]
	v_lshlrev_b32_e32 v184, 16, v162
	v_and_b32_e32 v185, 0xffff0000, v162
	v_rcp_f32_e32 v162, v149
	s_nop 0
	v_add_f32_e32 v150, v150, v38
	v_add_f32_e32 v151, v151, v39
	v_mul_f32_e32 v150, 0xbfb8aa3b, v150
	v_mul_f32_e32 v186, 1.0, v162
	v_fma_f32 v187, -v149, v186, 1.0
	v_fmac_f32_e32 v186, v187, v162
	v_div_fixup_f32 v149, v186, v149, 1.0
	v_rcp_f32_e32 v162, v148
	s_nop 0
	v_mul_f32_e32 v151, 0xbfb8aa3b, v151
	v_exp_f32_e32 v150, v150
	v_exp_f32_e32 v151, v151
	v_mul_f32_e32 v186, 1.0, v162
	v_fma_f32 v187, -v148, v186, 1.0
	v_fmac_f32_e32 v186, v187, v162
	v_div_fixup_f32 v148, v186, v148, 1.0
	v_pk_mul_f32 v[148:149], v[148:149], v[184:185]
	v_exp_f32_e32 v184, v158
; DI void unpack8(u32x4 w, float* f) { f[0] = bflo(w.x); f[1] = bfhi(w.x); f[2] = bflo(w.y); f[3] = bfhi(w.y); f[4] = bflo(w.z); f[5] = bfhi(w.z); f[6] = bflo(w.w); f[7] = bfhi(w.w); }
; DI u32x4 pack44(f32x4 a, f32x4 b) { u32x4 w; w.x = pk2(a[0], a[1]); w.y = pk2(a[2], a[3]); w.z = pk2(b[0], b[1]); w.w = pk2(b[2], b[3]); return w; }
; DI float sigmoidf_(float x) { return 1.f / (1.f + __expf(-x)); }
;     DI void operator()(const Acc& acc, const Unit& u, int wr, int wc, int fr, int fq) const {
;     ...
;                     for (int bj = 0; bj < 2; ++bj) { const int row = u.pm * 256 + ai * 128 + wr * 64 + (2 * mp + mi) * 16 + fr, col = u.pn * 256 + bj * 128 + wc * 32 + 8 * fq;
;                         zv[mi][bj] = *(const u32x4*)(zs + (size_t)row * 1024 + col); }
; #pragma unroll
;                 for (int mi = 0; mi < 2; ++mi)
; #pragma unroll
;                     for (int bj = 0; bj < 2; ++bj) { const int m = 2 * mp + mi, row = u.pm * 256 + ai * 128 + wr * 64 + m * 16 + fr, col = u.pn * 256 + bj * 128 + wc * 32 + 8 * fq;
;                         f32x4 v0 = acc[ai][bj][m][0], v1 = acc[ai][bj][m][1]; float zf[8]; unpack8(zv[mi][bj], zf);
;                         for (int j = 0; j < 4; ++j) { v0[j] = zf[j] * sigmoidf_(v0[j] + bv[bj][0][j]); v1[j] = zf[4 + j] * sigmoidf_(v1[j] + bv[bj][1][j]); }
;                         *(u32x4*)(y2 + (size_t)row * 1024 + col) = pack44(v0, v1); }
	v_add_f32_e32 v158, v159, v43
	v_mul_f32_e32 v158, 0xbfb8aa3b, v158
	v_exp_f32_e32 v185, v158
	v_lshlrev_b32_e32 v158, 16, v161
	v_and_b32_e32 v159, 0xffff0000, v161
	v_pk_add_f32 v[150:151], v[150:151], 1.0 op_sel_hi:[1,0]
	v_pk_add_f32 v[160:161], v[184:185], 1.0 op_sel_hi:[1,0]
	v_add_f32_e32 v140, v140, v24
	v_rcp_f32_e32 v175, v161
	s_nop 0
	v_add_f32_e32 v141, v141, v25
	v_mul_f32_e32 v140, 0xbfb8aa3b, v140
	v_mul_f32_e32 v141, 0xbfb8aa3b, v141
	v_mul_f32_e32 v185, 1.0, v175
	v_fma_f32 v186, -v161, v185, 1.0
	v_fmac_f32_e32 v185, v186, v175
	v_div_fixup_f32 v161, v185, v161, 1.0
	v_rcp_f32_e32 v175, v160
	s_nop 0
	v_exp_f32_e32 v140, v140
	v_exp_f32_e32 v141, v141
	v_cvt_pk_bf16_f32 v156, v156, v157
	v_mul_f32_e32 v185, 1.0, v175
	v_fma_f32 v186, -v160, v185, 1.0
	v_fmac_f32_e32 v185, v186, v175
	v_div_fixup_f32 v160, v185, v160, 1.0
	v_pk_mul_f32 v[158:159], v[160:161], v[158:159]
	v_lshlrev_b32_e32 v160, 16, v163
	v_and_b32_e32 v161, 0xffff0000, v163
	v_rcp_f32_e32 v163, v151
	s_nop 0
	v_cvt_pk_bf16_f32 v157, v158, v159
	v_cvt_pk_bf16_f32 v158, v148, v149
	v_lshl_add_u64 v[148:149], s[68:69], 0, v[178:179]
	v_mul_f32_e32 v184, 1.0, v163
	v_fma_f32 v185, -v151, v184, 1.0
	v_fmac_f32_e32 v184, v185, v163
	v_div_fixup_f32 v151, v184, v151, 1.0
	v_rcp_f32_e32 v163, v150
	s_nop 0
	v_pk_add_f32 v[140:141], v[140:141], 1.0 op_sel_hi:[1,0]
	v_lshl_add_u64 v[148:149], v[148:149], 0, v[172:173]
	v_add_f32_e32 v136, v136, v20
	v_mul_f32_e32 v184, 1.0, v163
	v_fma_f32 v185, -v150, v184, 1.0
	v_fmac_f32_e32 v184, v185, v163
	v_div_fixup_f32 v150, v184, v150, 1.0
	v_pk_mul_f32 v[150:151], v[150:151], v[160:161]
	v_add_f32_e32 v137, v137, v21
	v_cvt_pk_bf16_f32 v159, v150, v151
	v_lshlrev_b32_e32 v150, 16, v152
	v_and_b32_e32 v151, 0xffff0000, v152
	global_store_dwordx4 v[148:149], v[156:159], off
	v_mul_f32_e32 v136, 0xbfb8aa3b, v136
	v_mul_f32_e32 v137, 0xbfb8aa3b, v137
	v_rcp_f32_e32 v156, v141
	s_nop 0
	v_exp_f32_e32 v136, v136
	v_exp_f32_e32 v137, v137
	v_add_f32_e32 v128, v128, v40
	v_mul_f32_e32 v158, 1.0, v156
	v_fma_f32 v159, -v141, v158, 1.0
	v_fmac_f32_e32 v158, v159, v156
	v_div_fixup_f32 v141, v158, v141, 1.0
	v_rcp_f32_e32 v156, v140
	s_nop 0
	v_pk_add_f32 v[136:137], v[136:137], 1.0 op_sel_hi:[1,0]
	v_add_f32_e32 v129, v129, v41
	v_mul_f32_e32 v128, 0xbfb8aa3b, v128
	v_mul_f32_e32 v158, 1.0, v156
	v_fma_f32 v159, -v140, v158, 1.0
	v_fmac_f32_e32 v158, v159, v156
	v_div_fixup_f32 v140, v158, v140, 1.0
	v_pk_mul_f32 v[140:141], v[140:141], v[150:151]
	v_lshlrev_b32_e32 v150, 16, v154
	v_and_b32_e32 v151, 0xffff0000, v154
	v_rcp_f32_e32 v154, v137
	s_nop 0
	v_mul_f32_e32 v129, 0xbfb8aa3b, v129
	v_exp_f32_e32 v128, v128
	v_exp_f32_e32 v129, v129
	v_mul_f32_e32 v157, 1.0, v154
	v_fma_f32 v158, -v137, v157, 1.0
	v_fmac_f32_e32 v157, v158, v154
	v_div_fixup_f32 v137, v157, v137, 1.0
	v_rcp_f32_e32 v154, v136
	s_nop 0
	v_pk_add_f32 v[128:129], v[128:129], 1.0 op_sel_hi:[1,0]
	v_add_f32_e32 v124, v124, v36
	v_add_f32_e32 v125, v125, v37
	v_mul_f32_e32 v157, 1.0, v154
	v_fma_f32 v158, -v136, v157, 1.0
	v_fmac_f32_e32 v157, v158, v154
	v_div_fixup_f32 v136, v157, v136, 1.0
	v_pk_mul_f32 v[150:151], v[136:137], v[150:151]
	v_add_f32_e32 v137, v138, v22
	v_mul_f32_e32 v137, 0xbfb8aa3b, v137
	v_add_f32_e32 v136, v142, v26
	v_exp_f32_e32 v138, v137
	v_add_f32_e32 v137, v143, v27
	v_mul_f32_e32 v136, 0xbfb8aa3b, v136
	v_mul_f32_e32 v137, 0xbfb8aa3b, v137
	v_exp_f32_e32 v136, v136
	v_exp_f32_e32 v137, v137
	v_lshlrev_b32_e32 v142, 16, v153
	v_and_b32_e32 v143, 0xffff0000, v153
	v_mul_f32_e32 v124, 0xbfb8aa3b, v124
	v_pk_add_f32 v[136:137], v[136:137], 1.0 op_sel_hi:[1,0]
	v_mul_f32_e32 v125, 0xbfb8aa3b, v125
	v_rcp_f32_e32 v153, v137
	s_nop 0
	v_exp_f32_e32 v124, v124
	v_exp_f32_e32 v125, v125
	v_add_f32_e32 v130, v130, v42
	v_mul_f32_e32 v156, 1.0, v153
	v_fma_f32 v157, -v137, v156, 1.0
	v_fmac_f32_e32 v156, v157, v153
	v_div_fixup_f32 v137, v156, v137, 1.0
	v_rcp_f32_e32 v153, v136
	s_nop 0
	v_pk_add_f32 v[124:125], v[124:125], 1.0 op_sel_hi:[1,0]
	v_add_f32_e32 v131, v131, v43
	v_mul_f32_e32 v130, 0xbfb8aa3b, v130
	v_mul_f32_e32 v156, 1.0, v153
	v_fma_f32 v157, -v136, v156, 1.0
	v_fmac_f32_e32 v156, v157, v153
	v_div_fixup_f32 v136, v156, v136, 1.0
	v_pk_mul_f32 v[142:143], v[136:137], v[142:143]
	v_add_f32_e32 v136, v139, v23
	v_mul_f32_e32 v136, 0xbfb8aa3b, v136
	v_exp_f32_e32 v139, v136
	v_lshlrev_b32_e32 v136, 16, v155
	v_and_b32_e32 v137, 0xffff0000, v155
	v_mul_f32_e32 v131, 0xbfb8aa3b, v131
	v_pk_add_f32 v[138:139], v[138:139], 1.0 op_sel_hi:[1,0]
	v_exp_f32_e32 v130, v130
	v_rcp_f32_e32 v153, v139
	s_nop 0
	v_exp_f32_e32 v131, v131
	v_add_f32_e32 v126, v126, v38
	v_add_f32_e32 v127, v127, v39
	v_mul_f32_e32 v155, 1.0, v153
	v_fma_f32 v156, -v139, v155, 1.0
	v_fmac_f32_e32 v155, v156, v153
	v_div_fixup_f32 v139, v155, v139, 1.0
	v_rcp_f32_e32 v153, v138
	s_nop 0
	v_pk_add_f32 v[130:131], v[130:131], 1.0 op_sel_hi:[1,0]
	v_mul_f32_e32 v126, 0xbfb8aa3b, v126
	v_mul_f32_e32 v127, 0xbfb8aa3b, v127
	v_mul_f32_e32 v155, 1.0, v153
	v_fma_f32 v156, -v138, v155, 1.0
	v_fmac_f32_e32 v155, v156, v153
	v_div_fixup_f32 v138, v155, v138, 1.0
	v_pk_mul_f32 v[152:153], v[138:139], v[136:137]
	v_cvt_pk_bf16_f32 v136, v140, v141
	v_cvt_pk_bf16_f32 v137, v142, v143
	v_cvt_pk_bf16_f32 v138, v150, v151
	v_cvt_pk_bf16_f32 v139, v152, v153
	global_store_dwordx4 v[148:149], v[136:139], off offset:256
	v_exp_f32_e32 v126, v126
	v_exp_f32_e32 v127, v127
	v_rcp_f32_e32 v139, v129
	s_nop 0
	v_pk_add_f32 v[126:127], v[126:127], 1.0 op_sel_hi:[1,0]
	v_add_f32_e32 v120, v120, v24
	v_add_f32_e32 v121, v121, v25
	v_mul_f32_e32 v141, 1.0, v139
	v_fma_f32 v142, -v129, v141, 1.0
; DI void unpack8(u32x4 w, float* f) { f[0] = bflo(w.x); f[1] = bfhi(w.x); f[2] = bflo(w.y); f[3] = bfhi(w.y); f[4] = bflo(w.z); f[5] = bfhi(w.z); f[6] = bflo(w.w); f[7] = bfhi(w.w); }
; DI u32x4 pack44(f32x4 a, f32x4 b) { u32x4 w; w.x = pk2(a[0], a[1]); w.y = pk2(a[2], a[3]); w.z = pk2(b[0], b[1]); w.w = pk2(b[2], b[3]); return w; }
; DI float sigmoidf_(float x) { return 1.f / (1.f + __expf(-x)); }
;     DI void operator()(const Acc& acc, const Unit& u, int wr, int wc, int fr, int fq) const {
;     ...
;                     for (int bj = 0; bj < 2; ++bj) { const int row = u.pm * 256 + ai * 128 + wr * 64 + (2 * mp + mi) * 16 + fr, col = u.pn * 256 + bj * 128 + wc * 32 + 8 * fq;
;                         zv[mi][bj] = *(const u32x4*)(zs + (size_t)row * 1024 + col); }
; #pragma unroll
;                 for (int mi = 0; mi < 2; ++mi)
; #pragma unroll
;                     for (int bj = 0; bj < 2; ++bj) { const int m = 2 * mp + mi, row = u.pm * 256 + ai * 128 + wr * 64 + m * 16 + fr, col = u.pn * 256 + bj * 128 + wc * 32 + 8 * fq;
;                         f32x4 v0 = acc[ai][bj][m][0], v1 = acc[ai][bj][m][1]; float zf[8]; unpack8(zv[mi][bj], zf);
;                         for (int j = 0; j < 4; ++j) { v0[j] = zf[j] * sigmoidf_(v0[j] + bv[bj][0][j]); v1[j] = zf[4 + j] * sigmoidf_(v1[j] + bv[bj][1][j]); }
;                         *(u32x4*)(y2 + (size_t)row * 1024 + col) = pack44(v0, v1); }
	v_fmac_f32_e32 v141, v142, v139
	v_div_fixup_f32 v129, v141, v129, 1.0
	v_rcp_f32_e32 v139, v128
	s_nop 0
	v_lshlrev_b32_e32 v136, 16, v144
	v_and_b32_e32 v137, 0xffff0000, v144
	v_mul_f32_e32 v120, 0xbfb8aa3b, v120
	v_mul_f32_e32 v141, 1.0, v139
	v_fma_f32 v142, -v128, v141, 1.0
	v_fmac_f32_e32 v141, v142, v139
	v_div_fixup_f32 v128, v141, v128, 1.0
	v_rcp_f32_e32 v139, v125
	s_nop 0
	v_mul_f32_e32 v121, 0xbfb8aa3b, v121
	v_pk_mul_f32 v[128:129], v[128:129], v[136:137]
	v_lshlrev_b32_e32 v136, 16, v146
	v_mul_f32_e32 v141, 1.0, v139
	v_fma_f32 v142, -v125, v141, 1.0
	v_fmac_f32_e32 v141, v142, v139
	v_div_fixup_f32 v125, v141, v125, 1.0
	v_rcp_f32_e32 v139, v124
	s_nop 0
	v_and_b32_e32 v137, 0xffff0000, v146
	v_exp_f32_e32 v120, v120
	v_exp_f32_e32 v121, v121
	v_mul_f32_e32 v141, 1.0, v139
	v_fma_f32 v142, -v124, v141, 1.0
	v_fmac_f32_e32 v141, v142, v139
	v_div_fixup_f32 v124, v141, v124, 1.0
	v_rcp_f32_e32 v139, v131
	s_nop 0
	v_pk_mul_f32 v[124:125], v[124:125], v[136:137]
	v_lshlrev_b32_e32 v136, 16, v145
	v_and_b32_e32 v137, 0xffff0000, v145
	v_mul_f32_e32 v141, 1.0, v139
	v_fma_f32 v142, -v131, v141, 1.0
	v_fmac_f32_e32 v141, v142, v139
	v_div_fixup_f32 v131, v141, v131, 1.0
	v_rcp_f32_e32 v139, v130
	s_nop 0
	v_pk_add_f32 v[120:121], v[120:121], 1.0 op_sel_hi:[1,0]
	v_add_f32_e32 v116, v116, v20
	v_add_f32_e32 v117, v117, v21
	v_mul_f32_e32 v141, 1.0, v139
	v_fma_f32 v142, -v130, v141, 1.0
	v_fmac_f32_e32 v141, v142, v139
	v_div_fixup_f32 v130, v141, v130, 1.0
	v_rcp_f32_e32 v139, v127
	s_nop 0
	v_pk_mul_f32 v[130:131], v[130:131], v[136:137]
	v_lshlrev_b32_e32 v136, 16, v147
	v_and_b32_e32 v137, 0xffff0000, v147
	v_mul_f32_e32 v141, 1.0, v139
	v_fma_f32 v142, -v127, v141, 1.0
	v_fmac_f32_e32 v141, v142, v139
	v_div_fixup_f32 v127, v141, v127, 1.0
	v_rcp_f32_e32 v139, v126
	s_nop 0
	v_mul_f32_e32 v116, 0xbfb8aa3b, v116
	v_mul_f32_e32 v117, 0xbfb8aa3b, v117
	v_exp_f32_e32 v116, v116
	v_mul_f32_e32 v141, 1.0, v139
	v_fma_f32 v142, -v126, v141, 1.0
	v_fmac_f32_e32 v141, v142, v139
	v_div_fixup_f32 v126, v141, v126, 1.0
	v_pk_mul_f32 v[136:137], v[126:127], v[136:137]
	v_cvt_pk_bf16_f32 v126, v128, v129
	v_cvt_pk_bf16_f32 v128, v124, v125
	v_lshl_add_u64 v[124:125], s[68:69], 0, v[176:177]
	v_cvt_pk_bf16_f32 v127, v130, v131
	v_cvt_pk_bf16_f32 v129, v136, v137
	v_lshl_add_u64 v[124:125], v[124:125], 0, v[172:173]
	global_store_dwordx4 v[124:125], v[126:129], off
	v_exp_f32_e32 v117, v117
	v_add_f32_e32 v112, v112, v40
	v_rcp_f32_e32 v129, v121
	s_nop 0
	v_lshlrev_b32_e32 v126, 16, v132
	v_and_b32_e32 v127, 0xffff0000, v132
	v_pk_add_f32 v[116:117], v[116:117], 1.0 op_sel_hi:[1,0]
	v_mul_f32_e32 v131, 1.0, v129
	v_fma_f32 v132, -v121, v131, 1.0
	v_fmac_f32_e32 v131, v132, v129
	v_div_fixup_f32 v121, v131, v121, 1.0
	v_rcp_f32_e32 v129, v120
	s_nop 0
	v_add_f32_e32 v113, v113, v41
	v_mul_f32_e32 v112, 0xbfb8aa3b, v112
	v_mul_f32_e32 v113, 0xbfb8aa3b, v113
	v_mul_f32_e32 v131, 1.0, v129
	v_fma_f32 v132, -v120, v131, 1.0
	v_fmac_f32_e32 v131, v132, v129
	v_div_fixup_f32 v120, v131, v120, 1.0
	v_rcp_f32_e32 v129, v117
	s_nop 0
	v_pk_mul_f32 v[120:121], v[120:121], v[126:127]
	v_lshlrev_b32_e32 v126, 16, v134
	v_and_b32_e32 v127, 0xffff0000, v134
	v_mul_f32_e32 v131, 1.0, v129
	v_fma_f32 v132, -v117, v131, 1.0
	v_fmac_f32_e32 v131, v132, v129
	v_div_fixup_f32 v117, v131, v117, 1.0
	v_rcp_f32_e32 v129, v116
	s_nop 0
	v_exp_f32_e32 v112, v112
	v_exp_f32_e32 v113, v113
	v_add_f32_e32 v108, v108, v36
	v_mul_f32_e32 v131, 1.0, v129
	v_fma_f32 v132, -v116, v131, 1.0
	v_fmac_f32_e32 v131, v132, v129
	v_div_fixup_f32 v116, v131, v116, 1.0
	v_pk_mul_f32 v[126:127], v[116:117], v[126:127]
	v_add_f32_e32 v117, v118, v22
	v_mul_f32_e32 v117, 0xbfb8aa3b, v117
	v_add_f32_e32 v116, v122, v26
	v_exp_f32_e32 v118, v117
	v_add_f32_e32 v117, v123, v27
	v_mul_f32_e32 v116, 0xbfb8aa3b, v116
	v_mul_f32_e32 v117, 0xbfb8aa3b, v117
	v_exp_f32_e32 v116, v116
	v_exp_f32_e32 v117, v117
	v_lshlrev_b32_e32 v122, 16, v133
	v_and_b32_e32 v123, 0xffff0000, v133
	v_pk_add_f32 v[112:113], v[112:113], 1.0 op_sel_hi:[1,0]
	v_pk_add_f32 v[116:117], v[116:117], 1.0 op_sel_hi:[1,0]
	v_add_f32_e32 v109, v109, v37
	v_rcp_f32_e32 v129, v117
	s_nop 0
	v_mul_f32_e32 v108, 0xbfb8aa3b, v108
	v_mul_f32_e32 v109, 0xbfb8aa3b, v109
	v_exp_f32_e32 v108, v108
	v_mul_f32_e32 v131, 1.0, v129
	v_fma_f32 v132, -v117, v131, 1.0
	v_fmac_f32_e32 v131, v132, v129
	v_div_fixup_f32 v117, v131, v117, 1.0
	v_rcp_f32_e32 v129, v116
	s_nop 0
	v_exp_f32_e32 v109, v109
	v_add_f32_e32 v114, v114, v42
	v_add_f32_e32 v115, v115, v43
	v_mul_f32_e32 v131, 1.0, v129
	v_fma_f32 v132, -v116, v131, 1.0
	v_fmac_f32_e32 v131, v132, v129
	v_div_fixup_f32 v116, v131, v116, 1.0
	v_pk_mul_f32 v[122:123], v[116:117], v[122:123]
	v_add_f32_e32 v116, v119, v23
	v_mul_f32_e32 v116, 0xbfb8aa3b, v116
	v_exp_f32_e32 v119, v116
	v_lshlrev_b32_e32 v116, 16, v135
	v_and_b32_e32 v117, 0xffff0000, v135
	v_pk_add_f32 v[108:109], v[108:109], 1.0 op_sel_hi:[1,0]
	v_pk_add_f32 v[118:119], v[118:119], 1.0 op_sel_hi:[1,0]
	v_mul_f32_e32 v114, 0xbfb8aa3b, v114
	v_rcp_f32_e32 v129, v119
	s_nop 0
	v_mul_f32_e32 v115, 0xbfb8aa3b, v115
	v_exp_f32_e32 v114, v114
	v_exp_f32_e32 v115, v115
	v_mul_f32_e32 v131, 1.0, v129
	v_fma_f32 v132, -v119, v131, 1.0
	v_fmac_f32_e32 v131, v132, v129
	v_div_fixup_f32 v119, v131, v119, 1.0
	v_rcp_f32_e32 v129, v118
	s_nop 0
	v_pk_add_f32 v[114:115], v[114:115], 1.0 op_sel_hi:[1,0]
	v_add_f32_e32 v110, v110, v38
	v_add_f32_e32 v111, v111, v39
	v_mul_f32_e32 v131, 1.0, v129
	v_fma_f32 v132, -v118, v131, 1.0
	v_fmac_f32_e32 v131, v132, v129
	v_div_fixup_f32 v118, v131, v118, 1.0
	v_pk_mul_f32 v[128:129], v[118:119], v[116:117]
; DI void unpack8(u32x4 w, float* f) { f[0] = bflo(w.x); f[1] = bfhi(w.x); f[2] = bflo(w.y); f[3] = bfhi(w.y); f[4] = bflo(w.z); f[5] = bfhi(w.z); f[6] = bflo(w.w); f[7] = bfhi(w.w); }
; DI u32x4 pack44(f32x4 a, f32x4 b) { u32x4 w; w.x = pk2(a[0], a[1]); w.y = pk2(a[2], a[3]); w.z = pk2(b[0], b[1]); w.w = pk2(b[2], b[3]); return w; }
; DI float sigmoidf_(float x) { return 1.f / (1.f + __expf(-x)); }
;     DI void operator()(const Acc& acc, const Unit& u, int wr, int wc, int fr, int fq) const {
;     ...
;                     for (int bj = 0; bj < 2; ++bj) { const int row = u.pm * 256 + ai * 128 + wr * 64 + (2 * mp + mi) * 16 + fr, col = u.pn * 256 + bj * 128 + wc * 32 + 8 * fq;
;                         zv[mi][bj] = *(const u32x4*)(zs + (size_t)row * 1024 + col); }
; #pragma unroll
;                 for (int mi = 0; mi < 2; ++mi)
; #pragma unroll
;                     for (int bj = 0; bj < 2; ++bj) { const int m = 2 * mp + mi, row = u.pm * 256 + ai * 128 + wr * 64 + m * 16 + fr, col = u.pn * 256 + bj * 128 + wc * 32 + 8 * fq;
;                         f32x4 v0 = acc[ai][bj][m][0], v1 = acc[ai][bj][m][1]; float zf[8]; unpack8(zv[mi][bj], zf);
;                         for (int j = 0; j < 4; ++j) { v0[j] = zf[j] * sigmoidf_(v0[j] + bv[bj][0][j]); v1[j] = zf[4 + j] * sigmoidf_(v1[j] + bv[bj][1][j]); }
;                         *(u32x4*)(y2 + (size_t)row * 1024 + col) = pack44(v0, v1); }
	v_cvt_pk_bf16_f32 v116, v120, v121
	v_cvt_pk_bf16_f32 v117, v122, v123
	v_cvt_pk_bf16_f32 v118, v126, v127
	v_cvt_pk_bf16_f32 v119, v128, v129
	global_store_dwordx4 v[124:125], v[116:119], off offset:256
	v_mul_f32_e32 v110, 0xbfb8aa3b, v110
	v_mul_f32_e32 v111, 0xbfb8aa3b, v111
	v_or_b32_e32 v116, 32, v174
	v_ashrrev_i32_e32 v117, 31, v116
	v_lshlrev_b64 v[134:135], 11, v[116:117]
	v_lshl_add_u64 v[116:117], s[4:5], 0, v[134:135]
	v_lshl_add_u64 v[116:117], v[116:117], 0, v[172:173]
	global_load_dwordx4 v[128:131], v[116:117], off
	global_load_dwordx4 v[124:127], v[116:117], off offset:256
	v_exp_f32_e32 v110, v110
	v_exp_f32_e32 v111, v111
	v_add_f32_e32 v104, v104, v24
	v_add_f32_e32 v105, v105, v25
	v_mul_f32_e32 v104, 0xbfb8aa3b, v104
	v_pk_add_f32 v[110:111], v[110:111], 1.0 op_sel_hi:[1,0]
	v_mul_f32_e32 v105, 0xbfb8aa3b, v105
	v_or_b32_e32 v116, 48, v174
	v_exp_f32_e32 v104, v104
	v_exp_f32_e32 v105, v105
	v_ashrrev_i32_e32 v117, 31, v116
	v_lshlrev_b64 v[132:133], 11, v[116:117]
	v_lshl_add_u64 v[116:117], s[4:5], 0, v[132:133]
	v_lshl_add_u64 v[116:117], v[116:117], 0, v[172:173]
	v_pk_add_f32 v[104:105], v[104:105], 1.0 op_sel_hi:[1,0]
	global_load_dwordx4 v[120:123], v[116:117], off
	s_nop 0
	global_load_dwordx4 v[116:119], v[116:117], off offset:256
	v_add_f32_e32 v100, v100, v20
	v_add_f32_e32 v101, v101, v21
	v_mul_f32_e32 v100, 0xbfb8aa3b, v100
	v_mul_f32_e32 v101, 0xbfb8aa3b, v101
	v_exp_f32_e32 v100, v100
	v_exp_f32_e32 v101, v101
	v_add_f32_e32 v96, v96, v40
	v_add_f32_e32 v97, v97, v41
	v_mul_f32_e32 v96, 0xbfb8aa3b, v96
	v_pk_add_f32 v[100:101], v[100:101], 1.0 op_sel_hi:[1,0]
	v_mul_f32_e32 v97, 0xbfb8aa3b, v97
	v_exp_f32_e32 v96, v96
	v_exp_f32_e32 v97, v97
	v_add_f32_e32 v92, v92, v36
	v_add_f32_e32 v93, v93, v37
	v_mul_f32_e32 v92, 0xbfb8aa3b, v92
	v_pk_add_f32 v[96:97], v[96:97], 1.0 op_sel_hi:[1,0]
	v_mul_f32_e32 v93, 0xbfb8aa3b, v93
	v_exp_f32_e32 v92, v92
	v_exp_f32_e32 v93, v93
	v_add_f32_e32 v98, v98, v42
	v_add_f32_e32 v99, v99, v43
	v_mul_f32_e32 v98, 0xbfb8aa3b, v98
	v_pk_add_f32 v[92:93], v[92:93], 1.0 op_sel_hi:[1,0]
	v_mul_f32_e32 v99, 0xbfb8aa3b, v99
	v_exp_f32_e32 v98, v98
	v_exp_f32_e32 v99, v99
	v_add_f32_e32 v94, v94, v38
	v_add_f32_e32 v95, v95, v39
	v_mul_f32_e32 v94, 0xbfb8aa3b, v94
	v_pk_add_f32 v[98:99], v[98:99], 1.0 op_sel_hi:[1,0]
	v_mul_f32_e32 v95, 0xbfb8aa3b, v95
	v_exp_f32_e32 v94, v94
	v_exp_f32_e32 v95, v95
	v_add_f32_e32 v88, v88, v24
	v_add_f32_e32 v89, v89, v25
	v_mul_f32_e32 v88, 0xbfb8aa3b, v88
	v_pk_add_f32 v[94:95], v[94:95], 1.0 op_sel_hi:[1,0]
	v_mul_f32_e32 v89, 0xbfb8aa3b, v89
	v_exp_f32_e32 v88, v88
	v_exp_f32_e32 v89, v89
	v_add_f32_e32 v84, v84, v20
	v_add_f32_e32 v85, v85, v21
	v_mul_f32_e32 v84, 0xbfb8aa3b, v84
	v_pk_add_f32 v[88:89], v[88:89], 1.0 op_sel_hi:[1,0]
	v_mul_f32_e32 v85, 0xbfb8aa3b, v85
	v_exp_f32_e32 v84, v84
	v_exp_f32_e32 v85, v85
	v_add_f32_e32 v80, v80, v40
	v_add_f32_e32 v81, v81, v41
	v_mul_f32_e32 v80, 0xbfb8aa3b, v80
	v_pk_add_f32 v[84:85], v[84:85], 1.0 op_sel_hi:[1,0]
	v_mul_f32_e32 v81, 0xbfb8aa3b, v81
	v_exp_f32_e32 v80, v80
	v_exp_f32_e32 v81, v81
	v_add_f32_e32 v76, v76, v36
	v_add_f32_e32 v77, v77, v37
	v_mul_f32_e32 v76, 0xbfb8aa3b, v76
	v_pk_add_f32 v[80:81], v[80:81], 1.0 op_sel_hi:[1,0]
	v_mul_f32_e32 v77, 0xbfb8aa3b, v77
	v_exp_f32_e32 v76, v76
	v_exp_f32_e32 v77, v77
	s_waitcnt vmcnt(0)
	v_lshlrev_b32_e32 v136, 16, v128
	v_and_b32_e32 v137, 0xffff0000, v128
	v_rcp_f32_e32 v138, v113
	s_nop 0
	v_pk_add_f32 v[76:77], v[76:77], 1.0 op_sel_hi:[1,0]
	v_add_f32_e32 v82, v82, v42
	v_add_f32_e32 v83, v83, v43
	v_mul_f32_e32 v140, 1.0, v138
	v_fma_f32 v141, -v113, v140, 1.0
	v_fmac_f32_e32 v140, v141, v138
	v_div_fixup_f32 v113, v140, v113, 1.0
	v_rcp_f32_e32 v138, v112
	s_nop 0
	v_mul_f32_e32 v82, 0xbfb8aa3b, v82
	v_mul_f32_e32 v83, 0xbfb8aa3b, v83
	v_exp_f32_e32 v82, v82
	v_mul_f32_e32 v140, 1.0, v138
	v_fma_f32 v141, -v112, v140, 1.0
	v_fmac_f32_e32 v140, v141, v138
	v_div_fixup_f32 v112, v140, v112, 1.0
	v_pk_mul_f32 v[112:113], v[112:113], v[136:137]
	v_lshlrev_b32_e32 v136, 16, v130
	v_and_b32_e32 v137, 0xffff0000, v130
	v_rcp_f32_e32 v130, v109
	s_nop 0
	v_exp_f32_e32 v83, v83
	v_add_f32_e32 v78, v78, v38
	v_add_f32_e32 v79, v79, v39
	v_mul_f32_e32 v139, 1.0, v130
	v_fma_f32 v140, -v109, v139, 1.0
	v_fmac_f32_e32 v139, v140, v130
	v_div_fixup_f32 v109, v139, v109, 1.0
	v_rcp_f32_e32 v130, v108
	s_nop 0
	v_pk_add_f32 v[82:83], v[82:83], 1.0 op_sel_hi:[1,0]
	v_mul_f32_e32 v78, 0xbfb8aa3b, v78
	v_mul_f32_e32 v79, 0xbfb8aa3b, v79
	v_mul_f32_e32 v139, 1.0, v130
	v_fma_f32 v140, -v108, v139, 1.0
	v_fmac_f32_e32 v139, v140, v130
	v_div_fixup_f32 v108, v139, v108, 1.0
	v_pk_mul_f32 v[108:109], v[108:109], v[136:137]
	v_rcp_f32_e32 v136, v115
	s_nop 0
	v_lshlrev_b32_e32 v128, 16, v129
	v_and_b32_e32 v129, 0xffff0000, v129
	v_exp_f32_e32 v78, v78
	v_mul_f32_e32 v138, 1.0, v136
	v_fma_f32 v139, -v115, v138, 1.0
	v_fmac_f32_e32 v138, v139, v136
	v_div_fixup_f32 v115, v138, v115, 1.0
	v_rcp_f32_e32 v136, v114
	s_nop 0
	v_exp_f32_e32 v79, v79
	v_add_f32_e32 v72, v72, v24
	v_add_f32_e32 v73, v73, v25
	v_mul_f32_e32 v138, 1.0, v136
	v_fma_f32 v139, -v114, v138, 1.0
	v_fmac_f32_e32 v138, v139, v136
	v_div_fixup_f32 v114, v138, v114, 1.0
	v_pk_mul_f32 v[114:115], v[114:115], v[128:129]
	v_lshlrev_b32_e32 v128, 16, v131
	v_and_b32_e32 v129, 0xffff0000, v131
	v_rcp_f32_e32 v131, v111
	s_nop 0
	v_pk_add_f32 v[78:79], v[78:79], 1.0 op_sel_hi:[1,0]
	v_mul_f32_e32 v72, 0xbfb8aa3b, v72
	v_mul_f32_e32 v73, 0xbfb8aa3b, v73
	v_mul_f32_e32 v137, 1.0, v131
	v_fma_f32 v138, -v111, v137, 1.0
	v_fmac_f32_e32 v137, v138, v131
	v_div_fixup_f32 v111, v137, v111, 1.0
; DI void unpack8(u32x4 w, float* f) { f[0] = bflo(w.x); f[1] = bfhi(w.x); f[2] = bflo(w.y); f[3] = bfhi(w.y); f[4] = bflo(w.z); f[5] = bfhi(w.z); f[6] = bflo(w.w); f[7] = bfhi(w.w); }
; DI u32x4 pack44(f32x4 a, f32x4 b) { u32x4 w; w.x = pk2(a[0], a[1]); w.y = pk2(a[2], a[3]); w.z = pk2(b[0], b[1]); w.w = pk2(b[2], b[3]); return w; }
; DI float sigmoidf_(float x) { return 1.f / (1.f + __expf(-x)); }
;     DI void operator()(const Acc& acc, const Unit& u, int wr, int wc, int fr, int fq) const {
;     ...
;                     for (int bj = 0; bj < 2; ++bj) { const int row = u.pm * 256 + ai * 128 + wr * 64 + (2 * mp + mi) * 16 + fr, col = u.pn * 256 + bj * 128 + wc * 32 + 8 * fq;
;                         zv[mi][bj] = *(const u32x4*)(zs + (size_t)row * 1024 + col); }
; #pragma unroll
;                 for (int mi = 0; mi < 2; ++mi)
; #pragma unroll
;                     for (int bj = 0; bj < 2; ++bj) { const int m = 2 * mp + mi, row = u.pm * 256 + ai * 128 + wr * 64 + m * 16 + fr, col = u.pn * 256 + bj * 128 + wc * 32 + 8 * fq;
;                         f32x4 v0 = acc[ai][bj][m][0], v1 = acc[ai][bj][m][1]; float zf[8]; unpack8(zv[mi][bj], zf);
;                         for (int j = 0; j < 4; ++j) { v0[j] = zf[j] * sigmoidf_(v0[j] + bv[bj][0][j]); v1[j] = zf[4 + j] * sigmoidf_(v1[j] + bv[bj][1][j]); }
;                         *(u32x4*)(y2 + (size_t)row * 1024 + col) = pack44(v0, v1); }
	v_rcp_f32_e32 v131, v110
	s_nop 0
	v_exp_f32_e32 v72, v72
	v_exp_f32_e32 v73, v73
	v_add_f32_e32 v68, v68, v20
	v_mul_f32_e32 v137, 1.0, v131
	v_fma_f32 v138, -v110, v137, 1.0
	v_fmac_f32_e32 v137, v138, v131
	v_div_fixup_f32 v110, v137, v110, 1.0
	v_pk_mul_f32 v[128:129], v[110:111], v[128:129]
	v_cvt_pk_bf16_f32 v110, v112, v113
	v_cvt_pk_bf16_f32 v112, v108, v109
	v_lshl_add_u64 v[108:109], s[68:69], 0, v[134:135]
	v_cvt_pk_bf16_f32 v111, v114, v115
	v_cvt_pk_bf16_f32 v113, v128, v129
	v_lshl_add_u64 v[108:109], v[108:109], 0, v[172:173]
	global_store_dwordx4 v[108:109], v[110:113], off
	v_pk_add_f32 v[72:73], v[72:73], 1.0 op_sel_hi:[1,0]
	v_add_f32_e32 v69, v69, v21
	v_rcp_f32_e32 v113, v105
	s_nop 0
	v_lshlrev_b32_e32 v110, 16, v124
	v_and_b32_e32 v111, 0xffff0000, v124
	v_mul_f32_e32 v68, 0xbfb8aa3b, v68
	v_mul_f32_e32 v115, 1.0, v113
	v_fma_f32 v124, -v105, v115, 1.0
	v_fmac_f32_e32 v115, v124, v113
	v_div_fixup_f32 v105, v115, v105, 1.0
	v_rcp_f32_e32 v113, v104
	s_nop 0
	v_mul_f32_e32 v69, 0xbfb8aa3b, v69
	v_exp_f32_e32 v68, v68
	v_exp_f32_e32 v69, v69
	v_mul_f32_e32 v115, 1.0, v113
	v_fma_f32 v124, -v104, v115, 1.0
	v_fmac_f32_e32 v115, v124, v113
	v_div_fixup_f32 v104, v115, v104, 1.0
	v_rcp_f32_e32 v113, v101
	s_nop 0
	v_pk_mul_f32 v[104:105], v[104:105], v[110:111]
	v_lshlrev_b32_e32 v110, 16, v126
	v_and_b32_e32 v111, 0xffff0000, v126
	v_mul_f32_e32 v115, 1.0, v113
	v_fma_f32 v124, -v101, v115, 1.0
	v_fmac_f32_e32 v115, v124, v113
	v_div_fixup_f32 v101, v115, v101, 1.0
	v_rcp_f32_e32 v113, v100
	s_nop 0
	v_pk_add_f32 v[68:69], v[68:69], 1.0 op_sel_hi:[1,0]
	v_add_f32_e32 v64, v64, v40
	v_add_f32_e32 v65, v65, v41
	v_mul_f32_e32 v115, 1.0, v113
	v_fma_f32 v124, -v100, v115, 1.0
	v_fmac_f32_e32 v115, v124, v113
	v_div_fixup_f32 v100, v115, v100, 1.0
	v_pk_mul_f32 v[110:111], v[100:101], v[110:111]
	v_add_f32_e32 v101, v102, v22
	v_mul_f32_e32 v101, 0xbfb8aa3b, v101
	v_add_f32_e32 v100, v106, v26
	v_exp_f32_e32 v102, v101
	v_add_f32_e32 v101, v107, v27
	v_mul_f32_e32 v100, 0xbfb8aa3b, v100
	v_mul_f32_e32 v101, 0xbfb8aa3b, v101
	v_exp_f32_e32 v100, v100
	v_exp_f32_e32 v101, v101
	v_lshlrev_b32_e32 v106, 16, v125
	v_and_b32_e32 v107, 0xffff0000, v125
	v_mul_f32_e32 v64, 0xbfb8aa3b, v64
	v_pk_add_f32 v[100:101], v[100:101], 1.0 op_sel_hi:[1,0]
	v_mul_f32_e32 v65, 0xbfb8aa3b, v65
	v_rcp_f32_e32 v113, v101
	s_nop 0
	v_exp_f32_e32 v64, v64
	v_exp_f32_e32 v65, v65
	v_add_f32_e32 v60, v60, v36
	v_mul_f32_e32 v115, 1.0, v113
	v_fma_f32 v124, -v101, v115, 1.0
	v_fmac_f32_e32 v115, v124, v113
	v_div_fixup_f32 v101, v115, v101, 1.0
	v_rcp_f32_e32 v113, v100
	s_nop 0
	v_pk_add_f32 v[64:65], v[64:65], 1.0 op_sel_hi:[1,0]
	v_add_f32_e32 v61, v61, v37
	v_mul_f32_e32 v60, 0xbfb8aa3b, v60
	v_mul_f32_e32 v115, 1.0, v113
	v_fma_f32 v124, -v100, v115, 1.0
	v_fmac_f32_e32 v115, v124, v113
	v_div_fixup_f32 v100, v115, v100, 1.0
	v_pk_mul_f32 v[106:107], v[100:101], v[106:107]
	v_add_f32_e32 v100, v103, v23
	v_mul_f32_e32 v100, 0xbfb8aa3b, v100
	v_exp_f32_e32 v103, v100
	v_lshlrev_b32_e32 v100, 16, v127
	v_and_b32_e32 v101, 0xffff0000, v127
	v_mul_f32_e32 v61, 0xbfb8aa3b, v61
	v_pk_add_f32 v[102:103], v[102:103], 1.0 op_sel_hi:[1,0]
	v_exp_f32_e32 v60, v60
	v_rcp_f32_e32 v113, v103
	s_nop 0
	v_exp_f32_e32 v61, v61
	v_add_f32_e32 v66, v66, v42
	v_add_f32_e32 v67, v67, v43
	v_mul_f32_e32 v115, 1.0, v113
	v_fma_f32 v124, -v103, v115, 1.0
	v_fmac_f32_e32 v115, v124, v113
	v_div_fixup_f32 v103, v115, v103, 1.0
	v_rcp_f32_e32 v113, v102
	s_nop 0
	v_pk_add_f32 v[60:61], v[60:61], 1.0 op_sel_hi:[1,0]
	v_mul_f32_e32 v66, 0xbfb8aa3b, v66
	v_mul_f32_e32 v67, 0xbfb8aa3b, v67
	v_mul_f32_e32 v115, 1.0, v113
	v_fma_f32 v124, -v102, v115, 1.0
	v_fmac_f32_e32 v115, v124, v113
	v_div_fixup_f32 v102, v115, v102, 1.0
	v_pk_mul_f32 v[112:113], v[102:103], v[100:101]
	v_cvt_pk_bf16_f32 v100, v104, v105
	v_cvt_pk_bf16_f32 v101, v106, v107
	v_cvt_pk_bf16_f32 v102, v110, v111
	v_cvt_pk_bf16_f32 v103, v112, v113
	global_store_dwordx4 v[108:109], v[100:103], off offset:256
	v_exp_f32_e32 v66, v66
	v_exp_f32_e32 v67, v67
	v_rcp_f32_e32 v103, v97
	s_nop 0
	v_lshlrev_b32_e32 v100, 16, v120
	v_and_b32_e32 v101, 0xffff0000, v120
	v_pk_add_f32 v[66:67], v[66:67], 1.0 op_sel_hi:[1,0]
	v_mul_f32_e32 v105, 1.0, v103
	v_fma_f32 v106, -v97, v105, 1.0
	v_fmac_f32_e32 v105, v106, v103
	v_div_fixup_f32 v97, v105, v97, 1.0
	v_rcp_f32_e32 v103, v96
	s_nop 0
	v_add_f32_e32 v62, v62, v38
	v_add_f32_e32 v63, v63, v39
	v_mul_f32_e32 v62, 0xbfb8aa3b, v62
	v_mul_f32_e32 v105, 1.0, v103
	v_fma_f32 v106, -v96, v105, 1.0
	v_fmac_f32_e32 v105, v106, v103
	v_div_fixup_f32 v96, v105, v96, 1.0
	v_rcp_f32_e32 v103, v93
	s_nop 0
	v_pk_mul_f32 v[96:97], v[96:97], v[100:101]
	v_lshlrev_b32_e32 v100, 16, v122
	v_and_b32_e32 v101, 0xffff0000, v122
	v_mul_f32_e32 v105, 1.0, v103
	v_fma_f32 v106, -v93, v105, 1.0
	v_fmac_f32_e32 v105, v106, v103
	v_div_fixup_f32 v93, v105, v93, 1.0
	v_rcp_f32_e32 v103, v92
	s_nop 0
	v_mul_f32_e32 v63, 0xbfb8aa3b, v63
	v_exp_f32_e32 v62, v62
	v_exp_f32_e32 v63, v63
	v_mul_f32_e32 v105, 1.0, v103
	v_fma_f32 v106, -v92, v105, 1.0
	v_fmac_f32_e32 v105, v106, v103
	v_div_fixup_f32 v92, v105, v92, 1.0
	v_rcp_f32_e32 v103, v99
	s_nop 0
	v_pk_mul_f32 v[92:93], v[92:93], v[100:101]
	v_lshlrev_b32_e32 v100, 16, v121
	v_and_b32_e32 v101, 0xffff0000, v121
	v_mul_f32_e32 v105, 1.0, v103
	v_fma_f32 v106, -v99, v105, 1.0
	v_fmac_f32_e32 v105, v106, v103
	v_div_fixup_f32 v99, v105, v99, 1.0
	v_rcp_f32_e32 v103, v98
	s_nop 0
	v_pk_add_f32 v[62:63], v[62:63], 1.0 op_sel_hi:[1,0]
	v_add_f32_e32 v56, v56, v24
	v_add_f32_e32 v57, v57, v25
	v_mul_f32_e32 v105, 1.0, v103
	v_fma_f32 v106, -v98, v105, 1.0
; DI void unpack8(u32x4 w, float* f) { f[0] = bflo(w.x); f[1] = bfhi(w.x); f[2] = bflo(w.y); f[3] = bfhi(w.y); f[4] = bflo(w.z); f[5] = bfhi(w.z); f[6] = bflo(w.w); f[7] = bfhi(w.w); }
; DI u32x4 pack44(f32x4 a, f32x4 b) { u32x4 w; w.x = pk2(a[0], a[1]); w.y = pk2(a[2], a[3]); w.z = pk2(b[0], b[1]); w.w = pk2(b[2], b[3]); return w; }
; DI float sigmoidf_(float x) { return 1.f / (1.f + __expf(-x)); }
;     DI void operator()(const Acc& acc, const Unit& u, int wr, int wc, int fr, int fq) const {
;     ...
;                     for (int bj = 0; bj < 2; ++bj) { const int row = u.pm * 256 + ai * 128 + wr * 64 + (2 * mp + mi) * 16 + fr, col = u.pn * 256 + bj * 128 + wc * 32 + 8 * fq;
;                         zv[mi][bj] = *(const u32x4*)(zs + (size_t)row * 1024 + col); }
; #pragma unroll
;                 for (int mi = 0; mi < 2; ++mi)
; #pragma unroll
;                     for (int bj = 0; bj < 2; ++bj) { const int m = 2 * mp + mi, row = u.pm * 256 + ai * 128 + wr * 64 + m * 16 + fr, col = u.pn * 256 + bj * 128 + wc * 32 + 8 * fq;
;                         f32x4 v0 = acc[ai][bj][m][0], v1 = acc[ai][bj][m][1]; float zf[8]; unpack8(zv[mi][bj], zf);
;                         for (int j = 0; j < 4; ++j) { v0[j] = zf[j] * sigmoidf_(v0[j] + bv[bj][0][j]); v1[j] = zf[4 + j] * sigmoidf_(v1[j] + bv[bj][1][j]); }
;                         *(u32x4*)(y2 + (size_t)row * 1024 + col) = pack44(v0, v1); }
	v_fmac_f32_e32 v105, v106, v103
	v_div_fixup_f32 v98, v105, v98, 1.0
	v_rcp_f32_e32 v103, v95
	s_nop 0
	v_pk_mul_f32 v[98:99], v[98:99], v[100:101]
	v_lshlrev_b32_e32 v100, 16, v123
	v_and_b32_e32 v101, 0xffff0000, v123
	v_mul_f32_e32 v105, 1.0, v103
	v_fma_f32 v106, -v95, v105, 1.0
	v_fmac_f32_e32 v105, v106, v103
	v_div_fixup_f32 v95, v105, v95, 1.0
	v_rcp_f32_e32 v103, v94
	s_nop 0
	v_mul_f32_e32 v56, 0xbfb8aa3b, v56
	v_mul_f32_e32 v57, 0xbfb8aa3b, v57
	v_exp_f32_e32 v56, v56
	v_mul_f32_e32 v105, 1.0, v103
	v_fma_f32 v106, -v94, v105, 1.0
	v_fmac_f32_e32 v105, v106, v103
	v_div_fixup_f32 v94, v105, v94, 1.0
	v_pk_mul_f32 v[100:101], v[94:95], v[100:101]
	v_cvt_pk_bf16_f32 v94, v96, v97
	v_cvt_pk_bf16_f32 v96, v92, v93
	v_lshl_add_u64 v[92:93], s[68:69], 0, v[132:133]
	v_cvt_pk_bf16_f32 v95, v98, v99
	v_cvt_pk_bf16_f32 v97, v100, v101
	v_lshl_add_u64 v[92:93], v[92:93], 0, v[172:173]
	global_store_dwordx4 v[92:93], v[94:97], off
	v_exp_f32_e32 v57, v57
	v_add_f32_e32 v52, v52, v20
	v_rcp_f32_e32 v97, v89
	s_nop 0
	v_lshlrev_b32_e32 v94, 16, v116
	v_and_b32_e32 v95, 0xffff0000, v116
	v_pk_add_f32 v[56:57], v[56:57], 1.0 op_sel_hi:[1,0]
	v_mul_f32_e32 v99, 1.0, v97
	v_fma_f32 v100, -v89, v99, 1.0
	v_fmac_f32_e32 v99, v100, v97
	v_div_fixup_f32 v89, v99, v89, 1.0
	v_rcp_f32_e32 v97, v88
	s_nop 0
	v_add_f32_e32 v53, v53, v21
	v_mul_f32_e32 v52, 0xbfb8aa3b, v52
	v_mul_f32_e32 v53, 0xbfb8aa3b, v53
	v_mul_f32_e32 v99, 1.0, v97
	v_fma_f32 v100, -v88, v99, 1.0
	v_fmac_f32_e32 v99, v100, v97
	v_div_fixup_f32 v88, v99, v88, 1.0
	v_rcp_f32_e32 v97, v85
	s_nop 0
	v_pk_mul_f32 v[88:89], v[88:89], v[94:95]
	v_lshlrev_b32_e32 v94, 16, v118
	v_and_b32_e32 v95, 0xffff0000, v118
	v_mul_f32_e32 v99, 1.0, v97
	v_fma_f32 v100, -v85, v99, 1.0
	v_fmac_f32_e32 v99, v100, v97
	v_div_fixup_f32 v85, v99, v85, 1.0
	v_rcp_f32_e32 v97, v84
	s_nop 0
	v_exp_f32_e32 v52, v52
	v_exp_f32_e32 v53, v53
	v_add_f32_e32 v48, v48, v40
	v_mul_f32_e32 v99, 1.0, v97
	v_fma_f32 v100, -v84, v99, 1.0
	v_fmac_f32_e32 v99, v100, v97
	v_div_fixup_f32 v84, v99, v84, 1.0
	v_pk_mul_f32 v[94:95], v[84:85], v[94:95]
	v_add_f32_e32 v85, v86, v22
	v_mul_f32_e32 v85, 0xbfb8aa3b, v85
	v_add_f32_e32 v84, v90, v26
	v_exp_f32_e32 v86, v85
	v_add_f32_e32 v85, v91, v27
	v_mul_f32_e32 v84, 0xbfb8aa3b, v84
	v_mul_f32_e32 v85, 0xbfb8aa3b, v85
	v_exp_f32_e32 v84, v84
	v_exp_f32_e32 v85, v85
	v_lshlrev_b32_e32 v90, 16, v117
	v_and_b32_e32 v91, 0xffff0000, v117
	v_pk_add_f32 v[52:53], v[52:53], 1.0 op_sel_hi:[1,0]
	v_pk_add_f32 v[84:85], v[84:85], 1.0 op_sel_hi:[1,0]
	v_add_f32_e32 v49, v49, v41
	v_rcp_f32_e32 v97, v85
	s_nop 0
	v_mul_f32_e32 v48, 0xbfb8aa3b, v48
	v_mul_f32_e32 v49, 0xbfb8aa3b, v49
	v_exp_f32_e32 v48, v48
	v_mul_f32_e32 v99, 1.0, v97
	v_fma_f32 v100, -v85, v99, 1.0
	v_fmac_f32_e32 v99, v100, v97
	v_div_fixup_f32 v85, v99, v85, 1.0
	v_rcp_f32_e32 v97, v84
	s_nop 0
	v_exp_f32_e32 v49, v49
	v_add_f32_e32 v44, v44, v36
	v_add_f32_e32 v45, v45, v37
	v_mul_f32_e32 v99, 1.0, v97
	v_fma_f32 v100, -v84, v99, 1.0
	v_fmac_f32_e32 v99, v100, v97
	v_div_fixup_f32 v84, v99, v84, 1.0
	v_pk_mul_f32 v[90:91], v[84:85], v[90:91]
	v_add_f32_e32 v84, v87, v23
	v_mul_f32_e32 v84, 0xbfb8aa3b, v84
	v_exp_f32_e32 v87, v84
	v_lshlrev_b32_e32 v84, 16, v119
	v_and_b32_e32 v85, 0xffff0000, v119
	v_pk_add_f32 v[48:49], v[48:49], 1.0 op_sel_hi:[1,0]
	v_pk_add_f32 v[86:87], v[86:87], 1.0 op_sel_hi:[1,0]
	v_mul_f32_e32 v44, 0xbfb8aa3b, v44
	v_rcp_f32_e32 v97, v87
	s_nop 0
	v_mul_f32_e32 v45, 0xbfb8aa3b, v45
	v_exp_f32_e32 v44, v44
	v_exp_f32_e32 v45, v45
	v_mul_f32_e32 v99, 1.0, v97
	v_fma_f32 v100, -v87, v99, 1.0
	v_fmac_f32_e32 v99, v100, v97
	v_div_fixup_f32 v87, v99, v87, 1.0
	v_rcp_f32_e32 v97, v86
	s_nop 0
	v_pk_add_f32 v[44:45], v[44:45], 1.0 op_sel_hi:[1,0]
	v_add_f32_e32 v50, v50, v42
	v_add_f32_e32 v51, v51, v43
	v_mul_f32_e32 v99, 1.0, v97
	v_fma_f32 v100, -v86, v99, 1.0
	v_fmac_f32_e32 v99, v100, v97
	v_div_fixup_f32 v86, v99, v86, 1.0
	v_pk_mul_f32 v[96:97], v[86:87], v[84:85]
	v_cvt_pk_bf16_f32 v84, v88, v89
	v_cvt_pk_bf16_f32 v85, v90, v91
	v_cvt_pk_bf16_f32 v86, v94, v95
	v_cvt_pk_bf16_f32 v87, v96, v97
	global_store_dwordx4 v[92:93], v[84:87], off offset:256
	v_mul_f32_e32 v50, 0xbfb8aa3b, v50
	v_mul_f32_e32 v51, 0xbfb8aa3b, v51
	v_add_u32_e32 v84, 0x80, v174
	v_ashrrev_i32_e32 v85, 31, v84
	v_lshlrev_b64 v[102:103], 11, v[84:85]
	v_lshl_add_u64 v[84:85], s[4:5], 0, v[102:103]
	v_lshl_add_u64 v[84:85], v[84:85], 0, v[172:173]
	global_load_dwordx4 v[96:99], v[84:85], off
	global_load_dwordx4 v[92:95], v[84:85], off offset:256
	v_add_u32_e32 v84, 0x90, v174
	v_ashrrev_i32_e32 v85, 31, v84
	v_lshlrev_b64 v[100:101], 11, v[84:85]
	v_lshl_add_u64 v[84:85], s[4:5], 0, v[100:101]
	v_lshl_add_u64 v[84:85], v[84:85], 0, v[172:173]
	global_load_dwordx4 v[88:91], v[84:85], off
	s_nop 0
	global_load_dwordx4 v[84:87], v[84:85], off offset:256
	v_exp_f32_e32 v50, v50
	v_exp_f32_e32 v51, v51
	v_add_f32_e32 v46, v46, v38
	v_add_f32_e32 v47, v47, v39
	v_mul_f32_e32 v46, 0xbfb8aa3b, v46
	v_pk_add_f32 v[50:51], v[50:51], 1.0 op_sel_hi:[1,0]
	v_mul_f32_e32 v47, 0xbfb8aa3b, v47
	v_exp_f32_e32 v46, v46
	v_exp_f32_e32 v47, v47
	v_add_f32_e32 v32, v32, v24
	v_add_f32_e32 v33, v33, v25
	v_mul_f32_e32 v32, 0xbfb8aa3b, v32
	v_pk_add_f32 v[46:47], v[46:47], 1.0 op_sel_hi:[1,0]
	v_mul_f32_e32 v33, 0xbfb8aa3b, v33
	v_exp_f32_e32 v32, v32
	v_exp_f32_e32 v33, v33
	v_add_f32_e32 v28, v28, v20
	v_add_f32_e32 v29, v29, v21
	v_mul_f32_e32 v28, 0xbfb8aa3b, v28
	v_pk_add_f32 v[32:33], v[32:33], 1.0 op_sel_hi:[1,0]
	v_mul_f32_e32 v29, 0xbfb8aa3b, v29
	v_exp_f32_e32 v28, v28
	v_exp_f32_e32 v29, v29
	v_add_f32_e32 v16, v16, v40
	v_add_f32_e32 v17, v17, v41
	v_mul_f32_e32 v16, 0xbfb8aa3b, v16
	v_pk_add_f32 v[28:29], v[28:29], 1.0 op_sel_hi:[1,0]
	v_mul_f32_e32 v17, 0xbfb8aa3b, v17
	v_exp_f32_e32 v16, v16
	v_exp_f32_e32 v17, v17
	v_add_f32_e32 v12, v12, v36
	v_add_f32_e32 v13, v13, v37
	v_mul_f32_e32 v12, 0xbfb8aa3b, v12
	v_pk_add_f32 v[16:17], v[16:17], 1.0 op_sel_hi:[1,0]
	v_mul_f32_e32 v13, 0xbfb8aa3b, v13
	v_exp_f32_e32 v12, v12
	v_exp_f32_e32 v13, v13
	v_add_f32_e32 v18, v18, v42
	v_add_f32_e32 v19, v19, v43
	v_mul_f32_e32 v18, 0xbfb8aa3b, v18
	v_pk_add_f32 v[12:13], v[12:13], 1.0 op_sel_hi:[1,0]
	v_mul_f32_e32 v19, 0xbfb8aa3b, v19
	v_exp_f32_e32 v18, v18
	v_exp_f32_e32 v19, v19
	v_add_f32_e32 v14, v14, v38
	v_add_f32_e32 v15, v15, v39
	v_mul_f32_e32 v14, 0xbfb8aa3b, v14
	v_pk_add_f32 v[18:19], v[18:19], 1.0 op_sel_hi:[1,0]
	v_mul_f32_e32 v15, 0xbfb8aa3b, v15
	v_exp_f32_e32 v14, v14
	v_exp_f32_e32 v15, v15
	v_add_f32_e32 v8, v8, v24
	v_add_f32_e32 v9, v9, v25
	v_mul_f32_e32 v8, 0xbfb8aa3b, v8
	v_pk_add_f32 v[14:15], v[14:15], 1.0 op_sel_hi:[1,0]
	v_mul_f32_e32 v9, 0xbfb8aa3b, v9
	v_exp_f32_e32 v8, v8
	v_exp_f32_e32 v9, v9
	v_add_f32_e32 v4, v4, v20
	v_add_f32_e32 v5, v5, v21
	v_mul_f32_e32 v4, 0xbfb8aa3b, v4
	v_pk_add_f32 v[8:9], v[8:9], 1.0 op_sel_hi:[1,0]
	v_mul_f32_e32 v5, 0xbfb8aa3b, v5
	v_exp_f32_e32 v4, v4
	v_exp_f32_e32 v5, v5
	s_waitcnt vmcnt(0)
; DI void unpack8(u32x4 w, float* f) { f[0] = bflo(w.x); f[1] = bfhi(w.x); f[2] = bflo(w.y); f[3] = bfhi(w.y); f[4] = bflo(w.z); f[5] = bfhi(w.z); f[6] = bflo(w.w); f[7] = bfhi(w.w); }
; DI u32x4 pack44(f32x4 a, f32x4 b) { u32x4 w; w.x = pk2(a[0], a[1]); w.y = pk2(a[2], a[3]); w.z = pk2(b[0], b[1]); w.w = pk2(b[2], b[3]); return w; }
; DI float sigmoidf_(float x) { return 1.f / (1.f + __expf(-x)); }
;     DI void operator()(const Acc& acc, const Unit& u, int wr, int wc, int fr, int fq) const {
;     ...
;                     for (int bj = 0; bj < 2; ++bj) { const int row = u.pm * 256 + ai * 128 + wr * 64 + (2 * mp + mi) * 16 + fr, col = u.pn * 256 + bj * 128 + wc * 32 + 8 * fq;
;                         zv[mi][bj] = *(const u32x4*)(zs + (size_t)row * 1024 + col); }
; #pragma unroll
;                 for (int mi = 0; mi < 2; ++mi)
; #pragma unroll
;                     for (int bj = 0; bj < 2; ++bj) { const int m = 2 * mp + mi, row = u.pm * 256 + ai * 128 + wr * 64 + m * 16 + fr, col = u.pn * 256 + bj * 128 + wc * 32 + 8 * fq;
;                         f32x4 v0 = acc[ai][bj][m][0], v1 = acc[ai][bj][m][1]; float zf[8]; unpack8(zv[mi][bj], zf);
;                         for (int j = 0; j < 4; ++j) { v0[j] = zf[j] * sigmoidf_(v0[j] + bv[bj][0][j]); v1[j] = zf[4 + j] * sigmoidf_(v1[j] + bv[bj][1][j]); }
;                         *(u32x4*)(y2 + (size_t)row * 1024 + col) = pack44(v0, v1); }
	v_lshlrev_b32_e32 v104, 16, v96
	v_and_b32_e32 v105, 0xffff0000, v96
	v_rcp_f32_e32 v106, v81
	s_nop 0
	v_pk_add_f32 v[4:5], v[4:5], 1.0 op_sel_hi:[1,0]
	v_mul_f32_e32 v108, 1.0, v106
	v_fma_f32 v109, -v81, v108, 1.0
	v_fmac_f32_e32 v108, v109, v106
	v_div_fixup_f32 v81, v108, v81, 1.0
	v_rcp_f32_e32 v106, v80
	s_nop 0
	v_mul_f32_e32 v108, 1.0, v106
	v_fma_f32 v109, -v80, v108, 1.0
	v_fmac_f32_e32 v108, v109, v106
	v_div_fixup_f32 v80, v108, v80, 1.0
	v_pk_mul_f32 v[80:81], v[80:81], v[104:105]
	v_lshlrev_b32_e32 v104, 16, v98
	v_and_b32_e32 v105, 0xffff0000, v98
	v_rcp_f32_e32 v98, v77
	s_nop 0
	v_mul_f32_e32 v107, 1.0, v98
	v_fma_f32 v108, -v77, v107, 1.0
	v_fmac_f32_e32 v107, v108, v98
	v_div_fixup_f32 v77, v107, v77, 1.0
	v_rcp_f32_e32 v98, v76
	s_nop 0
	v_mul_f32_e32 v107, 1.0, v98
	v_fma_f32 v108, -v76, v107, 1.0
	v_fmac_f32_e32 v107, v108, v98
	v_div_fixup_f32 v76, v107, v76, 1.0
	v_pk_mul_f32 v[76:77], v[76:77], v[104:105]
	v_rcp_f32_e32 v104, v83
	s_nop 0
	v_lshlrev_b32_e32 v96, 16, v97
	v_and_b32_e32 v97, 0xffff0000, v97
	v_mul_f32_e32 v106, 1.0, v104
	v_fma_f32 v107, -v83, v106, 1.0
	v_fmac_f32_e32 v106, v107, v104
	v_div_fixup_f32 v83, v106, v83, 1.0
	v_rcp_f32_e32 v104, v82
	s_nop 0
	v_mul_f32_e32 v106, 1.0, v104
	v_fma_f32 v107, -v82, v106, 1.0
	v_fmac_f32_e32 v106, v107, v104
	v_div_fixup_f32 v82, v106, v82, 1.0
	v_pk_mul_f32 v[82:83], v[82:83], v[96:97]
	v_lshlrev_b32_e32 v96, 16, v99
	v_and_b32_e32 v97, 0xffff0000, v99
	v_rcp_f32_e32 v99, v79
	s_nop 0
	v_mul_f32_e32 v105, 1.0, v99
	v_fma_f32 v106, -v79, v105, 1.0
	v_fmac_f32_e32 v105, v106, v99
	v_div_fixup_f32 v79, v105, v79, 1.0
	v_rcp_f32_e32 v99, v78
	s_nop 0
	v_mul_f32_e32 v105, 1.0, v99
	v_fma_f32 v106, -v78, v105, 1.0
	v_fmac_f32_e32 v105, v106, v99
	v_div_fixup_f32 v78, v105, v78, 1.0
	v_pk_mul_f32 v[96:97], v[78:79], v[96:97]
	v_cvt_pk_bf16_f32 v78, v80, v81
	v_cvt_pk_bf16_f32 v80, v76, v77
	v_lshl_add_u64 v[76:77], s[68:69], 0, v[102:103]
	v_cvt_pk_bf16_f32 v79, v82, v83
	v_cvt_pk_bf16_f32 v81, v96, v97
	v_lshl_add_u64 v[76:77], v[76:77], 0, v[172:173]
	global_store_dwordx4 v[76:77], v[78:81], off
	s_nop 1
	v_rcp_f32_e32 v81, v73
	s_nop 0
	v_lshlrev_b32_e32 v78, 16, v92
	v_and_b32_e32 v79, 0xffff0000, v92
	v_mul_f32_e32 v83, 1.0, v81
	v_fma_f32 v92, -v73, v83, 1.0
	v_fmac_f32_e32 v83, v92, v81
	v_div_fixup_f32 v73, v83, v73, 1.0
	v_rcp_f32_e32 v81, v72
	s_nop 0
	v_mul_f32_e32 v83, 1.0, v81
	v_fma_f32 v92, -v72, v83, 1.0
	v_fmac_f32_e32 v83, v92, v81
	v_div_fixup_f32 v72, v83, v72, 1.0
	v_rcp_f32_e32 v81, v69
	s_nop 0
	v_pk_mul_f32 v[72:73], v[72:73], v[78:79]
	v_lshlrev_b32_e32 v78, 16, v94
	v_and_b32_e32 v79, 0xffff0000, v94
	v_mul_f32_e32 v83, 1.0, v81
	v_fma_f32 v92, -v69, v83, 1.0
	v_fmac_f32_e32 v83, v92, v81
	v_div_fixup_f32 v69, v83, v69, 1.0
	v_rcp_f32_e32 v81, v68
	s_nop 0
	v_mul_f32_e32 v83, 1.0, v81
	v_fma_f32 v92, -v68, v83, 1.0
	v_fmac_f32_e32 v83, v92, v81
	v_div_fixup_f32 v68, v83, v68, 1.0
	v_pk_mul_f32 v[78:79], v[68:69], v[78:79]
	v_add_f32_e32 v69, v70, v22
	v_mul_f32_e32 v69, 0xbfb8aa3b, v69
	v_add_f32_e32 v68, v74, v26
	v_exp_f32_e32 v70, v69
	v_add_f32_e32 v69, v75, v27
	v_mul_f32_e32 v68, 0xbfb8aa3b, v68
	v_mul_f32_e32 v69, 0xbfb8aa3b, v69
	v_exp_f32_e32 v68, v68
	v_exp_f32_e32 v69, v69
	v_lshlrev_b32_e32 v74, 16, v93
	v_and_b32_e32 v75, 0xffff0000, v93
	v_pk_add_f32 v[68:69], v[68:69], 1.0 op_sel_hi:[1,0]
	s_nop 0
	v_rcp_f32_e32 v81, v69
	s_nop 0
	v_mul_f32_e32 v83, 1.0, v81
	v_fma_f32 v92, -v69, v83, 1.0
	v_fmac_f32_e32 v83, v92, v81
	v_div_fixup_f32 v69, v83, v69, 1.0
	v_rcp_f32_e32 v81, v68
	s_nop 0
	v_mul_f32_e32 v83, 1.0, v81
	v_fma_f32 v92, -v68, v83, 1.0
	v_fmac_f32_e32 v83, v92, v81
	v_div_fixup_f32 v68, v83, v68, 1.0
	v_pk_mul_f32 v[74:75], v[68:69], v[74:75]
	v_add_f32_e32 v68, v71, v23
	v_mul_f32_e32 v68, 0xbfb8aa3b, v68
	v_exp_f32_e32 v71, v68
	v_lshlrev_b32_e32 v68, 16, v95
	v_and_b32_e32 v69, 0xffff0000, v95
	v_pk_add_f32 v[70:71], v[70:71], 1.0 op_sel_hi:[1,0]
	s_nop 0
	v_rcp_f32_e32 v81, v71
	s_nop 0
	v_mul_f32_e32 v83, 1.0, v81
	v_fma_f32 v92, -v71, v83, 1.0
	v_fmac_f32_e32 v83, v92, v81
	v_div_fixup_f32 v71, v83, v71, 1.0
	v_rcp_f32_e32 v81, v70
	s_nop 0
	v_mul_f32_e32 v83, 1.0, v81
	v_fma_f32 v92, -v70, v83, 1.0
	v_fmac_f32_e32 v83, v92, v81
	v_div_fixup_f32 v70, v83, v70, 1.0
	v_pk_mul_f32 v[80:81], v[70:71], v[68:69]
	v_cvt_pk_bf16_f32 v68, v72, v73
	v_cvt_pk_bf16_f32 v69, v74, v75
	v_cvt_pk_bf16_f32 v70, v78, v79
	v_cvt_pk_bf16_f32 v71, v80, v81
	global_store_dwordx4 v[76:77], v[68:71], off offset:256
	s_nop 1
	v_rcp_f32_e32 v71, v65
	s_nop 0
	v_lshlrev_b32_e32 v68, 16, v88
	v_and_b32_e32 v69, 0xffff0000, v88
	v_mul_f32_e32 v73, 1.0, v71
	v_fma_f32 v74, -v65, v73, 1.0
	v_fmac_f32_e32 v73, v74, v71
	v_div_fixup_f32 v65, v73, v65, 1.0
	v_rcp_f32_e32 v71, v64
	s_nop 0
	v_mul_f32_e32 v73, 1.0, v71
	v_fma_f32 v74, -v64, v73, 1.0
	v_fmac_f32_e32 v73, v74, v71
	v_div_fixup_f32 v64, v73, v64, 1.0
	v_rcp_f32_e32 v71, v61
	s_nop 0
	v_pk_mul_f32 v[64:65], v[64:65], v[68:69]
	v_lshlrev_b32_e32 v68, 16, v90
	v_and_b32_e32 v69, 0xffff0000, v90
	v_mul_f32_e32 v73, 1.0, v71
	v_fma_f32 v74, -v61, v73, 1.0
	v_fmac_f32_e32 v73, v74, v71
	v_div_fixup_f32 v61, v73, v61, 1.0
	v_rcp_f32_e32 v71, v60
	s_nop 0
	v_mul_f32_e32 v73, 1.0, v71
	v_fma_f32 v74, -v60, v73, 1.0
	v_fmac_f32_e32 v73, v74, v71
	v_div_fixup_f32 v60, v73, v60, 1.0
	v_rcp_f32_e32 v71, v67
	s_nop 0
	v_pk_mul_f32 v[60:61], v[60:61], v[68:69]
	v_lshlrev_b32_e32 v68, 16, v89
	v_and_b32_e32 v69, 0xffff0000, v89
	v_mul_f32_e32 v73, 1.0, v71
	v_fma_f32 v74, -v67, v73, 1.0
	v_fmac_f32_e32 v73, v74, v71
	v_div_fixup_f32 v67, v73, v67, 1.0
	v_rcp_f32_e32 v71, v66
	s_nop 0
; DI void unpack8(u32x4 w, float* f) { f[0] = bflo(w.x); f[1] = bfhi(w.x); f[2] = bflo(w.y); f[3] = bfhi(w.y); f[4] = bflo(w.z); f[5] = bfhi(w.z); f[6] = bflo(w.w); f[7] = bfhi(w.w); }
; DI u32x4 pack44(f32x4 a, f32x4 b) { u32x4 w; w.x = pk2(a[0], a[1]); w.y = pk2(a[2], a[3]); w.z = pk2(b[0], b[1]); w.w = pk2(b[2], b[3]); return w; }
; DI float sigmoidf_(float x) { return 1.f / (1.f + __expf(-x)); }
;     DI void operator()(const Acc& acc, const Unit& u, int wr, int wc, int fr, int fq) const {
;     ...
;                     for (int bj = 0; bj < 2; ++bj) { const int row = u.pm * 256 + ai * 128 + wr * 64 + (2 * mp + mi) * 16 + fr, col = u.pn * 256 + bj * 128 + wc * 32 + 8 * fq;
;                         zv[mi][bj] = *(const u32x4*)(zs + (size_t)row * 1024 + col); }
; #pragma unroll
;                 for (int mi = 0; mi < 2; ++mi)
; #pragma unroll
;                     for (int bj = 0; bj < 2; ++bj) { const int m = 2 * mp + mi, row = u.pm * 256 + ai * 128 + wr * 64 + m * 16 + fr, col = u.pn * 256 + bj * 128 + wc * 32 + 8 * fq;
;                         f32x4 v0 = acc[ai][bj][m][0], v1 = acc[ai][bj][m][1]; float zf[8]; unpack8(zv[mi][bj], zf);
;                         for (int j = 0; j < 4; ++j) { v0[j] = zf[j] * sigmoidf_(v0[j] + bv[bj][0][j]); v1[j] = zf[4 + j] * sigmoidf_(v1[j] + bv[bj][1][j]); }
;                         *(u32x4*)(y2 + (size_t)row * 1024 + col) = pack44(v0, v1); }
	v_mul_f32_e32 v73, 1.0, v71
	v_fma_f32 v74, -v66, v73, 1.0
	v_fmac_f32_e32 v73, v74, v71
	v_div_fixup_f32 v66, v73, v66, 1.0
	v_rcp_f32_e32 v71, v63
	s_nop 0
	v_pk_mul_f32 v[66:67], v[66:67], v[68:69]
	v_lshlrev_b32_e32 v68, 16, v91
	v_and_b32_e32 v69, 0xffff0000, v91
	v_mul_f32_e32 v73, 1.0, v71
	v_fma_f32 v74, -v63, v73, 1.0
	v_fmac_f32_e32 v73, v74, v71
	v_div_fixup_f32 v63, v73, v63, 1.0
	v_rcp_f32_e32 v71, v62
	s_nop 0
	v_mul_f32_e32 v73, 1.0, v71
	v_fma_f32 v74, -v62, v73, 1.0
	v_fmac_f32_e32 v73, v74, v71
	v_div_fixup_f32 v62, v73, v62, 1.0
	v_pk_mul_f32 v[68:69], v[62:63], v[68:69]
	v_cvt_pk_bf16_f32 v62, v64, v65
	v_cvt_pk_bf16_f32 v64, v60, v61
	v_lshl_add_u64 v[60:61], s[68:69], 0, v[100:101]
	v_cvt_pk_bf16_f32 v63, v66, v67
	v_cvt_pk_bf16_f32 v65, v68, v69
	v_lshl_add_u64 v[60:61], v[60:61], 0, v[172:173]
	global_store_dwordx4 v[60:61], v[62:65], off
	s_nop 1
	v_rcp_f32_e32 v65, v57
	s_nop 0
	v_lshlrev_b32_e32 v62, 16, v84
	v_and_b32_e32 v63, 0xffff0000, v84
	v_mul_f32_e32 v67, 1.0, v65
	v_fma_f32 v68, -v57, v67, 1.0
	v_fmac_f32_e32 v67, v68, v65
	v_div_fixup_f32 v57, v67, v57, 1.0
	v_rcp_f32_e32 v65, v56
	s_nop 0
	v_mul_f32_e32 v67, 1.0, v65
	v_fma_f32 v68, -v56, v67, 1.0
	v_fmac_f32_e32 v67, v68, v65
	v_div_fixup_f32 v56, v67, v56, 1.0
	v_rcp_f32_e32 v65, v53
	s_nop 0
	v_pk_mul_f32 v[56:57], v[56:57], v[62:63]
	v_lshlrev_b32_e32 v62, 16, v86
	v_and_b32_e32 v63, 0xffff0000, v86
	v_mul_f32_e32 v67, 1.0, v65
	v_fma_f32 v68, -v53, v67, 1.0
	v_fmac_f32_e32 v67, v68, v65
	v_div_fixup_f32 v53, v67, v53, 1.0
	v_rcp_f32_e32 v65, v52
	s_nop 0
	v_mul_f32_e32 v67, 1.0, v65
	v_fma_f32 v68, -v52, v67, 1.0
	v_fmac_f32_e32 v67, v68, v65
	v_div_fixup_f32 v52, v67, v52, 1.0
	v_pk_mul_f32 v[62:63], v[52:53], v[62:63]
	v_add_f32_e32 v53, v54, v22
	v_mul_f32_e32 v53, 0xbfb8aa3b, v53
	v_add_f32_e32 v52, v58, v26
	v_exp_f32_e32 v54, v53
	v_add_f32_e32 v53, v59, v27
	v_mul_f32_e32 v52, 0xbfb8aa3b, v52
	v_mul_f32_e32 v53, 0xbfb8aa3b, v53
	v_exp_f32_e32 v52, v52
	v_exp_f32_e32 v53, v53
	v_lshlrev_b32_e32 v58, 16, v85
	v_and_b32_e32 v59, 0xffff0000, v85
	v_pk_add_f32 v[52:53], v[52:53], 1.0 op_sel_hi:[1,0]
	s_nop 0
	v_rcp_f32_e32 v65, v53
	s_nop 0
	v_mul_f32_e32 v67, 1.0, v65
	v_fma_f32 v68, -v53, v67, 1.0
	v_fmac_f32_e32 v67, v68, v65
	v_div_fixup_f32 v53, v67, v53, 1.0
	v_rcp_f32_e32 v65, v52
	s_nop 0
	v_mul_f32_e32 v67, 1.0, v65
	v_fma_f32 v68, -v52, v67, 1.0
	v_fmac_f32_e32 v67, v68, v65
	v_div_fixup_f32 v52, v67, v52, 1.0
	v_pk_mul_f32 v[58:59], v[52:53], v[58:59]
	v_add_f32_e32 v52, v55, v23
	v_mul_f32_e32 v52, 0xbfb8aa3b, v52
	v_exp_f32_e32 v55, v52
	v_lshlrev_b32_e32 v52, 16, v87
	v_and_b32_e32 v53, 0xffff0000, v87
	v_pk_add_f32 v[54:55], v[54:55], 1.0 op_sel_hi:[1,0]
	s_nop 0
	v_rcp_f32_e32 v65, v55
	s_nop 0
	v_mul_f32_e32 v67, 1.0, v65
	v_fma_f32 v68, -v55, v67, 1.0
	v_fmac_f32_e32 v67, v68, v65
	v_div_fixup_f32 v55, v67, v55, 1.0
	v_rcp_f32_e32 v65, v54
	s_nop 0
	v_mul_f32_e32 v67, 1.0, v65
	v_fma_f32 v68, -v54, v67, 1.0
	v_fmac_f32_e32 v67, v68, v65
	v_div_fixup_f32 v54, v67, v54, 1.0
	v_pk_mul_f32 v[64:65], v[54:55], v[52:53]
	v_cvt_pk_bf16_f32 v52, v56, v57
	v_cvt_pk_bf16_f32 v53, v58, v59
	v_cvt_pk_bf16_f32 v54, v62, v63
	v_cvt_pk_bf16_f32 v55, v64, v65
	global_store_dwordx4 v[60:61], v[52:55], off offset:256
	s_nop 1
	v_add_u32_e32 v52, 0xa0, v174
	v_ashrrev_i32_e32 v53, 31, v52
	v_lshlrev_b64 v[70:71], 11, v[52:53]
	v_lshl_add_u64 v[52:53], s[4:5], 0, v[70:71]
	v_lshl_add_u64 v[52:53], v[52:53], 0, v[172:173]
	global_load_dwordx4 v[64:67], v[52:53], off
	global_load_dwordx4 v[60:63], v[52:53], off offset:256
	v_add_u32_e32 v52, 0xb0, v174
	v_ashrrev_i32_e32 v53, 31, v52
	v_lshlrev_b64 v[68:69], 11, v[52:53]
	v_lshl_add_u64 v[52:53], s[4:5], 0, v[68:69]
	v_lshl_add_u64 v[52:53], v[52:53], 0, v[172:173]
	global_load_dwordx4 v[56:59], v[52:53], off
	s_nop 0
	global_load_dwordx4 v[52:55], v[52:53], off offset:256
	s_waitcnt vmcnt(0)
	v_lshlrev_b32_e32 v72, 16, v64
	v_and_b32_e32 v73, 0xffff0000, v64
	v_rcp_f32_e32 v74, v49
	s_nop 0
	v_mul_f32_e32 v76, 1.0, v74
	v_fma_f32 v77, -v49, v76, 1.0
	v_fmac_f32_e32 v76, v77, v74
	v_div_fixup_f32 v49, v76, v49, 1.0
	v_rcp_f32_e32 v74, v48
	s_nop 0
	v_mul_f32_e32 v76, 1.0, v74
	v_fma_f32 v77, -v48, v76, 1.0
	v_fmac_f32_e32 v76, v77, v74
	v_div_fixup_f32 v48, v76, v48, 1.0
	v_pk_mul_f32 v[48:49], v[48:49], v[72:73]
	v_lshlrev_b32_e32 v72, 16, v66
	v_and_b32_e32 v73, 0xffff0000, v66
	v_rcp_f32_e32 v66, v45
	s_nop 0
	v_mul_f32_e32 v75, 1.0, v66
	v_fma_f32 v76, -v45, v75, 1.0
	v_fmac_f32_e32 v75, v76, v66
	v_div_fixup_f32 v45, v75, v45, 1.0
	v_rcp_f32_e32 v66, v44
	s_nop 0
	v_mul_f32_e32 v75, 1.0, v66
	v_fma_f32 v76, -v44, v75, 1.0
	v_fmac_f32_e32 v75, v76, v66
	v_div_fixup_f32 v44, v75, v44, 1.0
	v_pk_mul_f32 v[44:45], v[44:45], v[72:73]
	v_rcp_f32_e32 v72, v51
	s_nop 0
	v_lshlrev_b32_e32 v64, 16, v65
	v_and_b32_e32 v65, 0xffff0000, v65
	v_mul_f32_e32 v74, 1.0, v72
	v_fma_f32 v75, -v51, v74, 1.0
	v_fmac_f32_e32 v74, v75, v72
	v_div_fixup_f32 v51, v74, v51, 1.0
	v_rcp_f32_e32 v72, v50
	s_nop 0
	v_mul_f32_e32 v74, 1.0, v72
	v_fma_f32 v75, -v50, v74, 1.0
	v_fmac_f32_e32 v74, v75, v72
	v_div_fixup_f32 v50, v74, v50, 1.0
	v_pk_mul_f32 v[50:51], v[50:51], v[64:65]
	v_lshlrev_b32_e32 v64, 16, v67
	v_and_b32_e32 v65, 0xffff0000, v67
	v_rcp_f32_e32 v67, v47
	s_nop 0
	v_mul_f32_e32 v73, 1.0, v67
	v_fma_f32 v74, -v47, v73, 1.0
	v_fmac_f32_e32 v73, v74, v67
	v_div_fixup_f32 v47, v73, v47, 1.0
	v_rcp_f32_e32 v67, v46
	s_nop 0
	v_mul_f32_e32 v73, 1.0, v67
	v_fma_f32 v74, -v46, v73, 1.0
	v_fmac_f32_e32 v73, v74, v67
	v_div_fixup_f32 v46, v73, v46, 1.0
	v_pk_mul_f32 v[64:65], v[46:47], v[64:65]
	v_cvt_pk_bf16_f32 v46, v48, v49
; DI void unpack8(u32x4 w, float* f) { f[0] = bflo(w.x); f[1] = bfhi(w.x); f[2] = bflo(w.y); f[3] = bfhi(w.y); f[4] = bflo(w.z); f[5] = bfhi(w.z); f[6] = bflo(w.w); f[7] = bfhi(w.w); }
; DI u32x4 pack44(f32x4 a, f32x4 b) { u32x4 w; w.x = pk2(a[0], a[1]); w.y = pk2(a[2], a[3]); w.z = pk2(b[0], b[1]); w.w = pk2(b[2], b[3]); return w; }
; DI float sigmoidf_(float x) { return 1.f / (1.f + __expf(-x)); }
;     DI void operator()(const Acc& acc, const Unit& u, int wr, int wc, int fr, int fq) const {
;     ...
;                     for (int bj = 0; bj < 2; ++bj) { const int row = u.pm * 256 + ai * 128 + wr * 64 + (2 * mp + mi) * 16 + fr, col = u.pn * 256 + bj * 128 + wc * 32 + 8 * fq;
;                         zv[mi][bj] = *(const u32x4*)(zs + (size_t)row * 1024 + col); }
; #pragma unroll
;                 for (int mi = 0; mi < 2; ++mi)
; #pragma unroll
;                     for (int bj = 0; bj < 2; ++bj) { const int m = 2 * mp + mi, row = u.pm * 256 + ai * 128 + wr * 64 + m * 16 + fr, col = u.pn * 256 + bj * 128 + wc * 32 + 8 * fq;
;                         f32x4 v0 = acc[ai][bj][m][0], v1 = acc[ai][bj][m][1]; float zf[8]; unpack8(zv[mi][bj], zf);
;                         for (int j = 0; j < 4; ++j) { v0[j] = zf[j] * sigmoidf_(v0[j] + bv[bj][0][j]); v1[j] = zf[4 + j] * sigmoidf_(v1[j] + bv[bj][1][j]); }
;                         *(u32x4*)(y2 + (size_t)row * 1024 + col) = pack44(v0, v1); }
	v_cvt_pk_bf16_f32 v48, v44, v45
	v_lshl_add_u64 v[44:45], s[68:69], 0, v[70:71]
	v_cvt_pk_bf16_f32 v47, v50, v51
	v_cvt_pk_bf16_f32 v49, v64, v65
	v_lshl_add_u64 v[44:45], v[44:45], 0, v[172:173]
	global_store_dwordx4 v[44:45], v[46:49], off
	s_nop 1
	v_rcp_f32_e32 v49, v33
	s_nop 0
	v_lshlrev_b32_e32 v46, 16, v60
	v_and_b32_e32 v47, 0xffff0000, v60
	v_mul_f32_e32 v51, 1.0, v49
	v_fma_f32 v60, -v33, v51, 1.0
	v_fmac_f32_e32 v51, v60, v49
	v_div_fixup_f32 v33, v51, v33, 1.0
	v_rcp_f32_e32 v49, v32
	s_nop 0
	v_mul_f32_e32 v51, 1.0, v49
	v_fma_f32 v60, -v32, v51, 1.0
	v_fmac_f32_e32 v51, v60, v49
	v_div_fixup_f32 v32, v51, v32, 1.0
	v_rcp_f32_e32 v49, v29
	s_nop 0
	v_pk_mul_f32 v[32:33], v[32:33], v[46:47]
	v_lshlrev_b32_e32 v46, 16, v62
	v_and_b32_e32 v47, 0xffff0000, v62
	v_mul_f32_e32 v51, 1.0, v49
	v_fma_f32 v60, -v29, v51, 1.0
	v_fmac_f32_e32 v51, v60, v49
	v_div_fixup_f32 v29, v51, v29, 1.0
	v_rcp_f32_e32 v49, v28
	s_nop 0
	v_mul_f32_e32 v51, 1.0, v49
	v_fma_f32 v60, -v28, v51, 1.0
	v_fmac_f32_e32 v51, v60, v49
	v_div_fixup_f32 v28, v51, v28, 1.0
	v_pk_mul_f32 v[46:47], v[28:29], v[46:47]
	v_add_f32_e32 v29, v30, v22
	v_mul_f32_e32 v29, 0xbfb8aa3b, v29
	v_add_f32_e32 v28, v34, v26
	v_exp_f32_e32 v30, v29
	v_add_f32_e32 v29, v35, v27
	v_mul_f32_e32 v28, 0xbfb8aa3b, v28
	v_mul_f32_e32 v29, 0xbfb8aa3b, v29
	v_exp_f32_e32 v28, v28
	v_exp_f32_e32 v29, v29
	v_lshlrev_b32_e32 v34, 16, v61
	v_and_b32_e32 v35, 0xffff0000, v61
	v_pk_add_f32 v[28:29], v[28:29], 1.0 op_sel_hi:[1,0]
	s_nop 0
	v_rcp_f32_e32 v49, v29
	s_nop 0
	v_mul_f32_e32 v51, 1.0, v49
	v_fma_f32 v60, -v29, v51, 1.0
	v_fmac_f32_e32 v51, v60, v49
	v_div_fixup_f32 v29, v51, v29, 1.0
	v_rcp_f32_e32 v49, v28
	s_nop 0
	v_mul_f32_e32 v51, 1.0, v49
	v_fma_f32 v60, -v28, v51, 1.0
	v_fmac_f32_e32 v51, v60, v49
	v_div_fixup_f32 v28, v51, v28, 1.0
	v_pk_mul_f32 v[34:35], v[28:29], v[34:35]
	v_add_f32_e32 v28, v31, v23
	v_mul_f32_e32 v28, 0xbfb8aa3b, v28
	v_exp_f32_e32 v31, v28
	v_lshlrev_b32_e32 v28, 16, v63
	v_and_b32_e32 v29, 0xffff0000, v63
	v_pk_add_f32 v[30:31], v[30:31], 1.0 op_sel_hi:[1,0]
	s_nop 0
	v_rcp_f32_e32 v49, v31
	s_nop 0
	v_mul_f32_e32 v51, 1.0, v49
	v_fma_f32 v60, -v31, v51, 1.0
	v_fmac_f32_e32 v51, v60, v49
	v_div_fixup_f32 v31, v51, v31, 1.0
	v_rcp_f32_e32 v49, v30
	s_nop 0
	v_mul_f32_e32 v51, 1.0, v49
	v_fma_f32 v60, -v30, v51, 1.0
	v_fmac_f32_e32 v51, v60, v49
	v_div_fixup_f32 v30, v51, v30, 1.0
	v_pk_mul_f32 v[48:49], v[30:31], v[28:29]
	v_cvt_pk_bf16_f32 v28, v32, v33
	v_cvt_pk_bf16_f32 v29, v34, v35
	v_cvt_pk_bf16_f32 v30, v46, v47
	v_cvt_pk_bf16_f32 v31, v48, v49
	global_store_dwordx4 v[44:45], v[28:31], off offset:256
	s_nop 1
	v_rcp_f32_e32 v31, v17
	s_nop 0
	v_lshlrev_b32_e32 v28, 16, v56
	v_and_b32_e32 v29, 0xffff0000, v56
	v_mul_f32_e32 v33, 1.0, v31
	v_fma_f32 v34, -v17, v33, 1.0
	v_fmac_f32_e32 v33, v34, v31
	v_div_fixup_f32 v17, v33, v17, 1.0
	v_rcp_f32_e32 v31, v16
	s_nop 0
	v_mul_f32_e32 v33, 1.0, v31
	v_fma_f32 v34, -v16, v33, 1.0
	v_fmac_f32_e32 v33, v34, v31
	v_div_fixup_f32 v16, v33, v16, 1.0
	v_rcp_f32_e32 v31, v13
	s_nop 0
	v_pk_mul_f32 v[16:17], v[16:17], v[28:29]
	v_lshlrev_b32_e32 v28, 16, v58
	v_and_b32_e32 v29, 0xffff0000, v58
	v_mul_f32_e32 v33, 1.0, v31
	v_fma_f32 v34, -v13, v33, 1.0
	v_fmac_f32_e32 v33, v34, v31
	v_div_fixup_f32 v13, v33, v13, 1.0
	v_rcp_f32_e32 v31, v12
	s_nop 0
	v_mul_f32_e32 v33, 1.0, v31
	v_fma_f32 v34, -v12, v33, 1.0
	v_fmac_f32_e32 v33, v34, v31
	v_div_fixup_f32 v12, v33, v12, 1.0
	v_rcp_f32_e32 v31, v19
	s_nop 0
	v_pk_mul_f32 v[12:13], v[12:13], v[28:29]
	v_lshlrev_b32_e32 v28, 16, v57
	v_and_b32_e32 v29, 0xffff0000, v57
	v_mul_f32_e32 v33, 1.0, v31
	v_fma_f32 v34, -v19, v33, 1.0
	v_fmac_f32_e32 v33, v34, v31
	v_div_fixup_f32 v19, v33, v19, 1.0
	v_rcp_f32_e32 v31, v18
	s_nop 0
	v_mul_f32_e32 v33, 1.0, v31
	v_fma_f32 v34, -v18, v33, 1.0
	v_fmac_f32_e32 v33, v34, v31
	v_div_fixup_f32 v18, v33, v18, 1.0
	v_rcp_f32_e32 v31, v15
	s_nop 0
	v_pk_mul_f32 v[18:19], v[18:19], v[28:29]
	v_lshlrev_b32_e32 v28, 16, v59
	v_and_b32_e32 v29, 0xffff0000, v59
	v_mul_f32_e32 v33, 1.0, v31
	v_fma_f32 v34, -v15, v33, 1.0
	v_fmac_f32_e32 v33, v34, v31
	v_div_fixup_f32 v15, v33, v15, 1.0
	v_rcp_f32_e32 v31, v14
	s_nop 0
	v_mul_f32_e32 v33, 1.0, v31
	v_fma_f32 v34, -v14, v33, 1.0
	v_fmac_f32_e32 v33, v34, v31
	v_div_fixup_f32 v14, v33, v14, 1.0
	v_pk_mul_f32 v[28:29], v[14:15], v[28:29]
	v_cvt_pk_bf16_f32 v14, v16, v17
	v_cvt_pk_bf16_f32 v16, v12, v13
	v_lshl_add_u64 v[12:13], s[68:69], 0, v[68:69]
	v_cvt_pk_bf16_f32 v15, v18, v19
	v_cvt_pk_bf16_f32 v17, v28, v29
	v_lshl_add_u64 v[12:13], v[12:13], 0, v[172:173]
	global_store_dwordx4 v[12:13], v[14:17], off
	s_nop 1
	v_rcp_f32_e32 v17, v9
	s_nop 0
	v_lshlrev_b32_e32 v14, 16, v52
	v_and_b32_e32 v15, 0xffff0000, v52
	v_mul_f32_e32 v19, 1.0, v17
	v_fma_f32 v20, -v9, v19, 1.0
	v_fmac_f32_e32 v19, v20, v17
	v_div_fixup_f32 v9, v19, v9, 1.0
	v_rcp_f32_e32 v17, v8
	s_nop 0
	v_mul_f32_e32 v19, 1.0, v17
	v_fma_f32 v20, -v8, v19, 1.0
	v_fmac_f32_e32 v19, v20, v17
	v_div_fixup_f32 v8, v19, v8, 1.0
	v_rcp_f32_e32 v17, v5
	s_nop 0
	v_pk_mul_f32 v[8:9], v[8:9], v[14:15]
	v_lshlrev_b32_e32 v14, 16, v54
	v_and_b32_e32 v15, 0xffff0000, v54
	v_mul_f32_e32 v19, 1.0, v17
	v_fma_f32 v20, -v5, v19, 1.0
	v_fmac_f32_e32 v19, v20, v17
	v_div_fixup_f32 v5, v19, v5, 1.0
	v_rcp_f32_e32 v17, v4
	s_nop 0
	v_mul_f32_e32 v19, 1.0, v17
	v_fma_f32 v20, -v4, v19, 1.0
	v_fmac_f32_e32 v19, v20, v17
	v_div_fixup_f32 v4, v19, v4, 1.0
	v_pk_mul_f32 v[14:15], v[4:5], v[14:15]
	v_add_f32_e32 v5, v6, v22
	v_mul_f32_e32 v5, 0xbfb8aa3b, v5
	v_add_f32_e32 v4, v10, v26
	v_exp_f32_e32 v6, v5
	v_add_f32_e32 v5, v11, v27
	v_mul_f32_e32 v4, 0xbfb8aa3b, v4
	v_mul_f32_e32 v5, 0xbfb8aa3b, v5
	v_exp_f32_e32 v4, v4
	v_exp_f32_e32 v5, v5
	v_lshlrev_b32_e32 v10, 16, v53
	v_and_b32_e32 v11, 0xffff0000, v53
	v_pk_add_f32 v[4:5], v[4:5], 1.0 op_sel_hi:[1,0]
	s_nop 0
	v_rcp_f32_e32 v17, v5
	s_nop 0
	v_mul_f32_e32 v19, 1.0, v17
	v_fma_f32 v20, -v5, v19, 1.0
	v_fmac_f32_e32 v19, v20, v17
	v_div_fixup_f32 v5, v19, v5, 1.0
	v_rcp_f32_e32 v17, v4
	s_nop 0
	v_mul_f32_e32 v19, 1.0, v17
	v_fma_f32 v20, -v4, v19, 1.0
	v_fmac_f32_e32 v19, v20, v17
	v_div_fixup_f32 v4, v19, v4, 1.0
	v_pk_mul_f32 v[10:11], v[4:5], v[10:11]
	v_add_f32_e32 v4, v7, v23
	v_mul_f32_e32 v4, 0xbfb8aa3b, v4
	v_exp_f32_e32 v7, v4
	v_lshlrev_b32_e32 v4, 16, v55
	v_and_b32_e32 v5, 0xffff0000, v55
	v_pk_add_f32 v[6:7], v[6:7], 1.0 op_sel_hi:[1,0]
	s_nop 0
	v_rcp_f32_e32 v17, v7
	s_nop 0
	v_mul_f32_e32 v19, 1.0, v17
	v_fma_f32 v20, -v7, v19, 1.0
	v_fmac_f32_e32 v19, v20, v17
	v_div_fixup_f32 v7, v19, v7, 1.0
	v_rcp_f32_e32 v17, v6
	s_nop 0
	s_mov_b64 s[2:3], s[36:37]
	v_mul_f32_e32 v19, 1.0, v17
	v_fma_f32 v20, -v6, v19, 1.0
	v_fmac_f32_e32 v19, v20, v17
	v_div_fixup_f32 v6, v19, v6, 1.0
	v_pk_mul_f32 v[16:17], v[6:7], v[4:5]
	v_cvt_pk_bf16_f32 v4, v8, v9
	v_cvt_pk_bf16_f32 v5, v10, v11
	v_cvt_pk_bf16_f32 v6, v14, v15
	v_cvt_pk_bf16_f32 v7, v16, v17
	s_and_b64 vcc, exec, s[22:23]
	global_store_dwordx4 v[12:13], v[4:7], off offset:256
	s_cbranch_vccz .LBB0_130
; #define PG8_WAIT_V(n) asm volatile("s_waitcnt vmcnt(" #n ")" ::: "memory")
; #define PG8_BAR __builtin_amdgcn_s_barrier()
; template <class Epi, class Sched>
; DI void gemm_phase(LAS unsigned char* lds, const Gemm g, const Sched& S, const Epi& E) {
;     ...
;     PG8_WAIT_V(0);
;     if (wr == 0) PG8_BAR;
;     PG8_BAR;
	s_waitcnt vmcnt(0)
	s_cmpk_gt_u32 s41, 0xff
	s_cbranch_scc1 .LBB0_141
	s_barrier

; DI void phase_s5pre(LAS unsigned char* lds, PP p, int l, int bid, int nblk) {
;     ...
;         for (int id = tid; id < 1024; id += NTHR) { const int pp = id >> 4, hi = id & 15;
;             const float lr = p->in[5][(l * 64 + g) * 64 + pp], li = p->in[6][(l * 64 + g) * 64 + pp];
;             const float mg = expf(lr * dt), an = li * dt; float sn, cs; sincosf(an, &sn, &cs); const float nr = mg * cs - 1.0f, ni = mg * sn, den = lr * lr + li * li;
;             const float fr = (nr * lr + ni * li) / den, fi = (ni * lr - nr * li) / den;
;             const size_t bo = ((size_t)(l * 64 + g) * 64 + pp) * 16 + hi; const float br = p->in[8][bo], bi = p->in[9][bo];
;             bbr[id] = fr * br - fi * bi; bbi[id] = fr * bi + fi * br;
;             const int ho = id >> 6, p2 = id & 63; const size_t co = ((size_t)(l * 64 + g) * 16 + ho) * 64 + p2;
;             ccr[id] = p->in[10][co]; cci[id] = p->in[11][co]; }
.LBB0_250:
	s_or_b64 exec, exec, s[34:35]
	s_waitcnt vmcnt(0)
	v_mul_f32_e32 v22, v16, v18
	v_mul_f32_e32 v23, 0x3fb8aa3b, v22
	v_fma_f32 v29, v22, s13, -v23
	v_rndne_f32_e32 v30, v23
	v_fmac_f32_e32 v29, 0x32a5705f, v22
	v_sub_f32_e32 v23, v23, v30
	v_add_f32_e32 v23, v23, v29
	v_exp_f32_e32 v23, v23
	v_cvt_i32_f32_e32 v29, v30
	v_cmp_ngt_f32_e32 vcc, s15, v22
	v_xor_b32_e32 v20, v20, v19
	v_ldexp_f32 v23, v23, v29
	v_cndmask_b32_e32 v23, 0, v23, vcc
	v_cmp_nlt_f32_e32 vcc, s16, v22
	s_nop 1
	v_cndmask_b32_e32 v22, v223, v23, vcc
	v_mul_f32_e32 v23, v2, v2
	v_fmamk_f32 v29, v23, 0xb94c1982, v218
	v_fmaak_f32 v29, v23, v29, 0xbe2aaa9d
	v_mul_f32_e32 v29, v23, v29
	v_fmac_f32_e32 v2, v2, v29
	v_fmamk_f32 v29, v23, 0x37d75334, v219
	v_fmaak_f32 v29, v23, v29, 0x3d2aabf7
	v_fmaak_f32 v29, v23, v29, 0xbf000004
	v_fma_f32 v23, v23, v29, 1.0
	v_lshlrev_b32_e32 v29, 30, v21
	v_and_b32_e32 v21, 1, v21
	v_cmp_eq_u32_e32 vcc, 0, v21
	v_and_b32_e32 v30, 0x80000000, v29
	s_nop 0
	v_cndmask_b32_e32 v21, v23, v2, vcc
	v_xor_b32_e32 v20, v20, v21
	v_xor_b32_e32 v2, 0x80000000, v2
	v_xor_b32_e32 v20, v20, v30
	v_cndmask_b32_e32 v2, v2, v23, vcc
	v_cmp_class_f32_e64 vcc, v19, s11
	v_bitop3_b32 v2, v2, v29, s81 bitop3:0x78
	s_nop 0
	v_cndmask_b32_e32 v19, v226, v20, vcc
	v_cndmask_b32_e32 v2, v226, v2, vcc
	v_mul_f32_e32 v19, v22, v19
	v_fma_f32 v2, v22, v2, -1.0
	v_mul_f32_e32 v20, v9, v9
	v_mul_f32_e32 v21, v9, v19
	v_fmac_f32_e32 v20, v18, v18
	v_fmac_f32_e32 v21, v18, v2
	v_rcp_f32_e32 v23, v20
	s_nop 0
	v_mul_f32_e32 v2, v9, v2
	v_fma_f32 v2, v18, v19, -v2
	v_rcp_f32_e32 v18, v20
	s_nop 0
	v_mul_f32_e32 v30, v21, v23
	v_fma_f32 v31, -v20, v30, v21
	v_fmac_f32_e32 v30, v31, v23
	v_div_fixup_f32 v21, v30, v20, v21
	v_mul_f32_e32 v22, v2, v18
	v_fma_f32 v23, -v20, v22, v2
	v_fmac_f32_e32 v22, v23, v18
	v_div_fixup_f32 v2, v22, v20, v2
	v_ashrrev_i32_e32 v9, 31, v8
	v_lshl_add_u64 v[8:9], v[8:9], 4, v[4:5]
	v_lshlrev_b64 v[8:9], 2, v[8:9]
	v_lshl_add_u64 v[18:19], s[48:49], 0, v[8:9]
	v_lshl_add_u64 v[8:9], s[50:51], 0, v[8:9]
	global_load_dword v18, v[18:19], off
	v_cmp_lt_i32_e32 vcc, s74, v11
	global_load_dword v8, v[8:9], off
	s_or_b64 s[82:83], vcc, s[82:83]
	s_waitcnt vmcnt(0)
	v_mul_f32_e32 v9, v8, v2
	v_mul_f32_e32 v2, v18, v2
	v_fma_f32 v9, v18, v21, -v9
	v_fmac_f32_e32 v2, v8, v21
	v_ashrrev_i32_e32 v8, 6, v11
	ds_write2st64_b32 v10, v9, v2 offset1:16
	v_ashrrev_i32_e32 v9, 31, v8
	v_lshlrev_b64 v[8:9], 6, v[8:9]
	v_lshl_add_u64 v[8:9], v[8:9], 0, v[6:7]
	v_lshlrev_b64 v[8:9], 2, v[8:9]
	v_lshl_add_u64 v[18:19], s[52:53], 0, v[8:9]
	v_lshl_add_u64 v[8:9], s[54:55], 0, v[8:9]
	global_load_dword v2, v[18:19], off
	s_nop 0
	global_load_dword v8, v[8:9], off
	s_waitcnt vmcnt(0)
	ds_write2st64_b32 v10, v2, v8 offset0:32 offset1:48
	v_add_u32_e32 v2, 0x200, v11
	v_add_u32_e32 v10, 0x800, v10
	v_mov_b32_e32 v11, v2
	s_andn2_b64 exec, exec, s[82:83]
	s_cbranch_execz .LBB0_255

; #define LAS __attribute__((address_space(3)))
; DI void unpack8(u32x4 w, float* f) { f[0] = bflo(w.x); f[1] = bfhi(w.x); f[2] = bflo(w.y); f[3] = bfhi(w.y); f[4] = bflo(w.z); f[5] = bfhi(w.z); f[6] = bflo(w.w); f[7] = bfhi(w.w); }
; DI void gdn_intra(LAS unsigned char* lds, PP p, int l, int first, int stride) {
;     ...
;     for (int mat = 0; mat < 3; ++mat) {
; #pragma unroll
;         for (int it = 0; it < 2; ++it) {
;             const int id = tid + NTHR * it, j = id >> 4, o = id & 15;
;             float a[8];
; #pragma unroll
;             for (int i = 0; i < 8; ++i) a[i] = 0.f;
; #pragma unroll
;             for (int kk = 0; kk < 4; ++kk) { const bool ok = tok0 + j - 3 + kk >= 0;
;                 float x[8]; unpack8(R[(mat * 2 + it) * 4 + kk], x);
;                 const f32x4 w0 = *(const LAS f32x4*)(CW + kk * 384 + mat * 128 + o * 8), w1 = *(const LAS f32x4*)(CW + kk * 384 + mat * 128 + o * 8 + 4);
;                 for (int i = 0; i < 4; ++i) { a[i] += ok ? w0[i] * x[i] : 0.f; a[4 + i] += ok ? w1[i] * x[4 + i] : 0.f; } }
.LBB0_430:
	s_or_b64 exec, exec, s[2:3]
	v_and_b32_e32 v28, 15, v138
	v_lshlrev_b32_e32 v20, 5, v28
	s_waitcnt lgkmcnt(0)
	s_barrier
	v_add_u32_e32 v26, v0, v20
	ds_read_b128 v[12:15], v26
	ds_read_b128 v[16:19], v26 offset:16
	s_lshl_b32 s2, s54, 6
	s_and_b32 s20, s2, 0x3fc0
	v_ashrrev_i32_e32 v24, 4, v138
	v_add_u32_e32 v21, s20, v24
	v_lshlrev_b32_e32 v0, 16, v38
	v_lshlrev_b32_e32 v4, 16, v36
	v_and_b32_e32 v2, 0xffff0000, v38
	s_waitcnt lgkmcnt(1)
	v_fma_f32 v4, v12, v4, 0
	s_waitcnt lgkmcnt(0)
	v_mul_f32_e32 v5, v16, v0
	v_cmp_lt_i32_e64 s[40:41], 2, v21
	v_and_b32_e32 v1, 0xffff0000, v36
	v_fma_f32 v1, v13, v1, 0
	v_cndmask_b32_e64 v0, 0, v4, s[40:41]
	v_cndmask_b32_e64 v4, 0, v5, s[40:41]
	v_mul_f32_e32 v5, v17, v2
	v_cndmask_b32_e64 v5, 0, v5, s[40:41]
	v_cmp_gt_i32_e64 s[30:31], 3, v21
	v_add_f32_e32 v4, 0, v4
	v_cndmask_b32_e64 v1, 0, v1, s[40:41]
	v_mov_b32_e32 v2, v3
	v_mov_b32_e32 v6, v3
	v_mov_b32_e32 v7, v3
	v_add_f32_e32 v5, 0, v5
	s_and_saveexec_b64 s[2:3], s[30:31]
	s_xor_b64 s[2:3], exec, s[2:3]
	s_or_saveexec_b64 s[2:3], s[2:3]
	v_mov_b32_e32 v8, 0
	s_xor_b64 exec, exec, s[2:3]
	v_lshlrev_b32_e32 v8, 16, v39
	v_lshlrev_b32_e32 v2, 16, v37
	v_fma_f32 v2, v14, v2, 0
	v_mul_f32_e32 v8, v18, v8
	s_or_b64 exec, exec, s[2:3]
	v_add_f32_e32 v12, v6, v8
	v_mov_b64_e32 v[10:11], v[6:7]
	v_mov_b64_e32 v[8:9], v[4:5]
	v_mov_b64_e32 v[6:7], v[2:3]
	v_mov_b64_e32 v[4:5], v[0:1]
	v_mov_b32_e32 v10, v12
	s_and_saveexec_b64 s[2:3], s[30:31]
	s_xor_b64 s[2:3], exec, s[2:3]
	v_add_f32_e32 v7, 0, v3
	s_or_saveexec_b64 s[2:3], s[2:3]
	v_mov_b32_e32 v0, 0
	s_xor_b64 exec, exec, s[2:3]
	v_and_b32_e32 v0, 0xffff0000, v37
	v_and_b32_e32 v1, 0xffff0000, v39
	v_mov_b32_e32 v7, v3
	v_fmac_f32_e32 v7, v15, v0
	v_mul_f32_e32 v0, v19, v1
	s_or_b64 exec, exec, s[2:3]
	ds_read_b128 v[12:15], v26 offset:1536
	ds_read_b128 v[16:19], v26 offset:1552
	v_add_f32_e32 v11, v11, v0
	v_cmp_gt_i32_e64 s[24:25], 2, v21
	v_lshlrev_b32_e32 v0, 16, v42
	v_lshlrev_b32_e32 v1, 16, v40
	v_cndmask_b32_e64 v0, v0, 0, s[24:25]
	v_cndmask_b32_e64 v1, v1, 0, s[24:25]
	s_waitcnt lgkmcnt(1)
	v_fmac_f32_e32 v4, v12, v1
	s_waitcnt lgkmcnt(0)
	v_mul_f32_e32 v0, v16, v0
	v_add_f32_e32 v8, v8, v0
	v_and_b32_e32 v0, 0xffff0000, v40
	v_and_b32_e32 v1, 0xffff0000, v42
	v_cndmask_b32_e64 v0, v0, 0, s[24:25]
	v_cndmask_b32_e64 v1, v1, 0, s[24:25]
	s_waitcnt lgkmcnt(1)
	v_fmac_f32_e32 v5, v13, v0
	s_waitcnt lgkmcnt(0)
	v_mul_f32_e32 v0, v17, v1
	v_add_f32_e32 v9, v9, v0
	v_lshlrev_b32_e32 v0, 16, v41
	v_lshlrev_b32_e32 v1, 16, v43
	v_cndmask_b32_e64 v0, v0, 0, s[24:25]
	v_cndmask_b32_e64 v1, v1, 0, s[24:25]
	s_waitcnt lgkmcnt(1)
	v_fmac_f32_e32 v6, v14, v0
	s_waitcnt lgkmcnt(0)
	v_mul_f32_e32 v0, v18, v1
	v_add_f32_e32 v10, v10, v0
	v_and_b32_e32 v0, 0xffff0000, v41
	v_and_b32_e32 v1, 0xffff0000, v43
	v_cndmask_b32_e64 v0, v0, 0, s[24:25]
	v_cndmask_b32_e64 v1, v1, 0, s[24:25]
	s_waitcnt lgkmcnt(1)
	v_fmac_f32_e32 v7, v15, v0
	s_waitcnt lgkmcnt(0)
	v_mul_f32_e32 v0, v19, v1
	s_waitcnt lgkmcnt(1)
	ds_read_b128 v[12:15], v26 offset:3072
	s_waitcnt lgkmcnt(1)
	ds_read_b128 v[16:19], v26 offset:3088
	v_add_f32_e32 v11, v11, v0
	v_cmp_gt_i32_e64 s[26:27], 1, v21
	v_lshlrev_b32_e32 v0, 16, v46
	v_lshlrev_b32_e32 v1, 16, v44
	v_cndmask_b32_e64 v0, v0, 0, s[26:27]
	v_cndmask_b32_e64 v1, v1, 0, s[26:27]
	s_waitcnt lgkmcnt(1)
	v_fmac_f32_e32 v4, v12, v1
	s_waitcnt lgkmcnt(0)
	v_mul_f32_e32 v0, v16, v0
	v_add_f32_e32 v8, v8, v0
	v_and_b32_e32 v0, 0xffff0000, v44
	v_and_b32_e32 v1, 0xffff0000, v46
	v_cndmask_b32_e64 v0, v0, 0, s[26:27]
	v_cndmask_b32_e64 v1, v1, 0, s[26:27]
	s_waitcnt lgkmcnt(1)
	v_fmac_f32_e32 v5, v13, v0
	s_waitcnt lgkmcnt(0)
	v_mul_f32_e32 v0, v17, v1
	v_add_f32_e32 v9, v9, v0
	v_lshlrev_b32_e32 v0, 16, v45
	v_lshlrev_b32_e32 v1, 16, v47
	v_cndmask_b32_e64 v0, v0, 0, s[26:27]
	v_cndmask_b32_e64 v1, v1, 0, s[26:27]
	s_waitcnt lgkmcnt(1)
	v_fmac_f32_e32 v6, v14, v0
	s_waitcnt lgkmcnt(0)
	v_mul_f32_e32 v0, v18, v1
	v_add_f32_e32 v10, v10, v0
	v_and_b32_e32 v0, 0xffff0000, v45
	v_and_b32_e32 v1, 0xffff0000, v47
	v_cndmask_b32_e64 v0, v0, 0, s[26:27]
	v_cndmask_b32_e64 v1, v1, 0, s[26:27]
	s_waitcnt lgkmcnt(1)
	v_fmac_f32_e32 v7, v15, v0
	s_waitcnt lgkmcnt(0)
	v_mul_f32_e32 v0, v19, v1
	s_waitcnt lgkmcnt(1)
	ds_read_b128 v[12:15], v26 offset:4608
	s_waitcnt lgkmcnt(1)
	ds_read_b128 v[16:19], v26 offset:4624
	v_add_f32_e32 v11, v11, v0
	v_cmp_gt_i32_e64 s[28:29], 0, v21
	v_lshlrev_b32_e32 v0, 16, v54
	v_lshlrev_b32_e32 v1, 16, v52
	v_cndmask_b32_e64 v0, v0, 0, s[28:29]
	v_cndmask_b32_e64 v1, v1, 0, s[28:29]
	s_waitcnt lgkmcnt(1)
	v_fmac_f32_e32 v4, v12, v1
	s_waitcnt lgkmcnt(0)
	v_mul_f32_e32 v0, v16, v0
	v_add_f32_e32 v8, v8, v0
	v_and_b32_e32 v0, 0xffff0000, v52
	v_and_b32_e32 v1, 0xffff0000, v54
	v_cndmask_b32_e64 v0, v0, 0, s[28:29]
	v_cndmask_b32_e64 v1, v1, 0, s[28:29]
	s_waitcnt lgkmcnt(1)
	v_fmac_f32_e32 v5, v13, v0
	s_waitcnt lgkmcnt(0)
	v_mul_f32_e32 v0, v17, v1
	v_add_f32_e32 v9, v9, v0
	v_lshlrev_b32_e32 v0, 16, v53
	v_lshlrev_b32_e32 v1, 16, v55
	v_cndmask_b32_e64 v0, v0, 0, s[28:29]
	v_cndmask_b32_e64 v1, v1, 0, s[28:29]
	s_waitcnt lgkmcnt(1)
	v_fmac_f32_e32 v6, v14, v0
	s_waitcnt lgkmcnt(0)
	v_mul_f32_e32 v0, v18, v1
	v_add_f32_e32 v10, v10, v0
	v_and_b32_e32 v0, 0xffff0000, v53
	v_and_b32_e32 v1, 0xffff0000, v55
	v_cndmask_b32_e64 v0, v0, 0, s[28:29]
	v_cndmask_b32_e64 v1, v1, 0, s[28:29]
	s_waitcnt lgkmcnt(1)
	v_fmac_f32_e32 v7, v15, v0
	s_waitcnt lgkmcnt(0)
	v_mul_f32_e32 v0, v19, v1
	s_mul_i32 s3, s54, 0xe000
	s_mul_hi_i32 s2, s54, 0xe000
	s_add_u32 s58, s56, s3
	v_lshlrev_b32_e32 v25, 3, v138
	s_addc_u32 s59, s60, s2
	v_and_b32_e32 v2, 8, v25
	s_waitcnt lgkmcnt(1)
; #define LAS __attribute__((address_space(3)))
; DI unsigned pk2(float lo, float hi) { f32x2 v = {lo, hi}; bf2_t b = __builtin_convertvector(v, bf2_t); return __builtin_bit_cast(unsigned, b); }
; DI u32x4 pack8(const float* f) { u32x4 w; w.x = pk2(f[0], f[1]); w.y = pk2(f[2], f[3]); w.z = pk2(f[4], f[5]); w.w = pk2(f[6], f[7]); return w; }
; DI void gdn_intra(LAS unsigned char* lds, PP p, int l, int first, int stride) {
;     ...
; #pragma unroll
;             for (int i = 0; i < 8; ++i) a[i] = a[i] / (1.f + __expf(-a[i]));
;             if (mat < 2) {
;                 float ss = 0.f;
; #pragma unroll
;                 for (int i = 0; i < 8; ++i) ss += a[i] * a[i];
;                 ss += __shfl_xor(ss, 1); ss += __shfl_xor(ss, 2); ss += __shfl_xor(ss, 4); ss += __shfl_xor(ss, 8);
;                 const float sc = rsqrtf(ss + 1e-6f) * (mat == 0 ? 0.08838834764831845f : 1.f);
; #pragma unroll
;                 for (int i = 0; i < 8; ++i) a[i] *= sc;
;             }
;             if (mat == 0) {
;                 *(LAS u32x4*)(Qn + j * 136 + o * 8) = pack8(a);
;                 const float eg = sce[j]; const int ct = j >> 5, s = o >> 1, part = o & 1;
;                 unsigned char* q0 = fb + 16384 + ((size_t)((ct * 8 + s) * 64 + (j & 31))) * 16 + 8 * part;
;                 u32x2 lo, hi2; lo.x = pk2(a[0] * eg, a[1] * eg); lo.y = pk2(a[2] * eg, a[3] * eg); hi2.x = pk2(a[4] * eg, a[5] * eg); hi2.y = pk2(a[6] * eg, a[7] * eg);
;                 *(u32x2*)q0 = lo; *(u32x2*)(q0 + 32 * 16) = hi2;
	v_lshl_add_u64 v[12:13], s[58:59], 0, v[2:3]
	v_add_f32_e32 v2, v0, v11
	v_mul_f32_e32 v0, 0xbfb8aa3b, v2
	s_waitcnt lgkmcnt(0)
	v_and_b32_e32 v18, 64, v220
	s_mov_b64 s[2:3], 0x4000
	v_exp_f32_e32 v1, v0
	v_mul_f32_e32 v0, 0xbfb8aa3b, v4
	v_xor_b32_e32 v11, 1, v220
	v_add_u32_e32 v18, 64, v18
	v_and_b32_e32 v143, 0x1c0, v20
	v_lshl_add_u64 v[20:21], v[12:13], 0, s[2:3]
	v_exp_f32_e32 v12, v0
	v_mul_f32_e32 v0, 0xbfb8aa3b, v5
	v_cmp_lt_i32_e32 vcc, v11, v18
	v_exp_f32_e32 v13, v0
	v_mul_f32_e32 v0, 0xbfb8aa3b, v6
	v_cndmask_b32_e32 v11, v220, v11, vcc
	v_exp_f32_e32 v14, v0
	v_mul_f32_e32 v0, 0xbfb8aa3b, v7
	v_lshlrev_b32_e32 v31, 2, v11
	v_xor_b32_e32 v11, 2, v220
	v_exp_f32_e32 v15, v0
	v_mul_f32_e32 v0, 0xbfb8aa3b, v8
	v_cmp_lt_i32_e32 vcc, v11, v18
	v_exp_f32_e32 v16, v0
	v_mul_f32_e32 v0, 0xbfb8aa3b, v9
	v_cndmask_b32_e32 v11, v220, v11, vcc
	v_exp_f32_e32 v17, v0
	v_mul_f32_e32 v0, 0xbfb8aa3b, v10
	v_lshlrev_b32_e32 v32, 2, v11
	v_xor_b32_e32 v11, 4, v220
	v_exp_f32_e32 v0, v0
	v_cmp_lt_i32_e32 vcc, v11, v18
	v_pk_add_f32 v[16:17], v[16:17], 1.0 op_sel_hi:[1,0]
	v_pk_add_f32 v[14:15], v[14:15], 1.0 op_sel_hi:[1,0]
	v_cndmask_b32_e32 v11, v220, v11, vcc
	v_lshlrev_b32_e32 v33, 2, v11
	v_xor_b32_e32 v11, 8, v220
	v_cmp_lt_i32_e32 vcc, v11, v18
	v_pk_add_f32 v[0:1], v[0:1], 1.0 op_sel_hi:[1,0]
	v_pk_add_f32 v[12:13], v[12:13], 1.0 op_sel_hi:[1,0]
	v_cndmask_b32_e32 v11, v220, v11, vcc
	v_lshlrev_b32_e32 v34, 2, v11
	v_rcp_f32_e32 v18, v1
	s_nop 0
	v_lshl_add_u32 v141, v28, 4, v132
	v_lshl_add_u32 v139, v24, 2, v35
	v_mul_f32_e32 v27, v2, v18
	v_fma_f32 v29, -v1, v27, v2
	v_fmac_f32_e32 v27, v29, v18
	v_div_fixup_f32 v1, v27, v1, v2
	v_rcp_f32_e32 v11, v0
	s_nop 0
	v_mul_f32_e32 v19, v10, v11
	v_fma_f32 v27, -v0, v19, v10
	v_fmac_f32_e32 v19, v27, v11
	v_div_fixup_f32 v0, v19, v0, v10
	v_rcp_f32_e32 v18, v17
	s_nop 0
	v_pk_mul_f32 v[10:11], v[0:1], v[0:1]
	v_mul_f32_e32 v27, v9, v18
	v_fma_f32 v29, -v17, v27, v9
	v_fmac_f32_e32 v27, v29, v18
	v_div_fixup_f32 v9, v27, v17, v9
	v_rcp_f32_e32 v17, v16
	s_nop 0
	v_mul_f32_e32 v19, v8, v17
	v_fma_f32 v27, -v16, v19, v8
	v_fmac_f32_e32 v19, v27, v17
	v_div_fixup_f32 v8, v19, v16, v8
	v_rcp_f32_e32 v18, v15
	s_nop 0
	v_pk_mul_f32 v[16:17], v[8:9], v[8:9]
	v_mul_f32_e32 v27, v7, v18
	v_fma_f32 v29, -v15, v27, v7
	v_fmac_f32_e32 v27, v29, v18
	v_div_fixup_f32 v7, v27, v15, v7
	v_rcp_f32_e32 v15, v14
	s_nop 0
	v_mul_f32_e32 v19, v6, v15
	v_fma_f32 v27, -v14, v19, v6
	v_fmac_f32_e32 v19, v27, v15
	v_div_fixup_f32 v6, v19, v14, v6
	v_rcp_f32_e32 v18, v13
	s_nop 0
	v_pk_mul_f32 v[14:15], v[6:7], v[6:7]
	v_mul_f32_e32 v27, v5, v18
	v_fma_f32 v29, -v13, v27, v5
	v_fmac_f32_e32 v27, v29, v18
	v_div_fixup_f32 v5, v27, v13, v5
	v_rcp_f32_e32 v13, v12
	s_nop 0
	s_movk_i32 s2, 0x110
	v_mul_f32_e32 v19, v4, v13
	v_fma_f32 v27, -v12, v19, v4
	v_fmac_f32_e32 v19, v27, v13
	v_div_fixup_f32 v4, v19, v12, v4
	v_pk_mul_f32 v[12:13], v[4:5], v[4:5]
	s_nop 0
	v_add_f32_e32 v2, v12, v13
	v_add_f32_e32 v2, v14, v2
	v_add_f32_e32 v2, v15, v2
	v_add_f32_e32 v2, v16, v2
	v_add_f32_e32 v2, v17, v2
	v_add_f32_e32 v2, v10, v2
	v_add_f32_e32 v2, v11, v2
	ds_bpermute_b32 v10, v31, v2
	s_waitcnt lgkmcnt(0)
	v_add_f32_e32 v2, v2, v10
	ds_bpermute_b32 v10, v32, v2
	s_waitcnt lgkmcnt(0)
	v_add_f32_e32 v2, v2, v10
	ds_bpermute_b32 v10, v33, v2
	s_waitcnt lgkmcnt(0)
	v_add_f32_e32 v2, v2, v10
	ds_bpermute_b32 v10, v34, v2
	s_waitcnt lgkmcnt(0)
	v_add_f32_e32 v2, v2, v10
	v_add_f32_e32 v2, 0x358637bd, v2
	v_cmp_gt_f32_e32 vcc, s10, v2
	v_mul_f32_e32 v10, 0x4b800000, v2
	s_nop 0
	v_cndmask_b32_e32 v2, v2, v10, vcc
	v_rsq_f32_e32 v2, v2
	s_nop 0
	v_mul_f32_e32 v10, 0x45800000, v2
	v_cndmask_b32_e32 v2, v2, v10, vcc
	v_mul_f32_e32 v2, 0x3db504f3, v2
	v_pk_mul_f32 v[10:11], v[4:5], v[2:3] op_sel_hi:[1,0]
	v_pk_mul_f32 v[12:13], v[6:7], v[2:3] op_sel_hi:[1,0]
	v_pk_mul_f32 v[8:9], v[8:9], v[2:3] op_sel_hi:[1,0]
	v_pk_mul_f32 v[0:1], v[0:1], v[2:3] op_sel_hi:[1,0]
	v_mul_lo_u32 v2, v24, s2
	v_cvt_pk_bf16_f32 v4, v10, v11
	v_cvt_pk_bf16_f32 v5, v12, v13
	v_cvt_pk_bf16_f32 v6, v8, v9
	v_cvt_pk_bf16_f32 v7, v0, v1
	v_add_u32_e32 v140, v141, v2
	ds_write_b128 v140, v[4:7]
	ds_read_b32 v2, v139
	v_and_b32_e32 v4, 0xfffffe00, v138
	v_bfe_u32 v5, v138, 4, 5
	v_or3_b32 v4, v5, v4, v143
	v_ashrrev_i32_e32 v5, 31, v4
	s_waitcnt lgkmcnt(0)
	v_pk_mul_f32 v[6:7], v[2:3], v[10:11] op_sel_hi:[0,1]
	v_pk_mul_f32 v[10:11], v[2:3], v[12:13] op_sel_hi:[0,1]
	v_pk_mul_f32 v[8:9], v[2:3], v[8:9] op_sel_hi:[0,1]
	v_lshl_add_u64 v[4:5], v[4:5], 4, v[20:21]
	v_cvt_pk_bf16_f32 v6, v6, v7
	v_cvt_pk_bf16_f32 v7, v10, v11
	v_cvt_pk_bf16_f32 v8, v8, v9
	v_pk_mul_f32 v[0:1], v[2:3], v[0:1] op_sel_hi:[0,1]
	v_cvt_pk_bf16_f32 v9, v0, v1
	global_store_dwordx2 v[4:5], v[6:7], off
	global_store_dwordx2 v[4:5], v[8:9], off offset:512
	ds_read_b128 v[12:15], v26
	ds_read_b128 v[16:19], v26 offset:16
	v_add_u32_e32 v29, 0x200, v138
	v_ashrrev_i32_e32 v27, 4, v29
	v_add_u32_e32 v142, s20, v27
	v_lshlrev_b32_e32 v0, 16, v62
	v_lshlrev_b32_e32 v4, 16, v60
	v_and_b32_e32 v2, 0xffff0000, v62
	s_waitcnt lgkmcnt(1)
	v_fma_f32 v4, v12, v4, 0
	s_waitcnt lgkmcnt(0)
; #define LAS __attribute__((address_space(3)))
; DI void unpack8(u32x4 w, float* f) { f[0] = bflo(w.x); f[1] = bfhi(w.x); f[2] = bflo(w.y); f[3] = bfhi(w.y); f[4] = bflo(w.z); f[5] = bfhi(w.z); f[6] = bflo(w.w); f[7] = bfhi(w.w); }
; DI void gdn_intra(LAS unsigned char* lds, PP p, int l, int first, int stride) {
;     ...
;             const int id = tid + NTHR * it, j = id >> 4, o = id & 15;
;             float a[8];
; #pragma unroll
;             for (int i = 0; i < 8; ++i) a[i] = 0.f;
; #pragma unroll
;             for (int kk = 0; kk < 4; ++kk) { const bool ok = tok0 + j - 3 + kk >= 0;
;                 float x[8]; unpack8(R[(mat * 2 + it) * 4 + kk], x);
;                 const f32x4 w0 = *(const LAS f32x4*)(CW + kk * 384 + mat * 128 + o * 8), w1 = *(const LAS f32x4*)(CW + kk * 384 + mat * 128 + o * 8 + 4);
;                 for (int i = 0; i < 4; ++i) { a[i] += ok ? w0[i] * x[i] : 0.f; a[4 + i] += ok ? w1[i] * x[4 + i] : 0.f; } }
	v_mul_f32_e32 v5, v16, v0
	v_cmp_lt_i32_e64 s[44:45], 2, v142
	v_and_b32_e32 v1, 0xffff0000, v60
	v_fma_f32 v1, v13, v1, 0
	v_cndmask_b32_e64 v0, 0, v4, s[44:45]
	v_cndmask_b32_e64 v4, 0, v5, s[44:45]
	v_mul_f32_e32 v5, v17, v2
	v_cndmask_b32_e64 v5, 0, v5, s[44:45]
	v_cmp_gt_i32_e64 s[42:43], 3, v142
	v_add_f32_e32 v4, 0, v4
	v_cndmask_b32_e64 v1, 0, v1, s[44:45]
	v_mov_b32_e32 v2, v3
	v_mov_b32_e32 v6, v3
	v_mov_b32_e32 v7, v3
	v_add_f32_e32 v5, 0, v5
	s_and_saveexec_b64 s[2:3], s[42:43]
	s_xor_b64 s[2:3], exec, s[2:3]
	s_or_saveexec_b64 s[2:3], s[2:3]
	v_mov_b32_e32 v8, 0
	s_xor_b64 exec, exec, s[2:3]
	v_lshlrev_b32_e32 v8, 16, v63
	v_lshlrev_b32_e32 v2, 16, v61
	v_fma_f32 v2, v14, v2, 0
	v_mul_f32_e32 v8, v18, v8
	s_or_b64 exec, exec, s[2:3]
	v_add_f32_e32 v12, v6, v8
	v_mov_b64_e32 v[10:11], v[6:7]
	v_mov_b64_e32 v[8:9], v[4:5]
	v_mov_b64_e32 v[6:7], v[2:3]
	v_mov_b64_e32 v[4:5], v[0:1]
	v_mov_b32_e32 v10, v12
	s_and_saveexec_b64 s[2:3], s[42:43]
	s_xor_b64 s[2:3], exec, s[2:3]
	v_add_f32_e32 v7, 0, v3
	s_or_saveexec_b64 s[2:3], s[2:3]
	v_mov_b32_e32 v0, 0
	s_xor_b64 exec, exec, s[2:3]
	v_and_b32_e32 v0, 0xffff0000, v61
	v_and_b32_e32 v1, 0xffff0000, v63
	v_mov_b32_e32 v7, v3
	v_fmac_f32_e32 v7, v15, v0
	v_mul_f32_e32 v0, v19, v1
	s_or_b64 exec, exec, s[2:3]
	ds_read_b128 v[12:15], v26 offset:1536
	ds_read_b128 v[16:19], v26 offset:1552
	v_add_f32_e32 v11, v11, v0
	v_cmp_gt_i32_e64 s[34:35], 2, v142
	v_lshlrev_b32_e32 v0, 16, v74
	v_lshlrev_b32_e32 v1, 16, v72
	v_cndmask_b32_e64 v0, v0, 0, s[34:35]
	v_cndmask_b32_e64 v1, v1, 0, s[34:35]
	s_waitcnt lgkmcnt(1)
	v_fmac_f32_e32 v4, v12, v1
	s_waitcnt lgkmcnt(0)
	v_mul_f32_e32 v0, v16, v0
	v_add_f32_e32 v8, v8, v0
	v_and_b32_e32 v0, 0xffff0000, v72
	v_and_b32_e32 v1, 0xffff0000, v74
	v_cndmask_b32_e64 v0, v0, 0, s[34:35]
	v_cndmask_b32_e64 v1, v1, 0, s[34:35]
	s_waitcnt lgkmcnt(1)
	v_fmac_f32_e32 v5, v13, v0
	s_waitcnt lgkmcnt(0)
	v_mul_f32_e32 v0, v17, v1
	v_add_f32_e32 v9, v9, v0
	v_lshlrev_b32_e32 v0, 16, v73
	v_lshlrev_b32_e32 v1, 16, v75
	v_cndmask_b32_e64 v0, v0, 0, s[34:35]
	v_cndmask_b32_e64 v1, v1, 0, s[34:35]
	s_waitcnt lgkmcnt(1)
	v_fmac_f32_e32 v6, v14, v0
	s_waitcnt lgkmcnt(0)
	v_mul_f32_e32 v0, v18, v1
	v_add_f32_e32 v10, v10, v0
	v_and_b32_e32 v0, 0xffff0000, v73
	v_and_b32_e32 v1, 0xffff0000, v75
	v_cndmask_b32_e64 v0, v0, 0, s[34:35]
	v_cndmask_b32_e64 v1, v1, 0, s[34:35]
	s_waitcnt lgkmcnt(1)
	v_fmac_f32_e32 v7, v15, v0
	s_waitcnt lgkmcnt(0)
	v_mul_f32_e32 v0, v19, v1
	s_waitcnt lgkmcnt(1)
	ds_read_b128 v[12:15], v26 offset:3072
	s_waitcnt lgkmcnt(1)
	ds_read_b128 v[16:19], v26 offset:3088
	v_add_f32_e32 v11, v11, v0
	v_cmp_gt_i32_e64 s[36:37], 1, v142
	v_lshlrev_b32_e32 v0, 16, v78
	v_lshlrev_b32_e32 v1, 16, v76
	v_cndmask_b32_e64 v0, v0, 0, s[36:37]
	v_cndmask_b32_e64 v1, v1, 0, s[36:37]
	s_waitcnt lgkmcnt(1)
	v_fmac_f32_e32 v4, v12, v1
	s_waitcnt lgkmcnt(0)
	v_mul_f32_e32 v0, v16, v0
	v_add_f32_e32 v8, v8, v0
	v_and_b32_e32 v0, 0xffff0000, v76
	v_and_b32_e32 v1, 0xffff0000, v78
	v_cndmask_b32_e64 v0, v0, 0, s[36:37]
	v_cndmask_b32_e64 v1, v1, 0, s[36:37]
	s_waitcnt lgkmcnt(1)
	v_fmac_f32_e32 v5, v13, v0
	s_waitcnt lgkmcnt(0)
	v_mul_f32_e32 v0, v17, v1
	v_add_f32_e32 v9, v9, v0
	v_lshlrev_b32_e32 v0, 16, v77
	v_lshlrev_b32_e32 v1, 16, v79
	v_cndmask_b32_e64 v0, v0, 0, s[36:37]
	v_cndmask_b32_e64 v1, v1, 0, s[36:37]
	s_waitcnt lgkmcnt(1)
	v_fmac_f32_e32 v6, v14, v0
	s_waitcnt lgkmcnt(0)
	v_mul_f32_e32 v0, v18, v1
	v_add_f32_e32 v10, v10, v0
	v_and_b32_e32 v0, 0xffff0000, v77
	v_and_b32_e32 v1, 0xffff0000, v79
	v_cndmask_b32_e64 v0, v0, 0, s[36:37]
	v_cndmask_b32_e64 v1, v1, 0, s[36:37]
	s_waitcnt lgkmcnt(1)
	v_fmac_f32_e32 v7, v15, v0
	s_waitcnt lgkmcnt(0)
	v_mul_f32_e32 v0, v19, v1
	s_waitcnt lgkmcnt(1)
	ds_read_b128 v[12:15], v26 offset:4608
	s_waitcnt lgkmcnt(1)
	ds_read_b128 v[16:19], v26 offset:4624
	v_add_f32_e32 v11, v11, v0
	v_cmp_gt_i32_e64 s[38:39], 0, v142
	v_lshlrev_b32_e32 v0, 16, v86
	v_lshlrev_b32_e32 v1, 16, v84
	v_cndmask_b32_e64 v0, v0, 0, s[38:39]
	v_cndmask_b32_e64 v1, v1, 0, s[38:39]
	s_waitcnt lgkmcnt(1)
	v_fmac_f32_e32 v4, v12, v1
	s_waitcnt lgkmcnt(0)
	v_mul_f32_e32 v0, v16, v0
	v_add_f32_e32 v8, v8, v0
	v_and_b32_e32 v0, 0xffff0000, v84
	v_and_b32_e32 v1, 0xffff0000, v86
	v_cndmask_b32_e64 v0, v0, 0, s[38:39]
	v_cndmask_b32_e64 v1, v1, 0, s[38:39]
	s_waitcnt lgkmcnt(1)
	v_fmac_f32_e32 v5, v13, v0
	s_waitcnt lgkmcnt(0)
	v_mul_f32_e32 v0, v17, v1
	v_add_f32_e32 v9, v9, v0
	v_lshlrev_b32_e32 v0, 16, v85
	v_lshlrev_b32_e32 v1, 16, v87
	v_cndmask_b32_e64 v0, v0, 0, s[38:39]
	v_cndmask_b32_e64 v1, v1, 0, s[38:39]
	s_waitcnt lgkmcnt(1)
	v_fmac_f32_e32 v6, v14, v0
	s_waitcnt lgkmcnt(0)
	v_mul_f32_e32 v0, v18, v1
	v_add_f32_e32 v10, v10, v0
	v_and_b32_e32 v0, 0xffff0000, v85
	v_and_b32_e32 v1, 0xffff0000, v87
	v_cndmask_b32_e64 v0, v0, 0, s[38:39]
	v_cndmask_b32_e64 v1, v1, 0, s[38:39]
	s_waitcnt lgkmcnt(1)
	v_fmac_f32_e32 v7, v15, v0
	s_waitcnt lgkmcnt(0)
	v_mul_f32_e32 v0, v19, v1
	v_add_f32_e32 v2, v0, v11
	v_mul_f32_e32 v0, 0xbfb8aa3b, v2
	v_exp_f32_e32 v1, v0
	v_mul_f32_e32 v0, 0xbfb8aa3b, v4
	s_waitcnt lgkmcnt(1)
	v_exp_f32_e32 v12, v0
	v_mul_f32_e32 v0, 0xbfb8aa3b, v5
	v_exp_f32_e32 v13, v0
	v_mul_f32_e32 v0, 0xbfb8aa3b, v6
	v_exp_f32_e32 v14, v0
	v_mul_f32_e32 v0, 0xbfb8aa3b, v7
	v_exp_f32_e32 v15, v0
	v_mul_f32_e32 v0, 0xbfb8aa3b, v8
	s_waitcnt lgkmcnt(0)
; #define LAS __attribute__((address_space(3)))
; DI unsigned pk2(float lo, float hi) { f32x2 v = {lo, hi}; bf2_t b = __builtin_convertvector(v, bf2_t); return __builtin_bit_cast(unsigned, b); }
; DI void unpack8(u32x4 w, float* f) { f[0] = bflo(w.x); f[1] = bfhi(w.x); f[2] = bflo(w.y); f[3] = bfhi(w.y); f[4] = bflo(w.z); f[5] = bfhi(w.z); f[6] = bflo(w.w); f[7] = bfhi(w.w); }
; DI u32x4 pack8(const float* f) { u32x4 w; w.x = pk2(f[0], f[1]); w.y = pk2(f[2], f[3]); w.z = pk2(f[4], f[5]); w.w = pk2(f[6], f[7]); return w; }
; DI void gdn_intra(LAS unsigned char* lds, PP p, int l, int first, int stride) {
;     ...
;             const int id = tid + NTHR * it, j = id >> 4, o = id & 15;
;             float a[8];
; #pragma unroll
;             for (int i = 0; i < 8; ++i) a[i] = 0.f;
; #pragma unroll
;             for (int kk = 0; kk < 4; ++kk) { const bool ok = tok0 + j - 3 + kk >= 0;
;                 float x[8]; unpack8(R[(mat * 2 + it) * 4 + kk], x);
;                 const f32x4 w0 = *(const LAS f32x4*)(CW + kk * 384 + mat * 128 + o * 8), w1 = *(const LAS f32x4*)(CW + kk * 384 + mat * 128 + o * 8 + 4);
;                 for (int i = 0; i < 4; ++i) { a[i] += ok ? w0[i] * x[i] : 0.f; a[4 + i] += ok ? w1[i] * x[4 + i] : 0.f; } }
; #pragma unroll
;             for (int i = 0; i < 8; ++i) a[i] = a[i] / (1.f + __expf(-a[i]));
;             if (mat < 2) {
;                 float ss = 0.f;
; #pragma unroll
;                 for (int i = 0; i < 8; ++i) ss += a[i] * a[i];
;                 ss += __shfl_xor(ss, 1); ss += __shfl_xor(ss, 2); ss += __shfl_xor(ss, 4); ss += __shfl_xor(ss, 8);
;                 const float sc = rsqrtf(ss + 1e-6f) * (mat == 0 ? 0.08838834764831845f : 1.f);
; #pragma unroll
;                 for (int i = 0; i < 8; ++i) a[i] *= sc;
;             }
;             if (mat == 0) {
;                 *(LAS u32x4*)(Qn + j * 136 + o * 8) = pack8(a);
;                 const float eg = sce[j]; const int ct = j >> 5, s = o >> 1, part = o & 1;
;                 unsigned char* q0 = fb + 16384 + ((size_t)((ct * 8 + s) * 64 + (j & 31))) * 16 + 8 * part;
;                 u32x2 lo, hi2; lo.x = pk2(a[0] * eg, a[1] * eg); lo.y = pk2(a[2] * eg, a[3] * eg); hi2.x = pk2(a[4] * eg, a[5] * eg); hi2.y = pk2(a[6] * eg, a[7] * eg);
;                 *(u32x2*)q0 = lo; *(u32x2*)(q0 + 32 * 16) = hi2;
	v_exp_f32_e32 v16, v0
	v_mul_f32_e32 v0, 0xbfb8aa3b, v9
	v_exp_f32_e32 v17, v0
	v_mul_f32_e32 v0, 0xbfb8aa3b, v10
	v_exp_f32_e32 v0, v0
	v_pk_add_f32 v[14:15], v[14:15], 1.0 op_sel_hi:[1,0]
	v_pk_add_f32 v[16:17], v[16:17], 1.0 op_sel_hi:[1,0]
	v_pk_add_f32 v[12:13], v[12:13], 1.0 op_sel_hi:[1,0]
	v_pk_add_f32 v[0:1], v[0:1], 1.0 op_sel_hi:[1,0]
	s_nop 0
	v_rcp_f32_e32 v18, v1
	s_nop 0
	v_mul_f32_e32 v142, v2, v18
	v_fma_f32 v144, -v1, v142, v2
	v_fmac_f32_e32 v142, v144, v18
	v_div_fixup_f32 v1, v142, v1, v2
	v_rcp_f32_e32 v11, v0
	s_nop 0
	v_mul_f32_e32 v19, v10, v11
	v_fma_f32 v142, -v0, v19, v10
	v_fmac_f32_e32 v19, v142, v11
	v_div_fixup_f32 v0, v19, v0, v10
	v_rcp_f32_e32 v18, v17
	s_nop 0
	v_pk_mul_f32 v[10:11], v[0:1], v[0:1]
	v_mul_f32_e32 v142, v9, v18
	v_fma_f32 v144, -v17, v142, v9
	v_fmac_f32_e32 v142, v144, v18
	v_div_fixup_f32 v9, v142, v17, v9
	v_rcp_f32_e32 v17, v16
	s_nop 0
	v_mul_f32_e32 v19, v8, v17
	v_fma_f32 v142, -v16, v19, v8
	v_fmac_f32_e32 v19, v142, v17
	v_div_fixup_f32 v8, v19, v16, v8
	v_rcp_f32_e32 v18, v15
	s_nop 0
	v_pk_mul_f32 v[16:17], v[8:9], v[8:9]
	v_mul_f32_e32 v142, v7, v18
	v_fma_f32 v144, -v15, v142, v7
	v_fmac_f32_e32 v142, v144, v18
	v_div_fixup_f32 v7, v142, v15, v7
	v_rcp_f32_e32 v15, v14
	s_nop 0
	v_mul_f32_e32 v19, v6, v15
	v_fma_f32 v142, -v14, v19, v6
	v_fmac_f32_e32 v19, v142, v15
	v_div_fixup_f32 v6, v19, v14, v6
	v_rcp_f32_e32 v18, v13
	s_nop 0
	v_pk_mul_f32 v[14:15], v[6:7], v[6:7]
	v_mul_f32_e32 v142, v5, v18
	v_fma_f32 v144, -v13, v142, v5
	v_fmac_f32_e32 v142, v144, v18
	v_div_fixup_f32 v5, v142, v13, v5
	v_rcp_f32_e32 v13, v12
	s_nop 0
	s_movk_i32 s2, 0x110
	v_mul_f32_e32 v19, v4, v13
	v_fma_f32 v142, -v12, v19, v4
	v_fmac_f32_e32 v19, v142, v13
	v_div_fixup_f32 v4, v19, v12, v4
	v_pk_mul_f32 v[12:13], v[4:5], v[4:5]
	s_nop 0
	v_add_f32_e32 v2, v12, v13
	v_add_f32_e32 v2, v14, v2
	v_add_f32_e32 v2, v15, v2
	v_add_f32_e32 v2, v16, v2
	v_add_f32_e32 v2, v17, v2
	v_add_f32_e32 v2, v10, v2
	v_add_f32_e32 v2, v11, v2
	ds_bpermute_b32 v10, v31, v2
	s_waitcnt lgkmcnt(0)
	v_add_f32_e32 v2, v2, v10
	ds_bpermute_b32 v10, v32, v2
	s_waitcnt lgkmcnt(0)
	v_add_f32_e32 v2, v2, v10
	ds_bpermute_b32 v10, v33, v2
	s_waitcnt lgkmcnt(0)
	v_add_f32_e32 v2, v2, v10
	ds_bpermute_b32 v10, v34, v2
	s_waitcnt lgkmcnt(0)
	v_add_f32_e32 v2, v2, v10
	v_add_f32_e32 v2, 0x358637bd, v2
	v_cmp_gt_f32_e32 vcc, s10, v2
	v_mul_f32_e32 v10, 0x4b800000, v2
	s_nop 0
	v_cndmask_b32_e32 v2, v2, v10, vcc
	v_rsq_f32_e32 v2, v2
	s_nop 0
	v_mul_f32_e32 v10, 0x45800000, v2
	v_cndmask_b32_e32 v2, v2, v10, vcc
	v_mul_f32_e32 v2, 0x3db504f3, v2
	v_pk_mul_f32 v[10:11], v[4:5], v[2:3] op_sel_hi:[1,0]
	v_pk_mul_f32 v[12:13], v[6:7], v[2:3] op_sel_hi:[1,0]
	v_pk_mul_f32 v[8:9], v[8:9], v[2:3] op_sel_hi:[1,0]
	v_pk_mul_f32 v[0:1], v[0:1], v[2:3] op_sel_hi:[1,0]
	v_mul_lo_u32 v2, v27, s2
	v_cvt_pk_bf16_f32 v4, v10, v11
	v_cvt_pk_bf16_f32 v5, v12, v13
	v_cvt_pk_bf16_f32 v6, v8, v9
	v_cvt_pk_bf16_f32 v7, v0, v1
	v_add_u32_e32 v142, v141, v2
	ds_write_b128 v142, v[4:7]
	v_lshl_add_u32 v141, v27, 2, v35
	ds_read_b32 v2, v141
	v_and_b32_e32 v4, 0xfffffe00, v29
	v_bfe_u32 v5, v29, 4, 5
	v_or3_b32 v4, v5, v4, v143
	v_ashrrev_i32_e32 v5, 31, v4
	s_waitcnt lgkmcnt(0)
	v_pk_mul_f32 v[6:7], v[2:3], v[10:11] op_sel_hi:[0,1]
	v_pk_mul_f32 v[10:11], v[2:3], v[12:13] op_sel_hi:[0,1]
	v_pk_mul_f32 v[8:9], v[2:3], v[8:9] op_sel_hi:[0,1]
	v_lshl_add_u64 v[4:5], v[4:5], 4, v[20:21]
	v_cvt_pk_bf16_f32 v6, v6, v7
	v_cvt_pk_bf16_f32 v7, v10, v11
	v_cvt_pk_bf16_f32 v8, v8, v9
	v_pk_mul_f32 v[0:1], v[2:3], v[0:1] op_sel_hi:[0,1]
	v_cvt_pk_bf16_f32 v9, v0, v1
	global_store_dwordx2 v[4:5], v[6:7], off
	global_store_dwordx2 v[4:5], v[8:9], off offset:512
	ds_read_b128 v[12:15], v26 offset:512
	ds_read_b128 v[16:19], v26 offset:528
	v_lshlrev_b32_e32 v0, 16, v50
	v_lshlrev_b32_e32 v4, 16, v48
	v_and_b32_e32 v2, 0xffff0000, v50
	s_waitcnt lgkmcnt(1)
	v_fma_f32 v4, v12, v4, 0
	s_waitcnt lgkmcnt(0)
	v_mul_f32_e32 v5, v16, v0
	v_and_b32_e32 v1, 0xffff0000, v48
	v_cndmask_b32_e64 v0, 0, v4, s[40:41]
	v_cndmask_b32_e64 v4, 0, v5, s[40:41]
	v_mul_f32_e32 v5, v17, v2
	v_fma_f32 v1, v13, v1, 0
	v_cndmask_b32_e64 v5, 0, v5, s[40:41]
	v_add_f32_e32 v4, 0, v4
	v_cndmask_b32_e64 v1, 0, v1, s[40:41]
	v_mov_b32_e32 v2, v3
	v_mov_b32_e32 v6, v3
	v_mov_b32_e32 v7, v3
	v_add_f32_e32 v5, 0, v5
	s_and_saveexec_b64 s[2:3], s[30:31]
	s_xor_b64 s[2:3], exec, s[2:3]
	s_or_saveexec_b64 s[2:3], s[2:3]
	v_mov_b32_e32 v8, 0
	s_xor_b64 exec, exec, s[2:3]
	v_lshlrev_b32_e32 v8, 16, v51
	v_lshlrev_b32_e32 v2, 16, v49
	v_fma_f32 v2, v14, v2, 0
	v_mul_f32_e32 v8, v18, v8
	s_or_b64 exec, exec, s[2:3]
	v_add_f32_e32 v12, v6, v8
	v_mov_b64_e32 v[10:11], v[6:7]
	v_mov_b64_e32 v[8:9], v[4:5]
	v_mov_b64_e32 v[6:7], v[2:3]
	v_mov_b64_e32 v[4:5], v[0:1]
	v_mov_b32_e32 v10, v12
	s_and_saveexec_b64 s[2:3], s[30:31]
	s_xor_b64 s[2:3], exec, s[2:3]
	v_add_f32_e32 v7, 0, v3
	s_or_saveexec_b64 s[2:3], s[2:3]
	v_mov_b32_e32 v0, 0
	s_xor_b64 exec, exec, s[2:3]
	v_and_b32_e32 v0, 0xffff0000, v49
	v_and_b32_e32 v1, 0xffff0000, v51
	v_mov_b32_e32 v7, v3
	v_fmac_f32_e32 v7, v15, v0
	v_mul_f32_e32 v0, v19, v1
	s_or_b64 exec, exec, s[2:3]
	ds_read_b128 v[12:15], v26 offset:2048
	ds_read_b128 v[16:19], v26 offset:2064
	v_add_f32_e32 v11, v11, v0
	v_lshlrev_b32_e32 v0, 16, v58
	v_lshlrev_b32_e32 v1, 16, v56
	v_cndmask_b32_e64 v0, v0, 0, s[24:25]
	v_cndmask_b32_e64 v1, v1, 0, s[24:25]
	s_waitcnt lgkmcnt(1)
	v_fmac_f32_e32 v4, v12, v1
	s_waitcnt lgkmcnt(0)
	v_mul_f32_e32 v0, v16, v0
	v_add_f32_e32 v8, v8, v0
	v_and_b32_e32 v0, 0xffff0000, v56
	v_and_b32_e32 v1, 0xffff0000, v58
	v_cndmask_b32_e64 v0, v0, 0, s[24:25]
	v_cndmask_b32_e64 v1, v1, 0, s[24:25]
	s_waitcnt lgkmcnt(1)
; #define LAS __attribute__((address_space(3)))
; DI void unpack8(u32x4 w, float* f) { f[0] = bflo(w.x); f[1] = bfhi(w.x); f[2] = bflo(w.y); f[3] = bfhi(w.y); f[4] = bflo(w.z); f[5] = bfhi(w.z); f[6] = bflo(w.w); f[7] = bfhi(w.w); }
; DI void gdn_intra(LAS unsigned char* lds, PP p, int l, int first, int stride) {
;     ...
;             for (int kk = 0; kk < 4; ++kk) { const bool ok = tok0 + j - 3 + kk >= 0;
;                 float x[8]; unpack8(R[(mat * 2 + it) * 4 + kk], x);
;                 const f32x4 w0 = *(const LAS f32x4*)(CW + kk * 384 + mat * 128 + o * 8), w1 = *(const LAS f32x4*)(CW + kk * 384 + mat * 128 + o * 8 + 4);
;                 for (int i = 0; i < 4; ++i) { a[i] += ok ? w0[i] * x[i] : 0.f; a[4 + i] += ok ? w1[i] * x[4 + i] : 0.f; } }
; #pragma unroll
;             for (int i = 0; i < 8; ++i) a[i] = a[i] / (1.f + __expf(-a[i]));
;             if (mat < 2) {
;                 float ss = 0.f;
; #pragma unroll
;                 for (int i = 0; i < 8; ++i) ss += a[i] * a[i];
;                 ss += __shfl_xor(ss, 1); ss += __shfl_xor(ss, 2); ss += __shfl_xor(ss, 4); ss += __shfl_xor(ss, 8);
	v_fmac_f32_e32 v5, v13, v0
	s_waitcnt lgkmcnt(0)
	v_mul_f32_e32 v0, v17, v1
	v_add_f32_e32 v9, v9, v0
	v_lshlrev_b32_e32 v0, 16, v57
	v_lshlrev_b32_e32 v1, 16, v59
	v_cndmask_b32_e64 v0, v0, 0, s[24:25]
	v_cndmask_b32_e64 v1, v1, 0, s[24:25]
	s_waitcnt lgkmcnt(1)
	v_fmac_f32_e32 v6, v14, v0
	s_waitcnt lgkmcnt(0)
	v_mul_f32_e32 v0, v18, v1
	v_add_f32_e32 v10, v10, v0
	v_and_b32_e32 v0, 0xffff0000, v57
	v_and_b32_e32 v1, 0xffff0000, v59
	v_cndmask_b32_e64 v0, v0, 0, s[24:25]
	v_cndmask_b32_e64 v1, v1, 0, s[24:25]
	s_waitcnt lgkmcnt(1)
	v_fmac_f32_e32 v7, v15, v0
	s_waitcnt lgkmcnt(0)
	v_mul_f32_e32 v0, v19, v1
	s_waitcnt lgkmcnt(1)
	ds_read_b128 v[12:15], v26 offset:3584
	s_waitcnt lgkmcnt(1)
	ds_read_b128 v[16:19], v26 offset:3600
	v_add_f32_e32 v11, v11, v0
	v_lshlrev_b32_e32 v0, 16, v66
	v_lshlrev_b32_e32 v1, 16, v64
	v_cndmask_b32_e64 v0, v0, 0, s[26:27]
	v_cndmask_b32_e64 v1, v1, 0, s[26:27]
	s_waitcnt lgkmcnt(1)
	v_fmac_f32_e32 v4, v12, v1
	s_waitcnt lgkmcnt(0)
	v_mul_f32_e32 v0, v16, v0
	v_add_f32_e32 v8, v8, v0
	v_and_b32_e32 v0, 0xffff0000, v64
	v_and_b32_e32 v1, 0xffff0000, v66
	v_cndmask_b32_e64 v0, v0, 0, s[26:27]
	v_cndmask_b32_e64 v1, v1, 0, s[26:27]
	s_waitcnt lgkmcnt(1)
	v_fmac_f32_e32 v5, v13, v0
	s_waitcnt lgkmcnt(0)
	v_mul_f32_e32 v0, v17, v1
	v_add_f32_e32 v9, v9, v0
	v_lshlrev_b32_e32 v0, 16, v65
	v_lshlrev_b32_e32 v1, 16, v67
	v_cndmask_b32_e64 v0, v0, 0, s[26:27]
	v_cndmask_b32_e64 v1, v1, 0, s[26:27]
	s_waitcnt lgkmcnt(1)
	v_fmac_f32_e32 v6, v14, v0
	s_waitcnt lgkmcnt(0)
	v_mul_f32_e32 v0, v18, v1
	v_add_f32_e32 v10, v10, v0
	v_and_b32_e32 v0, 0xffff0000, v65
	v_and_b32_e32 v1, 0xffff0000, v67
	v_cndmask_b32_e64 v0, v0, 0, s[26:27]
	v_cndmask_b32_e64 v1, v1, 0, s[26:27]
	s_waitcnt lgkmcnt(1)
	v_fmac_f32_e32 v7, v15, v0
	s_waitcnt lgkmcnt(0)
	v_mul_f32_e32 v0, v19, v1
	s_waitcnt lgkmcnt(1)
	ds_read_b128 v[12:15], v26 offset:5120
	s_waitcnt lgkmcnt(1)
	ds_read_b128 v[16:19], v26 offset:5136
	v_add_f32_e32 v11, v11, v0
	v_lshlrev_b32_e32 v0, 16, v70
	v_lshlrev_b32_e32 v1, 16, v68
	v_cndmask_b32_e64 v0, v0, 0, s[28:29]
	v_cndmask_b32_e64 v1, v1, 0, s[28:29]
	s_waitcnt lgkmcnt(1)
	v_fmac_f32_e32 v4, v12, v1
	s_waitcnt lgkmcnt(0)
	v_mul_f32_e32 v0, v16, v0
	v_add_f32_e32 v8, v8, v0
	v_and_b32_e32 v0, 0xffff0000, v68
	v_and_b32_e32 v1, 0xffff0000, v70
	v_cndmask_b32_e64 v0, v0, 0, s[28:29]
	v_cndmask_b32_e64 v1, v1, 0, s[28:29]
	s_waitcnt lgkmcnt(1)
	v_fmac_f32_e32 v5, v13, v0
	s_waitcnt lgkmcnt(0)
	v_mul_f32_e32 v0, v17, v1
	v_add_f32_e32 v9, v9, v0
	v_lshlrev_b32_e32 v0, 16, v69
	v_lshlrev_b32_e32 v1, 16, v71
	v_cndmask_b32_e64 v0, v0, 0, s[28:29]
	v_cndmask_b32_e64 v1, v1, 0, s[28:29]
	s_waitcnt lgkmcnt(1)
	v_fmac_f32_e32 v6, v14, v0
	s_waitcnt lgkmcnt(0)
	v_mul_f32_e32 v0, v18, v1
	v_add_f32_e32 v10, v10, v0
	v_and_b32_e32 v0, 0xffff0000, v69
	v_and_b32_e32 v1, 0xffff0000, v71
	v_cndmask_b32_e64 v0, v0, 0, s[28:29]
	v_cndmask_b32_e64 v1, v1, 0, s[28:29]
	s_waitcnt lgkmcnt(1)
	v_fmac_f32_e32 v7, v15, v0
	s_waitcnt lgkmcnt(0)
	v_mul_f32_e32 v0, v19, v1
	v_add_f32_e32 v2, v0, v11
	v_mul_f32_e32 v0, 0xbfb8aa3b, v2
	v_exp_f32_e32 v1, v0
	v_mul_f32_e32 v0, 0xbfb8aa3b, v4
	s_waitcnt lgkmcnt(1)
	v_exp_f32_e32 v12, v0
	v_mul_f32_e32 v0, 0xbfb8aa3b, v5
	v_exp_f32_e32 v13, v0
	v_mul_f32_e32 v0, 0xbfb8aa3b, v6
	v_exp_f32_e32 v14, v0
	v_mul_f32_e32 v0, 0xbfb8aa3b, v7
	v_exp_f32_e32 v15, v0
	v_mul_f32_e32 v0, 0xbfb8aa3b, v8
	s_waitcnt lgkmcnt(0)
	v_exp_f32_e32 v16, v0
	v_mul_f32_e32 v0, 0xbfb8aa3b, v9
	v_exp_f32_e32 v17, v0
	v_mul_f32_e32 v0, 0xbfb8aa3b, v10
	v_exp_f32_e32 v0, v0
	v_pk_add_f32 v[14:15], v[14:15], 1.0 op_sel_hi:[1,0]
	v_pk_add_f32 v[16:17], v[16:17], 1.0 op_sel_hi:[1,0]
	v_pk_add_f32 v[12:13], v[12:13], 1.0 op_sel_hi:[1,0]
	v_pk_add_f32 v[0:1], v[0:1], 1.0 op_sel_hi:[1,0]
	v_lshlrev_b32_e32 v143, 3, v28
	v_rcp_f32_e32 v18, v1
	s_nop 0
	v_mul_u32_u24_e32 v144, 0x240, v28
	v_add_u32_e32 v20, 0x11800, v132
	v_mul_f32_e32 v21, v2, v18
	v_fma_f32 v35, -v1, v21, v2
	v_fmac_f32_e32 v21, v35, v18
	v_div_fixup_f32 v1, v21, v1, v2
	v_rcp_f32_e32 v11, v0
	s_nop 0
	v_mul_f32_e32 v19, v10, v11
	v_fma_f32 v21, -v0, v19, v10
	v_fmac_f32_e32 v19, v21, v11
	v_div_fixup_f32 v0, v19, v0, v10
	v_rcp_f32_e32 v18, v17
	s_nop 0
	v_pk_mul_f32 v[10:11], v[0:1], v[0:1]
	v_mul_f32_e32 v21, v9, v18
	v_fma_f32 v35, -v17, v21, v9
	v_fmac_f32_e32 v21, v35, v18
	v_div_fixup_f32 v9, v21, v17, v9
	v_rcp_f32_e32 v17, v16
	s_nop 0
	v_mul_f32_e32 v19, v8, v17
	v_fma_f32 v21, -v16, v19, v8
	v_fmac_f32_e32 v19, v21, v17
	v_div_fixup_f32 v8, v19, v16, v8
	v_rcp_f32_e32 v18, v15
	s_nop 0
	v_pk_mul_f32 v[16:17], v[8:9], v[8:9]
	v_mul_f32_e32 v21, v7, v18
	v_fma_f32 v35, -v15, v21, v7
	v_fmac_f32_e32 v21, v35, v18
	v_div_fixup_f32 v7, v21, v15, v7
	v_rcp_f32_e32 v15, v14
	s_nop 0
	v_mul_f32_e32 v19, v6, v15
	v_fma_f32 v21, -v14, v19, v6
	v_fmac_f32_e32 v19, v21, v15
	v_div_fixup_f32 v6, v19, v14, v6
	v_rcp_f32_e32 v18, v13
	s_nop 0
	v_pk_mul_f32 v[14:15], v[6:7], v[6:7]
	v_mul_f32_e32 v21, v5, v18
	v_fma_f32 v35, -v13, v21, v5
	v_fmac_f32_e32 v21, v35, v18
	v_div_fixup_f32 v5, v21, v13, v5
	v_rcp_f32_e32 v13, v12
	s_nop 0
	s_movk_i32 s2, 0x240
	v_mad_u32_u24 v151, v28, s2, v227
	v_mul_f32_e32 v19, v4, v13
	v_fma_f32 v21, -v12, v19, v4
	v_fmac_f32_e32 v19, v21, v13
	v_div_fixup_f32 v4, v19, v12, v4
	v_pk_mul_f32 v[12:13], v[4:5], v[4:5]
	s_nop 0
	v_add_f32_e32 v2, v12, v13
	v_add_f32_e32 v2, v14, v2
	v_add_f32_e32 v2, v15, v2
	v_add_f32_e32 v2, v16, v2
	v_add_f32_e32 v2, v17, v2
	v_add_f32_e32 v2, v10, v2
	v_add_f32_e32 v2, v11, v2
	ds_bpermute_b32 v10, v31, v2
	s_waitcnt lgkmcnt(0)
	v_add_f32_e32 v2, v2, v10
	ds_bpermute_b32 v10, v32, v2
	s_waitcnt lgkmcnt(0)
; #define LAS __attribute__((address_space(3)))
; DI unsigned pk2(float lo, float hi) { f32x2 v = {lo, hi}; bf2_t b = __builtin_convertvector(v, bf2_t); return __builtin_bit_cast(unsigned, b); }
; DI bf16_t f2bf(float f) { return (bf16_t)(pk2(f, 0.f) & 0xffffu); }
; DI void unpack8(u32x4 w, float* f) { f[0] = bflo(w.x); f[1] = bfhi(w.x); f[2] = bflo(w.y); f[3] = bfhi(w.y); f[4] = bflo(w.z); f[5] = bfhi(w.z); f[6] = bflo(w.w); f[7] = bfhi(w.w); }
; DI u32x4 pack8(const float* f) { u32x4 w; w.x = pk2(f[0], f[1]); w.y = pk2(f[2], f[3]); w.z = pk2(f[4], f[5]); w.w = pk2(f[6], f[7]); return w; }
; DI void gdn_intra(LAS unsigned char* lds, PP p, int l, int first, int stride) {
;     ...
;             for (int kk = 0; kk < 4; ++kk) { const bool ok = tok0 + j - 3 + kk >= 0;
;                 float x[8]; unpack8(R[(mat * 2 + it) * 4 + kk], x);
;                 const f32x4 w0 = *(const LAS f32x4*)(CW + kk * 384 + mat * 128 + o * 8), w1 = *(const LAS f32x4*)(CW + kk * 384 + mat * 128 + o * 8 + 4);
;                 for (int i = 0; i < 4; ++i) { a[i] += ok ? w0[i] * x[i] : 0.f; a[4 + i] += ok ? w1[i] * x[4 + i] : 0.f; } }
;     ...
;                 ss += __shfl_xor(ss, 1); ss += __shfl_xor(ss, 2); ss += __shfl_xor(ss, 4); ss += __shfl_xor(ss, 8);
;                 const float sc = rsqrtf(ss + 1e-6f) * (mat == 0 ? 0.08838834764831845f : 1.f);
; #pragma unroll
;                 for (int i = 0; i < 8; ++i) a[i] *= sc;
;             }
;             if (mat == 0) {
;                 *(LAS u32x4*)(Qn + j * 136 + o * 8) = pack8(a);
;                 const float eg = sce[j]; const int ct = j >> 5, s = o >> 1, part = o & 1;
;                 unsigned char* q0 = fb + 16384 + ((size_t)((ct * 8 + s) * 64 + (j & 31))) * 16 + 8 * part;
;                 u32x2 lo, hi2; lo.x = pk2(a[0] * eg, a[1] * eg); lo.y = pk2(a[2] * eg, a[3] * eg); hi2.x = pk2(a[4] * eg, a[5] * eg); hi2.y = pk2(a[6] * eg, a[7] * eg);
;                 *(u32x2*)q0 = lo; *(u32x2*)(q0 + 32 * 16) = hi2;
;             } else if (mat == 1) {
;                 *(LAS u32x4*)(Kn + j * 136 + o * 8) = pack8(a);
;                 const float f1 = scb[j] * sce[j], f2 = scl[j];
; #pragma unroll
;                 for (int i = 0; i < 8; ++i) { XTk[xsw(o * 8 + i, j)] = f2bf(a[i] * f1); KT2[xsw(o * 8 + i, j)] = f2bf(a[i] * f2); }
	v_add_f32_e32 v2, v2, v10
	ds_bpermute_b32 v10, v33, v2
	s_waitcnt lgkmcnt(0)
	v_add_f32_e32 v2, v2, v10
	ds_bpermute_b32 v10, v34, v2
	s_waitcnt lgkmcnt(0)
	v_add_f32_e32 v2, v2, v10
	v_add_f32_e32 v2, 0x358637bd, v2
	v_cmp_gt_f32_e32 vcc, s10, v2
	v_mul_f32_e32 v10, 0x4b800000, v2
	s_nop 0
	v_cndmask_b32_e32 v2, v2, v10, vcc
	v_rsq_f32_e32 v2, v2
	s_nop 0
	v_mul_f32_e32 v10, 0x45800000, v2
	v_cndmask_b32_e32 v2, v2, v10, vcc
	v_pk_mul_f32 v[10:11], v[4:5], v[2:3] op_sel_hi:[1,0]
	v_pk_mul_f32 v[12:13], v[6:7], v[2:3] op_sel_hi:[1,0]
	v_pk_mul_f32 v[8:9], v[8:9], v[2:3] op_sel_hi:[1,0]
	v_pk_mul_f32 v[0:1], v[0:1], v[2:3] op_sel_hi:[1,0]
	v_cvt_pk_bf16_f32 v4, v10, v11
	v_cvt_pk_bf16_f32 v5, v12, v13
	v_cvt_pk_bf16_f32 v6, v8, v9
	v_cvt_pk_bf16_f32 v7, v0, v1
	v_lshlrev_b32_e32 v2, 2, v24
	ds_write_b128 v140, v[4:7] offset:17408
	v_add_u32_e32 v35, v23, v2
	ds_read_b32 v4, v35
	ds_read_b32 v5, v139
	v_add_u32_e32 v2, v30, v2
	ds_read_b32 v2, v2
	v_bitop3_b32 v139, v143, 56, v24 bitop3:0x48
	v_bfe_u32 v140, v138, 4, 3
	s_waitcnt lgkmcnt(1)
	v_mul_f32_e32 v4, v4, v5
	v_or_b32_e32 v5, v139, v140
	v_or_b32_e32 v7, v5, v144
	v_mul_f32_e32 v6, v4, v10
	v_lshlrev_b32_e32 v7, 1, v7
	v_cvt_pk_bf16_f32 v6, v6, s0
	v_add_u32_e32 v14, v132, v7
	ds_write_b16 v14, v6 offset:34816
	s_waitcnt lgkmcnt(1)
	v_mul_f32_e32 v6, v2, v10
	v_cvt_pk_bf16_f32 v6, v6, s0
	v_add_u32_e32 v7, v20, v7
	ds_write_b16 v7, v6
	v_mul_f32_e32 v6, v4, v11
	v_mov_b32_e32 v7, 0x48
	v_cvt_pk_bf16_f32 v6, v6, s0
	v_mad_u32_u24 v145, v28, s2, v7
	v_add_u32_e32 v7, v5, v145
	ds_write_b16 v14, v6 offset:34960
	v_mul_f32_e32 v6, v2, v11
	v_cvt_pk_bf16_f32 v6, v6, s0
	v_lshl_add_u32 v7, v7, 1, v20
	ds_write_b16 v7, v6
	v_mul_f32_e32 v6, v4, v12
	v_mov_b32_e32 v7, 0x90
	v_cvt_pk_bf16_f32 v6, v6, s0
	v_mad_u32_u24 v146, v28, s2, v7
	v_add_u32_e32 v7, v5, v146
	ds_write_b16 v14, v6 offset:35104
	v_mul_f32_e32 v6, v2, v12
	v_cvt_pk_bf16_f32 v6, v6, s0
	v_lshl_add_u32 v7, v7, 1, v20
	ds_write_b16 v7, v6
	v_mul_f32_e32 v6, v4, v13
	v_mov_b32_e32 v7, 0xd8
	v_cvt_pk_bf16_f32 v6, v6, s0
	v_mad_u32_u24 v147, v28, s2, v7
	v_add_u32_e32 v7, v5, v147
	ds_write_b16 v14, v6 offset:35248
	v_mul_f32_e32 v6, v2, v13
	v_cvt_pk_bf16_f32 v6, v6, s0
	v_lshl_add_u32 v7, v7, 1, v20
	ds_write_b16 v7, v6
	v_mul_f32_e32 v6, v4, v8
	v_mov_b32_e32 v7, 0x120
	v_cvt_pk_bf16_f32 v6, v6, s0
	v_mad_u32_u24 v148, v28, s2, v7
	v_add_u32_e32 v7, v5, v148
	ds_write_b16 v14, v6 offset:35392
	v_mul_f32_e32 v6, v2, v8
	v_cvt_pk_bf16_f32 v6, v6, s0
	v_lshl_add_u32 v7, v7, 1, v20
	ds_write_b16 v7, v6
	v_mul_f32_e32 v6, v4, v9
	v_mov_b32_e32 v7, 0x168
	v_cvt_pk_bf16_f32 v6, v6, s0
	v_mad_u32_u24 v149, v28, s2, v7
	v_add_u32_e32 v7, v5, v149
	ds_write_b16 v14, v6 offset:35536
	v_mul_f32_e32 v6, v2, v9
	v_cvt_pk_bf16_f32 v6, v6, s0
	v_lshl_add_u32 v7, v7, 1, v20
	ds_write_b16 v7, v6
	v_mov_b32_e32 v7, 0x1b0
	v_mul_f32_e32 v6, v4, v0
	v_mad_u32_u24 v150, v28, s2, v7
	v_cvt_pk_bf16_f32 v6, v6, s0
	v_add_u32_e32 v7, v5, v150
	v_mul_f32_e32 v0, v2, v0
	ds_write_b16 v14, v6 offset:35680
	v_cvt_pk_bf16_f32 v0, v0, s0
	v_lshl_add_u32 v6, v7, 1, v20
	ds_write_b16 v6, v0
	v_mul_f32_e32 v0, v4, v1
	v_cvt_pk_bf16_f32 v0, v0, s0
	v_add_u32_e32 v4, v5, v151
	ds_write_b16 v14, v0 offset:35824
	v_mul_f32_e32 v0, v2, v1
	v_cvt_pk_bf16_f32 v0, v0, s0
	v_lshl_add_u32 v1, v4, 1, v20
	ds_write_b16 v1, v0
	ds_read_b128 v[12:15], v26 offset:512
	ds_read_b128 v[16:19], v26 offset:528
	v_lshlrev_b32_e32 v0, 16, v82
	v_lshlrev_b32_e32 v4, 16, v80
	v_and_b32_e32 v2, 0xffff0000, v82
	s_waitcnt lgkmcnt(1)
	v_fma_f32 v4, v12, v4, 0
	s_waitcnt lgkmcnt(0)
	v_mul_f32_e32 v5, v16, v0
	v_and_b32_e32 v1, 0xffff0000, v80
	v_cndmask_b32_e64 v0, 0, v4, s[44:45]
	v_cndmask_b32_e64 v4, 0, v5, s[44:45]
	v_mul_f32_e32 v5, v17, v2
	v_fma_f32 v1, v13, v1, 0
	v_cndmask_b32_e64 v5, 0, v5, s[44:45]
	v_add_f32_e32 v4, 0, v4
	v_cndmask_b32_e64 v1, 0, v1, s[44:45]
	v_mov_b32_e32 v2, v3
	v_mov_b32_e32 v6, v3
	v_mov_b32_e32 v7, v3
	v_add_f32_e32 v5, 0, v5
	s_and_saveexec_b64 s[2:3], s[42:43]
	s_xor_b64 s[2:3], exec, s[2:3]
	s_or_saveexec_b64 s[2:3], s[2:3]
	v_mov_b32_e32 v8, 0
	s_xor_b64 exec, exec, s[2:3]
	v_lshlrev_b32_e32 v8, 16, v83
	v_lshlrev_b32_e32 v2, 16, v81
	v_fma_f32 v2, v14, v2, 0
	v_mul_f32_e32 v8, v18, v8
	s_or_b64 exec, exec, s[2:3]
	v_add_f32_e32 v12, v6, v8
	v_mov_b64_e32 v[10:11], v[6:7]
	v_mov_b64_e32 v[8:9], v[4:5]
	v_mov_b64_e32 v[6:7], v[2:3]
	v_mov_b64_e32 v[4:5], v[0:1]
	v_mov_b32_e32 v10, v12
	s_and_saveexec_b64 s[2:3], s[42:43]
	s_xor_b64 s[2:3], exec, s[2:3]
	v_add_f32_e32 v7, 0, v3
	s_or_saveexec_b64 s[2:3], s[2:3]
	v_mov_b32_e32 v0, 0
	s_xor_b64 exec, exec, s[2:3]
	v_and_b32_e32 v0, 0xffff0000, v81
	v_and_b32_e32 v1, 0xffff0000, v83
	v_mov_b32_e32 v7, v3
	v_fmac_f32_e32 v7, v15, v0
	v_mul_f32_e32 v0, v19, v1
	s_or_b64 exec, exec, s[2:3]
	ds_read_b128 v[12:15], v26 offset:2048
	ds_read_b128 v[16:19], v26 offset:2064
	v_add_f32_e32 v11, v11, v0
	v_lshlrev_b32_e32 v0, 16, v90
	v_lshlrev_b32_e32 v1, 16, v88
	v_cndmask_b32_e64 v0, v0, 0, s[34:35]
	v_cndmask_b32_e64 v1, v1, 0, s[34:35]
	s_waitcnt lgkmcnt(1)
	v_fmac_f32_e32 v4, v12, v1
	s_waitcnt lgkmcnt(0)
	v_mul_f32_e32 v0, v16, v0
	v_add_f32_e32 v8, v8, v0
	v_and_b32_e32 v0, 0xffff0000, v88
	v_and_b32_e32 v1, 0xffff0000, v90
	v_cndmask_b32_e64 v0, v0, 0, s[34:35]
	v_cndmask_b32_e64 v1, v1, 0, s[34:35]
	s_waitcnt lgkmcnt(1)
	v_fmac_f32_e32 v5, v13, v0
	s_waitcnt lgkmcnt(0)
	v_mul_f32_e32 v0, v17, v1
	v_add_f32_e32 v9, v9, v0
	v_lshlrev_b32_e32 v0, 16, v89
	v_lshlrev_b32_e32 v1, 16, v91
	v_cndmask_b32_e64 v0, v0, 0, s[34:35]
	v_cndmask_b32_e64 v1, v1, 0, s[34:35]
	s_waitcnt lgkmcnt(1)
; #define LAS __attribute__((address_space(3)))
; DI void unpack8(u32x4 w, float* f) { f[0] = bflo(w.x); f[1] = bfhi(w.x); f[2] = bflo(w.y); f[3] = bfhi(w.y); f[4] = bflo(w.z); f[5] = bfhi(w.z); f[6] = bflo(w.w); f[7] = bfhi(w.w); }
; DI void gdn_intra(LAS unsigned char* lds, PP p, int l, int first, int stride) {
;     ...
;             for (int kk = 0; kk < 4; ++kk) { const bool ok = tok0 + j - 3 + kk >= 0;
;                 float x[8]; unpack8(R[(mat * 2 + it) * 4 + kk], x);
;                 const f32x4 w0 = *(const LAS f32x4*)(CW + kk * 384 + mat * 128 + o * 8), w1 = *(const LAS f32x4*)(CW + kk * 384 + mat * 128 + o * 8 + 4);
;                 for (int i = 0; i < 4; ++i) { a[i] += ok ? w0[i] * x[i] : 0.f; a[4 + i] += ok ? w1[i] * x[4 + i] : 0.f; } }
; #pragma unroll
;             for (int i = 0; i < 8; ++i) a[i] = a[i] / (1.f + __expf(-a[i]));
;             if (mat < 2) {
;                 float ss = 0.f;
; #pragma unroll
;                 for (int i = 0; i < 8; ++i) ss += a[i] * a[i];
;                 ss += __shfl_xor(ss, 1); ss += __shfl_xor(ss, 2); ss += __shfl_xor(ss, 4); ss += __shfl_xor(ss, 8);
	v_fmac_f32_e32 v6, v14, v0
	s_waitcnt lgkmcnt(0)
	v_mul_f32_e32 v0, v18, v1
	v_add_f32_e32 v10, v10, v0
	v_and_b32_e32 v0, 0xffff0000, v89
	v_and_b32_e32 v1, 0xffff0000, v91
	v_cndmask_b32_e64 v0, v0, 0, s[34:35]
	v_cndmask_b32_e64 v1, v1, 0, s[34:35]
	s_waitcnt lgkmcnt(1)
	v_fmac_f32_e32 v7, v15, v0
	s_waitcnt lgkmcnt(0)
	v_mul_f32_e32 v0, v19, v1
	s_waitcnt lgkmcnt(1)
	ds_read_b128 v[12:15], v26 offset:3584
	s_waitcnt lgkmcnt(1)
	ds_read_b128 v[16:19], v26 offset:3600
	v_add_f32_e32 v11, v11, v0
	v_lshlrev_b32_e32 v0, 16, v94
	v_lshlrev_b32_e32 v1, 16, v92
	v_cndmask_b32_e64 v0, v0, 0, s[36:37]
	v_cndmask_b32_e64 v1, v1, 0, s[36:37]
	s_waitcnt lgkmcnt(1)
	v_fmac_f32_e32 v4, v12, v1
	s_waitcnt lgkmcnt(0)
	v_mul_f32_e32 v0, v16, v0
	v_add_f32_e32 v8, v8, v0
	v_and_b32_e32 v0, 0xffff0000, v92
	v_and_b32_e32 v1, 0xffff0000, v94
	v_cndmask_b32_e64 v0, v0, 0, s[36:37]
	v_cndmask_b32_e64 v1, v1, 0, s[36:37]
	s_waitcnt lgkmcnt(1)
	v_fmac_f32_e32 v5, v13, v0
	s_waitcnt lgkmcnt(0)
	v_mul_f32_e32 v0, v17, v1
	v_add_f32_e32 v9, v9, v0
	v_lshlrev_b32_e32 v0, 16, v93
	v_lshlrev_b32_e32 v1, 16, v95
	v_cndmask_b32_e64 v0, v0, 0, s[36:37]
	v_cndmask_b32_e64 v1, v1, 0, s[36:37]
	s_waitcnt lgkmcnt(1)
	v_fmac_f32_e32 v6, v14, v0
	s_waitcnt lgkmcnt(0)
	v_mul_f32_e32 v0, v18, v1
	v_add_f32_e32 v10, v10, v0
	v_and_b32_e32 v0, 0xffff0000, v93
	v_and_b32_e32 v1, 0xffff0000, v95
	v_cndmask_b32_e64 v0, v0, 0, s[36:37]
	v_cndmask_b32_e64 v1, v1, 0, s[36:37]
	s_waitcnt lgkmcnt(1)
	v_fmac_f32_e32 v7, v15, v0
	s_waitcnt lgkmcnt(0)
	v_mul_f32_e32 v0, v19, v1
	s_waitcnt lgkmcnt(1)
	ds_read_b128 v[12:15], v26 offset:5120
	s_waitcnt lgkmcnt(1)
	ds_read_b128 v[16:19], v26 offset:5136
	v_add_f32_e32 v11, v11, v0
	v_lshlrev_b32_e32 v0, 16, v98
	v_lshlrev_b32_e32 v1, 16, v96
	v_cndmask_b32_e64 v0, v0, 0, s[38:39]
	v_cndmask_b32_e64 v1, v1, 0, s[38:39]
	s_waitcnt lgkmcnt(1)
	v_fmac_f32_e32 v4, v12, v1
	s_waitcnt lgkmcnt(0)
	v_mul_f32_e32 v0, v16, v0
	v_add_f32_e32 v8, v8, v0
	v_and_b32_e32 v0, 0xffff0000, v96
	v_and_b32_e32 v1, 0xffff0000, v98
	v_cndmask_b32_e64 v0, v0, 0, s[38:39]
	v_cndmask_b32_e64 v1, v1, 0, s[38:39]
	s_waitcnt lgkmcnt(1)
	v_fmac_f32_e32 v5, v13, v0
	s_waitcnt lgkmcnt(0)
	v_mul_f32_e32 v0, v17, v1
	v_add_f32_e32 v9, v9, v0
	v_lshlrev_b32_e32 v0, 16, v97
	v_lshlrev_b32_e32 v1, 16, v99
	v_cndmask_b32_e64 v0, v0, 0, s[38:39]
	v_cndmask_b32_e64 v1, v1, 0, s[38:39]
	s_waitcnt lgkmcnt(1)
	v_fmac_f32_e32 v6, v14, v0
	s_waitcnt lgkmcnt(0)
	v_mul_f32_e32 v0, v18, v1
	v_add_f32_e32 v10, v10, v0
	v_and_b32_e32 v0, 0xffff0000, v97
	v_and_b32_e32 v1, 0xffff0000, v99
	v_cndmask_b32_e64 v0, v0, 0, s[38:39]
	v_cndmask_b32_e64 v1, v1, 0, s[38:39]
	s_waitcnt lgkmcnt(1)
	v_fmac_f32_e32 v7, v15, v0
	s_waitcnt lgkmcnt(0)
	v_mul_f32_e32 v0, v19, v1
	v_add_f32_e32 v2, v0, v11
	v_mul_f32_e32 v0, 0xbfb8aa3b, v2
	v_exp_f32_e32 v1, v0
	v_mul_f32_e32 v0, 0xbfb8aa3b, v4
	s_waitcnt lgkmcnt(1)
	v_exp_f32_e32 v12, v0
	v_mul_f32_e32 v0, 0xbfb8aa3b, v5
	v_exp_f32_e32 v13, v0
	v_mul_f32_e32 v0, 0xbfb8aa3b, v6
	v_exp_f32_e32 v14, v0
	v_mul_f32_e32 v0, 0xbfb8aa3b, v7
	v_exp_f32_e32 v15, v0
	v_mul_f32_e32 v0, 0xbfb8aa3b, v8
	s_waitcnt lgkmcnt(0)
	v_exp_f32_e32 v16, v0
	v_mul_f32_e32 v0, 0xbfb8aa3b, v9
	v_exp_f32_e32 v17, v0
	v_mul_f32_e32 v0, 0xbfb8aa3b, v10
	v_exp_f32_e32 v0, v0
	v_pk_add_f32 v[14:15], v[14:15], 1.0 op_sel_hi:[1,0]
	v_pk_add_f32 v[16:17], v[16:17], 1.0 op_sel_hi:[1,0]
	v_pk_add_f32 v[12:13], v[12:13], 1.0 op_sel_hi:[1,0]
	v_pk_add_f32 v[0:1], v[0:1], 1.0 op_sel_hi:[1,0]
	s_nop 0
	v_rcp_f32_e32 v18, v1
	s_nop 0
	v_mul_f32_e32 v21, v2, v18
	v_fma_f32 v152, -v1, v21, v2
	v_fmac_f32_e32 v21, v152, v18
	v_div_fixup_f32 v1, v21, v1, v2
	v_rcp_f32_e32 v11, v0
	s_nop 0
	v_mul_f32_e32 v19, v10, v11
	v_fma_f32 v21, -v0, v19, v10
	v_fmac_f32_e32 v19, v21, v11
	v_div_fixup_f32 v0, v19, v0, v10
	v_rcp_f32_e32 v18, v17
	s_nop 0
	v_pk_mul_f32 v[10:11], v[0:1], v[0:1]
	v_mul_f32_e32 v21, v9, v18
	v_fma_f32 v152, -v17, v21, v9
	v_fmac_f32_e32 v21, v152, v18
	v_div_fixup_f32 v9, v21, v17, v9
	v_rcp_f32_e32 v17, v16
	s_nop 0
	v_mul_f32_e32 v19, v8, v17
	v_fma_f32 v21, -v16, v19, v8
	v_fmac_f32_e32 v19, v21, v17
	v_div_fixup_f32 v8, v19, v16, v8
	v_rcp_f32_e32 v18, v15
	s_nop 0
	v_pk_mul_f32 v[16:17], v[8:9], v[8:9]
	v_mul_f32_e32 v21, v7, v18
	v_fma_f32 v152, -v15, v21, v7
	v_fmac_f32_e32 v21, v152, v18
	v_div_fixup_f32 v7, v21, v15, v7
	v_rcp_f32_e32 v15, v14
	s_nop 0
	v_mul_f32_e32 v19, v6, v15
	v_fma_f32 v21, -v14, v19, v6
	v_fmac_f32_e32 v19, v21, v15
	v_div_fixup_f32 v6, v19, v14, v6
	v_rcp_f32_e32 v18, v13
	s_nop 0
	v_pk_mul_f32 v[14:15], v[6:7], v[6:7]
	v_mul_f32_e32 v21, v5, v18
	v_fma_f32 v152, -v13, v21, v5
	v_fmac_f32_e32 v21, v152, v18
	v_div_fixup_f32 v5, v21, v13, v5
	v_rcp_f32_e32 v13, v12
	s_nop 0
	v_mul_f32_e32 v19, v4, v13
	v_fma_f32 v21, -v12, v19, v4
	v_fmac_f32_e32 v19, v21, v13
	v_div_fixup_f32 v4, v19, v12, v4
	v_pk_mul_f32 v[12:13], v[4:5], v[4:5]
	s_nop 0
	v_add_f32_e32 v2, v12, v13
	v_add_f32_e32 v2, v14, v2
	v_add_f32_e32 v2, v15, v2
	v_add_f32_e32 v2, v16, v2
	v_add_f32_e32 v2, v17, v2
	v_add_f32_e32 v2, v10, v2
	v_add_f32_e32 v2, v11, v2
	ds_bpermute_b32 v10, v31, v2
	v_bfe_u32 v31, v29, 4, 3
	s_waitcnt lgkmcnt(0)
	v_add_f32_e32 v2, v2, v10
	ds_bpermute_b32 v10, v32, v2
	s_waitcnt lgkmcnt(0)
	v_add_f32_e32 v2, v2, v10
	ds_bpermute_b32 v10, v33, v2
	s_waitcnt lgkmcnt(0)
	v_add_f32_e32 v2, v2, v10
	ds_bpermute_b32 v10, v34, v2
	s_waitcnt lgkmcnt(0)
; #define LAS __attribute__((address_space(3)))
; DI unsigned pk2(float lo, float hi) { f32x2 v = {lo, hi}; bf2_t b = __builtin_convertvector(v, bf2_t); return __builtin_bit_cast(unsigned, b); }
; DI bf16_t f2bf(float f) { return (bf16_t)(pk2(f, 0.f) & 0xffffu); }
; DI void unpack8(u32x4 w, float* f) { f[0] = bflo(w.x); f[1] = bfhi(w.x); f[2] = bflo(w.y); f[3] = bfhi(w.y); f[4] = bflo(w.z); f[5] = bfhi(w.z); f[6] = bflo(w.w); f[7] = bfhi(w.w); }
; DI u32x4 pack8(const float* f) { u32x4 w; w.x = pk2(f[0], f[1]); w.y = pk2(f[2], f[3]); w.z = pk2(f[4], f[5]); w.w = pk2(f[6], f[7]); return w; }
; DI void gdn_intra(LAS unsigned char* lds, PP p, int l, int first, int stride) {
;     ...
;             for (int kk = 0; kk < 4; ++kk) { const bool ok = tok0 + j - 3 + kk >= 0;
;                 float x[8]; unpack8(R[(mat * 2 + it) * 4 + kk], x);
;                 const f32x4 w0 = *(const LAS f32x4*)(CW + kk * 384 + mat * 128 + o * 8), w1 = *(const LAS f32x4*)(CW + kk * 384 + mat * 128 + o * 8 + 4);
;                 for (int i = 0; i < 4; ++i) { a[i] += ok ? w0[i] * x[i] : 0.f; a[4 + i] += ok ? w1[i] * x[4 + i] : 0.f; } }
;     ...
;                 ss += __shfl_xor(ss, 1); ss += __shfl_xor(ss, 2); ss += __shfl_xor(ss, 4); ss += __shfl_xor(ss, 8);
;                 const float sc = rsqrtf(ss + 1e-6f) * (mat == 0 ? 0.08838834764831845f : 1.f);
; #pragma unroll
;                 for (int i = 0; i < 8; ++i) a[i] *= sc;
;             }
;             if (mat == 0) {
;                 *(LAS u32x4*)(Qn + j * 136 + o * 8) = pack8(a);
;                 const float eg = sce[j]; const int ct = j >> 5, s = o >> 1, part = o & 1;
;                 unsigned char* q0 = fb + 16384 + ((size_t)((ct * 8 + s) * 64 + (j & 31))) * 16 + 8 * part;
;                 u32x2 lo, hi2; lo.x = pk2(a[0] * eg, a[1] * eg); lo.y = pk2(a[2] * eg, a[3] * eg); hi2.x = pk2(a[4] * eg, a[5] * eg); hi2.y = pk2(a[6] * eg, a[7] * eg);
;                 *(u32x2*)q0 = lo; *(u32x2*)(q0 + 32 * 16) = hi2;
;             } else if (mat == 1) {
;                 *(LAS u32x4*)(Kn + j * 136 + o * 8) = pack8(a);
;                 const float f1 = scb[j] * sce[j], f2 = scl[j];
; #pragma unroll
;                 for (int i = 0; i < 8; ++i) { XTk[xsw(o * 8 + i, j)] = f2bf(a[i] * f1); KT2[xsw(o * 8 + i, j)] = f2bf(a[i] * f2); }
	v_add_f32_e32 v2, v2, v10
	v_add_f32_e32 v2, 0x358637bd, v2
	v_cmp_gt_f32_e32 vcc, s10, v2
	v_mul_f32_e32 v10, 0x4b800000, v2
	s_nop 0
	v_cndmask_b32_e32 v2, v2, v10, vcc
	v_rsq_f32_e32 v2, v2
	s_nop 0
	v_mul_f32_e32 v10, 0x45800000, v2
	v_cndmask_b32_e32 v2, v2, v10, vcc
	v_pk_mul_f32 v[10:11], v[4:5], v[2:3] op_sel_hi:[1,0]
	v_pk_mul_f32 v[12:13], v[6:7], v[2:3] op_sel_hi:[1,0]
	v_pk_mul_f32 v[8:9], v[8:9], v[2:3] op_sel_hi:[1,0]
	v_pk_mul_f32 v[0:1], v[0:1], v[2:3] op_sel_hi:[1,0]
	v_cvt_pk_bf16_f32 v4, v10, v11
	v_cvt_pk_bf16_f32 v5, v12, v13
	v_cvt_pk_bf16_f32 v6, v8, v9
	v_cvt_pk_bf16_f32 v7, v0, v1
	v_lshlrev_b32_e32 v2, 2, v27
	ds_write_b128 v142, v[4:7] offset:17408
	v_add_u32_e32 v21, v23, v2
	ds_read_b32 v4, v21
	ds_read_b32 v5, v141
	v_add_u32_e32 v2, v30, v2
	ds_read_b32 v2, v2
	v_bitop3_b32 v30, v27, 56, v143 bitop3:0x48
	s_waitcnt lgkmcnt(1)
	v_mul_f32_e32 v4, v4, v5
	v_or_b32_e32 v5, v30, v31
	v_or_b32_e32 v7, v5, v144
	v_mul_f32_e32 v6, v4, v10
	v_lshlrev_b32_e32 v7, 1, v7
	v_cvt_pk_bf16_f32 v6, v6, s0
	v_add_u32_e32 v14, v132, v7
	ds_write_b16 v14, v6 offset:34816
	s_waitcnt lgkmcnt(1)
	v_mul_f32_e32 v6, v2, v10
	v_cvt_pk_bf16_f32 v6, v6, s0
	v_add_u32_e32 v7, v20, v7
	ds_write_b16 v7, v6
	v_mul_f32_e32 v6, v4, v11
	v_add_u32_e32 v10, v5, v144
	v_cvt_pk_bf16_f32 v6, v6, s0
	v_lshl_add_u32 v10, v10, 1, v132
	v_add_u32_e32 v7, v5, v145
	ds_write_b16 v10, v6 offset:34960
	v_mul_f32_e32 v6, v2, v11
	v_cvt_pk_bf16_f32 v6, v6, s0
	v_lshl_add_u32 v7, v7, 1, v20
	ds_write_b16 v7, v6
	v_mul_f32_e32 v6, v4, v12
	v_cvt_pk_bf16_f32 v6, v6, s0
	v_add_u32_e32 v7, v5, v146
	ds_write_b16 v10, v6 offset:35104
	v_mul_f32_e32 v6, v2, v12
	v_cvt_pk_bf16_f32 v6, v6, s0
	v_lshl_add_u32 v7, v7, 1, v20
	ds_write_b16 v7, v6
	v_mul_f32_e32 v6, v4, v13
	v_cvt_pk_bf16_f32 v6, v6, s0
	v_add_u32_e32 v7, v5, v147
	ds_write_b16 v10, v6 offset:35248
	v_mul_f32_e32 v6, v2, v13
	v_cvt_pk_bf16_f32 v6, v6, s0
	v_lshl_add_u32 v7, v7, 1, v20
	ds_write_b16 v7, v6
	v_mul_f32_e32 v6, v4, v8
	v_cvt_pk_bf16_f32 v6, v6, s0
	v_add_u32_e32 v7, v5, v148
	ds_write_b16 v10, v6 offset:35392
	v_mul_f32_e32 v6, v2, v8
	v_cvt_pk_bf16_f32 v6, v6, s0
	v_lshl_add_u32 v7, v7, 1, v20
	ds_write_b16 v7, v6
	v_mul_f32_e32 v6, v4, v9
	v_cvt_pk_bf16_f32 v6, v6, s0
	v_add_u32_e32 v7, v5, v149
	ds_write_b16 v10, v6 offset:35536
	v_mul_f32_e32 v6, v2, v9
	v_cvt_pk_bf16_f32 v6, v6, s0
	v_lshl_add_u32 v7, v7, 1, v20
	ds_write_b16 v7, v6
	v_mul_f32_e32 v6, v4, v0
	v_cvt_pk_bf16_f32 v6, v6, s0
	v_add_u32_e32 v7, v5, v150
	v_mul_f32_e32 v0, v2, v0
	ds_write_b16 v10, v6 offset:35680
	v_cvt_pk_bf16_f32 v0, v0, s0
	v_lshl_add_u32 v6, v7, 1, v20
	ds_write_b16 v6, v0
	v_mul_f32_e32 v0, v4, v1
	v_cvt_pk_bf16_f32 v0, v0, s0
	v_add_u32_e32 v4, v5, v151
	ds_write_b16 v10, v0 offset:35824
	v_mul_f32_e32 v0, v2, v1
	v_cvt_pk_bf16_f32 v0, v0, s0
	v_lshl_add_u32 v1, v4, 1, v20
	ds_write_b16 v1, v0
	ds_read_b128 v[12:15], v26 offset:1024
	ds_read_b128 v[16:19], v26 offset:1040
	v_lshlrev_b32_e32 v0, 16, v102
	v_lshlrev_b32_e32 v4, 16, v100
	v_and_b32_e32 v2, 0xffff0000, v102
	s_waitcnt lgkmcnt(1)
	v_fma_f32 v4, v12, v4, 0
	s_waitcnt lgkmcnt(0)
	v_mul_f32_e32 v5, v16, v0
	v_and_b32_e32 v1, 0xffff0000, v100
	v_cndmask_b32_e64 v0, 0, v4, s[40:41]
	v_cndmask_b32_e64 v4, 0, v5, s[40:41]
	v_mul_f32_e32 v5, v17, v2
	v_fma_f32 v1, v13, v1, 0
	v_cndmask_b32_e64 v5, 0, v5, s[40:41]
	v_add_f32_e32 v4, 0, v4
	v_cndmask_b32_e64 v1, 0, v1, s[40:41]
	v_mov_b32_e32 v2, v3
	v_mov_b32_e32 v6, v3
	v_mov_b32_e32 v7, v3
	v_add_f32_e32 v5, 0, v5
	s_and_saveexec_b64 s[2:3], s[30:31]
	s_xor_b64 s[2:3], exec, s[2:3]
	s_or_saveexec_b64 s[2:3], s[2:3]
	v_mov_b32_e32 v8, 0
	s_xor_b64 exec, exec, s[2:3]
	v_lshlrev_b32_e32 v8, 16, v103
	v_lshlrev_b32_e32 v2, 16, v101
	v_fma_f32 v2, v14, v2, 0
	v_mul_f32_e32 v8, v18, v8
	s_or_b64 exec, exec, s[2:3]
	v_add_f32_e32 v12, v6, v8
	v_mov_b64_e32 v[10:11], v[6:7]
	v_mov_b64_e32 v[8:9], v[4:5]
	v_mov_b64_e32 v[6:7], v[2:3]
	v_mov_b64_e32 v[4:5], v[0:1]
	v_mov_b32_e32 v10, v12
	s_and_saveexec_b64 s[2:3], s[30:31]
	s_xor_b64 s[2:3], exec, s[2:3]
	v_add_f32_e32 v7, 0, v3
	s_or_saveexec_b64 s[2:3], s[2:3]
	v_mov_b32_e32 v0, 0
	s_xor_b64 exec, exec, s[2:3]
	v_and_b32_e32 v0, 0xffff0000, v101
	v_and_b32_e32 v1, 0xffff0000, v103
	v_mov_b32_e32 v7, v3
	v_fmac_f32_e32 v7, v15, v0
	v_mul_f32_e32 v0, v19, v1
	s_or_b64 exec, exec, s[2:3]
	ds_read_b128 v[12:15], v26 offset:2560
	ds_read_b128 v[16:19], v26 offset:2576
	v_add_f32_e32 v11, v11, v0
	v_lshlrev_b32_e32 v0, 16, v106
	v_lshlrev_b32_e32 v1, 16, v104
	v_cndmask_b32_e64 v0, v0, 0, s[24:25]
	v_cndmask_b32_e64 v1, v1, 0, s[24:25]
	s_waitcnt lgkmcnt(1)
	v_fmac_f32_e32 v4, v12, v1
	s_waitcnt lgkmcnt(0)
	v_mul_f32_e32 v0, v16, v0
	v_add_f32_e32 v8, v8, v0
	v_and_b32_e32 v0, 0xffff0000, v104
	v_and_b32_e32 v1, 0xffff0000, v106
	v_cndmask_b32_e64 v0, v0, 0, s[24:25]
	v_cndmask_b32_e64 v1, v1, 0, s[24:25]
	s_waitcnt lgkmcnt(1)
	v_fmac_f32_e32 v5, v13, v0
	s_waitcnt lgkmcnt(0)
	v_mul_f32_e32 v0, v17, v1
	v_add_f32_e32 v9, v9, v0
	v_lshlrev_b32_e32 v0, 16, v105
	v_lshlrev_b32_e32 v1, 16, v107
	v_cndmask_b32_e64 v0, v0, 0, s[24:25]
	v_cndmask_b32_e64 v1, v1, 0, s[24:25]
	s_waitcnt lgkmcnt(1)
	v_fmac_f32_e32 v6, v14, v0
	s_waitcnt lgkmcnt(0)
	v_mul_f32_e32 v0, v18, v1
	v_add_f32_e32 v10, v10, v0
	v_and_b32_e32 v0, 0xffff0000, v105
	v_and_b32_e32 v1, 0xffff0000, v107
	v_cndmask_b32_e64 v0, v0, 0, s[24:25]
	v_cndmask_b32_e64 v1, v1, 0, s[24:25]
	s_waitcnt lgkmcnt(1)
	v_fmac_f32_e32 v7, v15, v0
	s_waitcnt lgkmcnt(0)
	v_mul_f32_e32 v0, v19, v1
	s_waitcnt lgkmcnt(1)
	ds_read_b128 v[12:15], v26 offset:4096
	s_waitcnt lgkmcnt(1)
; #define LAS __attribute__((address_space(3)))
; DI bf16_t f2bf(float f) { return (bf16_t)(pk2(f, 0.f) & 0xffffu); }
; DI void unpack8(u32x4 w, float* f) { f[0] = bflo(w.x); f[1] = bfhi(w.x); f[2] = bflo(w.y); f[3] = bfhi(w.y); f[4] = bflo(w.z); f[5] = bfhi(w.z); f[6] = bflo(w.w); f[7] = bfhi(w.w); }
; DI void gdn_intra(LAS unsigned char* lds, PP p, int l, int first, int stride) {
;     ...
;             for (int kk = 0; kk < 4; ++kk) { const bool ok = tok0 + j - 3 + kk >= 0;
;                 float x[8]; unpack8(R[(mat * 2 + it) * 4 + kk], x);
;                 const f32x4 w0 = *(const LAS f32x4*)(CW + kk * 384 + mat * 128 + o * 8), w1 = *(const LAS f32x4*)(CW + kk * 384 + mat * 128 + o * 8 + 4);
;                 for (int i = 0; i < 4; ++i) { a[i] += ok ? w0[i] * x[i] : 0.f; a[4 + i] += ok ? w1[i] * x[4 + i] : 0.f; } }
; #pragma unroll
;             for (int i = 0; i < 8; ++i) a[i] = a[i] / (1.f + __expf(-a[i]));
;     ...
;             } else {
;                 const float f1 = scb[j];
; #pragma unroll
;                 for (int i = 0; i < 8; ++i) XTv[xsw(o * 8 + i, j)] = f2bf(a[i] * f1);
	ds_read_b128 v[16:19], v26 offset:4112
	v_add_f32_e32 v11, v11, v0
	v_lshlrev_b32_e32 v0, 16, v110
	v_lshlrev_b32_e32 v1, 16, v108
	v_cndmask_b32_e64 v0, v0, 0, s[26:27]
	v_cndmask_b32_e64 v1, v1, 0, s[26:27]
	s_waitcnt lgkmcnt(1)
	v_fmac_f32_e32 v4, v12, v1
	s_waitcnt lgkmcnt(0)
	v_mul_f32_e32 v0, v16, v0
	v_add_f32_e32 v8, v8, v0
	v_and_b32_e32 v0, 0xffff0000, v108
	v_and_b32_e32 v1, 0xffff0000, v110
	v_cndmask_b32_e64 v0, v0, 0, s[26:27]
	v_cndmask_b32_e64 v1, v1, 0, s[26:27]
	s_waitcnt lgkmcnt(1)
	v_fmac_f32_e32 v5, v13, v0
	s_waitcnt lgkmcnt(0)
	v_mul_f32_e32 v0, v17, v1
	v_add_f32_e32 v9, v9, v0
	v_lshlrev_b32_e32 v0, 16, v109
	v_lshlrev_b32_e32 v1, 16, v111
	v_cndmask_b32_e64 v0, v0, 0, s[26:27]
	v_cndmask_b32_e64 v1, v1, 0, s[26:27]
	s_waitcnt lgkmcnt(1)
	v_fmac_f32_e32 v6, v14, v0
	s_waitcnt lgkmcnt(0)
	v_mul_f32_e32 v0, v18, v1
	v_add_f32_e32 v10, v10, v0
	v_and_b32_e32 v0, 0xffff0000, v109
	v_and_b32_e32 v1, 0xffff0000, v111
	v_cndmask_b32_e64 v0, v0, 0, s[26:27]
	v_cndmask_b32_e64 v1, v1, 0, s[26:27]
	s_waitcnt lgkmcnt(1)
	v_fmac_f32_e32 v7, v15, v0
	s_waitcnt lgkmcnt(0)
	v_mul_f32_e32 v0, v19, v1
	s_waitcnt lgkmcnt(1)
	ds_read_b128 v[12:15], v26 offset:5632
	s_waitcnt lgkmcnt(1)
	ds_read_b128 v[16:19], v26 offset:5648
	v_add_f32_e32 v11, v11, v0
	v_lshlrev_b32_e32 v0, 16, v114
	v_lshlrev_b32_e32 v1, 16, v112
	v_cndmask_b32_e64 v0, v0, 0, s[28:29]
	v_cndmask_b32_e64 v1, v1, 0, s[28:29]
	s_waitcnt lgkmcnt(1)
	v_fmac_f32_e32 v4, v12, v1
	s_waitcnt lgkmcnt(0)
	v_mul_f32_e32 v0, v16, v0
	v_add_f32_e32 v8, v8, v0
	v_and_b32_e32 v0, 0xffff0000, v112
	v_and_b32_e32 v1, 0xffff0000, v114
	v_cndmask_b32_e64 v0, v0, 0, s[28:29]
	v_cndmask_b32_e64 v1, v1, 0, s[28:29]
	s_waitcnt lgkmcnt(1)
	v_fmac_f32_e32 v5, v13, v0
	s_waitcnt lgkmcnt(0)
	v_mul_f32_e32 v0, v17, v1
	v_add_f32_e32 v9, v9, v0
	v_lshlrev_b32_e32 v0, 16, v113
	v_lshlrev_b32_e32 v1, 16, v115
	v_cndmask_b32_e64 v0, v0, 0, s[28:29]
	v_cndmask_b32_e64 v1, v1, 0, s[28:29]
	s_waitcnt lgkmcnt(1)
	v_fmac_f32_e32 v6, v14, v0
	s_waitcnt lgkmcnt(0)
	v_mul_f32_e32 v0, v18, v1
	v_add_f32_e32 v10, v10, v0
	v_and_b32_e32 v0, 0xffff0000, v113
	v_and_b32_e32 v1, 0xffff0000, v115
	v_cndmask_b32_e64 v0, v0, 0, s[28:29]
	v_cndmask_b32_e64 v1, v1, 0, s[28:29]
	s_waitcnt lgkmcnt(1)
	v_fmac_f32_e32 v7, v15, v0
	s_waitcnt lgkmcnt(0)
	v_mul_f32_e32 v0, v19, v1
	v_add_f32_e32 v0, v11, v0
	v_mul_f32_e32 v1, 0xbfb8aa3b, v0
	v_exp_f32_e32 v1, v1
	v_mul_u32_u24_e32 v28, 0x480, v28
	v_add_f32_e32 v1, 1.0, v1
	v_rcp_f32_e32 v11, v1
	s_nop 0
	s_waitcnt lgkmcnt(1)
	v_mul_f32_e32 v13, v0, v11
	v_fma_f32 v14, -v1, v13, v0
	v_fmac_f32_e32 v13, v14, v11
	v_div_fixup_f32 v0, v13, v1, v0
	v_mul_f32_e32 v1, 0xbfb8aa3b, v10
	v_exp_f32_e32 v1, v1
	s_nop 0
	v_add_f32_e32 v1, 1.0, v1
	v_rcp_f32_e32 v11, v1
	s_nop 0
	v_mul_f32_e32 v13, v10, v11
	v_fma_f32 v14, -v1, v13, v10
	v_fmac_f32_e32 v13, v14, v11
	v_div_fixup_f32 v1, v13, v1, v10
	v_mul_f32_e32 v2, 0xbfb8aa3b, v9
	v_exp_f32_e32 v2, v2
	s_nop 0
	v_add_f32_e32 v2, 1.0, v2
	v_rcp_f32_e32 v11, v2
	s_nop 0
	v_mul_f32_e32 v13, v9, v11
	v_fma_f32 v14, -v2, v13, v9
	v_fmac_f32_e32 v13, v14, v11
	v_div_fixup_f32 v2, v13, v2, v9
	v_mul_f32_e32 v9, 0xbfb8aa3b, v8
	v_exp_f32_e32 v9, v9
	s_nop 0
	v_add_f32_e32 v9, 1.0, v9
	v_rcp_f32_e32 v11, v9
	s_nop 0
	v_mul_f32_e32 v13, v8, v11
	v_fma_f32 v14, -v9, v13, v8
	v_fmac_f32_e32 v13, v14, v11
	v_div_fixup_f32 v8, v13, v9, v8
	v_mul_f32_e32 v9, 0xbfb8aa3b, v7
	v_exp_f32_e32 v9, v9
	s_nop 0
	v_add_f32_e32 v9, 1.0, v9
	v_rcp_f32_e32 v11, v9
	s_nop 0
	v_mul_f32_e32 v13, v7, v11
	v_fma_f32 v14, -v9, v13, v7
	v_fmac_f32_e32 v13, v14, v11
	v_div_fixup_f32 v7, v13, v9, v7
	v_mul_f32_e32 v9, 0xbfb8aa3b, v6
	v_exp_f32_e32 v9, v9
	s_nop 0
	v_add_f32_e32 v9, 1.0, v9
	v_rcp_f32_e32 v11, v9
	s_nop 0
	v_mul_f32_e32 v13, v6, v11
	v_fma_f32 v14, -v9, v13, v6
	v_fmac_f32_e32 v13, v14, v11
	v_div_fixup_f32 v6, v13, v9, v6
	v_mul_f32_e32 v9, 0xbfb8aa3b, v5
	v_exp_f32_e32 v9, v9
	s_nop 0
	v_add_f32_e32 v9, 1.0, v9
	v_rcp_f32_e32 v11, v9
	s_nop 0
	v_mul_f32_e32 v13, v5, v11
	v_fma_f32 v14, -v9, v13, v5
	v_fmac_f32_e32 v13, v14, v11
	v_div_fixup_f32 v5, v13, v9, v5
	v_mul_f32_e32 v9, 0xbfb8aa3b, v4
	v_exp_f32_e32 v9, v9
	s_nop 0
	v_add_f32_e32 v9, 1.0, v9
	v_rcp_f32_e32 v11, v9
	s_nop 0
	v_mul_f32_e32 v13, v4, v11
	v_fma_f32 v14, -v9, v13, v4
	v_fmac_f32_e32 v13, v14, v11
	v_div_fixup_f32 v4, v13, v9, v4
	ds_read_b32 v9, v35
	v_lshl_add_u32 v10, v139, 1, v132
	v_lshlrev_b32_e32 v11, 1, v140
	v_add3_u32 v10, v10, v11, v28
	s_waitcnt lgkmcnt(0)
	v_mul_f32_e32 v4, v9, v4
	v_cvt_pk_bf16_f32 v4, v4, s0
	ds_write_b16 v10, v4 offset:53248
	v_mul_f32_e32 v4, v9, v5
	v_cvt_pk_bf16_f32 v4, v4, s0
	ds_write_b16 v10, v4 offset:53392
	v_mul_f32_e32 v4, v9, v6
	v_cvt_pk_bf16_f32 v4, v4, s0
	ds_write_b16 v10, v4 offset:53536
	v_mul_f32_e32 v4, v9, v7
	v_cvt_pk_bf16_f32 v4, v4, s0
	ds_write_b16 v10, v4 offset:53680
	v_mul_f32_e32 v4, v9, v8
	v_mul_f32_e32 v2, v9, v2
	v_mul_f32_e32 v1, v9, v1
	v_mul_f32_e32 v0, v9, v0
	v_cvt_pk_bf16_f32 v4, v4, s0
	v_cvt_pk_bf16_f32 v2, v2, s0
	v_cvt_pk_bf16_f32 v1, v1, s0
	v_cvt_pk_bf16_f32 v0, v0, s0
	ds_write_b16 v10, v4 offset:53824
	ds_write_b16 v10, v2 offset:53968
	ds_write_b16 v10, v1 offset:54112
	ds_write_b16 v10, v0 offset:54256
	ds_read_b128 v[12:15], v26 offset:1024
	ds_read_b128 v[16:19], v26 offset:1040
	v_lshlrev_b32_e32 v0, 16, v118
	v_lshlrev_b32_e32 v4, 16, v116
	v_and_b32_e32 v2, 0xffff0000, v118
	s_waitcnt lgkmcnt(1)
	v_fma_f32 v4, v12, v4, 0
	s_waitcnt lgkmcnt(0)
; #define LAS __attribute__((address_space(3)))
; DI void unpack8(u32x4 w, float* f) { f[0] = bflo(w.x); f[1] = bfhi(w.x); f[2] = bflo(w.y); f[3] = bfhi(w.y); f[4] = bflo(w.z); f[5] = bfhi(w.z); f[6] = bflo(w.w); f[7] = bfhi(w.w); }
; DI void gdn_intra(LAS unsigned char* lds, PP p, int l, int first, int stride) {
;     ...
;             for (int kk = 0; kk < 4; ++kk) { const bool ok = tok0 + j - 3 + kk >= 0;
;                 float x[8]; unpack8(R[(mat * 2 + it) * 4 + kk], x);
;                 const f32x4 w0 = *(const LAS f32x4*)(CW + kk * 384 + mat * 128 + o * 8), w1 = *(const LAS f32x4*)(CW + kk * 384 + mat * 128 + o * 8 + 4);
;                 for (int i = 0; i < 4; ++i) { a[i] += ok ? w0[i] * x[i] : 0.f; a[4 + i] += ok ? w1[i] * x[4 + i] : 0.f; } }
; #pragma unroll
;             for (int i = 0; i < 8; ++i) a[i] = a[i] / (1.f + __expf(-a[i]));
	v_mul_f32_e32 v5, v16, v0
	v_and_b32_e32 v1, 0xffff0000, v116
	v_cndmask_b32_e64 v0, 0, v4, s[44:45]
	v_cndmask_b32_e64 v4, 0, v5, s[44:45]
	v_mul_f32_e32 v5, v17, v2
	v_fma_f32 v1, v13, v1, 0
	v_cndmask_b32_e64 v5, 0, v5, s[44:45]
	v_add_f32_e32 v4, 0, v4
	v_cndmask_b32_e64 v1, 0, v1, s[44:45]
	v_mov_b32_e32 v2, v3
	v_mov_b32_e32 v6, v3
	v_mov_b32_e32 v7, v3
	v_add_f32_e32 v5, 0, v5
	s_and_saveexec_b64 s[2:3], s[42:43]
	s_xor_b64 s[2:3], exec, s[2:3]
	s_or_saveexec_b64 s[2:3], s[2:3]
	v_mov_b32_e32 v8, 0
	s_xor_b64 exec, exec, s[2:3]
	v_lshlrev_b32_e32 v8, 16, v119
	v_lshlrev_b32_e32 v2, 16, v117
	v_fma_f32 v2, v14, v2, 0
	v_mul_f32_e32 v8, v18, v8
	s_or_b64 exec, exec, s[2:3]
	v_add_f32_e32 v12, v6, v8
	v_mov_b64_e32 v[10:11], v[6:7]
	v_mov_b64_e32 v[8:9], v[4:5]
	v_mov_b64_e32 v[6:7], v[2:3]
	v_mov_b64_e32 v[4:5], v[0:1]
	v_mov_b32_e32 v10, v12
	s_and_saveexec_b64 s[2:3], s[42:43]
	s_xor_b64 s[2:3], exec, s[2:3]
	v_add_f32_e32 v7, 0, v3
	s_or_saveexec_b64 s[2:3], s[2:3]
	v_mov_b32_e32 v0, 0
	s_xor_b64 exec, exec, s[2:3]
	v_and_b32_e32 v0, 0xffff0000, v117
	v_and_b32_e32 v1, 0xffff0000, v119
	v_mov_b32_e32 v7, v3
	v_fmac_f32_e32 v7, v15, v0
	v_mul_f32_e32 v0, v19, v1
	s_or_b64 exec, exec, s[2:3]
	ds_read_b128 v[12:15], v26 offset:2560
	ds_read_b128 v[16:19], v26 offset:2576
	v_add_f32_e32 v11, v11, v0
	v_lshlrev_b32_e32 v0, 16, v122
	v_lshlrev_b32_e32 v1, 16, v120
	v_cndmask_b32_e64 v0, v0, 0, s[34:35]
	v_cndmask_b32_e64 v1, v1, 0, s[34:35]
	s_waitcnt lgkmcnt(1)
	v_fmac_f32_e32 v4, v12, v1
	s_waitcnt lgkmcnt(0)
	v_mul_f32_e32 v0, v16, v0
	v_add_f32_e32 v8, v8, v0
	v_and_b32_e32 v0, 0xffff0000, v120
	v_and_b32_e32 v1, 0xffff0000, v122
	v_cndmask_b32_e64 v0, v0, 0, s[34:35]
	v_cndmask_b32_e64 v1, v1, 0, s[34:35]
	s_waitcnt lgkmcnt(1)
	v_fmac_f32_e32 v5, v13, v0
	s_waitcnt lgkmcnt(0)
	v_mul_f32_e32 v0, v17, v1
	v_add_f32_e32 v9, v9, v0
	v_lshlrev_b32_e32 v0, 16, v121
	v_lshlrev_b32_e32 v1, 16, v123
	v_cndmask_b32_e64 v0, v0, 0, s[34:35]
	v_cndmask_b32_e64 v1, v1, 0, s[34:35]
	s_waitcnt lgkmcnt(1)
	v_fmac_f32_e32 v6, v14, v0
	s_waitcnt lgkmcnt(0)
	v_mul_f32_e32 v0, v18, v1
	v_add_f32_e32 v10, v10, v0
	v_and_b32_e32 v0, 0xffff0000, v121
	v_and_b32_e32 v1, 0xffff0000, v123
	v_cndmask_b32_e64 v0, v0, 0, s[34:35]
	v_cndmask_b32_e64 v1, v1, 0, s[34:35]
	s_waitcnt lgkmcnt(1)
	v_fmac_f32_e32 v7, v15, v0
	s_waitcnt lgkmcnt(0)
	v_mul_f32_e32 v0, v19, v1
	s_waitcnt lgkmcnt(1)
	ds_read_b128 v[12:15], v26 offset:4096
	s_waitcnt lgkmcnt(1)
	ds_read_b128 v[16:19], v26 offset:4112
	v_add_f32_e32 v11, v11, v0
	v_lshlrev_b32_e32 v0, 16, v126
	v_lshlrev_b32_e32 v1, 16, v124
	v_cndmask_b32_e64 v0, v0, 0, s[36:37]
	v_cndmask_b32_e64 v1, v1, 0, s[36:37]
	s_waitcnt lgkmcnt(1)
	v_fmac_f32_e32 v4, v12, v1
	s_waitcnt lgkmcnt(0)
	v_mul_f32_e32 v0, v16, v0
	v_add_f32_e32 v8, v8, v0
	v_and_b32_e32 v0, 0xffff0000, v124
	v_and_b32_e32 v1, 0xffff0000, v126
	v_cndmask_b32_e64 v0, v0, 0, s[36:37]
	v_cndmask_b32_e64 v1, v1, 0, s[36:37]
	s_waitcnt lgkmcnt(1)
	v_fmac_f32_e32 v5, v13, v0
	s_waitcnt lgkmcnt(0)
	v_mul_f32_e32 v0, v17, v1
	v_add_f32_e32 v9, v9, v0
	v_lshlrev_b32_e32 v0, 16, v125
	v_lshlrev_b32_e32 v1, 16, v127
	v_cndmask_b32_e64 v0, v0, 0, s[36:37]
	v_cndmask_b32_e64 v1, v1, 0, s[36:37]
	s_waitcnt lgkmcnt(1)
	v_fmac_f32_e32 v6, v14, v0
	s_waitcnt lgkmcnt(0)
	v_mul_f32_e32 v0, v18, v1
	v_add_f32_e32 v10, v10, v0
	v_and_b32_e32 v0, 0xffff0000, v125
	v_and_b32_e32 v1, 0xffff0000, v127
	v_cndmask_b32_e64 v0, v0, 0, s[36:37]
	v_cndmask_b32_e64 v1, v1, 0, s[36:37]
	s_waitcnt lgkmcnt(1)
	v_fmac_f32_e32 v7, v15, v0
	s_waitcnt lgkmcnt(0)
	v_mul_f32_e32 v0, v19, v1
	s_waitcnt lgkmcnt(1)
	ds_read_b128 v[12:15], v26 offset:5632
	s_waitcnt lgkmcnt(1)
	ds_read_b128 v[16:19], v26 offset:5648
	v_add_f32_e32 v11, v11, v0
	v_lshlrev_b32_e32 v0, 16, v130
	v_lshlrev_b32_e32 v1, 16, v128
	v_cndmask_b32_e64 v0, v0, 0, s[38:39]
	v_cndmask_b32_e64 v1, v1, 0, s[38:39]
	s_waitcnt lgkmcnt(1)
	v_fmac_f32_e32 v4, v12, v1
	s_waitcnt lgkmcnt(0)
	v_mul_f32_e32 v0, v16, v0
	v_add_f32_e32 v8, v8, v0
	v_and_b32_e32 v0, 0xffff0000, v128
	v_and_b32_e32 v1, 0xffff0000, v130
	v_cndmask_b32_e64 v0, v0, 0, s[38:39]
	v_cndmask_b32_e64 v1, v1, 0, s[38:39]
	s_waitcnt lgkmcnt(1)
	v_fmac_f32_e32 v5, v13, v0
	s_waitcnt lgkmcnt(0)
	v_mul_f32_e32 v0, v17, v1
	v_add_f32_e32 v9, v9, v0
	v_lshlrev_b32_e32 v0, 16, v129
	v_lshlrev_b32_e32 v1, 16, v131
	v_cndmask_b32_e64 v0, v0, 0, s[38:39]
	v_cndmask_b32_e64 v1, v1, 0, s[38:39]
	s_waitcnt lgkmcnt(1)
	v_fmac_f32_e32 v6, v14, v0
	s_waitcnt lgkmcnt(0)
	v_mul_f32_e32 v0, v18, v1
	v_add_f32_e32 v10, v10, v0
	v_and_b32_e32 v0, 0xffff0000, v129
	v_and_b32_e32 v1, 0xffff0000, v131
	v_cndmask_b32_e64 v0, v0, 0, s[38:39]
	v_cndmask_b32_e64 v1, v1, 0, s[38:39]
	s_waitcnt lgkmcnt(1)
	v_fmac_f32_e32 v7, v15, v0
	s_waitcnt lgkmcnt(0)
	v_mul_f32_e32 v0, v19, v1
	v_add_f32_e32 v0, v11, v0
	v_mul_f32_e32 v1, 0xbfb8aa3b, v0
	v_exp_f32_e32 v1, v1
	s_nop 0
	v_add_f32_e32 v1, 1.0, v1
	v_rcp_f32_e32 v11, v1
	s_nop 0
	s_waitcnt lgkmcnt(1)
; DI bf16_t f2bf(float f) { return (bf16_t)(pk2(f, 0.f) & 0xffffu); }
; DI void gdn_intra(LAS unsigned char* lds, PP p, int l, int first, int stride) {
;     ...
; #pragma unroll
;             for (int i = 0; i < 8; ++i) a[i] = a[i] / (1.f + __expf(-a[i]));
;     ...
;             } else {
;                 const float f1 = scb[j];
; #pragma unroll
;                 for (int i = 0; i < 8; ++i) XTv[xsw(o * 8 + i, j)] = f2bf(a[i] * f1);
;     ...
;     { const int nxt = item + stride; if (nxt < 2048) { INTRA_PREFETCH(nxt); INTRA_LOADRAW(nxt); } }
	v_mul_f32_e32 v13, v0, v11
	v_fma_f32 v14, -v1, v13, v0
	v_fmac_f32_e32 v13, v14, v11
	v_div_fixup_f32 v0, v13, v1, v0
	v_mul_f32_e32 v1, 0xbfb8aa3b, v10
	v_exp_f32_e32 v1, v1
	s_nop 0
	v_add_f32_e32 v1, 1.0, v1
	v_rcp_f32_e32 v11, v1
	s_nop 0
	v_mul_f32_e32 v13, v10, v11
	v_fma_f32 v14, -v1, v13, v10
	v_fmac_f32_e32 v13, v14, v11
	v_div_fixup_f32 v1, v13, v1, v10
	v_mul_f32_e32 v2, 0xbfb8aa3b, v4
	v_exp_f32_e32 v2, v2
	s_nop 0
	v_add_f32_e32 v2, 1.0, v2
	v_rcp_f32_e32 v11, v2
	s_nop 0
	v_mul_f32_e32 v13, v4, v11
	v_fma_f32 v14, -v2, v13, v4
	v_fmac_f32_e32 v13, v14, v11
	v_div_fixup_f32 v2, v13, v2, v4
	v_mul_f32_e32 v4, 0xbfb8aa3b, v5
	v_exp_f32_e32 v4, v4
	s_nop 0
	v_add_f32_e32 v4, 1.0, v4
	v_rcp_f32_e32 v11, v4
	s_nop 0
	v_mul_f32_e32 v13, v5, v11
	v_fma_f32 v14, -v4, v13, v5
	v_fmac_f32_e32 v13, v14, v11
	v_div_fixup_f32 v4, v13, v4, v5
	v_mul_f32_e32 v5, 0xbfb8aa3b, v6
	v_exp_f32_e32 v5, v5
	s_nop 0
	v_add_f32_e32 v5, 1.0, v5
	v_rcp_f32_e32 v11, v5
	s_nop 0
	v_mul_f32_e32 v13, v6, v11
	v_fma_f32 v14, -v5, v13, v6
	v_fmac_f32_e32 v13, v14, v11
	v_div_fixup_f32 v5, v13, v5, v6
	v_mul_f32_e32 v6, 0xbfb8aa3b, v7
	v_exp_f32_e32 v6, v6
	s_nop 0
	v_add_f32_e32 v6, 1.0, v6
	v_rcp_f32_e32 v11, v6
	s_nop 0
	v_mul_f32_e32 v13, v7, v11
	v_fma_f32 v14, -v6, v13, v7
	v_fmac_f32_e32 v13, v14, v11
	v_div_fixup_f32 v6, v13, v6, v7
	v_mul_f32_e32 v7, 0xbfb8aa3b, v8
	v_exp_f32_e32 v7, v7
	s_nop 0
	v_add_f32_e32 v7, 1.0, v7
	v_rcp_f32_e32 v11, v7
	s_nop 0
	v_mul_f32_e32 v13, v8, v11
	v_fma_f32 v14, -v7, v13, v8
	v_fmac_f32_e32 v13, v14, v11
	v_div_fixup_f32 v7, v13, v7, v8
	v_mul_f32_e32 v8, 0xbfb8aa3b, v9
	v_exp_f32_e32 v8, v8
	s_nop 0
	v_add_f32_e32 v8, 1.0, v8
	v_rcp_f32_e32 v11, v8
	s_nop 0
	v_mul_f32_e32 v13, v9, v11
	v_fma_f32 v14, -v8, v13, v9
	v_fmac_f32_e32 v13, v14, v11
	v_div_fixup_f32 v8, v13, v8, v9
	ds_read_b32 v9, v21
	v_lshl_add_u32 v10, v30, 1, v132
	v_lshlrev_b32_e32 v11, 1, v31
	v_add3_u32 v10, v10, v11, v28
	s_waitcnt lgkmcnt(0)
	v_mul_f32_e32 v2, v9, v2
	v_cvt_pk_bf16_f32 v2, v2, s0
	ds_write_b16 v10, v2 offset:53248
	v_mul_f32_e32 v2, v9, v4
	v_cvt_pk_bf16_f32 v2, v2, s0
	ds_write_b16 v10, v2 offset:53392
	v_mul_f32_e32 v2, v9, v5
	v_cvt_pk_bf16_f32 v2, v2, s0
	ds_write_b16 v10, v2 offset:53536
	v_mul_f32_e32 v2, v9, v6
	v_cvt_pk_bf16_f32 v2, v2, s0
	ds_write_b16 v10, v2 offset:53680
	v_mul_f32_e32 v2, v9, v7
	v_cvt_pk_bf16_f32 v2, v2, s0
	ds_write_b16 v10, v2 offset:53824
	v_mul_f32_e32 v2, v9, v8
	v_mul_f32_e32 v1, v9, v1
	v_mul_f32_e32 v0, v9, v0
	v_cvt_pk_bf16_f32 v2, v2, s0
	v_cvt_pk_bf16_f32 v1, v1, s0
	v_cvt_pk_bf16_f32 v0, v0, s0
	ds_write_b16 v10, v2 offset:53968
	ds_write_b16 v10, v1 offset:54112
	ds_write_b16 v10, v0 offset:54256
	v_readlane_b32 s2, v254, 11
	s_add_i32 s30, s2, s54
	s_cmpk_gt_i32 s30, 0x7ff
	s_cselect_b64 s[26:27], -1, 0
	s_and_b64 vcc, exec, s[26:27]
	s_cbranch_vccnz .LBB0_758
	s_ashr_i32 s3, s30, 8
	s_lshl_b32 s2, s3, 7
	v_and_b32_e32 v0, 0x7f, v138
	s_mov_b32 s21, 0x2aaaaaab
	v_or_b32_e32 v2, s2, v0
	v_mul_hi_i32 v0, v138, s21
	v_lshrrev_b32_e32 v1, 31, v0
	v_ashrrev_i32_e32 v0, 6, v0
	v_add_u32_e32 v0, v0, v1
	v_mul_i32_i24_e32 v1, 0xfffffe80, v0
	v_add_lshl_u32 v1, v1, v138, 3
	v_mul_i32_i24_e32 v0, 0xc00, v0
	v_and_b32_e32 v1, 0xfffffc00, v1
	v_add3_u32 v0, v2, v0, v1
	v_ashrrev_i32_e32 v1, 31, v0
	v_lshl_add_u64 v[0:1], v[0:1], 2, s[52:53]
	global_load_dword v133, v[0:1], off
	v_mul_hi_i32 v0, v29, s21
	v_lshrrev_b32_e32 v1, 31, v0
	v_ashrrev_i32_e32 v0, 6, v0
	v_add_u32_e32 v0, v0, v1
	v_mul_i32_i24_e32 v1, 0xfffffe80, v0
	v_add_lshl_u32 v1, v1, v29, 3
	v_mul_i32_i24_e32 v0, 0xc00, v0
	v_and_b32_e32 v1, 0xfffffc00, v1
	v_add3_u32 v0, v2, v0, v1
	v_ashrrev_i32_e32 v1, 31, v0
	v_lshl_add_u64 v[0:1], v[0:1], 2, s[52:53]
	global_load_dword v136, v[0:1], off
	v_add_u32_e32 v0, 0x400, v138
	v_mul_hi_i32 v1, v0, s21
	v_lshrrev_b32_e32 v4, 31, v1
	v_ashrrev_i32_e32 v1, 6, v1
	v_add_u32_e32 v1, v1, v4
	v_mul_i32_i24_e32 v4, 0xfffffe80, v1
	v_add_lshl_u32 v0, v4, v0, 3
	v_mul_i32_i24_e32 v1, 0xc00, v1
	v_and_b32_e32 v0, 0xfffffc00, v0
	v_add3_u32 v0, v2, v1, v0
	v_ashrrev_i32_e32 v1, 31, v0
	v_lshl_add_u64 v[0:1], v[0:1], 2, s[52:53]
	global_load_dword v137, v[0:1], off
	s_lshl_b32 s20, s30, 6
	s_and_b32 s24, s20, 0x3fc0
	s_and_saveexec_b64 s[20:21], s[22:23]
	s_cbranch_execz .LBB0_757
	v_add_u32_e32 v0, s24, v138
	s_ashr_i32 s22, s3, 31
	v_ashrrev_i32_e32 v1, 31, v0
	v_mov_b32_e32 v4, s3
	v_mov_b32_e32 v5, s22
	v_lshl_add_u64 v[0:1], v[0:1], 4, v[4:5]
	v_lshlrev_b64 v[0:1], 2, v[0:1]
	v_lshl_add_u64 v[4:5], s[48:49], 0, v[0:1]
	v_lshl_add_u64 v[0:1], s[50:51], 0, v[0:1]
	global_load_dword v7, v[4:5], off
	global_load_dword v9, v[0:1], off
	global_load_dword v8, v[0:1], off offset:32
	global_load_dword v6, v[4:5], off offset:32
	s_waitcnt vmcnt(0)
	v_pk_add_f32 v[134:135], v[6:7], v[8:9]

; #define LAS __attribute__((address_space(3)))
; DI void gdn_intra(LAS unsigned char* lds, PP p, int l, int first, int stride) {
;     ...
;     if (w < 2) {
;         float t[32];
;         const int base = 32 * w; const float cf = (float)r;
; #pragma unroll
;         for (int i = 0; i < 32; ++i) {
;             float a0 = fmaxf(0.f, 1.f - fabsf(cf - (float)i)), a1 = 0.f;
; #pragma unroll
;             for (int j4 = 0; j4 < (i + 3) / 4; ++j4) { const f32x4 mv = *(const LAS f32x4*)(Mm + (base + i) * 68 + base + j4 * 4);
; #pragma unroll
;                 for (int jj = 0; jj < 4; ++jj) { const int j = j4 * 4 + jj; if (j < i) { if (jj & 1) a1 -= mv[jj] * t[j]; else a0 -= mv[jj] * t[j]; } } }
;             t[i] = a0 + a1;
;             asm volatile("" : "+v"(t[i]) :: "memory");
;         }
.LBB0_927:
	s_or_saveexec_b64 s[28:29], s[2:3]
	v_and_b32_e32 v143, 63, v138
	v_add_u32_e32 v144, 0x16000, v132
	s_xor_b64 exec, exec, s[28:29]
	s_cbranch_execz .LBB0_420
	v_cvt_f32_ubyte0_e32 v4, v139
	v_sub_f32_e32 v4, 1.0, v4
	s_movk_i32 s2, 0x2200
	v_lshlrev_b32_e32 v0, 7, v142
	v_max_f32_e32 v4, 0, v4
	v_add_u32_e32 v5, -1, v139
	v_mul_lo_u32 v6, v142, s2
	v_cvt_f32_i32_e32 v5, v5
	v_add3_u32 v0, v21, v0, v6
	ds_read_b128 v[6:9], v0 offset:272
	v_cmp_gt_u32_e64 s[24:25], 32, v143
	v_sub_f32_e64 v5, 1.0, |v5|
	v_max_f32_e32 v5, 0, v5
	v_cmp_lt_u32_e64 s[22:23], 31, v143
	s_waitcnt lgkmcnt(0)
	v_fma_f32 v5, -v4, v6, v5
	v_add_u32_e32 v6, -2, v139
	v_cvt_f32_i32_e32 v6, v6
	v_cmp_eq_u32_e32 vcc, 1, v142
	v_sub_f32_e64 v6, 1.0, |v6|
	v_max_f32_e32 v10, 0, v6
	ds_read_b128 v[6:9], v0 offset:544
	s_waitcnt lgkmcnt(0)
	v_fma_f32 v6, -v4, v6, v10
	v_fma_f32 v7, -v5, v7, 0
	v_add_f32_e32 v6, v6, v7
	v_add_u32_e32 v7, -3, v139
	v_cvt_f32_i32_e32 v7, v7
	ds_read_b128 v[8:11], v0 offset:816
	v_sub_f32_e64 v7, 1.0, |v7|
	v_max_f32_e32 v7, 0, v7
	s_waitcnt lgkmcnt(0)
	v_fma_f32 v7, -v4, v8, v7
	v_fma_f32 v8, -v5, v9, 0
	v_fma_f32 v7, -v6, v10, v7
	v_add_f32_e32 v7, v8, v7
	v_add_u32_e32 v8, -4, v139
	v_cvt_f32_i32_e32 v8, v8
	v_sub_f32_e64 v8, 1.0, |v8|
	v_max_f32_e32 v12, 0, v8
	ds_read_b128 v[8:11], v0 offset:1088
	s_waitcnt lgkmcnt(0)
	v_fma_f32 v8, -v4, v8, v12
	v_fma_f32 v9, -v5, v9, 0
	v_fma_f32 v8, -v6, v10, v8
	v_fma_f32 v9, -v7, v11, v9
	v_add_f32_e32 v8, v8, v9
	v_add_u32_e32 v9, -5, v139
	v_cvt_f32_i32_e32 v9, v9
	ds_read_b128 v[10:13], v0 offset:1360
	ds_read_b128 v[14:17], v0 offset:1376
	v_sub_f32_e64 v9, 1.0, |v9|
	v_max_f32_e32 v9, 0, v9
	s_waitcnt lgkmcnt(1)
	v_fma_f32 v9, -v4, v10, v9
	v_fma_f32 v10, -v5, v11, 0
	v_fma_f32 v9, -v6, v12, v9
	v_fma_f32 v10, -v7, v13, v10
	s_waitcnt lgkmcnt(0)
	v_fma_f32 v9, -v8, v14, v9
	v_add_f32_e32 v9, v10, v9
	v_add_u32_e32 v10, -6, v139
	v_cvt_f32_i32_e32 v10, v10
	v_sub_f32_e64 v10, 1.0, |v10|
	v_max_f32_e32 v18, 0, v10
	ds_read_b128 v[10:13], v0 offset:1632
	ds_read_b128 v[14:17], v0 offset:1648
	s_waitcnt lgkmcnt(1)
	v_fma_f32 v10, -v4, v10, v18
	v_fma_f32 v11, -v5, v11, 0
	v_fma_f32 v10, -v6, v12, v10
	v_fma_f32 v11, -v7, v13, v11
	s_waitcnt lgkmcnt(0)
	v_fma_f32 v10, -v8, v14, v10
	v_fma_f32 v11, -v9, v15, v11
	v_add_f32_e32 v10, v10, v11
	v_add_u32_e32 v11, -7, v139
	v_cvt_f32_i32_e32 v11, v11
	ds_read_b128 v[12:15], v0 offset:1904
	ds_read_b128 v[16:19], v0 offset:1920
	v_sub_f32_e64 v11, 1.0, |v11|
	v_max_f32_e32 v11, 0, v11
	s_waitcnt lgkmcnt(1)
	v_fma_f32 v11, -v4, v12, v11
	v_fma_f32 v11, -v6, v14, v11
	v_fma_f32 v12, -v5, v13, 0
	s_waitcnt lgkmcnt(0)
	v_fma_f32 v11, -v8, v16, v11
	v_fma_f32 v12, -v7, v15, v12
	v_fma_f32 v11, -v10, v18, v11
	v_fma_f32 v12, -v9, v17, v12
	v_add_f32_e32 v11, v11, v12
	ds_read_b128 v[12:15], v0 offset:2176
	ds_read_b128 v[16:19], v0 offset:2192
	s_waitcnt lgkmcnt(1)
	v_fma_f32 v13, -v5, v13, 0
	v_fma_f32 v13, -v7, v15, v13
	v_add_u32_e32 v15, -8, v139
	v_cvt_f32_i32_e32 v15, v15
	s_waitcnt lgkmcnt(0)
	v_fma_f32 v13, -v9, v17, v13
	v_fma_f32 v13, -v11, v19, v13
	v_sub_f32_e64 v15, 1.0, |v15|
	v_max_f32_e32 v15, 0, v15
	v_fma_f32 v12, -v4, v12, v15
	v_fma_f32 v12, -v6, v14, v12
	v_fma_f32 v12, -v8, v16, v12
	v_fma_f32 v12, -v10, v18, v12
	v_add_f32_e32 v12, v12, v13
	ds_read_b128 v[14:17], v0 offset:2448
	ds_read_b128 v[22:25], v0 offset:2464
	ds_read_b128 v[26:29], v0 offset:2480
	s_waitcnt lgkmcnt(2)
	v_fma_f32 v13, -v5, v15, 0
	v_add_u32_e32 v15, -9, v139
	v_cvt_f32_i32_e32 v15, v15
	v_fma_f32 v13, -v7, v17, v13
	s_waitcnt lgkmcnt(1)
	v_fma_f32 v13, -v9, v23, v13
	v_fma_f32 v13, -v11, v25, v13
	v_sub_f32_e64 v15, 1.0, |v15|
	v_max_f32_e32 v15, 0, v15
	v_fma_f32 v14, -v4, v14, v15
	v_fma_f32 v14, -v6, v16, v14
	v_fma_f32 v14, -v8, v22, v14
	v_fma_f32 v14, -v10, v24, v14
	s_waitcnt lgkmcnt(0)
	v_fma_f32 v14, -v12, v26, v14
	v_add_f32_e32 v13, v14, v13
	ds_read_b128 v[14:17], v0 offset:2720
	ds_read_b128 v[22:25], v0 offset:2736
	ds_read_b128 v[26:29], v0 offset:2752
	s_waitcnt lgkmcnt(2)
	v_fma_f32 v15, -v5, v15, 0
	v_fma_f32 v15, -v7, v17, v15
	v_add_u32_e32 v17, -10, v139
	v_cvt_f32_i32_e32 v17, v17
	s_waitcnt lgkmcnt(1)
	v_fma_f32 v15, -v9, v23, v15
	v_fma_f32 v15, -v11, v25, v15
	s_waitcnt lgkmcnt(0)
	v_fma_f32 v15, -v13, v27, v15
	v_sub_f32_e64 v17, 1.0, |v17|
	v_max_f32_e32 v17, 0, v17
	v_fma_f32 v14, -v4, v14, v17
	v_fma_f32 v14, -v6, v16, v14
	v_fma_f32 v14, -v8, v22, v14
	v_fma_f32 v14, -v10, v24, v14
	v_fma_f32 v14, -v12, v26, v14
	v_add_f32_e32 v14, v14, v15
	v_add_u32_e32 v15, -11, v139
	v_cvt_f32_i32_e32 v15, v15
	ds_read_b128 v[16:19], v0 offset:2992
	ds_read_b128 v[22:25], v0 offset:3008
	ds_read_b128 v[26:29], v0 offset:3024
	v_sub_f32_e64 v15, 1.0, |v15|
	v_max_f32_e32 v15, 0, v15
	s_waitcnt lgkmcnt(2)
	v_fma_f32 v15, -v4, v16, v15
	v_fma_f32 v15, -v6, v18, v15
	v_fma_f32 v16, -v5, v17, 0
	s_waitcnt lgkmcnt(1)
	v_fma_f32 v15, -v8, v22, v15
	v_fma_f32 v16, -v7, v19, v16
	v_fma_f32 v15, -v10, v24, v15
	v_fma_f32 v16, -v9, v23, v16
	s_waitcnt lgkmcnt(0)
	v_fma_f32 v15, -v12, v26, v15
	v_fma_f32 v16, -v11, v25, v16
	v_fma_f32 v15, -v14, v28, v15
	v_fma_f32 v16, -v13, v27, v16
	v_add_f32_e32 v15, v15, v16
	ds_read_b128 v[16:19], v0 offset:3264
	ds_read_b128 v[22:25], v0 offset:3280
	ds_read_b128 v[26:29], v0 offset:3296
	s_waitcnt lgkmcnt(2)
	v_fma_f32 v17, -v5, v17, 0
	v_fma_f32 v17, -v7, v19, v17
	v_add_u32_e32 v19, -12, v139
	v_cvt_f32_i32_e32 v19, v19
	s_waitcnt lgkmcnt(1)
	v_fma_f32 v17, -v9, v23, v17
	v_fma_f32 v17, -v11, v25, v17
	s_waitcnt lgkmcnt(0)
; #define LAS __attribute__((address_space(3)))
; DI void gdn_intra(LAS unsigned char* lds, PP p, int l, int first, int stride) {
;     ...
; #pragma unroll
;         for (int i = 0; i < 32; ++i) {
;             float a0 = fmaxf(0.f, 1.f - fabsf(cf - (float)i)), a1 = 0.f;
; #pragma unroll
;             for (int j4 = 0; j4 < (i + 3) / 4; ++j4) { const f32x4 mv = *(const LAS f32x4*)(Mm + (base + i) * 68 + base + j4 * 4);
; #pragma unroll
;                 for (int jj = 0; jj < 4; ++jj) { const int j = j4 * 4 + jj; if (j < i) { if (jj & 1) a1 -= mv[jj] * t[j]; else a0 -= mv[jj] * t[j]; } } }
;             t[i] = a0 + a1;
;             asm volatile("" : "+v"(t[i]) :: "memory");
;         }
	v_fma_f32 v17, -v13, v27, v17
	v_sub_f32_e64 v19, 1.0, |v19|
	v_max_f32_e32 v19, 0, v19
	v_fma_f32 v16, -v4, v16, v19
	v_fma_f32 v16, -v6, v18, v16
	v_fma_f32 v16, -v8, v22, v16
	v_fma_f32 v16, -v10, v24, v16
	v_add_u32_e32 v18, -13, v139
	v_fma_f32 v16, -v12, v26, v16
	v_cvt_f32_i32_e32 v18, v18
	v_fma_f32 v17, -v15, v29, v17
	v_fma_f32 v16, -v14, v28, v16
	v_add_f32_e32 v16, v16, v17
	ds_read_b128 v[22:25], v0 offset:3536
	ds_read_b128 v[26:29], v0 offset:3552
	ds_read_b128 v[30:33], v0 offset:3568
	ds_read_b128 v[146:149], v0 offset:3584
	v_sub_f32_e64 v18, 1.0, |v18|
	v_max_f32_e32 v18, 0, v18
	s_waitcnt lgkmcnt(3)
	v_fma_f32 v18, -v4, v22, v18
	v_fma_f32 v17, -v5, v23, 0
	v_fma_f32 v18, -v6, v24, v18
	v_fma_f32 v17, -v7, v25, v17
	s_waitcnt lgkmcnt(2)
	v_fma_f32 v18, -v8, v26, v18
	v_fma_f32 v17, -v9, v27, v17
	v_fma_f32 v18, -v10, v28, v18
	v_fma_f32 v17, -v11, v29, v17
	s_waitcnt lgkmcnt(1)
	v_fma_f32 v18, -v12, v30, v18
	v_add_u32_e32 v19, -14, v139
	v_fma_f32 v17, -v13, v31, v17
	v_fma_f32 v18, -v14, v32, v18
	v_cvt_f32_i32_e32 v19, v19
	v_fma_f32 v17, -v15, v33, v17
	s_waitcnt lgkmcnt(0)
	v_fma_f32 v18, -v16, v146, v18
	v_add_f32_e32 v17, v18, v17
	ds_read_b128 v[22:25], v0 offset:3808
	ds_read_b128 v[26:29], v0 offset:3824
	ds_read_b128 v[30:33], v0 offset:3840
	ds_read_b128 v[146:149], v0 offset:3856
	v_sub_f32_e64 v19, 1.0, |v19|
	v_max_f32_e32 v19, 0, v19
	s_waitcnt lgkmcnt(3)
	v_fma_f32 v18, -v5, v23, 0
	v_fma_f32 v19, -v4, v22, v19
	v_fma_f32 v18, -v7, v25, v18
	v_fma_f32 v19, -v6, v24, v19
	s_waitcnt lgkmcnt(2)
	v_fma_f32 v18, -v9, v27, v18
	v_fma_f32 v19, -v8, v26, v19
	v_fma_f32 v18, -v11, v29, v18
	v_fma_f32 v19, -v10, v28, v19
	s_waitcnt lgkmcnt(1)
	v_fma_f32 v18, -v13, v31, v18
	v_fma_f32 v19, -v12, v30, v19
	v_fma_f32 v18, -v15, v33, v18
	v_fma_f32 v19, -v14, v32, v19
	s_waitcnt lgkmcnt(0)
	v_fma_f32 v18, -v17, v147, v18
	v_fma_f32 v19, -v16, v146, v19
	v_add_f32_e32 v18, v19, v18
	v_add_u32_e32 v19, -15, v139
	v_cvt_f32_i32_e32 v19, v19
	ds_read_b128 v[22:25], v0 offset:4080
	ds_read_b128 v[26:29], v0 offset:4096
	ds_read_b128 v[30:33], v0 offset:4112
	ds_read_b128 v[146:149], v0 offset:4128
	v_sub_f32_e64 v19, 1.0, |v19|
	v_max_f32_e32 v19, 0, v19
	s_waitcnt lgkmcnt(3)
	v_fma_f32 v19, -v4, v22, v19
	v_fma_f32 v19, -v6, v24, v19
	v_fma_f32 v20, -v5, v23, 0
	s_waitcnt lgkmcnt(2)
	v_fma_f32 v19, -v8, v26, v19
	v_fma_f32 v20, -v7, v25, v20
	v_fma_f32 v19, -v10, v28, v19
	v_fma_f32 v20, -v9, v27, v20
	s_waitcnt lgkmcnt(1)
	v_fma_f32 v19, -v12, v30, v19
	v_fma_f32 v20, -v11, v29, v20
	v_fma_f32 v19, -v14, v32, v19
	v_fma_f32 v20, -v13, v31, v20
	s_waitcnt lgkmcnt(0)
	v_fma_f32 v19, -v16, v146, v19
	v_fma_f32 v20, -v15, v33, v20
	v_fma_f32 v19, -v18, v148, v19
	v_fma_f32 v20, -v17, v147, v20
	v_add_f32_e32 v19, v19, v20
	ds_read_b128 v[22:25], v0 offset:4352
	ds_read_b128 v[26:29], v0 offset:4368
	ds_read_b128 v[30:33], v0 offset:4384
	ds_read_b128 v[146:149], v0 offset:4400
	s_waitcnt lgkmcnt(3)
	v_fma_f32 v20, -v5, v23, 0
	v_add_u32_e32 v23, -16, v139
	v_cvt_f32_i32_e32 v23, v23
	v_fma_f32 v20, -v7, v25, v20
	s_waitcnt lgkmcnt(2)
	v_fma_f32 v20, -v9, v27, v20
	v_fma_f32 v20, -v11, v29, v20
	v_sub_f32_e64 v23, 1.0, |v23|
	v_max_f32_e32 v23, 0, v23
	v_fma_f32 v22, -v4, v22, v23
	v_fma_f32 v22, -v6, v24, v22
	v_fma_f32 v22, -v8, v26, v22
	v_fma_f32 v22, -v10, v28, v22
	s_waitcnt lgkmcnt(1)
	v_fma_f32 v20, -v13, v31, v20
	v_fma_f32 v22, -v12, v30, v22
	v_fma_f32 v20, -v15, v33, v20
	v_fma_f32 v22, -v14, v32, v22
	s_waitcnt lgkmcnt(0)
	v_fma_f32 v20, -v17, v147, v20
	v_fma_f32 v22, -v16, v146, v22
	v_fma_f32 v20, -v19, v149, v20
	v_fma_f32 v22, -v18, v148, v22
	v_add_f32_e32 v20, v22, v20
	ds_read_b128 v[22:25], v0 offset:4624
	ds_read_b128 v[26:29], v0 offset:4640
	ds_read_b128 v[30:33], v0 offset:4656
	ds_read_b128 v[146:149], v0 offset:4672
	s_waitcnt lgkmcnt(3)
	v_fma_f32 v23, -v5, v23, 0
	v_fma_f32 v23, -v7, v25, v23
	s_waitcnt lgkmcnt(2)
	v_fma_f32 v23, -v9, v27, v23
	v_fma_f32 v23, -v11, v29, v23
	s_waitcnt lgkmcnt(1)
	v_fma_f32 v23, -v13, v31, v23
	v_fma_f32 v23, -v15, v33, v23
	s_waitcnt lgkmcnt(0)
	v_fma_f32 v23, -v17, v147, v23
	v_fma_f32 v27, -v19, v149, v23
	v_subrev_u32_e32 v23, 17, v139
	v_cvt_f32_i32_e32 v23, v23
	v_sub_f32_e64 v23, 1.0, |v23|
	v_max_f32_e32 v23, 0, v23
	v_fma_f32 v22, -v4, v22, v23
	v_fma_f32 v22, -v6, v24, v22
	v_fma_f32 v22, -v8, v26, v22
	v_fma_f32 v22, -v10, v28, v22
	v_fma_f32 v22, -v12, v30, v22
	v_fma_f32 v22, -v14, v32, v22
	v_fma_f32 v22, -v16, v146, v22
	v_fma_f32 v26, -v18, v148, v22
	ds_read_b128 v[22:25], v0 offset:4688
	s_waitcnt lgkmcnt(0)
	v_fma_f32 v22, -v20, v22, v26
	v_add_f32_e32 v22, v22, v27
	ds_read_b128 v[24:27], v0 offset:4896
	ds_read_b128 v[28:31], v0 offset:4912
	ds_read_b128 v[32:35], v0 offset:4928
	ds_read_b128 v[146:149], v0 offset:4944
	ds_read_b128 v[150:153], v0 offset:4960
	s_waitcnt lgkmcnt(4)
	v_fma_f32 v23, -v5, v25, 0
	v_subrev_u32_e32 v25, 18, v139
	v_cvt_f32_i32_e32 v25, v25
	v_fma_f32 v23, -v7, v27, v23
	s_waitcnt lgkmcnt(3)
	v_fma_f32 v23, -v9, v29, v23
	v_fma_f32 v23, -v11, v31, v23
	v_sub_f32_e64 v25, 1.0, |v25|
	v_max_f32_e32 v25, 0, v25
	v_fma_f32 v24, -v4, v24, v25
	v_fma_f32 v24, -v6, v26, v24
	v_fma_f32 v24, -v8, v28, v24
	v_fma_f32 v24, -v10, v30, v24
	s_waitcnt lgkmcnt(2)
	v_fma_f32 v23, -v13, v33, v23
	v_fma_f32 v24, -v12, v32, v24
	v_fma_f32 v23, -v15, v35, v23
	v_fma_f32 v24, -v14, v34, v24
	s_waitcnt lgkmcnt(1)
	v_fma_f32 v23, -v17, v147, v23
	v_fma_f32 v24, -v16, v146, v24
	v_fma_f32 v23, -v19, v149, v23
	v_fma_f32 v24, -v18, v148, v24
	s_waitcnt lgkmcnt(0)
; #define LAS __attribute__((address_space(3)))
; DI void gdn_intra(LAS unsigned char* lds, PP p, int l, int first, int stride) {
;     ...
; #pragma unroll
;         for (int i = 0; i < 32; ++i) {
;             float a0 = fmaxf(0.f, 1.f - fabsf(cf - (float)i)), a1 = 0.f;
; #pragma unroll
;             for (int j4 = 0; j4 < (i + 3) / 4; ++j4) { const f32x4 mv = *(const LAS f32x4*)(Mm + (base + i) * 68 + base + j4 * 4);
; #pragma unroll
;                 for (int jj = 0; jj < 4; ++jj) { const int j = j4 * 4 + jj; if (j < i) { if (jj & 1) a1 -= mv[jj] * t[j]; else a0 -= mv[jj] * t[j]; } } }
;             t[i] = a0 + a1;
;             asm volatile("" : "+v"(t[i]) :: "memory");
;         }
	v_fma_f32 v23, -v22, v151, v23
	v_fma_f32 v24, -v20, v150, v24
	v_add_f32_e32 v23, v24, v23
	v_subrev_u32_e32 v24, 19, v139
	v_cvt_f32_i32_e32 v24, v24
	v_sub_f32_e64 v24, 1.0, |v24|
	v_max_f32_e32 v145, 0, v24
	ds_read_b128 v[24:27], v0 offset:5168
	ds_read_b128 v[28:31], v0 offset:5184
	ds_read_b128 v[32:35], v0 offset:5200
	ds_read_b128 v[146:149], v0 offset:5216
	ds_read_b128 v[150:153], v0 offset:5232
	s_waitcnt lgkmcnt(4)
	v_fma_f32 v24, -v4, v24, v145
	v_fma_f32 v24, -v6, v26, v24
	v_fma_f32 v25, -v5, v25, 0
	s_waitcnt lgkmcnt(3)
	v_fma_f32 v24, -v8, v28, v24
	v_fma_f32 v25, -v7, v27, v25
	v_fma_f32 v24, -v10, v30, v24
	v_fma_f32 v25, -v9, v29, v25
	s_waitcnt lgkmcnt(2)
	v_fma_f32 v24, -v12, v32, v24
	v_fma_f32 v25, -v11, v31, v25
	v_fma_f32 v24, -v14, v34, v24
	v_fma_f32 v25, -v13, v33, v25
	s_waitcnt lgkmcnt(1)
	v_fma_f32 v24, -v16, v146, v24
	v_fma_f32 v25, -v15, v35, v25
	v_fma_f32 v24, -v18, v148, v24
	v_fma_f32 v25, -v17, v147, v25
	s_waitcnt lgkmcnt(0)
	v_fma_f32 v24, -v20, v150, v24
	v_fma_f32 v25, -v19, v149, v25
	v_fma_f32 v24, -v23, v152, v24
	v_fma_f32 v25, -v22, v151, v25
	v_add_f32_e32 v24, v24, v25
	ds_read_b128 v[26:29], v0 offset:5440
	ds_read_b128 v[30:33], v0 offset:5456
	ds_read_b128 v[146:149], v0 offset:5472
	ds_read_b128 v[150:153], v0 offset:5488
	ds_read_b128 v[154:157], v0 offset:5504
	s_waitcnt lgkmcnt(4)
	v_fma_f32 v25, -v5, v27, 0
	v_subrev_u32_e32 v27, 20, v139
	v_cvt_f32_i32_e32 v27, v27
	v_fma_f32 v25, -v7, v29, v25
	s_waitcnt lgkmcnt(3)
	v_fma_f32 v25, -v9, v31, v25
	v_fma_f32 v25, -v11, v33, v25
	v_sub_f32_e64 v27, 1.0, |v27|
	v_max_f32_e32 v27, 0, v27
	v_fma_f32 v26, -v4, v26, v27
	v_fma_f32 v26, -v6, v28, v26
	v_fma_f32 v26, -v8, v30, v26
	v_fma_f32 v26, -v10, v32, v26
	s_waitcnt lgkmcnt(2)
	v_fma_f32 v25, -v13, v147, v25
	v_fma_f32 v26, -v12, v146, v26
	v_fma_f32 v25, -v15, v149, v25
	v_fma_f32 v26, -v14, v148, v26
	s_waitcnt lgkmcnt(1)
	v_fma_f32 v25, -v17, v151, v25
	v_fma_f32 v26, -v16, v150, v26
	v_fma_f32 v25, -v19, v153, v25
	v_fma_f32 v26, -v18, v152, v26
	s_waitcnt lgkmcnt(0)
	v_fma_f32 v25, -v22, v155, v25
	v_fma_f32 v26, -v20, v154, v26
	v_fma_f32 v25, -v24, v157, v25
	v_fma_f32 v26, -v23, v156, v26
	v_add_f32_e32 v25, v26, v25
	ds_read_b128 v[26:29], v0 offset:5712
	ds_read_b128 v[30:33], v0 offset:5728
	ds_read_b128 v[146:149], v0 offset:5744
	ds_read_b128 v[150:153], v0 offset:5760
	ds_read_b128 v[154:157], v0 offset:5776
	s_waitcnt lgkmcnt(4)
	v_fma_f32 v27, -v5, v27, 0
	v_fma_f32 v27, -v7, v29, v27
	s_waitcnt lgkmcnt(3)
	v_fma_f32 v27, -v9, v31, v27
	v_fma_f32 v27, -v11, v33, v27
	s_waitcnt lgkmcnt(2)
	v_fma_f32 v27, -v13, v147, v27
	v_fma_f32 v27, -v15, v149, v27
	s_waitcnt lgkmcnt(1)
	v_fma_f32 v27, -v17, v151, v27
	v_fma_f32 v27, -v19, v153, v27
	s_waitcnt lgkmcnt(0)
	v_fma_f32 v27, -v22, v155, v27
	v_fma_f32 v31, -v24, v157, v27
	v_subrev_u32_e32 v27, 21, v139
	v_cvt_f32_i32_e32 v27, v27
	v_sub_f32_e64 v27, 1.0, |v27|
	v_max_f32_e32 v27, 0, v27
	v_fma_f32 v26, -v4, v26, v27
	v_fma_f32 v26, -v6, v28, v26
	v_fma_f32 v26, -v8, v30, v26
	v_fma_f32 v26, -v10, v32, v26
	v_fma_f32 v26, -v12, v146, v26
	v_fma_f32 v26, -v14, v148, v26
	v_fma_f32 v26, -v16, v150, v26
	v_fma_f32 v26, -v18, v152, v26
	v_fma_f32 v26, -v20, v154, v26
	v_fma_f32 v30, -v23, v156, v26
	ds_read_b128 v[26:29], v0 offset:5792
	s_waitcnt lgkmcnt(0)
	v_fma_f32 v26, -v25, v26, v30
	v_add_f32_e32 v26, v26, v31
	ds_read_b128 v[28:31], v0 offset:5984
	ds_read_b128 v[32:35], v0 offset:6000
	ds_read_b128 v[146:149], v0 offset:6016
	ds_read_b128 v[150:153], v0 offset:6032
	ds_read_b128 v[154:157], v0 offset:6048
	ds_read_b128 v[158:161], v0 offset:6064
	s_waitcnt lgkmcnt(5)
	v_fma_f32 v27, -v5, v29, 0
	v_subrev_u32_e32 v29, 22, v139
	v_cvt_f32_i32_e32 v29, v29
	v_fma_f32 v27, -v7, v31, v27
	s_waitcnt lgkmcnt(4)
	v_fma_f32 v27, -v9, v33, v27
	v_fma_f32 v27, -v11, v35, v27
	v_sub_f32_e64 v29, 1.0, |v29|
	v_max_f32_e32 v29, 0, v29
	v_fma_f32 v28, -v4, v28, v29
	v_fma_f32 v28, -v6, v30, v28
	v_fma_f32 v28, -v8, v32, v28
	v_fma_f32 v28, -v10, v34, v28
	s_waitcnt lgkmcnt(3)
	v_fma_f32 v27, -v13, v147, v27
	v_fma_f32 v28, -v12, v146, v28
	v_fma_f32 v27, -v15, v149, v27
	v_fma_f32 v28, -v14, v148, v28
	s_waitcnt lgkmcnt(2)
	v_fma_f32 v27, -v17, v151, v27
	v_fma_f32 v28, -v16, v150, v28
	v_fma_f32 v27, -v19, v153, v27
	v_fma_f32 v28, -v18, v152, v28
	s_waitcnt lgkmcnt(1)
	v_fma_f32 v27, -v22, v155, v27
	v_fma_f32 v28, -v20, v154, v28
	v_fma_f32 v27, -v24, v157, v27
	v_fma_f32 v28, -v23, v156, v28
	s_waitcnt lgkmcnt(0)
	v_fma_f32 v27, -v26, v159, v27
	v_fma_f32 v28, -v25, v158, v28
	v_add_f32_e32 v27, v28, v27
	v_subrev_u32_e32 v28, 23, v139
	v_cvt_f32_i32_e32 v28, v28
	v_sub_f32_e64 v28, 1.0, |v28|
	v_max_f32_e32 v145, 0, v28
	ds_read_b128 v[28:31], v0 offset:6256
	ds_read_b128 v[32:35], v0 offset:6272
	ds_read_b128 v[146:149], v0 offset:6288
	ds_read_b128 v[150:153], v0 offset:6304
	ds_read_b128 v[154:157], v0 offset:6320
	ds_read_b128 v[158:161], v0 offset:6336
	s_waitcnt lgkmcnt(5)
	v_fma_f32 v28, -v4, v28, v145
	v_fma_f32 v28, -v6, v30, v28
	v_fma_f32 v29, -v5, v29, 0
	s_waitcnt lgkmcnt(4)
	v_fma_f32 v28, -v8, v32, v28
	v_fma_f32 v29, -v7, v31, v29
	v_fma_f32 v28, -v10, v34, v28
	v_fma_f32 v29, -v9, v33, v29
	s_waitcnt lgkmcnt(3)
	v_fma_f32 v28, -v12, v146, v28
	v_fma_f32 v29, -v11, v35, v29
	v_fma_f32 v28, -v14, v148, v28
	v_fma_f32 v29, -v13, v147, v29
	s_waitcnt lgkmcnt(2)
	v_fma_f32 v28, -v16, v150, v28
	v_fma_f32 v29, -v15, v149, v29
	v_fma_f32 v28, -v18, v152, v28
	v_fma_f32 v29, -v17, v151, v29
	s_waitcnt lgkmcnt(1)
	v_fma_f32 v28, -v20, v154, v28
	v_fma_f32 v29, -v19, v153, v29
	v_fma_f32 v28, -v23, v156, v28
	v_fma_f32 v29, -v22, v155, v29
	s_waitcnt lgkmcnt(0)
; #define LAS __attribute__((address_space(3)))
; DI void gdn_intra(LAS unsigned char* lds, PP p, int l, int first, int stride) {
;     ...
; #pragma unroll
;         for (int i = 0; i < 32; ++i) {
;             float a0 = fmaxf(0.f, 1.f - fabsf(cf - (float)i)), a1 = 0.f;
; #pragma unroll
;             for (int j4 = 0; j4 < (i + 3) / 4; ++j4) { const f32x4 mv = *(const LAS f32x4*)(Mm + (base + i) * 68 + base + j4 * 4);
; #pragma unroll
;                 for (int jj = 0; jj < 4; ++jj) { const int j = j4 * 4 + jj; if (j < i) { if (jj & 1) a1 -= mv[jj] * t[j]; else a0 -= mv[jj] * t[j]; } } }
;             t[i] = a0 + a1;
;             asm volatile("" : "+v"(t[i]) :: "memory");
;         }
	v_fma_f32 v28, -v25, v158, v28
	v_fma_f32 v29, -v24, v157, v29
	v_fma_f32 v28, -v27, v160, v28
	v_fma_f32 v29, -v26, v159, v29
	v_add_f32_e32 v28, v28, v29
	ds_read_b128 v[30:33], v0 offset:6528
	ds_read_b128 v[146:149], v0 offset:6544
	ds_read_b128 v[150:153], v0 offset:6560
	ds_read_b128 v[154:157], v0 offset:6576
	ds_read_b128 v[158:161], v0 offset:6592
	ds_read_b128 v[162:165], v0 offset:6608
	s_waitcnt lgkmcnt(5)
	v_fma_f32 v29, -v5, v31, 0
	v_subrev_u32_e32 v31, 24, v139
	v_cvt_f32_i32_e32 v31, v31
	v_fma_f32 v29, -v7, v33, v29
	s_waitcnt lgkmcnt(4)
	v_fma_f32 v29, -v9, v147, v29
	v_fma_f32 v29, -v11, v149, v29
	v_sub_f32_e64 v31, 1.0, |v31|
	v_max_f32_e32 v31, 0, v31
	v_fma_f32 v30, -v4, v30, v31
	v_fma_f32 v30, -v6, v32, v30
	v_fma_f32 v30, -v8, v146, v30
	v_fma_f32 v30, -v10, v148, v30
	s_waitcnt lgkmcnt(3)
	v_fma_f32 v29, -v13, v151, v29
	v_fma_f32 v30, -v12, v150, v30
	v_fma_f32 v29, -v15, v153, v29
	v_fma_f32 v30, -v14, v152, v30
	s_waitcnt lgkmcnt(2)
	v_fma_f32 v29, -v17, v155, v29
	v_fma_f32 v30, -v16, v154, v30
	v_fma_f32 v29, -v19, v157, v29
	v_fma_f32 v30, -v18, v156, v30
	s_waitcnt lgkmcnt(1)
	v_fma_f32 v29, -v22, v159, v29
	v_fma_f32 v30, -v20, v158, v30
	v_fma_f32 v29, -v24, v161, v29
	v_fma_f32 v30, -v23, v160, v30
	s_waitcnt lgkmcnt(0)
	v_fma_f32 v29, -v26, v163, v29
	v_fma_f32 v30, -v25, v162, v30
	v_fma_f32 v29, -v28, v165, v29
	v_fma_f32 v30, -v27, v164, v30
	v_add_f32_e32 v29, v30, v29
	ds_read_b128 v[30:33], v0 offset:6800
	ds_read_b128 v[146:149], v0 offset:6816
	ds_read_b128 v[150:153], v0 offset:6832
	ds_read_b128 v[154:157], v0 offset:6848
	ds_read_b128 v[158:161], v0 offset:6864
	ds_read_b128 v[162:165], v0 offset:6880
	s_waitcnt lgkmcnt(5)
	v_fma_f32 v31, -v5, v31, 0
	v_fma_f32 v31, -v7, v33, v31
	s_waitcnt lgkmcnt(4)
	v_fma_f32 v31, -v9, v147, v31
	v_fma_f32 v31, -v11, v149, v31
	s_waitcnt lgkmcnt(3)
	v_fma_f32 v31, -v13, v151, v31
	v_fma_f32 v31, -v15, v153, v31
	s_waitcnt lgkmcnt(2)
	v_fma_f32 v31, -v17, v155, v31
	v_fma_f32 v31, -v19, v157, v31
	s_waitcnt lgkmcnt(1)
	v_fma_f32 v31, -v22, v159, v31
	v_fma_f32 v31, -v24, v161, v31
	s_waitcnt lgkmcnt(0)
	v_fma_f32 v31, -v26, v163, v31
	v_fma_f32 v34, -v28, v165, v31
	v_subrev_u32_e32 v31, 25, v139
	v_cvt_f32_i32_e32 v31, v31
	v_sub_f32_e64 v31, 1.0, |v31|
	v_max_f32_e32 v31, 0, v31
	v_fma_f32 v30, -v4, v30, v31
	v_fma_f32 v30, -v6, v32, v30
	v_fma_f32 v30, -v8, v146, v30
	v_fma_f32 v30, -v10, v148, v30
	v_fma_f32 v30, -v12, v150, v30
	v_fma_f32 v30, -v14, v152, v30
	v_fma_f32 v30, -v16, v154, v30
	v_fma_f32 v30, -v18, v156, v30
	v_fma_f32 v30, -v20, v158, v30
	v_fma_f32 v30, -v23, v160, v30
	v_fma_f32 v30, -v25, v162, v30
	v_fma_f32 v35, -v27, v164, v30
	ds_read_b128 v[30:33], v0 offset:6896
	s_waitcnt lgkmcnt(0)
	v_fma_f32 v30, -v29, v30, v35
	v_add_f32_e32 v30, v30, v34
	ds_read_b128 v[32:35], v0 offset:7072
	ds_read_b128 v[146:149], v0 offset:7088
	ds_read_b128 v[150:153], v0 offset:7104
	ds_read_b128 v[154:157], v0 offset:7120
	ds_read_b128 v[158:161], v0 offset:7136
	ds_read_b128 v[162:165], v0 offset:7152
	s_waitcnt lgkmcnt(5)
	v_fma_f32 v31, -v5, v33, 0
	v_subrev_u32_e32 v33, 26, v139
	v_cvt_f32_i32_e32 v33, v33
	v_fma_f32 v31, -v7, v35, v31
	s_waitcnt lgkmcnt(4)
	v_fma_f32 v31, -v9, v147, v31
	v_fma_f32 v31, -v11, v149, v31
	v_sub_f32_e64 v33, 1.0, |v33|
	v_max_f32_e32 v33, 0, v33
	v_fma_f32 v32, -v4, v32, v33
	v_fma_f32 v32, -v6, v34, v32
	v_fma_f32 v32, -v8, v146, v32
	v_fma_f32 v32, -v10, v148, v32
	s_waitcnt lgkmcnt(3)
	v_fma_f32 v31, -v13, v151, v31
	v_fma_f32 v32, -v12, v150, v32
	v_fma_f32 v31, -v15, v153, v31
	v_fma_f32 v32, -v14, v152, v32
	s_waitcnt lgkmcnt(2)
	v_fma_f32 v31, -v17, v155, v31
	v_fma_f32 v32, -v16, v154, v32
	v_fma_f32 v31, -v19, v157, v31
	ds_read_b128 v[166:169], v0 offset:7168
	v_fma_f32 v32, -v18, v156, v32
	s_waitcnt lgkmcnt(2)
	v_fma_f32 v31, -v22, v159, v31
	v_fma_f32 v32, -v20, v158, v32
	v_fma_f32 v31, -v24, v161, v31
	v_fma_f32 v32, -v23, v160, v32
	s_waitcnt lgkmcnt(1)
	v_fma_f32 v31, -v26, v163, v31
	v_fma_f32 v32, -v25, v162, v32
	v_fma_f32 v31, -v28, v165, v31
	v_fma_f32 v32, -v27, v164, v32
	s_waitcnt lgkmcnt(0)
	v_fma_f32 v31, -v30, v167, v31
	v_fma_f32 v32, -v29, v166, v32
	v_add_f32_e32 v31, v32, v31
	v_subrev_u32_e32 v32, 27, v139
	v_cvt_f32_i32_e32 v32, v32
	v_sub_f32_e64 v32, 1.0, |v32|
	v_max_f32_e32 v145, 0, v32
	ds_read_b128 v[32:35], v0 offset:7344
	ds_read_b128 v[146:149], v0 offset:7360
	ds_read_b128 v[150:153], v0 offset:7376
	ds_read_b128 v[154:157], v0 offset:7392
	ds_read_b128 v[158:161], v0 offset:7408
	ds_read_b128 v[162:165], v0 offset:7424
	s_waitcnt lgkmcnt(5)
	v_fma_f32 v32, -v4, v32, v145
	v_fma_f32 v32, -v6, v34, v32
	v_fma_f32 v33, -v5, v33, 0
	s_waitcnt lgkmcnt(4)
	v_fma_f32 v32, -v8, v146, v32
	v_fma_f32 v33, -v7, v35, v33
	v_fma_f32 v32, -v10, v148, v32
	v_fma_f32 v33, -v9, v147, v33
	s_waitcnt lgkmcnt(3)
	v_fma_f32 v32, -v12, v150, v32
	v_fma_f32 v33, -v11, v149, v33
	v_fma_f32 v32, -v14, v152, v32
	v_fma_f32 v33, -v13, v151, v33
	s_waitcnt lgkmcnt(2)
	v_fma_f32 v32, -v16, v154, v32
	v_fma_f32 v33, -v15, v153, v33
	v_fma_f32 v32, -v18, v156, v32
	ds_read_b128 v[166:169], v0 offset:7440
	v_fma_f32 v33, -v17, v155, v33
	s_waitcnt lgkmcnt(2)
	v_fma_f32 v32, -v20, v158, v32
	v_fma_f32 v33, -v19, v157, v33
	v_fma_f32 v32, -v23, v160, v32
	v_fma_f32 v33, -v22, v159, v33
	s_waitcnt lgkmcnt(1)
	v_fma_f32 v32, -v25, v162, v32
	v_fma_f32 v33, -v24, v161, v33
	v_fma_f32 v32, -v27, v164, v32
	v_fma_f32 v33, -v26, v163, v33
	v_subrev_u32_e32 v34, 28, v139
	s_waitcnt lgkmcnt(0)
; #define LAS __attribute__((address_space(3)))
; DI void gdn_intra(LAS unsigned char* lds, PP p, int l, int first, int stride) {
;     ...
; #pragma unroll
;         for (int i = 0; i < 32; ++i) {
;             float a0 = fmaxf(0.f, 1.f - fabsf(cf - (float)i)), a1 = 0.f;
; #pragma unroll
;             for (int j4 = 0; j4 < (i + 3) / 4; ++j4) { const f32x4 mv = *(const LAS f32x4*)(Mm + (base + i) * 68 + base + j4 * 4);
; #pragma unroll
;                 for (int jj = 0; jj < 4; ++jj) { const int j = j4 * 4 + jj; if (j < i) { if (jj & 1) a1 -= mv[jj] * t[j]; else a0 -= mv[jj] * t[j]; } } }
;             t[i] = a0 + a1;
;             asm volatile("" : "+v"(t[i]) :: "memory");
;         }
	v_fma_f32 v32, -v29, v166, v32
	v_fma_f32 v33, -v28, v165, v33
	v_cvt_f32_i32_e32 v34, v34
	v_fma_f32 v32, -v31, v168, v32
	v_fma_f32 v33, -v30, v167, v33
	v_add_f32_e32 v32, v32, v33
	ds_read_b128 v[146:149], v0 offset:7616
	ds_read_b128 v[150:153], v0 offset:7632
	ds_read_b128 v[154:157], v0 offset:7648
	ds_read_b128 v[158:161], v0 offset:7664
	v_sub_f32_e64 v34, 1.0, |v34|
	v_max_f32_e32 v34, 0, v34
	s_waitcnt lgkmcnt(3)
	v_fma_f32 v33, -v5, v147, 0
	v_fma_f32 v34, -v4, v146, v34
	v_fma_f32 v33, -v7, v149, v33
	v_fma_f32 v34, -v6, v148, v34
	s_waitcnt lgkmcnt(2)
	v_fma_f32 v33, -v9, v151, v33
	v_fma_f32 v34, -v8, v150, v34
	v_fma_f32 v33, -v11, v153, v33
	ds_read_b128 v[162:165], v0 offset:7680
	ds_read_b128 v[166:169], v0 offset:7696
	v_fma_f32 v34, -v10, v152, v34
	s_waitcnt lgkmcnt(3)
	v_fma_f32 v33, -v13, v155, v33
	v_fma_f32 v34, -v12, v154, v34
	v_fma_f32 v33, -v15, v157, v33
	v_fma_f32 v34, -v14, v156, v34
	s_waitcnt lgkmcnt(2)
	v_fma_f32 v33, -v17, v159, v33
	v_fma_f32 v34, -v16, v158, v34
	v_fma_f32 v33, -v19, v161, v33
	ds_read_b128 v[170:173], v0 offset:7712
	v_fma_f32 v34, -v18, v160, v34
	s_waitcnt lgkmcnt(2)
	v_fma_f32 v33, -v22, v163, v33
	v_fma_f32 v34, -v20, v162, v34
	v_fma_f32 v33, -v24, v165, v33
	v_fma_f32 v34, -v23, v164, v34
	s_waitcnt lgkmcnt(1)
	v_fma_f32 v33, -v26, v167, v33
	v_fma_f32 v34, -v25, v166, v34
	v_fma_f32 v33, -v28, v169, v33
	v_fma_f32 v34, -v27, v168, v34
	v_subrev_u32_e32 v35, 29, v139
	s_waitcnt lgkmcnt(0)
	v_fma_f32 v33, -v30, v171, v33
	v_fma_f32 v34, -v29, v170, v34
	v_cvt_f32_i32_e32 v35, v35
	v_fma_f32 v33, -v32, v173, v33
	v_fma_f32 v34, -v31, v172, v34
	v_add_f32_e32 v33, v34, v33
	ds_read_b128 v[146:149], v0 offset:7888
	ds_read_b128 v[150:153], v0 offset:7904
	ds_read_b128 v[154:157], v0 offset:7920
	ds_read_b128 v[158:161], v0 offset:7936
	v_sub_f32_e64 v35, 1.0, |v35|
	v_max_f32_e32 v35, 0, v35
	s_waitcnt lgkmcnt(3)
	v_fma_f32 v35, -v4, v146, v35
	v_fma_f32 v34, -v5, v147, 0
	v_fma_f32 v35, -v6, v148, v35
	v_fma_f32 v34, -v7, v149, v34
	s_waitcnt lgkmcnt(2)
	v_fma_f32 v35, -v8, v150, v35
	v_fma_f32 v34, -v9, v151, v34
	ds_read_b128 v[162:165], v0 offset:7952
	ds_read_b128 v[166:169], v0 offset:7968
	v_fma_f32 v35, -v10, v152, v35
	v_fma_f32 v34, -v11, v153, v34
	s_waitcnt lgkmcnt(3)
	v_fma_f32 v35, -v12, v154, v35
	v_fma_f32 v34, -v13, v155, v34
	v_fma_f32 v35, -v14, v156, v35
	v_fma_f32 v34, -v15, v157, v34
	s_waitcnt lgkmcnt(2)
	v_fma_f32 v35, -v16, v158, v35
	v_fma_f32 v34, -v17, v159, v34
	ds_read_b128 v[170:173], v0 offset:7984
	ds_read_b128 v[146:149], v0 offset:8000
	v_fma_f32 v35, -v18, v160, v35
	v_fma_f32 v34, -v19, v161, v34
	s_waitcnt lgkmcnt(3)
	v_fma_f32 v35, -v20, v162, v35
	v_fma_f32 v34, -v22, v163, v34
	v_fma_f32 v35, -v23, v164, v35
	v_fma_f32 v34, -v24, v165, v34
	s_waitcnt lgkmcnt(2)
	v_fma_f32 v35, -v25, v166, v35
	v_fma_f32 v34, -v26, v167, v34
	v_fma_f32 v35, -v27, v168, v35
	v_fma_f32 v34, -v28, v169, v34
	s_waitcnt lgkmcnt(1)
	v_fma_f32 v35, -v29, v170, v35
	v_subrev_u32_e32 v145, 30, v139
	v_fma_f32 v34, -v30, v171, v34
	v_fma_f32 v35, -v31, v172, v35
	v_cvt_f32_i32_e32 v145, v145
	v_fma_f32 v34, -v32, v173, v34
	s_waitcnt lgkmcnt(0)
	v_fma_f32 v35, -v33, v146, v35
	v_add_f32_e32 v34, v35, v34
	ds_read_b128 v[146:149], v0 offset:8160
	ds_read_b128 v[150:153], v0 offset:8176
	ds_read_b128 v[154:157], v0 offset:8192
	ds_read_b128 v[158:161], v0 offset:8208
	v_sub_f32_e64 v145, 1.0, |v145|
	v_max_f32_e32 v145, 0, v145
	s_waitcnt lgkmcnt(3)
	v_fma_f32 v35, -v5, v147, 0
	v_fma_f32 v145, -v4, v146, v145
	v_fma_f32 v35, -v7, v149, v35
	v_fma_f32 v145, -v6, v148, v145
	s_waitcnt lgkmcnt(2)
	v_fma_f32 v35, -v9, v151, v35
	v_fma_f32 v145, -v8, v150, v145
	v_fma_f32 v35, -v11, v153, v35
	ds_read_b128 v[162:165], v0 offset:8224
	ds_read_b128 v[166:169], v0 offset:8240
	v_fma_f32 v145, -v10, v152, v145
	s_waitcnt lgkmcnt(3)
	v_fma_f32 v35, -v13, v155, v35
	v_fma_f32 v145, -v12, v154, v145
	v_fma_f32 v35, -v15, v157, v35
	v_fma_f32 v145, -v14, v156, v145
	s_waitcnt lgkmcnt(2)
	v_fma_f32 v35, -v17, v159, v35
	v_fma_f32 v145, -v16, v158, v145
	v_fma_f32 v35, -v19, v161, v35
	ds_read_b128 v[170:173], v0 offset:8256
	ds_read_b128 v[174:177], v0 offset:8272
	v_fma_f32 v145, -v18, v160, v145
	s_waitcnt lgkmcnt(3)
	v_fma_f32 v35, -v22, v163, v35
	v_fma_f32 v145, -v20, v162, v145
	v_fma_f32 v35, -v24, v165, v35
	v_fma_f32 v145, -v23, v164, v145
	s_waitcnt lgkmcnt(2)
	v_fma_f32 v35, -v26, v167, v35
	v_fma_f32 v145, -v25, v166, v145
	v_fma_f32 v35, -v28, v169, v35
	v_fma_f32 v145, -v27, v168, v145
	s_waitcnt lgkmcnt(1)
	v_fma_f32 v35, -v30, v171, v35
	v_fma_f32 v145, -v29, v170, v145
	v_fma_f32 v35, -v32, v173, v35
	v_fma_f32 v145, -v31, v172, v145
	s_waitcnt lgkmcnt(0)
	v_fma_f32 v35, -v34, v175, v35
	v_fma_f32 v145, -v33, v174, v145
	v_add_f32_e32 v35, v145, v35
	v_subrev_u32_e32 v145, 31, v139
	v_cvt_f32_i32_e32 v145, v145
	ds_read_b128 v[146:149], v0 offset:8432
	ds_read_b128 v[150:153], v0 offset:8448
	ds_read_b128 v[154:157], v0 offset:8464
	ds_read_b128 v[158:161], v0 offset:8480
	ds_read_b128 v[162:165], v0 offset:8496
	ds_read_b128 v[166:169], v0 offset:8512
	v_sub_f32_e64 v145, 1.0, |v145|
	v_max_f32_e32 v145, 0, v145
	s_waitcnt lgkmcnt(5)
	v_fma_f32 v145, -v4, v146, v145
	v_fma_f32 v145, -v6, v148, v145
	s_waitcnt lgkmcnt(4)
	v_fma_f32 v145, -v8, v150, v145
	v_fma_f32 v145, -v10, v152, v145
	s_waitcnt lgkmcnt(3)
	v_fma_f32 v145, -v12, v154, v145
	v_fma_f32 v145, -v14, v156, v145
	s_waitcnt lgkmcnt(2)
	v_fma_f32 v145, -v16, v158, v145
	v_fma_f32 v145, -v18, v160, v145
	ds_read_b128 v[170:173], v0 offset:8528
	ds_read_b128 v[174:177], v0 offset:8544
	s_waitcnt lgkmcnt(3)
; DI bf16_t f2bf(float f) { return (bf16_t)(pk2(f, 0.f) & 0xffffu); }
; DI void gdn_intra(LAS unsigned char* lds, PP p, int l, int first, int stride) {
;     ...
; #pragma unroll
;         for (int i = 0; i < 32; ++i) {
;             if (h == 0) Timg[(base + i) * 72 + base + r] = f2bf(t[i]);
;             else if (w == 1) Timg[i * 72 + 32 + r] = 0;
;             if (w == 1 && h == 0) T22f[i * 33 + r] = t[i];
;         }
	v_fma_f32 v145, -v20, v162, v145
	v_fma_f32 v145, -v23, v164, v145
	s_waitcnt lgkmcnt(2)
	v_fma_f32 v145, -v25, v166, v145
	v_fma_f32 v145, -v27, v168, v145
	s_waitcnt lgkmcnt(1)
	v_fma_f32 v145, -v29, v170, v145
	v_fma_f32 v145, -v31, v172, v145
	s_waitcnt lgkmcnt(0)
	v_fma_f32 v0, -v33, v174, v145
	v_fma_f32 v145, -v5, v147, 0
	v_fma_f32 v145, -v7, v149, v145
	v_fma_f32 v145, -v9, v151, v145
	v_fma_f32 v145, -v11, v153, v145
	v_fma_f32 v145, -v13, v155, v145
	v_fma_f32 v145, -v15, v157, v145
	v_fma_f32 v145, -v17, v159, v145
	v_fma_f32 v145, -v19, v161, v145
	v_fma_f32 v145, -v22, v163, v145
	v_fma_f32 v145, -v24, v165, v145
	v_fma_f32 v145, -v26, v167, v145
	v_fma_f32 v145, -v28, v169, v145
	v_fma_f32 v145, -v30, v171, v145
	v_fma_f32 v145, -v32, v173, v145
	v_fma_f32 v0, -v35, v176, v0
	v_fma_f32 v145, -v34, v175, v145
	v_add_f32_e32 v146, v0, v145
	v_lshlrev_b32_e32 v145, 1, v139
	v_lshlrev_b32_e32 v0, 6, v142
	v_add3_u32 v0, v144, v0, v145
	v_mul_u32_u24_e32 v148, 0x1200, v142
	v_add_u32_e32 v148, v148, v0
	s_mov_b64 s[2:3], exec
	s_andn2_b64 exec, exec, s[22:23]
	v_cvt_pk_bf16_f32 v150, v4, s0
	ds_write_b16 v148, v150
	v_cvt_pk_bf16_f32 v149, v5, s0
	ds_write_b16 v148, v149 offset:144
	v_cvt_pk_bf16_f32 v150, v6, s0
	ds_write_b16 v148, v150 offset:288
	v_cvt_pk_bf16_f32 v149, v7, s0
	ds_write_b16 v148, v149 offset:432
	v_cvt_pk_bf16_f32 v150, v8, s0
	ds_write_b16 v148, v150 offset:576
	v_cvt_pk_bf16_f32 v149, v9, s0
	ds_write_b16 v148, v149 offset:720
	v_cvt_pk_bf16_f32 v150, v10, s0
	ds_write_b16 v148, v150 offset:864
	v_cvt_pk_bf16_f32 v149, v11, s0
	ds_write_b16 v148, v149 offset:1008
	v_cvt_pk_bf16_f32 v150, v12, s0
	ds_write_b16 v148, v150 offset:1152
	v_cvt_pk_bf16_f32 v149, v13, s0
	ds_write_b16 v148, v149 offset:1296
	v_cvt_pk_bf16_f32 v150, v14, s0
	ds_write_b16 v148, v150 offset:1440
	v_cvt_pk_bf16_f32 v149, v15, s0
	ds_write_b16 v148, v149 offset:1584
	v_cvt_pk_bf16_f32 v150, v16, s0
	ds_write_b16 v148, v150 offset:1728
	v_cvt_pk_bf16_f32 v149, v17, s0
	ds_write_b16 v148, v149 offset:1872
	v_cvt_pk_bf16_f32 v150, v18, s0
	ds_write_b16 v148, v150 offset:2016
	v_cvt_pk_bf16_f32 v149, v19, s0
	ds_write_b16 v148, v149 offset:2160
	v_cvt_pk_bf16_f32 v150, v20, s0
	ds_write_b16 v148, v150 offset:2304
	v_cvt_pk_bf16_f32 v149, v22, s0
	ds_write_b16 v148, v149 offset:2448
	v_cvt_pk_bf16_f32 v150, v23, s0
	ds_write_b16 v148, v150 offset:2592
	v_cvt_pk_bf16_f32 v149, v24, s0
	ds_write_b16 v148, v149 offset:2736
	v_cvt_pk_bf16_f32 v150, v25, s0
	ds_write_b16 v148, v150 offset:2880
	v_cvt_pk_bf16_f32 v149, v26, s0
	ds_write_b16 v148, v149 offset:3024
	v_cvt_pk_bf16_f32 v150, v27, s0
	ds_write_b16 v148, v150 offset:3168
	v_cvt_pk_bf16_f32 v149, v28, s0
	ds_write_b16 v148, v149 offset:3312
	v_cvt_pk_bf16_f32 v150, v29, s0
	ds_write_b16 v148, v150 offset:3456
	v_cvt_pk_bf16_f32 v149, v30, s0
	ds_write_b16 v148, v149 offset:3600
	v_cvt_pk_bf16_f32 v150, v31, s0
	ds_write_b16 v148, v150 offset:3744
	v_cvt_pk_bf16_f32 v149, v32, s0
	ds_write_b16 v148, v149 offset:3888
	v_cvt_pk_bf16_f32 v150, v33, s0
	ds_write_b16 v148, v150 offset:4032
	v_cvt_pk_bf16_f32 v149, v34, s0
	ds_write_b16 v148, v149 offset:4176
	v_cvt_pk_bf16_f32 v150, v35, s0
	ds_write_b16 v148, v150 offset:4320
	v_cvt_pk_bf16_f32 v149, v146, s0
	ds_write_b16 v148, v149 offset:4464
	s_and_b64 s[20:21], vcc, s[24:25]
	s_and_b64 exec, s[2:3], s[20:21]
	s_cbranch_execz .Ltimg_skipf
	v_lshl_add_u32 v147, v139, 2, v132
	ds_write_b32 v147, v4
	ds_write_b32 v147, v5 offset:132
	ds_write_b32 v147, v6 offset:264
	ds_write_b32 v147, v7 offset:396
	ds_write_b32 v147, v8 offset:528
	ds_write_b32 v147, v9 offset:660
	ds_write_b32 v147, v10 offset:792
	ds_write_b32 v147, v11 offset:924
	ds_write_b32 v147, v12 offset:1056
	ds_write_b32 v147, v13 offset:1188
	ds_write_b32 v147, v14 offset:1320
	ds_write_b32 v147, v15 offset:1452
	ds_write_b32 v147, v16 offset:1584
	ds_write_b32 v147, v17 offset:1716
	ds_write_b32 v147, v18 offset:1848
	ds_write_b32 v147, v19 offset:1980
	ds_write_b32 v147, v20 offset:2112
	ds_write_b32 v147, v22 offset:2244
	ds_write_b32 v147, v23 offset:2376
	ds_write_b32 v147, v24 offset:2508
	ds_write_b32 v147, v25 offset:2640
	ds_write_b32 v147, v26 offset:2772
	ds_write_b32 v147, v27 offset:2904
	ds_write_b32 v147, v28 offset:3036
	ds_write_b32 v147, v29 offset:3168
	ds_write_b32 v147, v30 offset:3300
	ds_write_b32 v147, v31 offset:3432
	ds_write_b32 v147, v32 offset:3564
	ds_write_b32 v147, v33 offset:3696
	ds_write_b32 v147, v34 offset:3828
	ds_write_b32 v147, v35 offset:3960
	ds_write_b32 v147, v146 offset:4092
.Ltimg_skipf:
	s_and_b64 s[20:21], s[22:23], vcc
	s_and_b64 exec, s[2:3], s[20:21]
	s_cbranch_execz .Ltimg_skipz
	s_mov_b32 s31, 0x16040
	v_add3_u32 v0, v132, v145, s31
	ds_write_b16 v0, v3
	ds_write_b16 v0, v3 offset:144
	ds_write_b16 v0, v3 offset:288
	ds_write_b16 v0, v3 offset:432
	ds_write_b16 v0, v3 offset:576
	ds_write_b16 v0, v3 offset:720
	ds_write_b16 v0, v3 offset:864
	ds_write_b16 v0, v3 offset:1008
	ds_write_b16 v0, v3 offset:1152
	ds_write_b16 v0, v3 offset:1296
	ds_write_b16 v0, v3 offset:1440
	ds_write_b16 v0, v3 offset:1584
	ds_write_b16 v0, v3 offset:1728
	ds_write_b16 v0, v3 offset:1872
	ds_write_b16 v0, v3 offset:2016
	ds_write_b16 v0, v3 offset:2160
	ds_write_b16 v0, v3 offset:2304
	ds_write_b16 v0, v3 offset:2448
	ds_write_b16 v0, v3 offset:2592
	ds_write_b16 v0, v3 offset:2736
	ds_write_b16 v0, v3 offset:2880
	ds_write_b16 v0, v3 offset:3024
	ds_write_b16 v0, v3 offset:3168
	ds_write_b16 v0, v3 offset:3312
	ds_write_b16 v0, v3 offset:3456
	ds_write_b16 v0, v3 offset:3600
	ds_write_b16 v0, v3 offset:3744
	ds_write_b16 v0, v3 offset:3888
	ds_write_b16 v0, v3 offset:4032
	ds_write_b16 v0, v3 offset:4176
	ds_write_b16 v0, v3 offset:4320
	ds_write_b16 v0, v3 offset:4464
; DI bf16_t f2bf(float f) { return (bf16_t)(pk2(f, 0.f) & 0xffffu); }
; DI void lds_barrier() { asm volatile("s_waitcnt lgkmcnt(0)" ::: "memory"); __builtin_amdgcn_s_barrier(); asm volatile("" ::: "memory"); }
; DI int crow(int reg, int h) { return (reg & 3) + 8 * (reg >> 2) + 4 * h; }
; DI void gdn_intra(LAS unsigned char* lds, PP p, int l, int first, int stride) {
;     ...
;         lds_barrier();
;         if (w == 0) {
;             unsigned hmask = h ? 0xffffffffu : 0u; asm volatile("" : "+v"(hmask));
;             f32x16 X; for (int i = 0; i < 16; ++i) X[i] = 0.f;
; #pragma unroll
;             for (int m = 0; m < 16; ++m) { const float a = Mm[(32 + r) * 68 + 2 * m + h]; const float b = __uint_as_float((__float_as_uint(t[2 * m]) & ~hmask) | (__float_as_uint(t[2 * m + 1]) & hmask));
;                 X = __builtin_amdgcn_mfma_f32_32x32x2f32(a, b, X, 0, 0, 0); }
;             f32x16 Y; for (int i = 0; i < 16; ++i) Y[i] = 0.f;
; #pragma unroll
;             for (int m = 0; m < 16; ++m) { const float a = T22f[r * 33 + crow(m, h)];
;                 Y = __builtin_amdgcn_mfma_f32_32x32x2f32(a, X[m], Y, 0, 0, 0); }
; #pragma unroll
;             for (int i = 0; i < 16; ++i) Timg[(32 + crow(i, h)) * 72 + r] = f2bf(-Y[i]);
.Ltimg_skipz:
	s_mov_b64 exec, s[2:3]
	s_waitcnt lgkmcnt(0)
	s_barrier
	v_cmp_gt_u32_e32 vcc, 64, v138
	s_and_saveexec_b64 s[2:3], vcc
	s_cbranch_execz .LBB0_419
	v_or_b32_e32 v147, 32, v138
	s_movk_i32 s20, 0x110
	v_cmp_lt_u32_e32 vcc, 31, v143
	v_mul_lo_u32 v147, v147, s20
	v_lshlrev_b32_e32 v148, 2, v141
	v_cndmask_b32_e64 v0, 0, -1, vcc
	v_add3_u32 v147, v21, v147, v148
	ds_read2_b32 v[148:149], v147 offset1:2
	ds_read2_b32 v[150:151], v147 offset0:4 offset1:6
	ds_read2_b32 v[152:153], v147 offset0:8 offset1:10
	ds_read2_b32 v[154:155], v147 offset0:12 offset1:14
	v_bfi_b32 v4, v0, v5, v4
	v_bfi_b32 v158, v0, v7, v6
	v_bfi_b32 v159, v0, v9, v8
	v_bfi_b32 v160, v0, v11, v10
	v_bfi_b32 v161, v0, v13, v12
	v_bfi_b32 v162, v0, v15, v14
	v_bfi_b32 v163, v0, v17, v16
	v_bfi_b32 v164, v0, v19, v18
	s_waitcnt lgkmcnt(3)
	v_mfma_f32_32x32x2_f32 v[4:19], v148, v4, 0
	ds_read2_b32 v[156:157], v147 offset0:16 offset1:18
	v_bfi_b32 v165, v0, v22, v20
	v_bfi_b32 v166, v0, v24, v23
	ds_read2_b32 v[20:21], v147 offset0:20 offset1:22
	v_bfi_b32 v26, v0, v26, v25
	v_bfi_b32 v27, v0, v28, v27
	ds_read2_b32 v[22:23], v147 offset0:24 offset1:26
	v_bfi_b32 v28, v0, v30, v29
	v_bfi_b32 v29, v0, v32, v31
	ds_read2_b32 v[24:25], v147 offset0:28 offset1:30
	v_bfi_b32 v30, v0, v34, v33
	v_bfi_b32 v0, v0, v146, v35
	v_mfma_f32_32x32x2_f32 v[4:19], v149, v158, v[4:19]
	s_waitcnt lgkmcnt(6)
	v_mfma_f32_32x32x2_f32 v[4:19], v150, v159, v[4:19]
	v_mfma_f32_32x32x2_f32 v[4:19], v151, v160, v[4:19]
	s_waitcnt lgkmcnt(5)
	v_mfma_f32_32x32x2_f32 v[4:19], v152, v161, v[4:19]
	v_mfma_f32_32x32x2_f32 v[4:19], v153, v162, v[4:19]
	s_waitcnt lgkmcnt(4)
	v_mfma_f32_32x32x2_f32 v[4:19], v154, v163, v[4:19]
	v_mfma_f32_32x32x2_f32 v[4:19], v155, v164, v[4:19]
	s_waitcnt lgkmcnt(3)
	v_mfma_f32_32x32x2_f32 v[4:19], v156, v165, v[4:19]
	v_mfma_f32_32x32x2_f32 v[4:19], v157, v166, v[4:19]
	s_waitcnt lgkmcnt(2)
	v_mfma_f32_32x32x2_f32 v[4:19], v20, v26, v[4:19]
	v_mfma_f32_32x32x2_f32 v[4:19], v21, v27, v[4:19]
	s_waitcnt lgkmcnt(1)
	v_mfma_f32_32x32x2_f32 v[4:19], v22, v28, v[4:19]
	v_mfma_f32_32x32x2_f32 v[4:19], v23, v29, v[4:19]
	s_waitcnt lgkmcnt(0)
	v_mfma_f32_32x32x2_f32 v[4:19], v24, v30, v[4:19]
	v_mfma_f32_32x32x2_f32 v[4:19], v25, v0, v[4:19]
	v_mul_u32_u24_e32 v0, 0x84, v139
	v_add3_u32 v0, v132, v0, v2
	ds_read2_b32 v[146:147], v0 offset1:1
	v_mul_u32_u24_e32 v2, 0x240, v141
	v_add3_u32 v2, v144, v2, v145
	s_waitcnt lgkmcnt(0)
	s_nop 11
	v_mfma_f32_32x32x2_f32 v[20:35], v146, v4, 0
	v_mfma_f32_32x32x2_f32 v[20:35], v147, v5, v[20:35]
	ds_read2_b32 v[4:5], v0 offset0:2 offset1:3
	s_waitcnt lgkmcnt(0)
	v_mfma_f32_32x32x2_f32 v[20:35], v4, v6, v[20:35]
	v_mfma_f32_32x32x2_f32 v[20:35], v5, v7, v[20:35]
	ds_read2_b32 v[4:5], v0 offset0:8 offset1:9
	s_waitcnt lgkmcnt(0)
	v_mfma_f32_32x32x2_f32 v[20:35], v4, v8, v[20:35]
	v_mfma_f32_32x32x2_f32 v[20:35], v5, v9, v[20:35]
	ds_read2_b32 v[4:5], v0 offset0:10 offset1:11
	s_waitcnt lgkmcnt(0)
	v_mfma_f32_32x32x2_f32 v[20:35], v4, v10, v[20:35]
	v_mfma_f32_32x32x2_f32 v[20:35], v5, v11, v[20:35]
	ds_read2_b32 v[4:5], v0 offset0:16 offset1:17
	s_waitcnt lgkmcnt(0)
	v_mfma_f32_32x32x2_f32 v[20:35], v4, v12, v[20:35]
	v_mfma_f32_32x32x2_f32 v[20:35], v5, v13, v[20:35]
	ds_read2_b32 v[4:5], v0 offset0:18 offset1:19
	s_waitcnt lgkmcnt(0)
	v_mfma_f32_32x32x2_f32 v[20:35], v4, v14, v[20:35]
	v_mfma_f32_32x32x2_f32 v[20:35], v5, v15, v[20:35]
	ds_read2_b32 v[4:5], v0 offset0:24 offset1:25
	s_waitcnt lgkmcnt(0)
	v_mfma_f32_32x32x2_f32 v[20:35], v4, v16, v[20:35]
	v_mfma_f32_32x32x2_f32 v[20:35], v5, v17, v[20:35]
	ds_read2_b32 v[4:5], v0 offset0:26 offset1:27
	s_waitcnt lgkmcnt(0)
	v_mfma_f32_32x32x2_f32 v[20:35], v4, v18, v[20:35]
	v_mfma_f32_32x32x2_f32 v[20:35], v5, v19, v[20:35]
	s_nop 15
	s_nop 1
	v_cvt_pk_bf16_f32 v0, -v20, s0
	ds_write_b16 v2, v0 offset:4608
	v_cvt_pk_bf16_f32 v0, -v21, s0
	ds_write_b16 v2, v0 offset:4752
	v_cvt_pk_bf16_f32 v0, -v22, s0
	ds_write_b16 v2, v0 offset:4896
	v_cvt_pk_bf16_f32 v0, -v23, s0
	ds_write_b16 v2, v0 offset:5040
	v_cvt_pk_bf16_f32 v0, -v24, s0
	ds_write_b16 v2, v0 offset:5760
	v_cvt_pk_bf16_f32 v0, -v25, s0
	ds_write_b16 v2, v0 offset:5904
	v_cvt_pk_bf16_f32 v0, -v26, s0
	ds_write_b16 v2, v0 offset:6048
	v_cvt_pk_bf16_f32 v0, -v27, s0
	ds_write_b16 v2, v0 offset:6192
	v_cvt_pk_bf16_f32 v0, -v28, s0
	ds_write_b16 v2, v0 offset:6912
	v_cvt_pk_bf16_f32 v0, -v29, s0
	ds_write_b16 v2, v0 offset:7056
	v_cvt_pk_bf16_f32 v0, -v30, s0
	ds_write_b16 v2, v0 offset:7200
	v_cvt_pk_bf16_f32 v0, -v31, s0
	ds_write_b16 v2, v0 offset:7344
	v_cvt_pk_bf16_f32 v0, -v32, s0
	ds_write_b16 v2, v0 offset:8064
	v_cvt_pk_bf16_f32 v0, -v33, s0
	ds_write_b16 v2, v0 offset:8208
	v_cvt_pk_bf16_f32 v0, -v34, s0
	ds_write_b16 v2, v0 offset:8352
	v_cvt_pk_bf16_f32 v0, -v35, s0
	ds_write_b16 v2, v0 offset:8496
	s_branch .LBB0_419

; DI unsigned pk2(float lo, float hi) { f32x2 v = {lo, hi}; bf2_t b = __builtin_convertvector(v, bf2_t); return __builtin_bit_cast(unsigned, b); }
; #define EPI_LOOP_PERM(...) _Pragma("unroll") for (int ai = 0; ai < 2; ++ai) _Pragma("unroll") for (int m = 0; m < 4; ++m) { const int row = u.pm * 256 + ai * 128 + wr * 64 + m * 16 + fr; \
;     _Pragma("unroll") for (int bj = 0; bj < 2; ++bj) { const int c8 = bj * 128 + wc * 32 + 8 * fq; f32x4 v0 = acc[ai][bj][m][0], v1 = acc[ai][bj][m][1]; __VA_ARGS__ } }
; DI u32x4 pack44(f32x4 a, f32x4 b) { u32x4 w; w.x = pk2(a[0], a[1]); w.y = pk2(a[2], a[3]); w.z = pk2(b[0], b[1]); w.w = pk2(b[2], b[3]); return w; }
; DI float sigmoidf_(float x) { return 1.f / (1.f + __expf(-x)); }
;     DI void operator()(const Acc& acc, const Unit& u, int wr, int wc, int fr, int fq) const {
;     ...
;         } else if (pn < 36) {
;             bf16_t* dst = pn < 28 ? sgs + (pn - 20) * 256 : sgg + (pn - 28) * 256;
;             EPI_LOOP_PERM({ for (int j = 0; j < 4; ++j) { v0[j] = sigmoidf_(v0[j]); v1[j] = sigmoidf_(v1[j]); } *(u32x4*)(dst + (size_t)row * 2048 + c8) = pack44(v0, v1); })
.LBB0_1216:
	s_andn2_b64 vcc, exec, s[2:3]
	s_cbranch_vccnz .LBB0_1218
	v_mul_f32_e32 v2, 0xbfb8aa3b, v128
	v_exp_f32_e32 v160, v2
	v_mul_f32_e32 v2, 0xbfb8aa3b, v124
	s_cmp_lt_u32 s24, 28
	v_readlane_b32 s3, v254, 56
	v_readlane_b32 s20, v254, 49
	v_exp_f32_e32 v162, v2
	v_mul_f32_e32 v2, 0xbfb8aa3b, v129
	s_movk_i32 s2, 0xd800
	s_cselect_b32 s3, s3, s20
	v_readlane_b32 s20, v254, 55
	v_readlane_b32 s21, v254, 51
	v_exp_f32_e32 v161, v2
	s_cselect_b32 s2, s2, 0xffffc800
	s_cselect_b32 s20, s20, s21
	s_lshl_b32 s21, s24, 9
	s_add_u32 s20, s20, s21
	s_addc_u32 s3, s3, 0
	s_add_u32 s44, s20, s2
	v_pk_add_f32 v[160:161], v[160:161], 1.0 op_sel_hi:[1,0]
	s_addc_u32 s45, s3, -1
	v_rcp_f32_e32 v151, v161
	s_nop 0
	v_lshl_add_u32 v152, s26, 8, v139
	v_ashrrev_i32_e32 v153, 31, v152
	v_lshlrev_b64 v[154:155], 12, v[152:153]
	v_mul_f32_e32 v163, 1.0, v151
	v_fma_f32 v164, -v161, v163, 1.0
	v_fmac_f32_e32 v163, v164, v151
	v_div_scale_f32 v151, s[2:3], v160, v160, 1.0
	v_rcp_f32_e32 v153, v151
	v_div_fixup_f32 v2, v163, v161, 1.0
	v_lshl_add_u64 v[154:155], s[44:45], 0, v[154:155]
	v_fma_f32 v161, -v151, v153, 1.0
	v_fmac_f32_e32 v153, v161, v153
	v_div_scale_f32 v161, vcc, 1.0, v160, 1.0
	v_mul_f32_e32 v163, v161, v153
	v_fma_f32 v164, -v151, v163, v161
	v_fmac_f32_e32 v163, v164, v153
	v_fma_f32 v151, -v151, v163, v161
	v_div_fmas_f32 v151, v151, v153, v163
	v_mul_f32_e32 v153, 0xbfb8aa3b, v125
	v_exp_f32_e32 v163, v153
	v_div_fixup_f32 v151, v151, v160, 1.0
	v_pk_add_f32 v[160:161], v[162:163], 1.0 op_sel_hi:[1,0]
	s_nop 0
	v_rcp_f32_e32 v162, v161
	s_nop 0
	v_mul_f32_e32 v164, 1.0, v162
	v_fma_f32 v165, -v161, v164, 1.0
	v_fmac_f32_e32 v164, v165, v162
	v_div_fixup_f32 v153, v164, v161, 1.0
	v_rcp_f32_e32 v162, v160
	s_nop 0
	v_mul_f32_e32 v164, 1.0, v162
	v_fma_f32 v165, -v160, v164, 1.0
	v_fmac_f32_e32 v164, v165, v162
	v_div_fixup_f32 v164, v164, v160, 1.0
	v_mul_f32_e32 v161, 0xbfb8aa3b, v126
	v_mul_f32_e32 v160, 0xbfb8aa3b, v130
	v_exp_f32_e32 v162, v161
	v_mul_f32_e32 v161, 0xbfb8aa3b, v131
	v_exp_f32_e32 v160, v160
	v_exp_f32_e32 v161, v161
	s_nop 0
	v_pk_add_f32 v[160:161], v[160:161], 1.0 op_sel_hi:[1,0]
	s_nop 0
	v_rcp_f32_e32 v165, v161
	s_nop 0
	v_mul_f32_e32 v167, 1.0, v165
	v_fma_f32 v168, -v161, v167, 1.0
	v_fmac_f32_e32 v167, v168, v165
	v_div_fixup_f32 v165, v167, v161, 1.0
	v_rcp_f32_e32 v163, v160
	s_nop 0
	v_mul_f32_e32 v167, 1.0, v163
	v_fma_f32 v168, -v160, v167, 1.0
	v_fmac_f32_e32 v167, v168, v163
	v_div_fixup_f32 v166, v167, v160, 1.0
	v_mul_f32_e32 v160, 0xbfb8aa3b, v127
	v_exp_f32_e32 v163, v160
	s_nop 0
	v_pk_add_f32 v[160:161], v[162:163], 1.0 op_sel_hi:[1,0]
	s_nop 0
	v_rcp_f32_e32 v163, v161
	s_nop 0
	v_mul_f32_e32 v168, 1.0, v163
	v_fma_f32 v169, -v161, v168, 1.0
	v_fmac_f32_e32 v168, v169, v163
	v_div_fixup_f32 v163, v168, v161, 1.0
	v_rcp_f32_e32 v162, v160
	s_nop 0
	v_mul_f32_e32 v168, 1.0, v162
	v_fma_f32 v169, -v160, v168, 1.0
	v_fmac_f32_e32 v168, v169, v162
	v_div_fixup_f32 v167, v168, v160, 1.0
	v_cvt_pk_bf16_f32 v160, v151, v2
	v_lshlrev_b32_e32 v2, 1, v138
	v_cvt_pk_bf16_f32 v161, v166, v165
	v_cvt_pk_bf16_f32 v162, v164, v153
	v_cvt_pk_bf16_f32 v163, v167, v163
	v_lshl_add_u64 v[154:155], v[154:155], 0, v[2:3]
	v_mul_f32_e32 v151, 0xbfb8aa3b, v112
	global_store_dwordx4 v[154:155], v[160:163], off
	s_nop 1
	v_exp_f32_e32 v160, v151
	v_mul_f32_e32 v151, 0xbfb8aa3b, v108
	v_exp_f32_e32 v162, v151
	v_mul_f32_e32 v151, 0xbfb8aa3b, v113
	v_exp_f32_e32 v161, v151
	s_nop 0
	v_pk_add_f32 v[160:161], v[160:161], 1.0 op_sel_hi:[1,0]
	s_nop 0
	v_rcp_f32_e32 v153, v161
	s_nop 0
	v_mul_f32_e32 v164, 1.0, v153
	v_fma_f32 v165, -v161, v164, 1.0
	v_fmac_f32_e32 v164, v165, v153
	v_div_fixup_f32 v151, v164, v161, 1.0
	v_rcp_f32_e32 v161, v160
	s_nop 0
	v_mul_f32_e32 v164, 1.0, v161
	v_fma_f32 v165, -v160, v164, 1.0
	v_fmac_f32_e32 v164, v165, v161
	v_div_fixup_f32 v153, v164, v160, 1.0
	v_mul_f32_e32 v160, 0xbfb8aa3b, v109
	v_exp_f32_e32 v163, v160
	s_nop 0
	v_pk_add_f32 v[160:161], v[162:163], 1.0 op_sel_hi:[1,0]
	s_nop 0
	v_rcp_f32_e32 v163, v161
	s_nop 0
	v_mul_f32_e32 v165, 1.0, v163
	v_fma_f32 v166, -v161, v165, 1.0
	v_fmac_f32_e32 v165, v166, v163
	v_div_fixup_f32 v164, v165, v161, 1.0
	v_rcp_f32_e32 v162, v160
	s_nop 0
	v_mul_f32_e32 v165, 1.0, v162
	v_fma_f32 v166, -v160, v165, 1.0
	v_fmac_f32_e32 v165, v166, v162
	v_div_fixup_f32 v165, v165, v160, 1.0
	v_mul_f32_e32 v161, 0xbfb8aa3b, v110
	v_mul_f32_e32 v160, 0xbfb8aa3b, v114
	v_exp_f32_e32 v162, v161
	v_mul_f32_e32 v161, 0xbfb8aa3b, v115
	v_exp_f32_e32 v160, v160
	v_exp_f32_e32 v161, v161
	s_nop 0
	v_pk_add_f32 v[160:161], v[160:161], 1.0 op_sel_hi:[1,0]
	s_nop 0
	v_rcp_f32_e32 v166, v161
	s_nop 0
	v_mul_f32_e32 v168, 1.0, v166
	v_fma_f32 v169, -v161, v168, 1.0
	v_fmac_f32_e32 v168, v169, v166
	v_div_fixup_f32 v166, v168, v161, 1.0
	v_rcp_f32_e32 v163, v160
	s_nop 0
	v_mul_f32_e32 v168, 1.0, v163
	v_fma_f32 v169, -v160, v168, 1.0
	v_fmac_f32_e32 v168, v169, v163
	v_div_fixup_f32 v167, v168, v160, 1.0
	v_mul_f32_e32 v160, 0xbfb8aa3b, v111
	v_exp_f32_e32 v163, v160
	s_nop 0
	v_pk_add_f32 v[160:161], v[162:163], 1.0 op_sel_hi:[1,0]
	s_nop 0
	v_rcp_f32_e32 v163, v161
	s_nop 0
	v_mul_f32_e32 v169, 1.0, v163
	v_fma_f32 v170, -v161, v169, 1.0
	v_fmac_f32_e32 v169, v170, v163
	v_div_fixup_f32 v163, v169, v161, 1.0
	v_rcp_f32_e32 v162, v160
	s_nop 0
	v_mul_f32_e32 v169, 1.0, v162
	v_fma_f32 v170, -v160, v169, 1.0
	v_fmac_f32_e32 v169, v170, v162
	v_div_fixup_f32 v168, v169, v160, 1.0
	v_cvt_pk_bf16_f32 v160, v153, v151
	v_cvt_pk_bf16_f32 v161, v167, v166
	v_cvt_pk_bf16_f32 v162, v165, v164
	v_cvt_pk_bf16_f32 v163, v168, v163
	v_mul_f32_e32 v151, 0xbfb8aa3b, v120
; DI unsigned pk2(float lo, float hi) { f32x2 v = {lo, hi}; bf2_t b = __builtin_convertvector(v, bf2_t); return __builtin_bit_cast(unsigned, b); }
; #define EPI_LOOP_PERM(...) _Pragma("unroll") for (int ai = 0; ai < 2; ++ai) _Pragma("unroll") for (int m = 0; m < 4; ++m) { const int row = u.pm * 256 + ai * 128 + wr * 64 + m * 16 + fr; \
;     _Pragma("unroll") for (int bj = 0; bj < 2; ++bj) { const int c8 = bj * 128 + wc * 32 + 8 * fq; f32x4 v0 = acc[ai][bj][m][0], v1 = acc[ai][bj][m][1]; __VA_ARGS__ } }
; DI u32x4 pack44(f32x4 a, f32x4 b) { u32x4 w; w.x = pk2(a[0], a[1]); w.y = pk2(a[2], a[3]); w.z = pk2(b[0], b[1]); w.w = pk2(b[2], b[3]); return w; }
; DI float sigmoidf_(float x) { return 1.f / (1.f + __expf(-x)); }
;     DI void operator()(const Acc& acc, const Unit& u, int wr, int wc, int fr, int fq) const {
;     ...
;         } else if (pn < 36) {
;             bf16_t* dst = pn < 28 ? sgs + (pn - 20) * 256 : sgg + (pn - 28) * 256;
;             EPI_LOOP_PERM({ for (int j = 0; j < 4; ++j) { v0[j] = sigmoidf_(v0[j]); v1[j] = sigmoidf_(v1[j]); } *(u32x4*)(dst + (size_t)row * 2048 + c8) = pack44(v0, v1); })
	global_store_dwordx4 v[154:155], v[160:163], off offset:256
	v_or_b32_e32 v154, 16, v152
	v_ashrrev_i32_e32 v155, 31, v154
	v_exp_f32_e32 v160, v151
	v_mul_f32_e32 v151, 0xbfb8aa3b, v116
	v_exp_f32_e32 v162, v151
	v_mul_f32_e32 v151, 0xbfb8aa3b, v121
	v_exp_f32_e32 v161, v151
	v_lshlrev_b64 v[154:155], 12, v[154:155]
	v_lshl_add_u64 v[154:155], s[44:45], 0, v[154:155]
	v_lshl_add_u64 v[154:155], v[154:155], 0, v[2:3]
	v_pk_add_f32 v[160:161], v[160:161], 1.0 op_sel_hi:[1,0]
	s_nop 0
	v_rcp_f32_e32 v153, v161
	s_nop 0
	v_mul_f32_e32 v164, 1.0, v153
	v_fma_f32 v165, -v161, v164, 1.0
	v_fmac_f32_e32 v164, v165, v153
	v_div_fixup_f32 v151, v164, v161, 1.0
	v_rcp_f32_e32 v161, v160
	s_nop 0
	v_mul_f32_e32 v164, 1.0, v161
	v_fma_f32 v165, -v160, v164, 1.0
	v_fmac_f32_e32 v164, v165, v161
	v_div_fixup_f32 v153, v164, v160, 1.0
	v_mul_f32_e32 v160, 0xbfb8aa3b, v117
	v_exp_f32_e32 v163, v160
	s_nop 0
	v_pk_add_f32 v[160:161], v[162:163], 1.0 op_sel_hi:[1,0]
	s_nop 0
	v_rcp_f32_e32 v163, v161
	s_nop 0
	v_mul_f32_e32 v165, 1.0, v163
	v_fma_f32 v166, -v161, v165, 1.0
	v_fmac_f32_e32 v165, v166, v163
	v_div_fixup_f32 v164, v165, v161, 1.0
	v_rcp_f32_e32 v162, v160
	s_nop 0
	v_mul_f32_e32 v165, 1.0, v162
	v_fma_f32 v166, -v160, v165, 1.0
	v_fmac_f32_e32 v165, v166, v162
	v_div_fixup_f32 v165, v165, v160, 1.0
	v_mul_f32_e32 v161, 0xbfb8aa3b, v118
	v_mul_f32_e32 v160, 0xbfb8aa3b, v122
	v_exp_f32_e32 v162, v161
	v_mul_f32_e32 v161, 0xbfb8aa3b, v123
	v_exp_f32_e32 v160, v160
	v_exp_f32_e32 v161, v161
	s_nop 0
	v_pk_add_f32 v[160:161], v[160:161], 1.0 op_sel_hi:[1,0]
	s_nop 0
	v_rcp_f32_e32 v166, v161
	s_nop 0
	v_mul_f32_e32 v168, 1.0, v166
	v_fma_f32 v169, -v161, v168, 1.0
	v_fmac_f32_e32 v168, v169, v166
	v_div_fixup_f32 v166, v168, v161, 1.0
	v_rcp_f32_e32 v163, v160
	s_nop 0
	v_mul_f32_e32 v168, 1.0, v163
	v_fma_f32 v169, -v160, v168, 1.0
	v_fmac_f32_e32 v168, v169, v163
	v_div_fixup_f32 v167, v168, v160, 1.0
	v_mul_f32_e32 v160, 0xbfb8aa3b, v119
	v_exp_f32_e32 v163, v160
	s_nop 0
	v_pk_add_f32 v[160:161], v[162:163], 1.0 op_sel_hi:[1,0]
	s_nop 0
	v_rcp_f32_e32 v163, v161
	s_nop 0
	v_mul_f32_e32 v169, 1.0, v163
	v_fma_f32 v170, -v161, v169, 1.0
	v_fmac_f32_e32 v169, v170, v163
	v_div_fixup_f32 v163, v169, v161, 1.0
	v_rcp_f32_e32 v162, v160
	s_nop 0
	v_mul_f32_e32 v169, 1.0, v162
	v_fma_f32 v170, -v160, v169, 1.0
	v_fmac_f32_e32 v169, v170, v162
	v_div_fixup_f32 v168, v169, v160, 1.0
	v_cvt_pk_bf16_f32 v160, v153, v151
	v_cvt_pk_bf16_f32 v161, v167, v166
	v_cvt_pk_bf16_f32 v162, v165, v164
	v_cvt_pk_bf16_f32 v163, v168, v163
	v_mul_f32_e32 v151, 0xbfb8aa3b, v96
	global_store_dwordx4 v[154:155], v[160:163], off
	s_nop 1
	v_exp_f32_e32 v160, v151
	v_mul_f32_e32 v151, 0xbfb8aa3b, v92
	v_exp_f32_e32 v162, v151
	v_mul_f32_e32 v151, 0xbfb8aa3b, v97
	v_exp_f32_e32 v161, v151
	s_nop 0
	v_pk_add_f32 v[160:161], v[160:161], 1.0 op_sel_hi:[1,0]
	s_nop 0
	v_rcp_f32_e32 v153, v161
	s_nop 0
	v_mul_f32_e32 v164, 1.0, v153
	v_fma_f32 v165, -v161, v164, 1.0
	v_fmac_f32_e32 v164, v165, v153
	v_div_fixup_f32 v151, v164, v161, 1.0
	v_rcp_f32_e32 v161, v160
	s_nop 0
	v_mul_f32_e32 v164, 1.0, v161
	v_fma_f32 v165, -v160, v164, 1.0
	v_fmac_f32_e32 v164, v165, v161
	v_div_fixup_f32 v153, v164, v160, 1.0
	v_mul_f32_e32 v160, 0xbfb8aa3b, v93
	v_exp_f32_e32 v163, v160
	s_nop 0
	v_pk_add_f32 v[160:161], v[162:163], 1.0 op_sel_hi:[1,0]
	s_nop 0
	v_rcp_f32_e32 v163, v161
	s_nop 0
	v_mul_f32_e32 v165, 1.0, v163
	v_fma_f32 v166, -v161, v165, 1.0
	v_fmac_f32_e32 v165, v166, v163
	v_div_fixup_f32 v164, v165, v161, 1.0
	v_rcp_f32_e32 v162, v160
	s_nop 0
	v_mul_f32_e32 v165, 1.0, v162
	v_fma_f32 v166, -v160, v165, 1.0
	v_fmac_f32_e32 v165, v166, v162
	v_div_fixup_f32 v165, v165, v160, 1.0
	v_mul_f32_e32 v161, 0xbfb8aa3b, v94
	v_mul_f32_e32 v160, 0xbfb8aa3b, v98
	v_exp_f32_e32 v162, v161
	v_mul_f32_e32 v161, 0xbfb8aa3b, v99
	v_exp_f32_e32 v160, v160
	v_exp_f32_e32 v161, v161
	s_nop 0
	v_pk_add_f32 v[160:161], v[160:161], 1.0 op_sel_hi:[1,0]
	s_nop 0
	v_rcp_f32_e32 v166, v161
	s_nop 0
	v_mul_f32_e32 v168, 1.0, v166
	v_fma_f32 v169, -v161, v168, 1.0
	v_fmac_f32_e32 v168, v169, v166
	v_div_fixup_f32 v166, v168, v161, 1.0
	v_rcp_f32_e32 v163, v160
	s_nop 0
	v_mul_f32_e32 v168, 1.0, v163
	v_fma_f32 v169, -v160, v168, 1.0
	v_fmac_f32_e32 v168, v169, v163
	v_div_fixup_f32 v167, v168, v160, 1.0
	v_mul_f32_e32 v160, 0xbfb8aa3b, v95
	v_exp_f32_e32 v163, v160
	s_nop 0
	v_pk_add_f32 v[160:161], v[162:163], 1.0 op_sel_hi:[1,0]
	s_nop 0
	v_rcp_f32_e32 v163, v161
	s_nop 0
	v_mul_f32_e32 v169, 1.0, v163
	v_fma_f32 v170, -v161, v169, 1.0
	v_fmac_f32_e32 v169, v170, v163
	v_div_fixup_f32 v163, v169, v161, 1.0
	v_rcp_f32_e32 v162, v160
	s_nop 0
	v_mul_f32_e32 v169, 1.0, v162
	v_fma_f32 v170, -v160, v169, 1.0
	v_fmac_f32_e32 v169, v170, v162
	v_div_fixup_f32 v168, v169, v160, 1.0
	v_cvt_pk_bf16_f32 v160, v153, v151
	v_cvt_pk_bf16_f32 v161, v167, v166
	v_cvt_pk_bf16_f32 v162, v165, v164
	v_cvt_pk_bf16_f32 v163, v168, v163
	v_mul_f32_e32 v151, 0xbfb8aa3b, v104
	global_store_dwordx4 v[154:155], v[160:163], off offset:256
	v_or_b32_e32 v154, 32, v152
	v_ashrrev_i32_e32 v155, 31, v154
	v_exp_f32_e32 v160, v151
	v_mul_f32_e32 v151, 0xbfb8aa3b, v100
	v_exp_f32_e32 v162, v151
	v_mul_f32_e32 v151, 0xbfb8aa3b, v105
	v_exp_f32_e32 v161, v151
	v_lshlrev_b64 v[154:155], 12, v[154:155]
	v_lshl_add_u64 v[154:155], s[44:45], 0, v[154:155]
	v_lshl_add_u64 v[154:155], v[154:155], 0, v[2:3]
	v_pk_add_f32 v[160:161], v[160:161], 1.0 op_sel_hi:[1,0]
	s_nop 0
	v_rcp_f32_e32 v153, v161
	s_nop 0
	v_mul_f32_e32 v164, 1.0, v153
	v_fma_f32 v165, -v161, v164, 1.0
	v_fmac_f32_e32 v164, v165, v153
	v_div_fixup_f32 v151, v164, v161, 1.0
; DI unsigned pk2(float lo, float hi) { f32x2 v = {lo, hi}; bf2_t b = __builtin_convertvector(v, bf2_t); return __builtin_bit_cast(unsigned, b); }
; #define EPI_LOOP_PERM(...) _Pragma("unroll") for (int ai = 0; ai < 2; ++ai) _Pragma("unroll") for (int m = 0; m < 4; ++m) { const int row = u.pm * 256 + ai * 128 + wr * 64 + m * 16 + fr; \
;     _Pragma("unroll") for (int bj = 0; bj < 2; ++bj) { const int c8 = bj * 128 + wc * 32 + 8 * fq; f32x4 v0 = acc[ai][bj][m][0], v1 = acc[ai][bj][m][1]; __VA_ARGS__ } }
; DI u32x4 pack44(f32x4 a, f32x4 b) { u32x4 w; w.x = pk2(a[0], a[1]); w.y = pk2(a[2], a[3]); w.z = pk2(b[0], b[1]); w.w = pk2(b[2], b[3]); return w; }
; DI float sigmoidf_(float x) { return 1.f / (1.f + __expf(-x)); }
;     DI void operator()(const Acc& acc, const Unit& u, int wr, int wc, int fr, int fq) const {
;     ...
;         } else if (pn < 36) {
;             bf16_t* dst = pn < 28 ? sgs + (pn - 20) * 256 : sgg + (pn - 28) * 256;
;             EPI_LOOP_PERM({ for (int j = 0; j < 4; ++j) { v0[j] = sigmoidf_(v0[j]); v1[j] = sigmoidf_(v1[j]); } *(u32x4*)(dst + (size_t)row * 2048 + c8) = pack44(v0, v1); })
	v_rcp_f32_e32 v161, v160
	s_nop 0
	v_mul_f32_e32 v164, 1.0, v161
	v_fma_f32 v165, -v160, v164, 1.0
	v_fmac_f32_e32 v164, v165, v161
	v_div_fixup_f32 v153, v164, v160, 1.0
	v_mul_f32_e32 v160, 0xbfb8aa3b, v101
	v_exp_f32_e32 v163, v160
	s_nop 0
	v_pk_add_f32 v[160:161], v[162:163], 1.0 op_sel_hi:[1,0]
	s_nop 0
	v_rcp_f32_e32 v163, v161
	s_nop 0
	v_mul_f32_e32 v165, 1.0, v163
	v_fma_f32 v166, -v161, v165, 1.0
	v_fmac_f32_e32 v165, v166, v163
	v_div_fixup_f32 v164, v165, v161, 1.0
	v_rcp_f32_e32 v162, v160
	s_nop 0
	v_mul_f32_e32 v165, 1.0, v162
	v_fma_f32 v166, -v160, v165, 1.0
	v_fmac_f32_e32 v165, v166, v162
	v_div_fixup_f32 v165, v165, v160, 1.0
	v_mul_f32_e32 v161, 0xbfb8aa3b, v102
	v_mul_f32_e32 v160, 0xbfb8aa3b, v106
	v_exp_f32_e32 v162, v161
	v_mul_f32_e32 v161, 0xbfb8aa3b, v107
	v_exp_f32_e32 v160, v160
	v_exp_f32_e32 v161, v161
	s_nop 0
	v_pk_add_f32 v[160:161], v[160:161], 1.0 op_sel_hi:[1,0]
	s_nop 0
	v_rcp_f32_e32 v166, v161
	s_nop 0
	v_mul_f32_e32 v168, 1.0, v166
	v_fma_f32 v169, -v161, v168, 1.0
	v_fmac_f32_e32 v168, v169, v166
	v_div_fixup_f32 v166, v168, v161, 1.0
	v_rcp_f32_e32 v163, v160
	s_nop 0
	v_mul_f32_e32 v168, 1.0, v163
	v_fma_f32 v169, -v160, v168, 1.0
	v_fmac_f32_e32 v168, v169, v163
	v_div_fixup_f32 v167, v168, v160, 1.0
	v_mul_f32_e32 v160, 0xbfb8aa3b, v103
	v_exp_f32_e32 v163, v160
	s_nop 0
	v_pk_add_f32 v[160:161], v[162:163], 1.0 op_sel_hi:[1,0]
	s_nop 0
	v_rcp_f32_e32 v163, v161
	s_nop 0
	v_mul_f32_e32 v169, 1.0, v163
	v_fma_f32 v170, -v161, v169, 1.0
	v_fmac_f32_e32 v169, v170, v163
	v_div_fixup_f32 v163, v169, v161, 1.0
	v_rcp_f32_e32 v162, v160
	s_nop 0
	v_mul_f32_e32 v169, 1.0, v162
	v_fma_f32 v170, -v160, v169, 1.0
	v_fmac_f32_e32 v169, v170, v162
	v_div_fixup_f32 v168, v169, v160, 1.0
	v_cvt_pk_bf16_f32 v160, v153, v151
	v_cvt_pk_bf16_f32 v161, v167, v166
	v_cvt_pk_bf16_f32 v162, v165, v164
	v_cvt_pk_bf16_f32 v163, v168, v163
	v_mul_f32_e32 v151, 0xbfb8aa3b, v80
	global_store_dwordx4 v[154:155], v[160:163], off
	s_nop 1
	v_exp_f32_e32 v160, v151
	v_mul_f32_e32 v151, 0xbfb8aa3b, v76
	v_exp_f32_e32 v162, v151
	v_mul_f32_e32 v151, 0xbfb8aa3b, v81
	v_exp_f32_e32 v161, v151
	s_nop 0
	v_pk_add_f32 v[160:161], v[160:161], 1.0 op_sel_hi:[1,0]
	s_nop 0
	v_rcp_f32_e32 v153, v161
	s_nop 0
	v_mul_f32_e32 v164, 1.0, v153
	v_fma_f32 v165, -v161, v164, 1.0
	v_fmac_f32_e32 v164, v165, v153
	v_div_fixup_f32 v151, v164, v161, 1.0
	v_rcp_f32_e32 v161, v160
	s_nop 0
	v_mul_f32_e32 v164, 1.0, v161
	v_fma_f32 v165, -v160, v164, 1.0
	v_fmac_f32_e32 v164, v165, v161
	v_div_fixup_f32 v153, v164, v160, 1.0
	v_mul_f32_e32 v160, 0xbfb8aa3b, v77
	v_exp_f32_e32 v163, v160
	s_nop 0
	v_pk_add_f32 v[160:161], v[162:163], 1.0 op_sel_hi:[1,0]
	s_nop 0
	v_rcp_f32_e32 v163, v161
	s_nop 0
	v_mul_f32_e32 v165, 1.0, v163
	v_fma_f32 v166, -v161, v165, 1.0
	v_fmac_f32_e32 v165, v166, v163
	v_div_fixup_f32 v164, v165, v161, 1.0
	v_rcp_f32_e32 v162, v160
	s_nop 0
	v_mul_f32_e32 v165, 1.0, v162
	v_fma_f32 v166, -v160, v165, 1.0
	v_fmac_f32_e32 v165, v166, v162
	v_div_fixup_f32 v165, v165, v160, 1.0
	v_mul_f32_e32 v161, 0xbfb8aa3b, v78
	v_mul_f32_e32 v160, 0xbfb8aa3b, v82
	v_exp_f32_e32 v162, v161
	v_mul_f32_e32 v161, 0xbfb8aa3b, v83
	v_exp_f32_e32 v160, v160
	v_exp_f32_e32 v161, v161
	s_nop 0
	v_pk_add_f32 v[160:161], v[160:161], 1.0 op_sel_hi:[1,0]
	s_nop 0
	v_rcp_f32_e32 v166, v161
	s_nop 0
	v_mul_f32_e32 v168, 1.0, v166
	v_fma_f32 v169, -v161, v168, 1.0
	v_fmac_f32_e32 v168, v169, v166
	v_div_fixup_f32 v166, v168, v161, 1.0
	v_rcp_f32_e32 v163, v160
	s_nop 0
	v_mul_f32_e32 v168, 1.0, v163
	v_fma_f32 v169, -v160, v168, 1.0
	v_fmac_f32_e32 v168, v169, v163
	v_div_fixup_f32 v167, v168, v160, 1.0
	v_mul_f32_e32 v160, 0xbfb8aa3b, v79
	v_exp_f32_e32 v163, v160
	s_nop 0
	v_pk_add_f32 v[160:161], v[162:163], 1.0 op_sel_hi:[1,0]
	s_nop 0
	v_rcp_f32_e32 v163, v161
	s_nop 0
	v_mul_f32_e32 v169, 1.0, v163
	v_fma_f32 v170, -v161, v169, 1.0
	v_fmac_f32_e32 v169, v170, v163
	v_div_fixup_f32 v163, v169, v161, 1.0
	v_rcp_f32_e32 v162, v160
	s_nop 0
	v_mul_f32_e32 v169, 1.0, v162
	v_fma_f32 v170, -v160, v169, 1.0
	v_fmac_f32_e32 v169, v170, v162
	v_div_fixup_f32 v168, v169, v160, 1.0
	v_cvt_pk_bf16_f32 v160, v153, v151
	v_cvt_pk_bf16_f32 v161, v167, v166
	v_cvt_pk_bf16_f32 v162, v165, v164
	v_cvt_pk_bf16_f32 v163, v168, v163
	v_mul_f32_e32 v151, 0xbfb8aa3b, v88
	global_store_dwordx4 v[154:155], v[160:163], off offset:256
	v_or_b32_e32 v154, 48, v152
	v_ashrrev_i32_e32 v155, 31, v154
	v_exp_f32_e32 v160, v151
	v_mul_f32_e32 v151, 0xbfb8aa3b, v84
	v_exp_f32_e32 v162, v151
	v_mul_f32_e32 v151, 0xbfb8aa3b, v89
	v_exp_f32_e32 v161, v151
	v_lshlrev_b64 v[154:155], 12, v[154:155]
	v_lshl_add_u64 v[154:155], s[44:45], 0, v[154:155]
	v_lshl_add_u64 v[154:155], v[154:155], 0, v[2:3]
	v_pk_add_f32 v[160:161], v[160:161], 1.0 op_sel_hi:[1,0]
	s_nop 0
	v_rcp_f32_e32 v153, v161
	s_nop 0
	v_mul_f32_e32 v164, 1.0, v153
	v_fma_f32 v165, -v161, v164, 1.0
	v_fmac_f32_e32 v164, v165, v153
	v_div_fixup_f32 v151, v164, v161, 1.0
	v_rcp_f32_e32 v161, v160
	s_nop 0
	v_mul_f32_e32 v164, 1.0, v161
	v_fma_f32 v165, -v160, v164, 1.0
	v_fmac_f32_e32 v164, v165, v161
	v_div_fixup_f32 v153, v164, v160, 1.0
	v_mul_f32_e32 v160, 0xbfb8aa3b, v85
	v_exp_f32_e32 v163, v160
	s_nop 0
	v_pk_add_f32 v[160:161], v[162:163], 1.0 op_sel_hi:[1,0]
	s_nop 0
	v_rcp_f32_e32 v163, v161
	s_nop 0
	v_mul_f32_e32 v165, 1.0, v163
	v_fma_f32 v166, -v161, v165, 1.0
	v_fmac_f32_e32 v165, v166, v163
	v_div_fixup_f32 v164, v165, v161, 1.0
	v_rcp_f32_e32 v162, v160
	s_nop 0
	v_mul_f32_e32 v165, 1.0, v162
	v_fma_f32 v166, -v160, v165, 1.0
	v_fmac_f32_e32 v165, v166, v162
	v_div_fixup_f32 v165, v165, v160, 1.0
; DI unsigned pk2(float lo, float hi) { f32x2 v = {lo, hi}; bf2_t b = __builtin_convertvector(v, bf2_t); return __builtin_bit_cast(unsigned, b); }
; #define EPI_LOOP_PERM(...) _Pragma("unroll") for (int ai = 0; ai < 2; ++ai) _Pragma("unroll") for (int m = 0; m < 4; ++m) { const int row = u.pm * 256 + ai * 128 + wr * 64 + m * 16 + fr; \
;     _Pragma("unroll") for (int bj = 0; bj < 2; ++bj) { const int c8 = bj * 128 + wc * 32 + 8 * fq; f32x4 v0 = acc[ai][bj][m][0], v1 = acc[ai][bj][m][1]; __VA_ARGS__ } }
; DI u32x4 pack44(f32x4 a, f32x4 b) { u32x4 w; w.x = pk2(a[0], a[1]); w.y = pk2(a[2], a[3]); w.z = pk2(b[0], b[1]); w.w = pk2(b[2], b[3]); return w; }
; DI float sigmoidf_(float x) { return 1.f / (1.f + __expf(-x)); }
;     DI void operator()(const Acc& acc, const Unit& u, int wr, int wc, int fr, int fq) const {
;     ...
;         } else if (pn < 36) {
;             bf16_t* dst = pn < 28 ? sgs + (pn - 20) * 256 : sgg + (pn - 28) * 256;
;             EPI_LOOP_PERM({ for (int j = 0; j < 4; ++j) { v0[j] = sigmoidf_(v0[j]); v1[j] = sigmoidf_(v1[j]); } *(u32x4*)(dst + (size_t)row * 2048 + c8) = pack44(v0, v1); })
	v_mul_f32_e32 v161, 0xbfb8aa3b, v86
	v_mul_f32_e32 v160, 0xbfb8aa3b, v90
	v_exp_f32_e32 v162, v161
	v_mul_f32_e32 v161, 0xbfb8aa3b, v91
	v_exp_f32_e32 v160, v160
	v_exp_f32_e32 v161, v161
	s_nop 0
	v_pk_add_f32 v[160:161], v[160:161], 1.0 op_sel_hi:[1,0]
	s_nop 0
	v_rcp_f32_e32 v166, v161
	s_nop 0
	v_mul_f32_e32 v168, 1.0, v166
	v_fma_f32 v169, -v161, v168, 1.0
	v_fmac_f32_e32 v168, v169, v166
	v_div_fixup_f32 v166, v168, v161, 1.0
	v_rcp_f32_e32 v163, v160
	s_nop 0
	v_mul_f32_e32 v168, 1.0, v163
	v_fma_f32 v169, -v160, v168, 1.0
	v_fmac_f32_e32 v168, v169, v163
	v_div_fixup_f32 v167, v168, v160, 1.0
	v_mul_f32_e32 v160, 0xbfb8aa3b, v87
	v_exp_f32_e32 v163, v160
	s_nop 0
	v_pk_add_f32 v[160:161], v[162:163], 1.0 op_sel_hi:[1,0]
	s_nop 0
	v_rcp_f32_e32 v163, v161
	s_nop 0
	v_mul_f32_e32 v169, 1.0, v163
	v_fma_f32 v170, -v161, v169, 1.0
	v_fmac_f32_e32 v169, v170, v163
	v_div_fixup_f32 v163, v169, v161, 1.0
	v_rcp_f32_e32 v162, v160
	s_nop 0
	v_mul_f32_e32 v169, 1.0, v162
	v_fma_f32 v170, -v160, v169, 1.0
	v_fmac_f32_e32 v169, v170, v162
	v_div_fixup_f32 v168, v169, v160, 1.0
	v_cvt_pk_bf16_f32 v160, v153, v151
	v_cvt_pk_bf16_f32 v161, v167, v166
	v_cvt_pk_bf16_f32 v162, v165, v164
	v_cvt_pk_bf16_f32 v163, v168, v163
	v_mul_f32_e32 v151, 0xbfb8aa3b, v72
	global_store_dwordx4 v[154:155], v[160:163], off
	s_nop 1
	v_exp_f32_e32 v160, v151
	v_mul_f32_e32 v151, 0xbfb8aa3b, v68
	v_exp_f32_e32 v162, v151
	v_mul_f32_e32 v151, 0xbfb8aa3b, v73
	v_exp_f32_e32 v161, v151
	s_nop 0
	v_pk_add_f32 v[160:161], v[160:161], 1.0 op_sel_hi:[1,0]
	s_nop 0
	v_rcp_f32_e32 v153, v161
	s_nop 0
	v_mul_f32_e32 v164, 1.0, v153
	v_fma_f32 v165, -v161, v164, 1.0
	v_fmac_f32_e32 v164, v165, v153
	v_div_fixup_f32 v151, v164, v161, 1.0
	v_rcp_f32_e32 v161, v160
	s_nop 0
	v_mul_f32_e32 v164, 1.0, v161
	v_fma_f32 v165, -v160, v164, 1.0
	v_fmac_f32_e32 v164, v165, v161
	v_div_fixup_f32 v153, v164, v160, 1.0
	v_mul_f32_e32 v160, 0xbfb8aa3b, v69
	v_exp_f32_e32 v163, v160
	s_nop 0
	v_pk_add_f32 v[160:161], v[162:163], 1.0 op_sel_hi:[1,0]
	s_nop 0
	v_rcp_f32_e32 v163, v161
	s_nop 0
	v_mul_f32_e32 v165, 1.0, v163
	v_fma_f32 v166, -v161, v165, 1.0
	v_fmac_f32_e32 v165, v166, v163
	v_div_fixup_f32 v164, v165, v161, 1.0
	v_rcp_f32_e32 v162, v160
	s_nop 0
	v_mul_f32_e32 v165, 1.0, v162
	v_fma_f32 v166, -v160, v165, 1.0
	v_fmac_f32_e32 v165, v166, v162
	v_div_fixup_f32 v165, v165, v160, 1.0
	v_mul_f32_e32 v161, 0xbfb8aa3b, v70
	v_mul_f32_e32 v160, 0xbfb8aa3b, v74
	v_exp_f32_e32 v162, v161
	v_mul_f32_e32 v161, 0xbfb8aa3b, v75
	v_exp_f32_e32 v160, v160
	v_exp_f32_e32 v161, v161
	s_nop 0
	v_pk_add_f32 v[160:161], v[160:161], 1.0 op_sel_hi:[1,0]
	s_nop 0
	v_rcp_f32_e32 v166, v161
	s_nop 0
	v_mul_f32_e32 v168, 1.0, v166
	v_fma_f32 v169, -v161, v168, 1.0
	v_fmac_f32_e32 v168, v169, v166
	v_div_fixup_f32 v166, v168, v161, 1.0
	v_rcp_f32_e32 v163, v160
	s_nop 0
	v_mul_f32_e32 v168, 1.0, v163
	v_fma_f32 v169, -v160, v168, 1.0
	v_fmac_f32_e32 v168, v169, v163
	v_div_fixup_f32 v167, v168, v160, 1.0
	v_mul_f32_e32 v160, 0xbfb8aa3b, v71
	v_exp_f32_e32 v163, v160
	s_nop 0
	v_pk_add_f32 v[160:161], v[162:163], 1.0 op_sel_hi:[1,0]
	s_nop 0
	v_rcp_f32_e32 v163, v161
	s_nop 0
	v_mul_f32_e32 v169, 1.0, v163
	v_fma_f32 v170, -v161, v169, 1.0
	v_fmac_f32_e32 v169, v170, v163
	v_div_fixup_f32 v163, v169, v161, 1.0
	v_rcp_f32_e32 v162, v160
	s_nop 0
	v_mul_f32_e32 v169, 1.0, v162
	v_fma_f32 v170, -v160, v169, 1.0
	v_fmac_f32_e32 v169, v170, v162
	v_div_fixup_f32 v168, v169, v160, 1.0
	v_cvt_pk_bf16_f32 v160, v153, v151
	v_cvt_pk_bf16_f32 v161, v167, v166
	v_cvt_pk_bf16_f32 v162, v165, v164
	v_cvt_pk_bf16_f32 v163, v168, v163
	v_mul_f32_e32 v151, 0xbfb8aa3b, v64
	global_store_dwordx4 v[154:155], v[160:163], off offset:256
	v_add_u32_e32 v154, 0x80, v152
	v_ashrrev_i32_e32 v155, 31, v154
	v_exp_f32_e32 v160, v151
	v_mul_f32_e32 v151, 0xbfb8aa3b, v60
	v_exp_f32_e32 v162, v151
	v_mul_f32_e32 v151, 0xbfb8aa3b, v65
	v_exp_f32_e32 v161, v151
	v_lshlrev_b64 v[154:155], 12, v[154:155]
	v_lshl_add_u64 v[154:155], s[44:45], 0, v[154:155]
	v_lshl_add_u64 v[154:155], v[154:155], 0, v[2:3]
	v_pk_add_f32 v[160:161], v[160:161], 1.0 op_sel_hi:[1,0]
	s_nop 0
	v_rcp_f32_e32 v153, v161
	s_nop 0
	v_mul_f32_e32 v164, 1.0, v153
	v_fma_f32 v165, -v161, v164, 1.0
	v_fmac_f32_e32 v164, v165, v153
	v_div_fixup_f32 v151, v164, v161, 1.0
	v_rcp_f32_e32 v161, v160
	s_nop 0
	v_mul_f32_e32 v164, 1.0, v161
	v_fma_f32 v165, -v160, v164, 1.0
	v_fmac_f32_e32 v164, v165, v161
	v_div_fixup_f32 v153, v164, v160, 1.0
	v_mul_f32_e32 v160, 0xbfb8aa3b, v61
	v_exp_f32_e32 v163, v160
	s_nop 0
	v_pk_add_f32 v[160:161], v[162:163], 1.0 op_sel_hi:[1,0]
	s_nop 0
	v_rcp_f32_e32 v163, v161
	s_nop 0
	v_mul_f32_e32 v165, 1.0, v163
	v_fma_f32 v166, -v161, v165, 1.0
	v_fmac_f32_e32 v165, v166, v163
	v_div_fixup_f32 v164, v165, v161, 1.0
	v_rcp_f32_e32 v162, v160
	s_nop 0
	v_mul_f32_e32 v165, 1.0, v162
	v_fma_f32 v166, -v160, v165, 1.0
	v_fmac_f32_e32 v165, v166, v162
	v_div_fixup_f32 v165, v165, v160, 1.0
	v_mul_f32_e32 v161, 0xbfb8aa3b, v62
	v_mul_f32_e32 v160, 0xbfb8aa3b, v66
	v_exp_f32_e32 v162, v161
	v_mul_f32_e32 v161, 0xbfb8aa3b, v67
	v_exp_f32_e32 v160, v160
	v_exp_f32_e32 v161, v161
	s_nop 0
	v_pk_add_f32 v[160:161], v[160:161], 1.0 op_sel_hi:[1,0]
	s_nop 0
	v_rcp_f32_e32 v166, v161
	s_nop 0
	v_mul_f32_e32 v168, 1.0, v166
	v_fma_f32 v169, -v161, v168, 1.0
	v_fmac_f32_e32 v168, v169, v166
	v_div_fixup_f32 v166, v168, v161, 1.0
	v_rcp_f32_e32 v163, v160
	s_nop 0
	v_mul_f32_e32 v168, 1.0, v163
	v_fma_f32 v169, -v160, v168, 1.0
	v_fmac_f32_e32 v168, v169, v163
	v_div_fixup_f32 v167, v168, v160, 1.0
	v_mul_f32_e32 v160, 0xbfb8aa3b, v63
	v_exp_f32_e32 v163, v160
; DI unsigned pk2(float lo, float hi) { f32x2 v = {lo, hi}; bf2_t b = __builtin_convertvector(v, bf2_t); return __builtin_bit_cast(unsigned, b); }
; #define EPI_LOOP_PERM(...) _Pragma("unroll") for (int ai = 0; ai < 2; ++ai) _Pragma("unroll") for (int m = 0; m < 4; ++m) { const int row = u.pm * 256 + ai * 128 + wr * 64 + m * 16 + fr; \
;     _Pragma("unroll") for (int bj = 0; bj < 2; ++bj) { const int c8 = bj * 128 + wc * 32 + 8 * fq; f32x4 v0 = acc[ai][bj][m][0], v1 = acc[ai][bj][m][1]; __VA_ARGS__ } }
; DI u32x4 pack44(f32x4 a, f32x4 b) { u32x4 w; w.x = pk2(a[0], a[1]); w.y = pk2(a[2], a[3]); w.z = pk2(b[0], b[1]); w.w = pk2(b[2], b[3]); return w; }
; DI float sigmoidf_(float x) { return 1.f / (1.f + __expf(-x)); }
;     DI void operator()(const Acc& acc, const Unit& u, int wr, int wc, int fr, int fq) const {
;     ...
;         } else if (pn < 36) {
;             bf16_t* dst = pn < 28 ? sgs + (pn - 20) * 256 : sgg + (pn - 28) * 256;
;             EPI_LOOP_PERM({ for (int j = 0; j < 4; ++j) { v0[j] = sigmoidf_(v0[j]); v1[j] = sigmoidf_(v1[j]); } *(u32x4*)(dst + (size_t)row * 2048 + c8) = pack44(v0, v1); })
	s_nop 0
	v_pk_add_f32 v[160:161], v[162:163], 1.0 op_sel_hi:[1,0]
	s_nop 0
	v_rcp_f32_e32 v163, v161
	s_nop 0
	v_mul_f32_e32 v169, 1.0, v163
	v_fma_f32 v170, -v161, v169, 1.0
	v_fmac_f32_e32 v169, v170, v163
	v_div_fixup_f32 v163, v169, v161, 1.0
	v_rcp_f32_e32 v162, v160
	s_nop 0
	v_mul_f32_e32 v169, 1.0, v162
	v_fma_f32 v170, -v160, v169, 1.0
	v_fmac_f32_e32 v169, v170, v162
	v_div_fixup_f32 v168, v169, v160, 1.0
	v_cvt_pk_bf16_f32 v160, v153, v151
	v_cvt_pk_bf16_f32 v161, v167, v166
	v_cvt_pk_bf16_f32 v162, v165, v164
	v_cvt_pk_bf16_f32 v163, v168, v163
	v_mul_f32_e32 v151, 0xbfb8aa3b, v48
	global_store_dwordx4 v[154:155], v[160:163], off
	s_nop 1
	v_exp_f32_e32 v160, v151
	v_mul_f32_e32 v151, 0xbfb8aa3b, v44
	v_exp_f32_e32 v162, v151
	v_mul_f32_e32 v151, 0xbfb8aa3b, v49
	v_exp_f32_e32 v161, v151
	s_nop 0
	v_pk_add_f32 v[160:161], v[160:161], 1.0 op_sel_hi:[1,0]
	s_nop 0
	v_rcp_f32_e32 v153, v161
	s_nop 0
	v_mul_f32_e32 v164, 1.0, v153
	v_fma_f32 v165, -v161, v164, 1.0
	v_fmac_f32_e32 v164, v165, v153
	v_div_fixup_f32 v151, v164, v161, 1.0
	v_rcp_f32_e32 v161, v160
	s_nop 0
	v_mul_f32_e32 v164, 1.0, v161
	v_fma_f32 v165, -v160, v164, 1.0
	v_fmac_f32_e32 v164, v165, v161
	v_div_fixup_f32 v153, v164, v160, 1.0
	v_mul_f32_e32 v160, 0xbfb8aa3b, v45
	v_exp_f32_e32 v163, v160
	s_nop 0
	v_pk_add_f32 v[160:161], v[162:163], 1.0 op_sel_hi:[1,0]
	s_nop 0
	v_rcp_f32_e32 v163, v161
	s_nop 0
	v_mul_f32_e32 v165, 1.0, v163
	v_fma_f32 v166, -v161, v165, 1.0
	v_fmac_f32_e32 v165, v166, v163
	v_div_fixup_f32 v164, v165, v161, 1.0
	v_rcp_f32_e32 v162, v160
	s_nop 0
	v_mul_f32_e32 v165, 1.0, v162
	v_fma_f32 v166, -v160, v165, 1.0
	v_fmac_f32_e32 v165, v166, v162
	v_div_fixup_f32 v165, v165, v160, 1.0
	v_mul_f32_e32 v161, 0xbfb8aa3b, v46
	v_mul_f32_e32 v160, 0xbfb8aa3b, v50
	v_exp_f32_e32 v162, v161
	v_mul_f32_e32 v161, 0xbfb8aa3b, v51
	v_exp_f32_e32 v160, v160
	v_exp_f32_e32 v161, v161
	s_nop 0
	v_pk_add_f32 v[160:161], v[160:161], 1.0 op_sel_hi:[1,0]
	s_nop 0
	v_rcp_f32_e32 v166, v161
	s_nop 0
	v_mul_f32_e32 v168, 1.0, v166
	v_fma_f32 v169, -v161, v168, 1.0
	v_fmac_f32_e32 v168, v169, v166
	v_div_fixup_f32 v166, v168, v161, 1.0
	v_rcp_f32_e32 v163, v160
	s_nop 0
	v_mul_f32_e32 v168, 1.0, v163
	v_fma_f32 v169, -v160, v168, 1.0
	v_fmac_f32_e32 v168, v169, v163
	v_div_fixup_f32 v167, v168, v160, 1.0
	v_mul_f32_e32 v160, 0xbfb8aa3b, v47
	v_exp_f32_e32 v163, v160
	s_nop 0
	v_pk_add_f32 v[160:161], v[162:163], 1.0 op_sel_hi:[1,0]
	s_nop 0
	v_rcp_f32_e32 v163, v161
	s_nop 0
	v_mul_f32_e32 v169, 1.0, v163
	v_fma_f32 v170, -v161, v169, 1.0
	v_fmac_f32_e32 v169, v170, v163
	v_div_fixup_f32 v163, v169, v161, 1.0
	v_rcp_f32_e32 v162, v160
	s_nop 0
	v_mul_f32_e32 v169, 1.0, v162
	v_fma_f32 v170, -v160, v169, 1.0
	v_fmac_f32_e32 v169, v170, v162
	v_div_fixup_f32 v168, v169, v160, 1.0
	v_cvt_pk_bf16_f32 v160, v153, v151
	v_cvt_pk_bf16_f32 v161, v167, v166
	v_cvt_pk_bf16_f32 v162, v165, v164
	v_cvt_pk_bf16_f32 v163, v168, v163
	v_mul_f32_e32 v151, 0xbfb8aa3b, v56
	global_store_dwordx4 v[154:155], v[160:163], off offset:256
	v_add_u32_e32 v154, 0x90, v152
	v_ashrrev_i32_e32 v155, 31, v154
	v_exp_f32_e32 v160, v151
	v_mul_f32_e32 v151, 0xbfb8aa3b, v52
	v_exp_f32_e32 v162, v151
	v_mul_f32_e32 v151, 0xbfb8aa3b, v57
	v_exp_f32_e32 v161, v151
	v_lshlrev_b64 v[154:155], 12, v[154:155]
	v_lshl_add_u64 v[154:155], s[44:45], 0, v[154:155]
	v_lshl_add_u64 v[154:155], v[154:155], 0, v[2:3]
	v_pk_add_f32 v[160:161], v[160:161], 1.0 op_sel_hi:[1,0]
	s_nop 0
	v_rcp_f32_e32 v153, v161
	s_nop 0
	v_mul_f32_e32 v164, 1.0, v153
	v_fma_f32 v165, -v161, v164, 1.0
	v_fmac_f32_e32 v164, v165, v153
	v_div_fixup_f32 v151, v164, v161, 1.0
	v_rcp_f32_e32 v161, v160
	s_nop 0
	v_mul_f32_e32 v164, 1.0, v161
	v_fma_f32 v165, -v160, v164, 1.0
	v_fmac_f32_e32 v164, v165, v161
	v_div_fixup_f32 v153, v164, v160, 1.0
	v_mul_f32_e32 v160, 0xbfb8aa3b, v53
	v_exp_f32_e32 v163, v160
	s_nop 0
	v_pk_add_f32 v[160:161], v[162:163], 1.0 op_sel_hi:[1,0]
	s_nop 0
	v_rcp_f32_e32 v163, v161
	s_nop 0
	v_mul_f32_e32 v165, 1.0, v163
	v_fma_f32 v166, -v161, v165, 1.0
	v_fmac_f32_e32 v165, v166, v163
	v_div_fixup_f32 v164, v165, v161, 1.0
	v_rcp_f32_e32 v162, v160
	s_nop 0
	v_mul_f32_e32 v165, 1.0, v162
	v_fma_f32 v166, -v160, v165, 1.0
	v_fmac_f32_e32 v165, v166, v162
	v_div_fixup_f32 v165, v165, v160, 1.0
	v_mul_f32_e32 v161, 0xbfb8aa3b, v54
	v_mul_f32_e32 v160, 0xbfb8aa3b, v58
	v_exp_f32_e32 v162, v161
	v_mul_f32_e32 v161, 0xbfb8aa3b, v59
	v_exp_f32_e32 v160, v160
	v_exp_f32_e32 v161, v161
	s_nop 0
	v_pk_add_f32 v[160:161], v[160:161], 1.0 op_sel_hi:[1,0]
	s_nop 0
	v_rcp_f32_e32 v166, v161
	s_nop 0
	v_mul_f32_e32 v168, 1.0, v166
	v_fma_f32 v169, -v161, v168, 1.0
	v_fmac_f32_e32 v168, v169, v166
	v_div_fixup_f32 v166, v168, v161, 1.0
	v_rcp_f32_e32 v163, v160
	s_nop 0
	v_mul_f32_e32 v168, 1.0, v163
	v_fma_f32 v169, -v160, v168, 1.0
	v_fmac_f32_e32 v168, v169, v163
	v_div_fixup_f32 v167, v168, v160, 1.0
	v_mul_f32_e32 v160, 0xbfb8aa3b, v55
	v_exp_f32_e32 v163, v160
	s_nop 0
	v_pk_add_f32 v[160:161], v[162:163], 1.0 op_sel_hi:[1,0]
	s_nop 0
	v_rcp_f32_e32 v163, v161
	s_nop 0
	v_mul_f32_e32 v169, 1.0, v163
	v_fma_f32 v170, -v161, v169, 1.0
	v_fmac_f32_e32 v169, v170, v163
	v_div_fixup_f32 v163, v169, v161, 1.0
	v_rcp_f32_e32 v162, v160
	s_nop 0
	v_mul_f32_e32 v169, 1.0, v162
	v_fma_f32 v170, -v160, v169, 1.0
	v_fmac_f32_e32 v169, v170, v162
	v_div_fixup_f32 v168, v169, v160, 1.0
	v_cvt_pk_bf16_f32 v160, v153, v151
	v_cvt_pk_bf16_f32 v161, v167, v166
	v_cvt_pk_bf16_f32 v162, v165, v164
	v_cvt_pk_bf16_f32 v163, v168, v163
	v_mul_f32_e32 v151, 0xbfb8aa3b, v32
	global_store_dwordx4 v[154:155], v[160:163], off
	s_nop 1
; DI unsigned pk2(float lo, float hi) { f32x2 v = {lo, hi}; bf2_t b = __builtin_convertvector(v, bf2_t); return __builtin_bit_cast(unsigned, b); }
; #define EPI_LOOP_PERM(...) _Pragma("unroll") for (int ai = 0; ai < 2; ++ai) _Pragma("unroll") for (int m = 0; m < 4; ++m) { const int row = u.pm * 256 + ai * 128 + wr * 64 + m * 16 + fr; \
;     _Pragma("unroll") for (int bj = 0; bj < 2; ++bj) { const int c8 = bj * 128 + wc * 32 + 8 * fq; f32x4 v0 = acc[ai][bj][m][0], v1 = acc[ai][bj][m][1]; __VA_ARGS__ } }
; DI u32x4 pack44(f32x4 a, f32x4 b) { u32x4 w; w.x = pk2(a[0], a[1]); w.y = pk2(a[2], a[3]); w.z = pk2(b[0], b[1]); w.w = pk2(b[2], b[3]); return w; }
; DI float sigmoidf_(float x) { return 1.f / (1.f + __expf(-x)); }
;     DI void operator()(const Acc& acc, const Unit& u, int wr, int wc, int fr, int fq) const {
;     ...
;         } else if (pn < 36) {
;             bf16_t* dst = pn < 28 ? sgs + (pn - 20) * 256 : sgg + (pn - 28) * 256;
;             EPI_LOOP_PERM({ for (int j = 0; j < 4; ++j) { v0[j] = sigmoidf_(v0[j]); v1[j] = sigmoidf_(v1[j]); } *(u32x4*)(dst + (size_t)row * 2048 + c8) = pack44(v0, v1); })
	v_exp_f32_e32 v160, v151
	v_mul_f32_e32 v151, 0xbfb8aa3b, v28
	v_exp_f32_e32 v162, v151
	v_mul_f32_e32 v151, 0xbfb8aa3b, v33
	v_exp_f32_e32 v161, v151
	s_nop 0
	v_pk_add_f32 v[160:161], v[160:161], 1.0 op_sel_hi:[1,0]
	s_nop 0
	v_rcp_f32_e32 v153, v161
	s_nop 0
	v_mul_f32_e32 v164, 1.0, v153
	v_fma_f32 v165, -v161, v164, 1.0
	v_fmac_f32_e32 v164, v165, v153
	v_div_fixup_f32 v151, v164, v161, 1.0
	v_rcp_f32_e32 v161, v160
	s_nop 0
	v_mul_f32_e32 v164, 1.0, v161
	v_fma_f32 v165, -v160, v164, 1.0
	v_fmac_f32_e32 v164, v165, v161
	v_div_fixup_f32 v153, v164, v160, 1.0
	v_mul_f32_e32 v160, 0xbfb8aa3b, v29
	v_exp_f32_e32 v163, v160
	s_nop 0
	v_pk_add_f32 v[160:161], v[162:163], 1.0 op_sel_hi:[1,0]
	s_nop 0
	v_rcp_f32_e32 v163, v161
	s_nop 0
	v_mul_f32_e32 v165, 1.0, v163
	v_fma_f32 v166, -v161, v165, 1.0
	v_fmac_f32_e32 v165, v166, v163
	v_div_fixup_f32 v164, v165, v161, 1.0
	v_rcp_f32_e32 v162, v160
	s_nop 0
	v_mul_f32_e32 v165, 1.0, v162
	v_fma_f32 v166, -v160, v165, 1.0
	v_fmac_f32_e32 v165, v166, v162
	v_div_fixup_f32 v165, v165, v160, 1.0
	v_mul_f32_e32 v161, 0xbfb8aa3b, v30
	v_mul_f32_e32 v160, 0xbfb8aa3b, v34
	v_exp_f32_e32 v162, v161
	v_mul_f32_e32 v161, 0xbfb8aa3b, v35
	v_exp_f32_e32 v160, v160
	v_exp_f32_e32 v161, v161
	s_nop 0
	v_pk_add_f32 v[160:161], v[160:161], 1.0 op_sel_hi:[1,0]
	s_nop 0
	v_rcp_f32_e32 v166, v161
	s_nop 0
	v_mul_f32_e32 v168, 1.0, v166
	v_fma_f32 v169, -v161, v168, 1.0
	v_fmac_f32_e32 v168, v169, v166
	v_div_fixup_f32 v166, v168, v161, 1.0
	v_rcp_f32_e32 v163, v160
	s_nop 0
	v_mul_f32_e32 v168, 1.0, v163
	v_fma_f32 v169, -v160, v168, 1.0
	v_fmac_f32_e32 v168, v169, v163
	v_div_fixup_f32 v167, v168, v160, 1.0
	v_mul_f32_e32 v160, 0xbfb8aa3b, v31
	v_exp_f32_e32 v163, v160
	s_nop 0
	v_pk_add_f32 v[160:161], v[162:163], 1.0 op_sel_hi:[1,0]
	s_nop 0
	v_rcp_f32_e32 v163, v161
	s_nop 0
	v_mul_f32_e32 v169, 1.0, v163
	v_fma_f32 v170, -v161, v169, 1.0
	v_fmac_f32_e32 v169, v170, v163
	v_div_fixup_f32 v163, v169, v161, 1.0
	v_rcp_f32_e32 v162, v160
	s_nop 0
	v_mul_f32_e32 v169, 1.0, v162
	v_fma_f32 v170, -v160, v169, 1.0
	v_fmac_f32_e32 v169, v170, v162
	v_div_fixup_f32 v168, v169, v160, 1.0
	v_cvt_pk_bf16_f32 v160, v153, v151
	v_cvt_pk_bf16_f32 v161, v167, v166
	v_cvt_pk_bf16_f32 v162, v165, v164
	v_cvt_pk_bf16_f32 v163, v168, v163
	v_mul_f32_e32 v151, 0xbfb8aa3b, v40
	global_store_dwordx4 v[154:155], v[160:163], off offset:256
	v_add_u32_e32 v154, 0xa0, v152
	v_ashrrev_i32_e32 v155, 31, v154
	v_exp_f32_e32 v160, v151
	v_mul_f32_e32 v151, 0xbfb8aa3b, v36
	v_exp_f32_e32 v162, v151
	v_mul_f32_e32 v151, 0xbfb8aa3b, v41
	v_exp_f32_e32 v161, v151
	v_lshlrev_b64 v[154:155], 12, v[154:155]
	v_lshl_add_u64 v[154:155], s[44:45], 0, v[154:155]
	v_lshl_add_u64 v[154:155], v[154:155], 0, v[2:3]
	v_pk_add_f32 v[160:161], v[160:161], 1.0 op_sel_hi:[1,0]
	v_add_u32_e32 v152, 0xb0, v152
	v_rcp_f32_e32 v153, v161
	s_nop 0
	v_mul_f32_e32 v164, 1.0, v153
	v_fma_f32 v165, -v161, v164, 1.0
	v_fmac_f32_e32 v164, v165, v153
	v_div_fixup_f32 v151, v164, v161, 1.0
	v_rcp_f32_e32 v161, v160
	s_nop 0
	v_mul_f32_e32 v164, 1.0, v161
	v_fma_f32 v165, -v160, v164, 1.0
	v_fmac_f32_e32 v164, v165, v161
	v_div_fixup_f32 v153, v164, v160, 1.0
	v_mul_f32_e32 v160, 0xbfb8aa3b, v37
	v_exp_f32_e32 v163, v160
	s_nop 0
	v_pk_add_f32 v[160:161], v[162:163], 1.0 op_sel_hi:[1,0]
	s_nop 0
	v_rcp_f32_e32 v163, v161
	s_nop 0
	v_mul_f32_e32 v165, 1.0, v163
	v_fma_f32 v166, -v161, v165, 1.0
	v_fmac_f32_e32 v165, v166, v163
	v_div_fixup_f32 v164, v165, v161, 1.0
	v_rcp_f32_e32 v162, v160
	s_nop 0
	v_mul_f32_e32 v165, 1.0, v162
	v_fma_f32 v166, -v160, v165, 1.0
	v_fmac_f32_e32 v165, v166, v162
	v_div_fixup_f32 v165, v165, v160, 1.0
	v_mul_f32_e32 v161, 0xbfb8aa3b, v38
	v_mul_f32_e32 v160, 0xbfb8aa3b, v42
	v_exp_f32_e32 v162, v161
	v_mul_f32_e32 v161, 0xbfb8aa3b, v43
	v_exp_f32_e32 v160, v160
	v_exp_f32_e32 v161, v161
	s_nop 0
	v_pk_add_f32 v[160:161], v[160:161], 1.0 op_sel_hi:[1,0]
	s_nop 0
	v_rcp_f32_e32 v166, v161
	s_nop 0
	v_mul_f32_e32 v168, 1.0, v166
	v_fma_f32 v169, -v161, v168, 1.0
	v_fmac_f32_e32 v168, v169, v166
	v_div_fixup_f32 v166, v168, v161, 1.0
	v_rcp_f32_e32 v163, v160
	s_nop 0
	v_mul_f32_e32 v168, 1.0, v163
	v_fma_f32 v169, -v160, v168, 1.0
	v_fmac_f32_e32 v168, v169, v163
	v_div_fixup_f32 v167, v168, v160, 1.0
	v_mul_f32_e32 v160, 0xbfb8aa3b, v39
	v_exp_f32_e32 v163, v160
	s_nop 0
	v_pk_add_f32 v[160:161], v[162:163], 1.0 op_sel_hi:[1,0]
	s_nop 0
	v_rcp_f32_e32 v163, v161
	s_nop 0
	v_mul_f32_e32 v169, 1.0, v163
	v_fma_f32 v170, -v161, v169, 1.0
	v_fmac_f32_e32 v169, v170, v163
	v_div_fixup_f32 v163, v169, v161, 1.0
	v_rcp_f32_e32 v162, v160
	s_nop 0
	v_mul_f32_e32 v169, 1.0, v162
	v_fma_f32 v170, -v160, v169, 1.0
	v_fmac_f32_e32 v169, v170, v162
	v_div_fixup_f32 v168, v169, v160, 1.0
	v_cvt_pk_bf16_f32 v160, v153, v151
	v_cvt_pk_bf16_f32 v161, v167, v166
	v_cvt_pk_bf16_f32 v162, v165, v164
	v_cvt_pk_bf16_f32 v163, v168, v163
	v_mul_f32_e32 v151, 0xbfb8aa3b, v16
	global_store_dwordx4 v[154:155], v[160:163], off
	s_nop 1
	v_exp_f32_e32 v160, v151
	v_mul_f32_e32 v151, 0xbfb8aa3b, v12
	v_exp_f32_e32 v162, v151
	v_mul_f32_e32 v151, 0xbfb8aa3b, v17
	v_exp_f32_e32 v161, v151
	s_nop 0
	v_pk_add_f32 v[160:161], v[160:161], 1.0 op_sel_hi:[1,0]
	s_nop 0
	v_rcp_f32_e32 v153, v161
	s_nop 0
	v_mul_f32_e32 v164, 1.0, v153
	v_fma_f32 v165, -v161, v164, 1.0
	v_fmac_f32_e32 v164, v165, v153
	v_div_fixup_f32 v151, v164, v161, 1.0
	v_rcp_f32_e32 v161, v160
	s_nop 0
	v_mul_f32_e32 v164, 1.0, v161
	v_fma_f32 v165, -v160, v164, 1.0
	v_fmac_f32_e32 v164, v165, v161
	v_div_fixup_f32 v153, v164, v160, 1.0
	v_mul_f32_e32 v160, 0xbfb8aa3b, v13
	v_exp_f32_e32 v163, v160
	s_nop 0
; DI unsigned pk2(float lo, float hi) { f32x2 v = {lo, hi}; bf2_t b = __builtin_convertvector(v, bf2_t); return __builtin_bit_cast(unsigned, b); }
; #define EPI_LOOP_PERM(...) _Pragma("unroll") for (int ai = 0; ai < 2; ++ai) _Pragma("unroll") for (int m = 0; m < 4; ++m) { const int row = u.pm * 256 + ai * 128 + wr * 64 + m * 16 + fr; \
;     _Pragma("unroll") for (int bj = 0; bj < 2; ++bj) { const int c8 = bj * 128 + wc * 32 + 8 * fq; f32x4 v0 = acc[ai][bj][m][0], v1 = acc[ai][bj][m][1]; __VA_ARGS__ } }
; DI u32x4 pack44(f32x4 a, f32x4 b) { u32x4 w; w.x = pk2(a[0], a[1]); w.y = pk2(a[2], a[3]); w.z = pk2(b[0], b[1]); w.w = pk2(b[2], b[3]); return w; }
; DI float sigmoidf_(float x) { return 1.f / (1.f + __expf(-x)); }
;     DI void operator()(const Acc& acc, const Unit& u, int wr, int wc, int fr, int fq) const {
;     ...
;         } else if (pn < 36) {
;             bf16_t* dst = pn < 28 ? sgs + (pn - 20) * 256 : sgg + (pn - 28) * 256;
;             EPI_LOOP_PERM({ for (int j = 0; j < 4; ++j) { v0[j] = sigmoidf_(v0[j]); v1[j] = sigmoidf_(v1[j]); } *(u32x4*)(dst + (size_t)row * 2048 + c8) = pack44(v0, v1); })
	v_pk_add_f32 v[160:161], v[162:163], 1.0 op_sel_hi:[1,0]
	s_nop 0
	v_rcp_f32_e32 v163, v161
	s_nop 0
	v_mul_f32_e32 v165, 1.0, v163
	v_fma_f32 v166, -v161, v165, 1.0
	v_fmac_f32_e32 v165, v166, v163
	v_div_fixup_f32 v164, v165, v161, 1.0
	v_rcp_f32_e32 v162, v160
	s_nop 0
	v_mul_f32_e32 v165, 1.0, v162
	v_fma_f32 v166, -v160, v165, 1.0
	v_fmac_f32_e32 v165, v166, v162
	v_div_fixup_f32 v165, v165, v160, 1.0
	v_mul_f32_e32 v161, 0xbfb8aa3b, v14
	v_mul_f32_e32 v160, 0xbfb8aa3b, v18
	v_exp_f32_e32 v162, v161
	v_mul_f32_e32 v161, 0xbfb8aa3b, v19
	v_exp_f32_e32 v160, v160
	v_exp_f32_e32 v161, v161
	s_nop 0
	v_pk_add_f32 v[160:161], v[160:161], 1.0 op_sel_hi:[1,0]
	s_nop 0
	v_rcp_f32_e32 v166, v161
	s_nop 0
	v_mul_f32_e32 v168, 1.0, v166
	v_fma_f32 v169, -v161, v168, 1.0
	v_fmac_f32_e32 v168, v169, v166
	v_div_fixup_f32 v166, v168, v161, 1.0
	v_rcp_f32_e32 v163, v160
	s_nop 0
	v_mul_f32_e32 v168, 1.0, v163
	v_fma_f32 v169, -v160, v168, 1.0
	v_fmac_f32_e32 v168, v169, v163
	v_div_fixup_f32 v167, v168, v160, 1.0
	v_mul_f32_e32 v160, 0xbfb8aa3b, v15
	v_exp_f32_e32 v163, v160
	s_nop 0
	v_pk_add_f32 v[160:161], v[162:163], 1.0 op_sel_hi:[1,0]
	s_nop 0
	v_rcp_f32_e32 v163, v161
	s_nop 0
	v_mul_f32_e32 v169, 1.0, v163
	v_fma_f32 v170, -v161, v169, 1.0
	v_fmac_f32_e32 v169, v170, v163
	v_div_fixup_f32 v163, v169, v161, 1.0
	v_rcp_f32_e32 v162, v160
	s_nop 0
	v_mul_f32_e32 v169, 1.0, v162
	v_fma_f32 v170, -v160, v169, 1.0
	v_fmac_f32_e32 v169, v170, v162
	v_div_fixup_f32 v168, v169, v160, 1.0
	v_cvt_pk_bf16_f32 v160, v153, v151
	v_cvt_pk_bf16_f32 v161, v167, v166
	v_cvt_pk_bf16_f32 v162, v165, v164
	v_cvt_pk_bf16_f32 v163, v168, v163
	v_mul_f32_e32 v151, 0xbfb8aa3b, v24
	global_store_dwordx4 v[154:155], v[160:163], off offset:256
	v_exp_f32_e32 v154, v151
	v_mul_f32_e32 v151, 0xbfb8aa3b, v20
	v_exp_f32_e32 v160, v151
	v_mul_f32_e32 v151, 0xbfb8aa3b, v25
	v_exp_f32_e32 v155, v151
	v_ashrrev_i32_e32 v153, 31, v152
	v_lshlrev_b64 v[152:153], 12, v[152:153]
	v_lshl_add_u64 v[152:153], s[44:45], 0, v[152:153]
	v_pk_add_f32 v[154:155], v[154:155], 1.0 op_sel_hi:[1,0]
	v_lshl_add_u64 v[152:153], v[152:153], 0, v[2:3]
	v_rcp_f32_e32 v161, v155
	s_nop 0
	v_mul_f32_e32 v2, 0xbfb8aa3b, v8
	v_mul_f32_e32 v163, 1.0, v161
	v_fma_f32 v164, -v155, v163, 1.0
	v_fmac_f32_e32 v163, v164, v161
	v_div_fixup_f32 v151, v163, v155, 1.0
	v_rcp_f32_e32 v161, v154
	s_nop 0
	v_mul_f32_e32 v163, 1.0, v161
	v_fma_f32 v164, -v154, v163, 1.0
	v_fmac_f32_e32 v163, v164, v161
	v_div_fixup_f32 v162, v163, v154, 1.0
	v_mul_f32_e32 v154, 0xbfb8aa3b, v21
	v_exp_f32_e32 v161, v154
	s_nop 0
	v_pk_add_f32 v[154:155], v[160:161], 1.0 op_sel_hi:[1,0]
	s_nop 0
	v_rcp_f32_e32 v161, v155
	s_nop 0
	v_mul_f32_e32 v164, 1.0, v161
	v_fma_f32 v165, -v155, v164, 1.0
	v_fmac_f32_e32 v164, v165, v161
	v_div_fixup_f32 v163, v164, v155, 1.0
	v_rcp_f32_e32 v160, v154
	s_nop 0
	v_mul_f32_e32 v164, 1.0, v160
	v_fma_f32 v165, -v154, v164, 1.0
	v_fmac_f32_e32 v164, v165, v160
	v_div_fixup_f32 v164, v164, v154, 1.0
	v_mul_f32_e32 v155, 0xbfb8aa3b, v22
	v_mul_f32_e32 v154, 0xbfb8aa3b, v26
	v_exp_f32_e32 v160, v155
	v_mul_f32_e32 v155, 0xbfb8aa3b, v27
	v_exp_f32_e32 v154, v154
	v_exp_f32_e32 v155, v155
	s_nop 0
	v_pk_add_f32 v[154:155], v[154:155], 1.0 op_sel_hi:[1,0]
	s_nop 0
	v_rcp_f32_e32 v165, v155
	s_nop 0
	v_mul_f32_e32 v167, 1.0, v165
	v_fma_f32 v168, -v155, v167, 1.0
	v_fmac_f32_e32 v167, v168, v165
	v_div_fixup_f32 v165, v167, v155, 1.0
	v_rcp_f32_e32 v161, v154
	s_nop 0
	v_mul_f32_e32 v167, 1.0, v161
	v_fma_f32 v168, -v154, v167, 1.0
	v_fmac_f32_e32 v167, v168, v161
	v_div_fixup_f32 v166, v167, v154, 1.0
	v_mul_f32_e32 v154, 0xbfb8aa3b, v23
	v_exp_f32_e32 v161, v154
	s_nop 0
	v_pk_add_f32 v[154:155], v[160:161], 1.0 op_sel_hi:[1,0]
	s_nop 0
	v_rcp_f32_e32 v161, v155
	s_nop 0
	v_mul_f32_e32 v168, 1.0, v161
	v_fma_f32 v169, -v155, v168, 1.0
	v_fmac_f32_e32 v168, v169, v161
	v_div_fixup_f32 v155, v168, v155, 1.0
	v_rcp_f32_e32 v161, v154
	s_nop 0
	v_mul_f32_e32 v168, 1.0, v161
	v_fma_f32 v169, -v154, v168, 1.0
	v_fmac_f32_e32 v168, v169, v161
	v_div_fixup_f32 v154, v168, v154, 1.0
	v_cvt_pk_bf16_f32 v160, v162, v151
	v_cvt_pk_bf16_f32 v161, v166, v165
	v_cvt_pk_bf16_f32 v162, v164, v163
	v_cvt_pk_bf16_f32 v163, v154, v155
	v_exp_f32_e32 v154, v2
	v_mul_f32_e32 v2, 0xbfb8aa3b, v4
	global_store_dwordx4 v[152:153], v[160:163], off
	s_nop 1
	v_exp_f32_e32 v160, v2
	v_mul_f32_e32 v2, 0xbfb8aa3b, v9
	v_exp_f32_e32 v155, v2
	s_nop 0
	v_pk_add_f32 v[154:155], v[154:155], 1.0 op_sel_hi:[1,0]
	s_nop 0
	v_rcp_f32_e32 v151, v155
	s_nop 0
	v_mul_f32_e32 v162, 1.0, v151
	v_fma_f32 v163, -v155, v162, 1.0
	v_fmac_f32_e32 v162, v163, v151
	v_div_fixup_f32 v2, v162, v155, 1.0
	v_rcp_f32_e32 v155, v154
	s_nop 0
	v_mul_f32_e32 v162, 1.0, v155
	v_fma_f32 v163, -v154, v162, 1.0
	v_fmac_f32_e32 v162, v163, v155
	v_div_fixup_f32 v151, v162, v154, 1.0
	v_mul_f32_e32 v154, 0xbfb8aa3b, v5
	v_exp_f32_e32 v161, v154
	s_nop 0
	v_pk_add_f32 v[154:155], v[160:161], 1.0 op_sel_hi:[1,0]
	s_nop 0
	v_rcp_f32_e32 v161, v155
	s_nop 0
	v_mul_f32_e32 v163, 1.0, v161
	v_fma_f32 v164, -v155, v163, 1.0
	v_fmac_f32_e32 v163, v164, v161
	v_div_fixup_f32 v162, v163, v155, 1.0
	v_rcp_f32_e32 v160, v154
	s_nop 0
	v_mul_f32_e32 v163, 1.0, v160
	v_fma_f32 v164, -v154, v163, 1.0
	v_fmac_f32_e32 v163, v164, v160
	v_div_fixup_f32 v163, v163, v154, 1.0
	v_mul_f32_e32 v155, 0xbfb8aa3b, v6
	v_mul_f32_e32 v154, 0xbfb8aa3b, v10
	v_exp_f32_e32 v160, v155
	v_mul_f32_e32 v155, 0xbfb8aa3b, v11
	v_exp_f32_e32 v154, v154
	v_exp_f32_e32 v155, v155
	v_cvt_pk_bf16_f32 v162, v163, v162
	v_pk_add_f32 v[154:155], v[154:155], 1.0 op_sel_hi:[1,0]
	s_nop 0
	v_rcp_f32_e32 v164, v155
	s_nop 0
	v_mul_f32_e32 v166, 1.0, v164
	v_fma_f32 v167, -v155, v166, 1.0
	v_fmac_f32_e32 v166, v167, v164
	v_div_fixup_f32 v164, v166, v155, 1.0
	v_rcp_f32_e32 v161, v154
	s_nop 0
	v_mul_f32_e32 v166, 1.0, v161
	v_fma_f32 v167, -v154, v166, 1.0
	v_fmac_f32_e32 v166, v167, v161
	v_div_fixup_f32 v165, v166, v154, 1.0
	v_mul_f32_e32 v154, 0xbfb8aa3b, v7
	v_exp_f32_e32 v161, v154
	s_nop 0
	v_pk_add_f32 v[154:155], v[160:161], 1.0 op_sel_hi:[1,0]
	s_nop 0
	v_rcp_f32_e32 v161, v155
	s_nop 0
	v_mul_f32_e32 v167, 1.0, v161
	v_fma_f32 v168, -v155, v167, 1.0
	v_fmac_f32_e32 v167, v168, v161
	v_div_fixup_f32 v155, v167, v155, 1.0
	v_rcp_f32_e32 v161, v154
	s_nop 0
	v_mul_f32_e32 v167, 1.0, v161
	v_fma_f32 v168, -v154, v167, 1.0
	v_fmac_f32_e32 v167, v168, v161
	v_div_fixup_f32 v154, v167, v154, 1.0
	v_cvt_pk_bf16_f32 v160, v151, v2
	v_cvt_pk_bf16_f32 v161, v165, v164
	v_cvt_pk_bf16_f32 v163, v154, v155
	global_store_dwordx4 v[152:153], v[160:163], off offset:256

; DI void phase_s5pre(LAS unsigned char* lds, PP p, int l, int bid, int nblk) {
;     ...
;         for (int id = tid; id < 1024; id += NTHR) { const int pp = id >> 4, hi = id & 15;
;             const float lr = p->in[5][(l * 64 + g) * 64 + pp], li = p->in[6][(l * 64 + g) * 64 + pp];
;             const float mg = expf(lr * dt), an = li * dt; float sn, cs; sincosf(an, &sn, &cs); const float nr = mg * cs - 1.0f, ni = mg * sn, den = lr * lr + li * li;
;             const float fr = (nr * lr + ni * li) / den, fi = (ni * lr - nr * li) / den;
;             const size_t bo = ((size_t)(l * 64 + g) * 64 + pp) * 16 + hi; const float br = p->in[8][bo], bi = p->in[9][bo];
;             bbr[id] = fr * br - fi * bi; bbi[id] = fr * bi + fi * br;
;             const int ho = id >> 6, p2 = id & 63; const size_t co = ((size_t)(l * 64 + g) * 16 + ho) * 64 + p2;
;             ccr[id] = p->in[10][co]; cci[id] = p->in[11][co]; }
.LBB0_1285:
	s_or_b64 exec, exec, s[34:35]
	v_ashrrev_i32_e32 v9, 31, v8
	v_lshl_add_u64 v[8:9], v[8:9], 4, v[4:5]
	v_lshlrev_b64 v[8:9], 2, v[8:9]
	v_lshl_add_u64 v[30:31], s[48:49], 0, v[8:9]
	v_lshl_add_u64 v[8:9], s[50:51], 0, v[8:9]
	global_load_dword v35, v[8:9], off
	v_ashrrev_i32_e32 v8, 6, v11
	v_ashrrev_i32_e32 v9, 31, v8
	v_lshlrev_b64 v[8:9], 6, v[8:9]
	global_load_dword v34, v[30:31], off
	v_lshl_add_u64 v[8:9], v[8:9], 0, v[6:7]
	v_lshlrev_b64 v[8:9], 2, v[8:9]
	v_lshl_add_u64 v[30:31], s[52:53], 0, v[8:9]
	v_lshl_add_u64 v[8:9], s[54:55], 0, v[8:9]
	global_load_dword v30, v[30:31], off
	s_waitcnt vmcnt(3)
	v_mul_f32_e32 v23, v16, v19
	global_load_dword v8, v[8:9], off
	v_mul_f32_e32 v29, 0x3fb8aa3b, v23
	v_fma_f32 v32, v23, s13, -v29
	v_rndne_f32_e32 v33, v29
	v_fmac_f32_e32 v32, 0x32a5705f, v23
	v_sub_f32_e32 v9, v29, v33
	v_add_f32_e32 v9, v9, v32
	v_exp_f32_e32 v9, v9
	v_cvt_i32_f32_e32 v29, v33
	v_cmp_ngt_f32_e32 vcc, s15, v23
	v_xor_b32_e32 v21, v21, v20
	v_ldexp_f32 v9, v9, v29
	v_cndmask_b32_e32 v9, 0, v9, vcc
	v_cmp_nlt_f32_e32 vcc, s16, v23
	v_mul_f32_e32 v23, v2, v2
	v_fmamk_f32 v29, v23, 0xb94c1982, v218
	v_fmaak_f32 v29, v23, v29, 0xbe2aaa9d
	v_mul_f32_e32 v29, v23, v29
	v_fmac_f32_e32 v2, v2, v29
	v_fmamk_f32 v29, v23, 0x37d75334, v219
	v_fmaak_f32 v29, v23, v29, 0x3d2aabf7
	v_fmaak_f32 v29, v23, v29, 0xbf000004
	v_fma_f32 v23, v23, v29, 1.0
	v_lshlrev_b32_e32 v29, 30, v22
	v_and_b32_e32 v22, 1, v22
	v_cndmask_b32_e32 v9, v223, v9, vcc
	v_cmp_eq_u32_e32 vcc, 0, v22
	v_and_b32_e32 v31, 0x80000000, v29
	s_nop 0
	v_cndmask_b32_e32 v22, v23, v2, vcc
	v_xor_b32_e32 v2, 0x80000000, v2
	v_xor_b32_e32 v21, v21, v22
	v_cndmask_b32_e32 v2, v2, v23, vcc
	v_xor_b32_e32 v21, v21, v31
	v_bitop3_b32 v2, v2, v29, s81 bitop3:0x78
	v_cmp_class_f32_e64 vcc, v20, s11
	s_nop 1
	v_cndmask_b32_e32 v2, v226, v2, vcc
	v_cndmask_b32_e32 v20, v226, v21, vcc
	v_fma_f32 v2, v9, v2, -1.0
	v_mul_f32_e32 v9, v9, v20
	v_mul_f32_e32 v20, v18, v18
	v_mul_f32_e32 v21, v18, v9
	v_fmac_f32_e32 v20, v19, v19
	v_fmac_f32_e32 v21, v19, v2
	v_div_scale_f32 v22, s[34:35], v20, v20, v21
	v_rcp_f32_e32 v23, v22
	v_mul_f32_e32 v2, v18, v2
	v_fma_f32 v2, v19, v9, -v2
	v_fma_f32 v29, -v22, v23, 1.0
	v_fmac_f32_e32 v23, v29, v23
	v_div_scale_f32 v29, vcc, v21, v20, v21
	v_mul_f32_e32 v31, v29, v23
	v_fma_f32 v32, -v22, v31, v29
	v_rcp_f32_e32 v18, v20
	s_nop 0
	v_fmac_f32_e32 v31, v32, v23
	v_fma_f32 v22, -v22, v31, v29
	v_div_fmas_f32 v19, v22, v23, v31
	v_div_fixup_f32 v19, v19, v20, v21
	v_mul_f32_e32 v22, v2, v18
	v_fma_f32 v23, -v20, v22, v2
	v_fmac_f32_e32 v22, v23, v18
	v_div_fixup_f32 v2, v22, v20, v2
	s_waitcnt vmcnt(3)
	v_mul_f32_e32 v9, v35, v2
	s_waitcnt vmcnt(2)
	v_mul_f32_e32 v2, v34, v2
	v_fma_f32 v9, v34, v19, -v9
	v_fmac_f32_e32 v2, v35, v19
	ds_write2st64_b32 v10, v9, v2 offset1:16
	s_waitcnt vmcnt(0)
	ds_write2st64_b32 v10, v30, v8 offset0:32 offset1:48
	v_add_u32_e32 v2, 0x200, v11
	v_cmp_lt_i32_e32 vcc, s74, v11
	v_add_u32_e32 v10, 0x800, v10
	s_or_b64 s[58:59], vcc, s[58:59]
	v_mov_b32_e32 v11, v2
	s_andn2_b64 exec, exec, s[58:59]
	s_cbranch_execz .LBB0_1290
